# load-segment SALU diet: redundant s_nop after m0 writes removed where the scalar address sum already provides the wait state
# speedup vs baseline: 1.0053x; 1.0053x over previous
; #define G_STAGE(bufoff, gbase, o0, h64) do { \
;         __builtin_amdgcn_global_load_lds((const unsigned*)((const char*)(gbase) + (o0)), (LAS unsigned*)(lds + (bufoff) + ldsw), 16, 0, 0); \
;         __builtin_amdgcn_global_load_lds((const unsigned*)((const char*)(gbase) + (h64) + (o0)), (LAS unsigned*)(lds + (bufoff) + ldsw + 8192), 16, 0, 0); } while (0)
; #define G_LDA(dst, b, h) do { _Pragma("unroll") for (int m = 0; m < 4; ++m) _Pragma("unroll") for (int k = 0; k < 2; ++k) dst[m][k] = *(const LAS bf16x8*)(lds + G_SA(b, h) + aoff + m * 2048 + k * 1024); } while (0)
; #define G_LDB(dst, b, h) do { _Pragma("unroll") for (int n = 0; n < 2; ++n) _Pragma("unroll") for (int k = 0; k < 2; ++k) dst[n][k] = *(const LAS bf16x8*)(lds + G_SB(b, h) + boff + n * 2048 + k * 1024); } while (0)
; #define G_WAIT_L(n) asm volatile("s_waitcnt lgkmcnt(" #n ")" ::: "memory")
; #define G_BAR __builtin_amdgcn_s_barrier()
; #define G_SCHED __builtin_amdgcn_sched_barrier(0)
;     ...
;         for (int t = 0; t < nt; t += 2) {
;             const bool last = (t == nt - 2);
;             const char* a1 = cA + (size_t)(t + 1) * ckA;
;             const char* a2 = last ? nA : cA + (size_t)(t + 2) * ckA; const char* b2 = last ? nB : cB + (size_t)(t + 2) * kB;
;             const char* a3 = a2 + ckA; const char* b3 = b2 + kB;
;             G_LDB(B0, 0, 0); G_SCHED; G_LDA(At, 0, 0); G_STAGE(G_SA(1, 1), a1 + chA, cA0, qA);
;             G_WAIT_L(8); G_BAR; G_WAIT_L(0); G_MMA(0, 0, At, B0); G_BAR; G_SCHED;
;             G_LDB(B1, 0, 1); G_STAGE(G_SB(0, 0), b2, cB0, qB);
;             G_BAR; G_WAIT_L(0); G_MMA(0, 1, At, B1); G_BAR;
;             G_LDA(At, 0, 1); G_STAGE(G_SA(0, 0), a2, cA0, qA);
;             G_BAR; G_WAIT_L(0); G_MMA(1, 0, At, B0); G_BAR; G_SCHED;
.LBB0_211:
	s_add_u32 s2, s2, 0x40080
	s_addc_u32 s3, s3, 0
	s_add_u32 s7, s22, 0x100
	s_addc_u32 s22, s23, 0
	s_mov_b32 s23, -2
	s_mov_b64 s[52:53], 0x40000
	s_mov_b64 s[54:55], 0x60000
	s_mov_b64 s[58:59], 0x20080
	s_mov_b64 s[62:63], 0x40080
	s_mov_b64 s[64:65], 0x60080
	s_cmp_eq_u32 s101, 2
	s_cselect_b32 s101, 0, s101
	s_setprio 0
	v_add_u32_e32 v255, 0x10000, v167
	s_add_u32 s4, s2, 0xfffc0080
	s_addc_u32 s5, s3, -1
	s_add_i32 s41, 0, 0x10000
	ds_read_b128 v[136:139], v255 offset:0
	ds_read_b128 v[144:147], v255 offset:1024
	ds_read_b128 v[148:151], v255 offset:2048
	ds_read_b128 v[152:155], v255 offset:3072
	s_cmp_eq_u32 s23, 12
	s_cselect_b32 s43, s19, s5
	s_cselect_b32 s42, s18, s4
	s_cselect_b32 s51, s21, s22
	s_cselect_b32 s50, s20, s7
	s_add_i32 m0, s27, 0xc000
	ds_read_b128 v[156:159], v172
	ds_read_b128 v[160:163], v172 offset:1024
	ds_read_b128 v[174:177], v172 offset:2048
	ds_read_b128 v[178:181], v172 offset:3072
	ds_read_b128 v[182:185], v172 offset:4096
	ds_read_b128 v[196:199], v172 offset:5120
	ds_read_b128 v[200:203], v172 offset:6144
	ds_read_b128 v[204:207], v172 offset:7168
	global_load_lds_dwordx4 v142, s[2:3]
	s_add_i32 m0, s27, 0xe000
	s_add_u32 vcc_lo, s2, s0
	s_addc_u32 vcc_hi, s3, s1
	global_load_lds_dwordx4 v142, vcc
	s_waitcnt lgkmcnt(8)
	s_cmp_eq_u32 s101, 1
	s_cbranch_scc1 .Ldb_WIN_skp
	s_barrier
.Ldb_WIN_skp:
	s_mov_b32 s101, 0
	s_waitcnt lgkmcnt(0)
	v_mfma_f32_16x16x32_bf16 v[132:135], v[136:139], v[156:159], 0
	v_mfma_f32_16x16x32_bf16 v[128:131], v[148:151], v[156:159], 0
	v_mfma_f32_16x16x32_bf16 v[116:119], v[136:139], v[174:177], 0
	v_mfma_f32_16x16x32_bf16 v[112:115], v[148:151], v[174:177], 0
	v_mfma_f32_16x16x32_bf16 v[100:103], v[136:139], v[182:185], 0
	v_mfma_f32_16x16x32_bf16 v[96:99], v[148:151], v[182:185], 0
	v_mfma_f32_16x16x32_bf16 v[84:87], v[136:139], v[200:203], 0
	v_mfma_f32_16x16x32_bf16 v[80:83], v[148:151], v[200:203], 0
	v_mfma_f32_16x16x32_bf16 v[132:135], v[144:147], v[160:163], v[132:135]
	v_mfma_f32_16x16x32_bf16 v[128:131], v[152:155], v[160:163], v[128:131]
	v_mfma_f32_16x16x32_bf16 v[116:119], v[144:147], v[178:181], v[116:119]
	v_mfma_f32_16x16x32_bf16 v[112:115], v[152:155], v[178:181], v[112:115]
	v_mfma_f32_16x16x32_bf16 v[100:103], v[144:147], v[196:199], v[100:103]
	v_mfma_f32_16x16x32_bf16 v[96:99], v[152:155], v[196:199], v[96:99]
	v_mfma_f32_16x16x32_bf16 v[84:87], v[144:147], v[204:207], v[84:87]
	v_mfma_f32_16x16x32_bf16 v[80:83], v[152:155], v[204:207], v[80:83]
	s_barrier
	s_add_i32 s4, 0, 0x14000
	s_add_i32 s5, s41, s26
	s_mov_b32 m0, s5
	ds_read_b128 v[208:211], v255 offset:16384
	ds_read_b128 v[212:215], v255 offset:17408
	ds_read_b128 v[216:219], v255 offset:18432
	ds_read_b128 v[220:223], v255 offset:19456
	global_load_lds_dwordx4 v140, s[50:51]
	s_add_i32 m0, s5, 0x2000
	s_add_u32 vcc_lo, s50, s0
	s_addc_u32 vcc_hi, s51, s1
	global_load_lds_dwordx4 v140, vcc
	s_barrier
	s_waitcnt lgkmcnt(0)
	v_mfma_f32_16x16x32_bf16 v[124:127], v[208:211], v[156:159], 0
	v_mfma_f32_16x16x32_bf16 v[120:123], v[216:219], v[156:159], 0
	v_mfma_f32_16x16x32_bf16 v[108:111], v[208:211], v[174:177], 0
	v_mfma_f32_16x16x32_bf16 v[104:107], v[216:219], v[174:177], 0
	v_mfma_f32_16x16x32_bf16 v[92:95], v[208:211], v[182:185], 0
	v_mfma_f32_16x16x32_bf16 v[88:91], v[216:219], v[182:185], 0
	v_mfma_f32_16x16x32_bf16 v[76:79], v[208:211], v[200:203], 0
	v_mfma_f32_16x16x32_bf16 v[72:75], v[216:219], v[200:203], 0
	v_mfma_f32_16x16x32_bf16 v[124:127], v[212:215], v[160:163], v[124:127]
	v_mfma_f32_16x16x32_bf16 v[120:123], v[220:223], v[160:163], v[120:123]
	v_mfma_f32_16x16x32_bf16 v[108:111], v[212:215], v[178:181], v[108:111]
	v_mfma_f32_16x16x32_bf16 v[104:107], v[220:223], v[178:181], v[104:107]
	v_mfma_f32_16x16x32_bf16 v[92:95], v[212:215], v[196:199], v[92:95]
	v_mfma_f32_16x16x32_bf16 v[88:91], v[220:223], v[196:199], v[88:91]
	v_mfma_f32_16x16x32_bf16 v[76:79], v[212:215], v[204:207], v[76:79]
	v_mfma_f32_16x16x32_bf16 v[72:75], v[220:223], v[204:207], v[72:75]
	s_barrier
	s_mov_b32 m0, s27
	ds_read_b128 v[156:159], v172 offset:16384
	ds_read_b128 v[160:163], v172 offset:17408
	ds_read_b128 v[174:177], v172 offset:18432
	ds_read_b128 v[178:181], v172 offset:19456
	ds_read_b128 v[182:185], v172 offset:20480
	ds_read_b128 v[196:199], v172 offset:21504
	ds_read_b128 v[200:203], v172 offset:22528
	ds_read_b128 v[204:207], v172 offset:23552
	global_load_lds_dwordx4 v2, s[42:43]
	s_mov_b32 m0, s28
	s_add_u32 vcc_lo, s42, s0
	s_addc_u32 vcc_hi, s43, s1
	global_load_lds_dwordx4 v2, vcc
	s_barrier
	s_waitcnt lgkmcnt(0)
	v_mfma_f32_16x16x32_bf16 v[68:71], v[136:139], v[156:159], 0
	v_mfma_f32_16x16x32_bf16 v[64:67], v[148:151], v[156:159], 0
	v_mfma_f32_16x16x32_bf16 v[52:55], v[136:139], v[174:177], 0
	v_mfma_f32_16x16x32_bf16 v[48:51], v[148:151], v[174:177], 0
	v_mfma_f32_16x16x32_bf16 v[36:39], v[136:139], v[182:185], 0
	v_mfma_f32_16x16x32_bf16 v[32:35], v[148:151], v[182:185], 0
	v_mfma_f32_16x16x32_bf16 v[20:23], v[136:139], v[200:203], 0
	v_mfma_f32_16x16x32_bf16 v[16:19], v[148:151], v[200:203], 0
	v_mfma_f32_16x16x32_bf16 v[68:71], v[144:147], v[160:163], v[68:71]
	v_mfma_f32_16x16x32_bf16 v[64:67], v[152:155], v[160:163], v[64:67]
	v_mfma_f32_16x16x32_bf16 v[52:55], v[144:147], v[178:181], v[52:55]
	v_mfma_f32_16x16x32_bf16 v[48:51], v[152:155], v[178:181], v[48:51]
	v_mfma_f32_16x16x32_bf16 v[36:39], v[144:147], v[196:199], v[36:39]
	v_mfma_f32_16x16x32_bf16 v[32:35], v[152:155], v[196:199], v[32:35]
	v_mfma_f32_16x16x32_bf16 v[20:23], v[144:147], v[204:207], v[20:23]
	v_mfma_f32_16x16x32_bf16 v[16:19], v[152:155], v[204:207], v[16:19]
	s_barrier
; #define G_STAGE(bufoff, gbase, o0, h64) do { \
;         __builtin_amdgcn_global_load_lds((const unsigned*)((const char*)(gbase) + (o0)), (LAS unsigned*)(lds + (bufoff) + ldsw), 16, 0, 0); \
;         __builtin_amdgcn_global_load_lds((const unsigned*)((const char*)(gbase) + (h64) + (o0)), (LAS unsigned*)(lds + (bufoff) + ldsw + 8192), 16, 0, 0); } while (0)
; #define G_LDA(dst, b, h) do { _Pragma("unroll") for (int m = 0; m < 4; ++m) _Pragma("unroll") for (int k = 0; k < 2; ++k) dst[m][k] = *(const LAS bf16x8*)(lds + G_SA(b, h) + aoff + m * 2048 + k * 1024); } while (0)
; #define G_LDB(dst, b, h) do { _Pragma("unroll") for (int n = 0; n < 2; ++n) _Pragma("unroll") for (int k = 0; k < 2; ++k) dst[n][k] = *(const LAS bf16x8*)(lds + G_SB(b, h) + boff + n * 2048 + k * 1024); } while (0)
; #define G_WAIT_V(n) asm volatile("s_waitcnt vmcnt(" #n ")" ::: "memory")
; #define G_BAR __builtin_amdgcn_s_barrier()
;     ...
;         for (int t = 0; t < nt; t += 2) {
;             const bool last = (t == nt - 2);
;             const char* a1 = cA + (size_t)(t + 1) * ckA;
;             const char* a2 = last ? nA : cA + (size_t)(t + 2) * ckA; const char* b2 = last ? nB : cB + (size_t)(t + 2) * kB;
;             const char* a3 = a2 + ckA; const char* b3 = b2 + kB;
;             G_LDB(B0, 0, 0); G_SCHED; G_LDA(At, 0, 0); G_STAGE(G_SA(1, 1), a1 + chA, cA0, qA);
;             G_WAIT_L(8); G_BAR; G_WAIT_L(0); G_MMA(0, 0, At, B0); G_BAR; G_SCHED;
;             G_LDB(B1, 0, 1); G_STAGE(G_SB(0, 0), b2, cB0, qB);
;             G_BAR; G_WAIT_L(0); G_MMA(0, 1, At, B1); G_BAR;
;             G_LDA(At, 0, 1); G_STAGE(G_SA(0, 0), a2, cA0, qA);
;             G_BAR; G_WAIT_L(0); G_MMA(1, 0, At, B0); G_BAR; G_SCHED;
;             G_STAGE(G_SB(0, 1), b2 + chB, cB0, qB);
;             G_WAIT_V(6); G_BAR; G_MMA(1, 1, At, B1); G_BAR;
;             G_LDB(B0, 1, 0); G_SCHED; G_LDA(At, 1, 0); G_STAGE(G_SA(0, 1), a2 + chA, cA0, qA);
;             G_WAIT_L(8); G_BAR; G_WAIT_L(0); G_MMA(0, 0, At, B0); G_BAR; G_SCHED;
;             G_LDB(B1, 1, 1); G_STAGE(G_SB(1, 0), b3, cB0, qB);
;             G_BAR; G_WAIT_L(0); G_MMA(0, 1, At, B1); G_BAR;
;             G_LDA(At, 1, 1); G_STAGE(G_SA(1, 0), a3, cA0, qA);
;             G_BAR; G_WAIT_L(0); G_MMA(1, 0, At, B0); G_BAR; G_SCHED;
;             G_STAGE(G_SB(1, 1), b3 + chB, cB0, qB);
;             G_WAIT_V(6); G_BAR; G_MMA(1, 1, At, B1); G_BAR;
	s_add_i32 s4, s4, s26
	s_mov_b32 m0, s4
	s_add_u32 vcc_lo, s50, s52
	s_addc_u32 vcc_hi, s51, s53
	global_load_lds_dwordx4 v140, vcc
	s_add_i32 m0, s4, 0x2000
	s_add_u32 vcc_lo, s50, s54
	s_addc_u32 vcc_hi, s51, s55
	global_load_lds_dwordx4 v140, vcc
	s_waitcnt vmcnt(6)
	s_barrier
	v_mfma_f32_16x16x32_bf16 v[60:63], v[208:211], v[156:159], 0
	v_mfma_f32_16x16x32_bf16 v[56:59], v[216:219], v[156:159], 0
	v_mfma_f32_16x16x32_bf16 v[44:47], v[208:211], v[174:177], 0
	v_mfma_f32_16x16x32_bf16 v[40:43], v[216:219], v[174:177], 0
	v_mfma_f32_16x16x32_bf16 v[28:31], v[208:211], v[182:185], 0
	v_mfma_f32_16x16x32_bf16 v[24:27], v[216:219], v[182:185], 0
	v_mfma_f32_16x16x32_bf16 v[12:15], v[208:211], v[200:203], 0
	v_mfma_f32_16x16x32_bf16 v[8:11], v[216:219], v[200:203], 0
	v_mfma_f32_16x16x32_bf16 v[60:63], v[212:215], v[160:163], v[60:63]
	v_mfma_f32_16x16x32_bf16 v[56:59], v[220:223], v[160:163], v[56:59]
	v_mfma_f32_16x16x32_bf16 v[44:47], v[212:215], v[178:181], v[44:47]
	v_mfma_f32_16x16x32_bf16 v[40:43], v[220:223], v[178:181], v[40:43]
	v_mfma_f32_16x16x32_bf16 v[28:31], v[212:215], v[196:199], v[28:31]
	v_mfma_f32_16x16x32_bf16 v[24:27], v[220:223], v[196:199], v[24:27]
	v_mfma_f32_16x16x32_bf16 v[12:15], v[212:215], v[204:207], v[12:15]
	v_mfma_f32_16x16x32_bf16 v[8:11], v[220:223], v[204:207], v[8:11]
	s_barrier
	s_add_i32 s4, 0, 0x18000
	ds_read_b128 v[136:139], v255 offset:32768
	ds_read_b128 v[144:147], v255 offset:33792
	ds_read_b128 v[148:151], v255 offset:34816
	ds_read_b128 v[152:155], v255 offset:35840
	s_mov_b32 m0, s29
	ds_read_b128 v[156:159], v172 offset:32768
	ds_read_b128 v[160:163], v172 offset:33792
	ds_read_b128 v[174:177], v172 offset:34816
	ds_read_b128 v[178:181], v172 offset:35840
	ds_read_b128 v[182:185], v172 offset:36864
	ds_read_b128 v[196:199], v172 offset:37888
	ds_read_b128 v[200:203], v172 offset:38912
	ds_read_b128 v[204:207], v172 offset:39936
	s_add_u32 vcc_lo, s42, s52
	s_addc_u32 vcc_hi, s43, s53
	global_load_lds_dwordx4 v2, vcc
	s_mov_b32 m0, s30
	s_add_u32 vcc_lo, s42, s54
	s_addc_u32 vcc_hi, s43, s55
	global_load_lds_dwordx4 v2, vcc
	s_waitcnt lgkmcnt(8)
	s_barrier
	s_waitcnt lgkmcnt(0)
	v_mfma_f32_16x16x32_bf16 v[132:135], v[136:139], v[156:159], v[132:135]
	v_mfma_f32_16x16x32_bf16 v[128:131], v[148:151], v[156:159], v[128:131]
	v_mfma_f32_16x16x32_bf16 v[116:119], v[136:139], v[174:177], v[116:119]
	v_mfma_f32_16x16x32_bf16 v[112:115], v[148:151], v[174:177], v[112:115]
	v_mfma_f32_16x16x32_bf16 v[100:103], v[136:139], v[182:185], v[100:103]
	v_mfma_f32_16x16x32_bf16 v[96:99], v[148:151], v[182:185], v[96:99]
	v_mfma_f32_16x16x32_bf16 v[84:87], v[136:139], v[200:203], v[84:87]
	v_mfma_f32_16x16x32_bf16 v[80:83], v[148:151], v[200:203], v[80:83]
	v_mfma_f32_16x16x32_bf16 v[132:135], v[144:147], v[160:163], v[132:135]
	v_mfma_f32_16x16x32_bf16 v[128:131], v[152:155], v[160:163], v[128:131]
	v_mfma_f32_16x16x32_bf16 v[116:119], v[144:147], v[178:181], v[116:119]
	v_mfma_f32_16x16x32_bf16 v[112:115], v[152:155], v[178:181], v[112:115]
	v_mfma_f32_16x16x32_bf16 v[100:103], v[144:147], v[196:199], v[100:103]
	v_mfma_f32_16x16x32_bf16 v[96:99], v[152:155], v[196:199], v[96:99]
	v_mfma_f32_16x16x32_bf16 v[84:87], v[144:147], v[204:207], v[84:87]
	v_mfma_f32_16x16x32_bf16 v[80:83], v[152:155], v[204:207], v[80:83]
	s_barrier
	s_add_i32 s5, 0, 0x1c000
	s_add_i32 s4, s4, s26
	s_mov_b32 m0, s4
	ds_read_b128 v[208:211], v255 offset:49152
	ds_read_b128 v[212:215], v255 offset:50176
	ds_read_b128 v[216:219], v255 offset:51200
	ds_read_b128 v[220:223], v255 offset:52224
	s_add_u32 vcc_lo, s50, s46
	s_addc_u32 vcc_hi, s51, s47
	global_load_lds_dwordx4 v140, vcc
	s_add_i32 m0, s4, 0x2000
	s_add_u32 vcc_lo, s50, s58
	s_addc_u32 vcc_hi, s51, s59
	global_load_lds_dwordx4 v140, vcc
	s_barrier
	s_waitcnt lgkmcnt(0)
	v_mfma_f32_16x16x32_bf16 v[124:127], v[208:211], v[156:159], v[124:127]
	v_mfma_f32_16x16x32_bf16 v[120:123], v[216:219], v[156:159], v[120:123]
	v_mfma_f32_16x16x32_bf16 v[108:111], v[208:211], v[174:177], v[108:111]
	v_mfma_f32_16x16x32_bf16 v[104:107], v[216:219], v[174:177], v[104:107]
	v_mfma_f32_16x16x32_bf16 v[92:95], v[208:211], v[182:185], v[92:95]
	v_mfma_f32_16x16x32_bf16 v[88:91], v[216:219], v[182:185], v[88:91]
	v_mfma_f32_16x16x32_bf16 v[76:79], v[208:211], v[200:203], v[76:79]
	v_mfma_f32_16x16x32_bf16 v[72:75], v[216:219], v[200:203], v[72:75]
	v_mfma_f32_16x16x32_bf16 v[124:127], v[212:215], v[160:163], v[124:127]
	v_mfma_f32_16x16x32_bf16 v[120:123], v[220:223], v[160:163], v[120:123]
	v_mfma_f32_16x16x32_bf16 v[108:111], v[212:215], v[178:181], v[108:111]
	v_mfma_f32_16x16x32_bf16 v[104:107], v[220:223], v[178:181], v[104:107]
	v_mfma_f32_16x16x32_bf16 v[92:95], v[212:215], v[196:199], v[92:95]
	v_mfma_f32_16x16x32_bf16 v[88:91], v[220:223], v[196:199], v[88:91]
	v_mfma_f32_16x16x32_bf16 v[76:79], v[212:215], v[204:207], v[76:79]
	v_mfma_f32_16x16x32_bf16 v[72:75], v[220:223], v[204:207], v[72:75]
	s_barrier
	s_mov_b32 m0, s31
	ds_read_b128 v[156:159], v172 offset:49152
	ds_read_b128 v[160:163], v172 offset:50176
	ds_read_b128 v[174:177], v172 offset:51200
	ds_read_b128 v[178:181], v172 offset:52224
	ds_read_b128 v[182:185], v172 offset:53248
	ds_read_b128 v[196:199], v172 offset:54272
	ds_read_b128 v[200:203], v172 offset:55296
	ds_read_b128 v[204:207], v172 offset:56320
	s_add_u32 vcc_lo, s42, s46
	s_addc_u32 vcc_hi, s43, s47
	global_load_lds_dwordx4 v2, vcc
	s_mov_b32 m0, s34
	s_add_u32 vcc_lo, s42, s58
	s_addc_u32 vcc_hi, s43, s59
	global_load_lds_dwordx4 v2, vcc
	s_barrier
; #define G_STAGE(bufoff, gbase, o0, h64) do { \
;         __builtin_amdgcn_global_load_lds((const unsigned*)((const char*)(gbase) + (o0)), (LAS unsigned*)(lds + (bufoff) + ldsw), 16, 0, 0); \
;         __builtin_amdgcn_global_load_lds((const unsigned*)((const char*)(gbase) + (h64) + (o0)), (LAS unsigned*)(lds + (bufoff) + ldsw + 8192), 16, 0, 0); } while (0)
; #define G_LDA(dst, b, h) do { _Pragma("unroll") for (int m = 0; m < 4; ++m) _Pragma("unroll") for (int k = 0; k < 2; ++k) dst[m][k] = *(const LAS bf16x8*)(lds + G_SA(b, h) + aoff + m * 2048 + k * 1024); } while (0)
; #define G_LDB(dst, b, h) do { _Pragma("unroll") for (int n = 0; n < 2; ++n) _Pragma("unroll") for (int k = 0; k < 2; ++k) dst[n][k] = *(const LAS bf16x8*)(lds + G_SB(b, h) + boff + n * 2048 + k * 1024); } while (0)
; #define G_WAIT_V(n) asm volatile("s_waitcnt vmcnt(" #n ")" ::: "memory")
; #define G_BAR __builtin_amdgcn_s_barrier()
;     ...
;         for (int t = 0; t < nt; t += 2) {
;             const bool last = (t == nt - 2);
;             const char* a1 = cA + (size_t)(t + 1) * ckA;
;             const char* a2 = last ? nA : cA + (size_t)(t + 2) * ckA; const char* b2 = last ? nB : cB + (size_t)(t + 2) * kB;
;             const char* a3 = a2 + ckA; const char* b3 = b2 + kB;
;             G_LDB(B0, 0, 0); G_SCHED; G_LDA(At, 0, 0); G_STAGE(G_SA(1, 1), a1 + chA, cA0, qA);
;             G_WAIT_L(8); G_BAR; G_WAIT_L(0); G_MMA(0, 0, At, B0); G_BAR; G_SCHED;
;             G_LDB(B1, 0, 1); G_STAGE(G_SB(0, 0), b2, cB0, qB);
;             G_BAR; G_WAIT_L(0); G_MMA(0, 1, At, B1); G_BAR;
;             G_LDA(At, 0, 1); G_STAGE(G_SA(0, 0), a2, cA0, qA);
;             G_BAR; G_WAIT_L(0); G_MMA(1, 0, At, B0); G_BAR; G_SCHED;
;             G_STAGE(G_SB(0, 1), b2 + chB, cB0, qB);
;             G_WAIT_V(6); G_BAR; G_MMA(1, 1, At, B1); G_BAR;
;             G_LDB(B0, 1, 0); G_SCHED; G_LDA(At, 1, 0); G_STAGE(G_SA(0, 1), a2 + chA, cA0, qA);
;             G_WAIT_L(8); G_BAR; G_WAIT_L(0); G_MMA(0, 0, At, B0); G_BAR; G_SCHED;
;             G_LDB(B1, 1, 1); G_STAGE(G_SB(1, 0), b3, cB0, qB);
;             G_BAR; G_WAIT_L(0); G_MMA(0, 1, At, B1); G_BAR;
;             G_LDA(At, 1, 1); G_STAGE(G_SA(1, 0), a3, cA0, qA);
;             G_BAR; G_WAIT_L(0); G_MMA(1, 0, At, B0); G_BAR; G_SCHED;
;             G_STAGE(G_SB(1, 1), b3 + chB, cB0, qB);
;             G_WAIT_V(6); G_BAR; G_MMA(1, 1, At, B1); G_BAR;
	s_waitcnt lgkmcnt(0)
	v_mfma_f32_16x16x32_bf16 v[68:71], v[136:139], v[156:159], v[68:71]
	v_mfma_f32_16x16x32_bf16 v[64:67], v[148:151], v[156:159], v[64:67]
	v_mfma_f32_16x16x32_bf16 v[52:55], v[136:139], v[174:177], v[52:55]
	v_mfma_f32_16x16x32_bf16 v[48:51], v[148:151], v[174:177], v[48:51]
	v_mfma_f32_16x16x32_bf16 v[36:39], v[136:139], v[182:185], v[36:39]
	v_mfma_f32_16x16x32_bf16 v[32:35], v[148:151], v[182:185], v[32:35]
	v_mfma_f32_16x16x32_bf16 v[20:23], v[136:139], v[200:203], v[20:23]
	v_mfma_f32_16x16x32_bf16 v[16:19], v[148:151], v[200:203], v[16:19]
	v_mfma_f32_16x16x32_bf16 v[68:71], v[144:147], v[160:163], v[68:71]
	v_mfma_f32_16x16x32_bf16 v[64:67], v[152:155], v[160:163], v[64:67]
	v_mfma_f32_16x16x32_bf16 v[52:55], v[144:147], v[178:181], v[52:55]
	v_mfma_f32_16x16x32_bf16 v[48:51], v[152:155], v[178:181], v[48:51]
	v_mfma_f32_16x16x32_bf16 v[36:39], v[144:147], v[196:199], v[36:39]
	v_mfma_f32_16x16x32_bf16 v[32:35], v[152:155], v[196:199], v[32:35]
	v_mfma_f32_16x16x32_bf16 v[20:23], v[144:147], v[204:207], v[20:23]
	v_mfma_f32_16x16x32_bf16 v[16:19], v[152:155], v[204:207], v[16:19]
	s_barrier
	s_add_i32 s4, s5, s26
	s_mov_b32 m0, s4
	s_add_u32 vcc_lo, s50, s62
	s_addc_u32 vcc_hi, s51, s63
	global_load_lds_dwordx4 v140, vcc
	s_add_i32 m0, s4, 0x2000
	s_add_u32 vcc_lo, s50, s64
	s_addc_u32 vcc_hi, s51, s65
	global_load_lds_dwordx4 v140, vcc
	s_add_i32 s23, s23, 2
	s_add_u32 s2, s2, 0x100
	s_addc_u32 s3, s3, 0
	s_add_u32 s7, s7, 0x100
	s_addc_u32 s22, s22, 0
	s_cmp_gt_u32 s23, 13
	s_waitcnt vmcnt(6)
	s_barrier
	v_mfma_f32_16x16x32_bf16 v[60:63], v[208:211], v[156:159], v[60:63]
	v_mfma_f32_16x16x32_bf16 v[56:59], v[216:219], v[156:159], v[56:59]
	v_mfma_f32_16x16x32_bf16 v[44:47], v[208:211], v[174:177], v[44:47]
	v_mfma_f32_16x16x32_bf16 v[40:43], v[216:219], v[174:177], v[40:43]
	v_mfma_f32_16x16x32_bf16 v[28:31], v[208:211], v[182:185], v[28:31]
	v_mfma_f32_16x16x32_bf16 v[24:27], v[216:219], v[182:185], v[24:27]
	v_mfma_f32_16x16x32_bf16 v[12:15], v[208:211], v[200:203], v[12:15]
	v_mfma_f32_16x16x32_bf16 v[8:11], v[216:219], v[200:203], v[8:11]
	v_mfma_f32_16x16x32_bf16 v[60:63], v[212:215], v[160:163], v[60:63]
	v_mfma_f32_16x16x32_bf16 v[56:59], v[220:223], v[160:163], v[56:59]
	v_mfma_f32_16x16x32_bf16 v[44:47], v[212:215], v[178:181], v[44:47]
	v_mfma_f32_16x16x32_bf16 v[40:43], v[220:223], v[178:181], v[40:43]
	v_mfma_f32_16x16x32_bf16 v[28:31], v[212:215], v[196:199], v[28:31]
	v_mfma_f32_16x16x32_bf16 v[24:27], v[220:223], v[196:199], v[24:27]
	v_mfma_f32_16x16x32_bf16 v[12:15], v[212:215], v[204:207], v[12:15]
	v_mfma_f32_16x16x32_bf16 v[8:11], v[220:223], v[204:207], v[8:11]
	s_cbranch_scc0 .Ldb_WIN_cont
	s_branch .Ldb_WIN_xl
.LBB0_212:
	s_add_u32 s4, s2, 0xfffc0080
	s_addc_u32 s5, s3, -1
	s_add_i32 s41, 0, 0x10000
	ds_read_b128 v[136:139], v255 offset:0
	ds_read_b128 v[144:147], v255 offset:1024
	ds_read_b128 v[148:151], v255 offset:2048
	ds_read_b128 v[152:155], v255 offset:3072
	s_cmp_eq_u32 s23, 12
	s_cselect_b32 s43, s19, s5
	s_cselect_b32 s42, s18, s4
	s_cselect_b32 s51, s21, s22
	s_cselect_b32 s50, s20, s7
	s_add_i32 m0, s27, 0xc000
	ds_read_b128 v[156:159], v172
	ds_read_b128 v[160:163], v172 offset:1024
	ds_read_b128 v[174:177], v172 offset:2048
	ds_read_b128 v[178:181], v172 offset:3072
	ds_read_b128 v[182:185], v172 offset:4096
	ds_read_b128 v[196:199], v172 offset:5120
	ds_read_b128 v[200:203], v172 offset:6144
	ds_read_b128 v[204:207], v172 offset:7168
	global_load_lds_dwordx4 v142, s[2:3]
	s_add_i32 m0, s27, 0xe000
	s_add_u32 vcc_lo, s2, s0
	s_addc_u32 vcc_hi, s3, s1
	global_load_lds_dwordx4 v142, vcc
	s_waitcnt lgkmcnt(8)
	s_barrier
	s_waitcnt lgkmcnt(0)
	v_mfma_f32_16x16x32_bf16 v[132:135], v[136:139], v[156:159], v[132:135]
	v_mfma_f32_16x16x32_bf16 v[128:131], v[148:151], v[156:159], v[128:131]
	v_mfma_f32_16x16x32_bf16 v[116:119], v[136:139], v[174:177], v[116:119]
	v_mfma_f32_16x16x32_bf16 v[112:115], v[148:151], v[174:177], v[112:115]
	v_mfma_f32_16x16x32_bf16 v[100:103], v[136:139], v[182:185], v[100:103]
	v_mfma_f32_16x16x32_bf16 v[96:99], v[148:151], v[182:185], v[96:99]
	v_mfma_f32_16x16x32_bf16 v[84:87], v[136:139], v[200:203], v[84:87]
	v_mfma_f32_16x16x32_bf16 v[80:83], v[148:151], v[200:203], v[80:83]
	v_mfma_f32_16x16x32_bf16 v[132:135], v[144:147], v[160:163], v[132:135]
	v_mfma_f32_16x16x32_bf16 v[128:131], v[152:155], v[160:163], v[128:131]
	v_mfma_f32_16x16x32_bf16 v[116:119], v[144:147], v[178:181], v[116:119]
	v_mfma_f32_16x16x32_bf16 v[112:115], v[152:155], v[178:181], v[112:115]
	v_mfma_f32_16x16x32_bf16 v[100:103], v[144:147], v[196:199], v[100:103]
	v_mfma_f32_16x16x32_bf16 v[96:99], v[152:155], v[196:199], v[96:99]
	v_mfma_f32_16x16x32_bf16 v[84:87], v[144:147], v[204:207], v[84:87]
	v_mfma_f32_16x16x32_bf16 v[80:83], v[152:155], v[204:207], v[80:83]
	s_barrier
	s_add_i32 s4, 0, 0x14000
	s_add_i32 s5, s41, s26
	s_mov_b32 m0, s5
	ds_read_b128 v[208:211], v255 offset:16384
	ds_read_b128 v[212:215], v255 offset:17408
	ds_read_b128 v[216:219], v255 offset:18432
	ds_read_b128 v[220:223], v255 offset:19456
	global_load_lds_dwordx4 v140, s[50:51]
	s_add_i32 m0, s5, 0x2000
	s_add_u32 vcc_lo, s50, s0
	s_addc_u32 vcc_hi, s51, s1
	global_load_lds_dwordx4 v140, vcc
	s_barrier
; #define G_STAGE(bufoff, gbase, o0, h64) do { \
;         __builtin_amdgcn_global_load_lds((const unsigned*)((const char*)(gbase) + (o0)), (LAS unsigned*)(lds + (bufoff) + ldsw), 16, 0, 0); \
;         __builtin_amdgcn_global_load_lds((const unsigned*)((const char*)(gbase) + (h64) + (o0)), (LAS unsigned*)(lds + (bufoff) + ldsw + 8192), 16, 0, 0); } while (0)
; #define G_LDA(dst, b, h) do { _Pragma("unroll") for (int m = 0; m < 4; ++m) _Pragma("unroll") for (int k = 0; k < 2; ++k) dst[m][k] = *(const LAS bf16x8*)(lds + G_SA(b, h) + aoff + m * 2048 + k * 1024); } while (0)
; #define G_LDB(dst, b, h) do { _Pragma("unroll") for (int n = 0; n < 2; ++n) _Pragma("unroll") for (int k = 0; k < 2; ++k) dst[n][k] = *(const LAS bf16x8*)(lds + G_SB(b, h) + boff + n * 2048 + k * 1024); } while (0)
; #define G_WAIT_V(n) asm volatile("s_waitcnt vmcnt(" #n ")" ::: "memory")
; #define G_BAR __builtin_amdgcn_s_barrier()
;     ...
;         for (int t = 0; t < nt; t += 2) {
;             const bool last = (t == nt - 2);
;             const char* a1 = cA + (size_t)(t + 1) * ckA;
;             const char* a2 = last ? nA : cA + (size_t)(t + 2) * ckA; const char* b2 = last ? nB : cB + (size_t)(t + 2) * kB;
;             const char* a3 = a2 + ckA; const char* b3 = b2 + kB;
;             G_LDB(B0, 0, 0); G_SCHED; G_LDA(At, 0, 0); G_STAGE(G_SA(1, 1), a1 + chA, cA0, qA);
;             G_WAIT_L(8); G_BAR; G_WAIT_L(0); G_MMA(0, 0, At, B0); G_BAR; G_SCHED;
;             G_LDB(B1, 0, 1); G_STAGE(G_SB(0, 0), b2, cB0, qB);
;             G_BAR; G_WAIT_L(0); G_MMA(0, 1, At, B1); G_BAR;
;             G_LDA(At, 0, 1); G_STAGE(G_SA(0, 0), a2, cA0, qA);
;             G_BAR; G_WAIT_L(0); G_MMA(1, 0, At, B0); G_BAR; G_SCHED;
;             G_STAGE(G_SB(0, 1), b2 + chB, cB0, qB);
;             G_WAIT_V(6); G_BAR; G_MMA(1, 1, At, B1); G_BAR;
;             G_LDB(B0, 1, 0); G_SCHED; G_LDA(At, 1, 0); G_STAGE(G_SA(0, 1), a2 + chA, cA0, qA);
;             G_WAIT_L(8); G_BAR; G_WAIT_L(0); G_MMA(0, 0, At, B0); G_BAR; G_SCHED;
;             G_LDB(B1, 1, 1); G_STAGE(G_SB(1, 0), b3, cB0, qB);
;             G_BAR; G_WAIT_L(0); G_MMA(0, 1, At, B1); G_BAR;
;             G_LDA(At, 1, 1); G_STAGE(G_SA(1, 0), a3, cA0, qA);
;             G_BAR; G_WAIT_L(0); G_MMA(1, 0, At, B0); G_BAR; G_SCHED;
;             G_STAGE(G_SB(1, 1), b3 + chB, cB0, qB);
;             G_WAIT_V(6); G_BAR; G_MMA(1, 1, At, B1); G_BAR;
	s_waitcnt lgkmcnt(0)
	v_mfma_f32_16x16x32_bf16 v[124:127], v[208:211], v[156:159], v[124:127]
	v_mfma_f32_16x16x32_bf16 v[120:123], v[216:219], v[156:159], v[120:123]
	v_mfma_f32_16x16x32_bf16 v[108:111], v[208:211], v[174:177], v[108:111]
	v_mfma_f32_16x16x32_bf16 v[104:107], v[216:219], v[174:177], v[104:107]
	v_mfma_f32_16x16x32_bf16 v[92:95], v[208:211], v[182:185], v[92:95]
	v_mfma_f32_16x16x32_bf16 v[88:91], v[216:219], v[182:185], v[88:91]
	v_mfma_f32_16x16x32_bf16 v[76:79], v[208:211], v[200:203], v[76:79]
	v_mfma_f32_16x16x32_bf16 v[72:75], v[216:219], v[200:203], v[72:75]
	v_mfma_f32_16x16x32_bf16 v[124:127], v[212:215], v[160:163], v[124:127]
	v_mfma_f32_16x16x32_bf16 v[120:123], v[220:223], v[160:163], v[120:123]
	v_mfma_f32_16x16x32_bf16 v[108:111], v[212:215], v[178:181], v[108:111]
	v_mfma_f32_16x16x32_bf16 v[104:107], v[220:223], v[178:181], v[104:107]
	v_mfma_f32_16x16x32_bf16 v[92:95], v[212:215], v[196:199], v[92:95]
	v_mfma_f32_16x16x32_bf16 v[88:91], v[220:223], v[196:199], v[88:91]
	v_mfma_f32_16x16x32_bf16 v[76:79], v[212:215], v[204:207], v[76:79]
	v_mfma_f32_16x16x32_bf16 v[72:75], v[220:223], v[204:207], v[72:75]
	s_barrier
	s_mov_b32 m0, s27
	ds_read_b128 v[156:159], v172 offset:16384
	ds_read_b128 v[160:163], v172 offset:17408
	ds_read_b128 v[174:177], v172 offset:18432
	ds_read_b128 v[178:181], v172 offset:19456
	ds_read_b128 v[182:185], v172 offset:20480
	ds_read_b128 v[196:199], v172 offset:21504
	ds_read_b128 v[200:203], v172 offset:22528
	ds_read_b128 v[204:207], v172 offset:23552
	global_load_lds_dwordx4 v2, s[42:43]
	s_mov_b32 m0, s28
	s_add_u32 vcc_lo, s42, s0
	s_addc_u32 vcc_hi, s43, s1
	global_load_lds_dwordx4 v2, vcc
	s_barrier
	s_waitcnt lgkmcnt(0)
	v_mfma_f32_16x16x32_bf16 v[68:71], v[136:139], v[156:159], v[68:71]
	v_mfma_f32_16x16x32_bf16 v[64:67], v[148:151], v[156:159], v[64:67]
	v_mfma_f32_16x16x32_bf16 v[52:55], v[136:139], v[174:177], v[52:55]
	v_mfma_f32_16x16x32_bf16 v[48:51], v[148:151], v[174:177], v[48:51]
	v_mfma_f32_16x16x32_bf16 v[36:39], v[136:139], v[182:185], v[36:39]
	v_mfma_f32_16x16x32_bf16 v[32:35], v[148:151], v[182:185], v[32:35]
	v_mfma_f32_16x16x32_bf16 v[20:23], v[136:139], v[200:203], v[20:23]
	v_mfma_f32_16x16x32_bf16 v[16:19], v[148:151], v[200:203], v[16:19]
	v_mfma_f32_16x16x32_bf16 v[68:71], v[144:147], v[160:163], v[68:71]
	v_mfma_f32_16x16x32_bf16 v[64:67], v[152:155], v[160:163], v[64:67]
	v_mfma_f32_16x16x32_bf16 v[52:55], v[144:147], v[178:181], v[52:55]
	v_mfma_f32_16x16x32_bf16 v[48:51], v[152:155], v[178:181], v[48:51]
	v_mfma_f32_16x16x32_bf16 v[36:39], v[144:147], v[196:199], v[36:39]
	v_mfma_f32_16x16x32_bf16 v[32:35], v[152:155], v[196:199], v[32:35]
	v_mfma_f32_16x16x32_bf16 v[20:23], v[144:147], v[204:207], v[20:23]
	v_mfma_f32_16x16x32_bf16 v[16:19], v[152:155], v[204:207], v[16:19]
	s_barrier
	s_add_i32 s4, s4, s26
	s_mov_b32 m0, s4
	s_add_u32 vcc_lo, s50, s52
	s_addc_u32 vcc_hi, s51, s53
	global_load_lds_dwordx4 v140, vcc
	s_add_i32 m0, s4, 0x2000
	s_add_u32 vcc_lo, s50, s54
	s_addc_u32 vcc_hi, s51, s55
	global_load_lds_dwordx4 v140, vcc
	s_waitcnt vmcnt(6)
	s_barrier
	v_mfma_f32_16x16x32_bf16 v[60:63], v[208:211], v[156:159], v[60:63]
	v_mfma_f32_16x16x32_bf16 v[56:59], v[216:219], v[156:159], v[56:59]
	v_mfma_f32_16x16x32_bf16 v[44:47], v[208:211], v[174:177], v[44:47]
	v_mfma_f32_16x16x32_bf16 v[40:43], v[216:219], v[174:177], v[40:43]
	v_mfma_f32_16x16x32_bf16 v[28:31], v[208:211], v[182:185], v[28:31]
	v_mfma_f32_16x16x32_bf16 v[24:27], v[216:219], v[182:185], v[24:27]
	v_mfma_f32_16x16x32_bf16 v[12:15], v[208:211], v[200:203], v[12:15]
	v_mfma_f32_16x16x32_bf16 v[8:11], v[216:219], v[200:203], v[8:11]
	v_mfma_f32_16x16x32_bf16 v[60:63], v[212:215], v[160:163], v[60:63]
	v_mfma_f32_16x16x32_bf16 v[56:59], v[220:223], v[160:163], v[56:59]
	v_mfma_f32_16x16x32_bf16 v[44:47], v[212:215], v[178:181], v[44:47]
	v_mfma_f32_16x16x32_bf16 v[40:43], v[220:223], v[178:181], v[40:43]
	v_mfma_f32_16x16x32_bf16 v[28:31], v[212:215], v[196:199], v[28:31]
	v_mfma_f32_16x16x32_bf16 v[24:27], v[220:223], v[196:199], v[24:27]
	v_mfma_f32_16x16x32_bf16 v[12:15], v[212:215], v[204:207], v[12:15]
	v_mfma_f32_16x16x32_bf16 v[8:11], v[220:223], v[204:207], v[8:11]
	s_barrier
	s_add_i32 s4, 0, 0x18000
	ds_read_b128 v[136:139], v255 offset:32768
	ds_read_b128 v[144:147], v255 offset:33792
	ds_read_b128 v[148:151], v255 offset:34816
	ds_read_b128 v[152:155], v255 offset:35840
	s_mov_b32 m0, s29
	ds_read_b128 v[156:159], v172 offset:32768
	ds_read_b128 v[160:163], v172 offset:33792
	ds_read_b128 v[174:177], v172 offset:34816
	ds_read_b128 v[178:181], v172 offset:35840
	ds_read_b128 v[182:185], v172 offset:36864
	ds_read_b128 v[196:199], v172 offset:37888
	ds_read_b128 v[200:203], v172 offset:38912
	ds_read_b128 v[204:207], v172 offset:39936
	s_add_u32 vcc_lo, s42, s52
	s_addc_u32 vcc_hi, s43, s53
	global_load_lds_dwordx4 v2, vcc
	s_mov_b32 m0, s30
	s_add_u32 vcc_lo, s42, s54
	s_addc_u32 vcc_hi, s43, s55
	global_load_lds_dwordx4 v2, vcc
	s_waitcnt lgkmcnt(8)
	s_barrier
; #define G_STAGE(bufoff, gbase, o0, h64) do { \
;         __builtin_amdgcn_global_load_lds((const unsigned*)((const char*)(gbase) + (o0)), (LAS unsigned*)(lds + (bufoff) + ldsw), 16, 0, 0); \
;         __builtin_amdgcn_global_load_lds((const unsigned*)((const char*)(gbase) + (h64) + (o0)), (LAS unsigned*)(lds + (bufoff) + ldsw + 8192), 16, 0, 0); } while (0)
; #define G_LDA(dst, b, h) do { _Pragma("unroll") for (int m = 0; m < 4; ++m) _Pragma("unroll") for (int k = 0; k < 2; ++k) dst[m][k] = *(const LAS bf16x8*)(lds + G_SA(b, h) + aoff + m * 2048 + k * 1024); } while (0)
; #define G_LDB(dst, b, h) do { _Pragma("unroll") for (int n = 0; n < 2; ++n) _Pragma("unroll") for (int k = 0; k < 2; ++k) dst[n][k] = *(const LAS bf16x8*)(lds + G_SB(b, h) + boff + n * 2048 + k * 1024); } while (0)
; #define G_WAIT_V(n) asm volatile("s_waitcnt vmcnt(" #n ")" ::: "memory")
; #define G_BAR __builtin_amdgcn_s_barrier()
;     ...
;         for (int t = 0; t < nt; t += 2) {
;             const bool last = (t == nt - 2);
;             const char* a1 = cA + (size_t)(t + 1) * ckA;
;             const char* a2 = last ? nA : cA + (size_t)(t + 2) * ckA; const char* b2 = last ? nB : cB + (size_t)(t + 2) * kB;
;             const char* a3 = a2 + ckA; const char* b3 = b2 + kB;
;             G_LDB(B0, 0, 0); G_SCHED; G_LDA(At, 0, 0); G_STAGE(G_SA(1, 1), a1 + chA, cA0, qA);
;             G_WAIT_L(8); G_BAR; G_WAIT_L(0); G_MMA(0, 0, At, B0); G_BAR; G_SCHED;
;             G_LDB(B1, 0, 1); G_STAGE(G_SB(0, 0), b2, cB0, qB);
;             G_BAR; G_WAIT_L(0); G_MMA(0, 1, At, B1); G_BAR;
;             G_LDA(At, 0, 1); G_STAGE(G_SA(0, 0), a2, cA0, qA);
;             G_BAR; G_WAIT_L(0); G_MMA(1, 0, At, B0); G_BAR; G_SCHED;
;             G_STAGE(G_SB(0, 1), b2 + chB, cB0, qB);
;             G_WAIT_V(6); G_BAR; G_MMA(1, 1, At, B1); G_BAR;
;             G_LDB(B0, 1, 0); G_SCHED; G_LDA(At, 1, 0); G_STAGE(G_SA(0, 1), a2 + chA, cA0, qA);
;             G_WAIT_L(8); G_BAR; G_WAIT_L(0); G_MMA(0, 0, At, B0); G_BAR; G_SCHED;
;             G_LDB(B1, 1, 1); G_STAGE(G_SB(1, 0), b3, cB0, qB);
;             G_BAR; G_WAIT_L(0); G_MMA(0, 1, At, B1); G_BAR;
;             G_LDA(At, 1, 1); G_STAGE(G_SA(1, 0), a3, cA0, qA);
;             G_BAR; G_WAIT_L(0); G_MMA(1, 0, At, B0); G_BAR; G_SCHED;
;             G_STAGE(G_SB(1, 1), b3 + chB, cB0, qB);
;             G_WAIT_V(6); G_BAR; G_MMA(1, 1, At, B1); G_BAR;
;         }
	s_waitcnt lgkmcnt(0)
	v_mfma_f32_16x16x32_bf16 v[132:135], v[136:139], v[156:159], v[132:135]
	v_mfma_f32_16x16x32_bf16 v[128:131], v[148:151], v[156:159], v[128:131]
	v_mfma_f32_16x16x32_bf16 v[116:119], v[136:139], v[174:177], v[116:119]
	v_mfma_f32_16x16x32_bf16 v[112:115], v[148:151], v[174:177], v[112:115]
	v_mfma_f32_16x16x32_bf16 v[100:103], v[136:139], v[182:185], v[100:103]
	v_mfma_f32_16x16x32_bf16 v[96:99], v[148:151], v[182:185], v[96:99]
	v_mfma_f32_16x16x32_bf16 v[84:87], v[136:139], v[200:203], v[84:87]
	v_mfma_f32_16x16x32_bf16 v[80:83], v[148:151], v[200:203], v[80:83]
	v_mfma_f32_16x16x32_bf16 v[132:135], v[144:147], v[160:163], v[132:135]
	v_mfma_f32_16x16x32_bf16 v[128:131], v[152:155], v[160:163], v[128:131]
	v_mfma_f32_16x16x32_bf16 v[116:119], v[144:147], v[178:181], v[116:119]
	v_mfma_f32_16x16x32_bf16 v[112:115], v[152:155], v[178:181], v[112:115]
	v_mfma_f32_16x16x32_bf16 v[100:103], v[144:147], v[196:199], v[100:103]
	v_mfma_f32_16x16x32_bf16 v[96:99], v[152:155], v[196:199], v[96:99]
	v_mfma_f32_16x16x32_bf16 v[84:87], v[144:147], v[204:207], v[84:87]
	v_mfma_f32_16x16x32_bf16 v[80:83], v[152:155], v[204:207], v[80:83]
	s_barrier
	s_add_i32 s5, 0, 0x1c000
	s_add_i32 s4, s4, s26
	s_mov_b32 m0, s4
	ds_read_b128 v[208:211], v255 offset:49152
	ds_read_b128 v[212:215], v255 offset:50176
	ds_read_b128 v[216:219], v255 offset:51200
	ds_read_b128 v[220:223], v255 offset:52224
	s_add_u32 vcc_lo, s50, s46
	s_addc_u32 vcc_hi, s51, s47
	global_load_lds_dwordx4 v140, vcc
	s_add_i32 m0, s4, 0x2000
	s_add_u32 vcc_lo, s50, s58
	s_addc_u32 vcc_hi, s51, s59
	global_load_lds_dwordx4 v140, vcc
	s_barrier
	s_waitcnt lgkmcnt(0)
	v_mfma_f32_16x16x32_bf16 v[124:127], v[208:211], v[156:159], v[124:127]
	v_mfma_f32_16x16x32_bf16 v[120:123], v[216:219], v[156:159], v[120:123]
	v_mfma_f32_16x16x32_bf16 v[108:111], v[208:211], v[174:177], v[108:111]
	v_mfma_f32_16x16x32_bf16 v[104:107], v[216:219], v[174:177], v[104:107]
	v_mfma_f32_16x16x32_bf16 v[92:95], v[208:211], v[182:185], v[92:95]
	v_mfma_f32_16x16x32_bf16 v[88:91], v[216:219], v[182:185], v[88:91]
	v_mfma_f32_16x16x32_bf16 v[76:79], v[208:211], v[200:203], v[76:79]
	v_mfma_f32_16x16x32_bf16 v[72:75], v[216:219], v[200:203], v[72:75]
	v_mfma_f32_16x16x32_bf16 v[124:127], v[212:215], v[160:163], v[124:127]
	v_mfma_f32_16x16x32_bf16 v[120:123], v[220:223], v[160:163], v[120:123]
	v_mfma_f32_16x16x32_bf16 v[108:111], v[212:215], v[178:181], v[108:111]
	v_mfma_f32_16x16x32_bf16 v[104:107], v[220:223], v[178:181], v[104:107]
	v_mfma_f32_16x16x32_bf16 v[92:95], v[212:215], v[196:199], v[92:95]
	v_mfma_f32_16x16x32_bf16 v[88:91], v[220:223], v[196:199], v[88:91]
	v_mfma_f32_16x16x32_bf16 v[76:79], v[212:215], v[204:207], v[76:79]
	v_mfma_f32_16x16x32_bf16 v[72:75], v[220:223], v[204:207], v[72:75]
	s_barrier
	s_mov_b32 m0, s31
	ds_read_b128 v[156:159], v172 offset:49152
	ds_read_b128 v[160:163], v172 offset:50176
	ds_read_b128 v[174:177], v172 offset:51200
	ds_read_b128 v[178:181], v172 offset:52224
	ds_read_b128 v[182:185], v172 offset:53248
	ds_read_b128 v[196:199], v172 offset:54272
	ds_read_b128 v[200:203], v172 offset:55296
	ds_read_b128 v[204:207], v172 offset:56320
	s_add_u32 vcc_lo, s42, s46
	s_addc_u32 vcc_hi, s43, s47
	global_load_lds_dwordx4 v2, vcc
	s_mov_b32 m0, s34
	s_add_u32 vcc_lo, s42, s58
	s_addc_u32 vcc_hi, s43, s59
	global_load_lds_dwordx4 v2, vcc
	s_barrier
	s_waitcnt lgkmcnt(0)
	v_mfma_f32_16x16x32_bf16 v[68:71], v[136:139], v[156:159], v[68:71]
	v_mfma_f32_16x16x32_bf16 v[64:67], v[148:151], v[156:159], v[64:67]
	v_mfma_f32_16x16x32_bf16 v[52:55], v[136:139], v[174:177], v[52:55]
	v_mfma_f32_16x16x32_bf16 v[48:51], v[148:151], v[174:177], v[48:51]
	v_mfma_f32_16x16x32_bf16 v[36:39], v[136:139], v[182:185], v[36:39]
	v_mfma_f32_16x16x32_bf16 v[32:35], v[148:151], v[182:185], v[32:35]
	v_mfma_f32_16x16x32_bf16 v[20:23], v[136:139], v[200:203], v[20:23]
	v_mfma_f32_16x16x32_bf16 v[16:19], v[148:151], v[200:203], v[16:19]
	v_mfma_f32_16x16x32_bf16 v[68:71], v[144:147], v[160:163], v[68:71]
	v_mfma_f32_16x16x32_bf16 v[64:67], v[152:155], v[160:163], v[64:67]
	v_mfma_f32_16x16x32_bf16 v[52:55], v[144:147], v[178:181], v[52:55]
	v_mfma_f32_16x16x32_bf16 v[48:51], v[152:155], v[178:181], v[48:51]
	v_mfma_f32_16x16x32_bf16 v[36:39], v[144:147], v[196:199], v[36:39]
	v_mfma_f32_16x16x32_bf16 v[32:35], v[152:155], v[196:199], v[32:35]
	v_mfma_f32_16x16x32_bf16 v[20:23], v[144:147], v[204:207], v[20:23]
	v_mfma_f32_16x16x32_bf16 v[16:19], v[152:155], v[204:207], v[16:19]
	s_barrier
	s_add_i32 s4, s5, s26
	s_mov_b32 m0, s4
	s_add_u32 vcc_lo, s50, s62
	s_addc_u32 vcc_hi, s51, s63
	global_load_lds_dwordx4 v140, vcc
	s_add_i32 m0, s4, 0x2000
	s_add_u32 vcc_lo, s50, s64
	s_addc_u32 vcc_hi, s51, s65
	global_load_lds_dwordx4 v140, vcc
	s_add_i32 s23, s23, 2
	s_add_u32 s2, s2, 0x100
	s_addc_u32 s3, s3, 0
	s_add_u32 s7, s7, 0x100
	s_addc_u32 s22, s22, 0
	s_cmp_gt_u32 s23, 13
	s_waitcnt vmcnt(6)
	s_barrier
	v_mfma_f32_16x16x32_bf16 v[60:63], v[208:211], v[156:159], v[60:63]
	v_mfma_f32_16x16x32_bf16 v[56:59], v[216:219], v[156:159], v[56:59]
	v_mfma_f32_16x16x32_bf16 v[44:47], v[208:211], v[174:177], v[44:47]
	v_mfma_f32_16x16x32_bf16 v[40:43], v[216:219], v[174:177], v[40:43]
	v_mfma_f32_16x16x32_bf16 v[28:31], v[208:211], v[182:185], v[28:31]
	v_mfma_f32_16x16x32_bf16 v[24:27], v[216:219], v[182:185], v[24:27]
	v_mfma_f32_16x16x32_bf16 v[12:15], v[208:211], v[200:203], v[12:15]
	v_mfma_f32_16x16x32_bf16 v[8:11], v[216:219], v[200:203], v[8:11]
	v_mfma_f32_16x16x32_bf16 v[60:63], v[212:215], v[160:163], v[60:63]
	v_mfma_f32_16x16x32_bf16 v[56:59], v[220:223], v[160:163], v[56:59]
	v_mfma_f32_16x16x32_bf16 v[44:47], v[212:215], v[178:181], v[44:47]
	v_mfma_f32_16x16x32_bf16 v[40:43], v[220:223], v[178:181], v[40:43]
	v_mfma_f32_16x16x32_bf16 v[28:31], v[212:215], v[196:199], v[28:31]
	v_mfma_f32_16x16x32_bf16 v[24:27], v[220:223], v[196:199], v[24:27]
	v_mfma_f32_16x16x32_bf16 v[12:15], v[212:215], v[204:207], v[12:15]
	v_mfma_f32_16x16x32_bf16 v[8:11], v[220:223], v[204:207], v[8:11]
	s_cbranch_scc0 .Ldb_WIN_cont

; #define G_STAGE(bufoff, gbase, o0, h64) do { \
;         __builtin_amdgcn_global_load_lds((const unsigned*)((const char*)(gbase) + (o0)), (LAS unsigned*)(lds + (bufoff) + ldsw), 16, 0, 0); \
;         __builtin_amdgcn_global_load_lds((const unsigned*)((const char*)(gbase) + (h64) + (o0)), (LAS unsigned*)(lds + (bufoff) + ldsw + 8192), 16, 0, 0); } while (0)
; #define G_LDA(dst, b, h) do { _Pragma("unroll") for (int m = 0; m < 4; ++m) _Pragma("unroll") for (int k = 0; k < 2; ++k) dst[m][k] = *(const LAS bf16x8*)(lds + G_SA(b, h) + aoff + m * 2048 + k * 1024); } while (0)
; #define G_WAIT_V(n) asm volatile("s_waitcnt vmcnt(" #n ")" ::: "memory")
; #define G_BAR __builtin_amdgcn_s_barrier()
;     ...
;     for (;;) {
;         const bool has_next = sched_next<PH, SUB>(E.ws, E.layer, ui + 1, nxt, E.x);
;         if (!has_next) nxt = cur;
;         const char* nA = nxt.A; const char* nB = nxt.B;
; #pragma unroll 1
;         for (int t = 0; t < nt; t += 2) {
;             const bool last = (t == nt - 2);
;             const char* a1 = cA + (size_t)(t + 1) * ckA;
;             const char* a2 = last ? nA : cA + (size_t)(t + 2) * ckA; const char* b2 = last ? nB : cB + (size_t)(t + 2) * kB;
;             const char* a3 = a2 + ckA; const char* b3 = b2 + kB;
;             G_LDB(B0, 0, 0); G_SCHED; G_LDA(At, 0, 0); G_STAGE(G_SA(1, 1), a1 + chA, cA0, qA);
;             G_WAIT_L(8); G_BAR; G_WAIT_L(0); G_MMA(0, 0, At, B0); G_BAR; G_SCHED;
;             G_LDB(B1, 0, 1); G_STAGE(G_SB(0, 0), b2, cB0, qB);
;             G_BAR; G_WAIT_L(0); G_MMA(0, 1, At, B1); G_BAR;
;             G_LDA(At, 0, 1); G_STAGE(G_SA(0, 0), a2, cA0, qA);
;             G_BAR; G_WAIT_L(0); G_MMA(1, 0, At, B0); G_BAR; G_SCHED;
;             G_STAGE(G_SB(0, 1), b2 + chB, cB0, qB);
;             G_WAIT_V(6); G_BAR; G_MMA(1, 1, At, B1); G_BAR;
;             G_LDB(B0, 1, 0); G_SCHED; G_LDA(At, 1, 0); G_STAGE(G_SA(0, 1), a2 + chA, cA0, qA);
;             G_WAIT_L(8); G_BAR; G_WAIT_L(0); G_MMA(0, 0, At, B0); G_BAR; G_SCHED;
;             G_LDB(B1, 1, 1); G_STAGE(G_SB(1, 0), b3, cB0, qB);
;             G_BAR; G_WAIT_L(0); G_MMA(0, 1, At, B1); G_BAR;
;             G_LDA(At, 1, 1); G_STAGE(G_SA(1, 0), a3, cA0, qA);
;             G_BAR; G_WAIT_L(0); G_MMA(1, 0, At, B0); G_BAR; G_SCHED;
;             G_STAGE(G_SB(1, 1), b3 + chB, cB0, qB);
;             G_WAIT_V(6); G_BAR; G_MMA(1, 1, At, B1); G_BAR;
.LBB0_449:
	s_add_u32 s6, s22, 0x20080
	s_addc_u32 s7, s23, 0
	s_add_u32 s19, s20, 0x100
	s_addc_u32 s20, s21, 0
	s_mov_b32 s21, -2
	s_mov_b64 s[50:51], 0x20080
	s_mov_b64 s[52:53], 0x10000
	s_mov_b64 s[54:55], 0x30000
	s_mov_b64 s[58:59], 0x10080
	s_mov_b64 s[62:63], 0x30080
	s_cmp_eq_u32 s101, 2
	s_cselect_b32 s101, 0, s101
	s_setprio 0
	v_add_u32_e32 v255, 0x10000, v145
	s_add_u32 s4, s6, 0xfffe0080
	s_addc_u32 s5, s7, -1
	s_add_i32 s41, 0, 0x10000
	ds_read_b128 v[140:143], v255 offset:0
	ds_read_b128 v[148:151], v255 offset:1024
	ds_read_b128 v[152:155], v255 offset:2048
	ds_read_b128 v[156:159], v255 offset:3072
	s_cmp_eq_u32 s21, 4
	s_cselect_b32 s23, s11, s5
	s_cselect_b32 s22, s10, s4
	s_cselect_b32 s43, s17, s20
	s_cselect_b32 s42, s16, s19
	s_add_i32 m0, s27, 0xc000
	ds_read_b128 v[160:163], v146
	ds_read_b128 v[164:167], v146 offset:1024
	ds_read_b128 v[172:175], v146 offset:2048
	ds_read_b128 v[176:179], v146 offset:3072
	ds_read_b128 v[180:183], v146 offset:4096
	ds_read_b128 v[196:199], v146 offset:5120
	ds_read_b128 v[200:203], v146 offset:6144
	ds_read_b128 v[204:207], v146 offset:7168
	global_load_lds_dwordx4 v138, s[6:7]
	s_add_i32 m0, s27, 0xe000
	s_add_u32 vcc_lo, s6, s52
	s_addc_u32 vcc_hi, s7, s53
	global_load_lds_dwordx4 v138, vcc
	s_waitcnt lgkmcnt(8)
	s_cmp_eq_u32 s101, 1
	s_cbranch_scc1 .Ldb_SSM1_skp
	s_barrier
.Ldb_SSM1_skp:
	s_mov_b32 s101, 0
	s_waitcnt lgkmcnt(0)
	v_mfma_f32_16x16x32_bf16 v[132:135], v[140:143], v[160:163], 0
	v_mfma_f32_16x16x32_bf16 v[128:131], v[152:155], v[160:163], 0
	v_mfma_f32_16x16x32_bf16 v[116:119], v[140:143], v[172:175], 0
	v_mfma_f32_16x16x32_bf16 v[112:115], v[152:155], v[172:175], 0
	v_mfma_f32_16x16x32_bf16 v[100:103], v[140:143], v[180:183], 0
	v_mfma_f32_16x16x32_bf16 v[96:99], v[152:155], v[180:183], 0
	v_mfma_f32_16x16x32_bf16 v[84:87], v[140:143], v[200:203], 0
	v_mfma_f32_16x16x32_bf16 v[80:83], v[152:155], v[200:203], 0
	v_mfma_f32_16x16x32_bf16 v[132:135], v[148:151], v[164:167], v[132:135]
	v_mfma_f32_16x16x32_bf16 v[128:131], v[156:159], v[164:167], v[128:131]
	v_mfma_f32_16x16x32_bf16 v[116:119], v[148:151], v[176:179], v[116:119]
	v_mfma_f32_16x16x32_bf16 v[112:115], v[156:159], v[176:179], v[112:115]
	v_mfma_f32_16x16x32_bf16 v[100:103], v[148:151], v[196:199], v[100:103]
	v_mfma_f32_16x16x32_bf16 v[96:99], v[156:159], v[196:199], v[96:99]
	v_mfma_f32_16x16x32_bf16 v[84:87], v[148:151], v[204:207], v[84:87]
	v_mfma_f32_16x16x32_bf16 v[80:83], v[156:159], v[204:207], v[80:83]
	s_barrier
	s_add_i32 s4, 0, 0x14000
	s_add_i32 s5, s41, s26
	s_mov_b32 m0, s5
	ds_read_b128 v[208:211], v255 offset:16384
	ds_read_b128 v[212:215], v255 offset:17408
	ds_read_b128 v[216:219], v255 offset:18432
	ds_read_b128 v[220:223], v255 offset:19456
	global_load_lds_dwordx4 v136, s[42:43]
	s_add_i32 m0, s5, 0x2000
	s_add_u32 vcc_lo, s42, s52
	s_addc_u32 vcc_hi, s43, s53
	global_load_lds_dwordx4 v136, vcc
	s_barrier
	s_waitcnt lgkmcnt(0)
	v_mfma_f32_16x16x32_bf16 v[124:127], v[208:211], v[160:163], 0
	v_mfma_f32_16x16x32_bf16 v[120:123], v[216:219], v[160:163], 0
	v_mfma_f32_16x16x32_bf16 v[108:111], v[208:211], v[172:175], 0
	v_mfma_f32_16x16x32_bf16 v[104:107], v[216:219], v[172:175], 0
	v_mfma_f32_16x16x32_bf16 v[92:95], v[208:211], v[180:183], 0
	v_mfma_f32_16x16x32_bf16 v[88:91], v[216:219], v[180:183], 0
	v_mfma_f32_16x16x32_bf16 v[76:79], v[208:211], v[200:203], 0
	v_mfma_f32_16x16x32_bf16 v[72:75], v[216:219], v[200:203], 0
	v_mfma_f32_16x16x32_bf16 v[124:127], v[212:215], v[164:167], v[124:127]
	v_mfma_f32_16x16x32_bf16 v[120:123], v[220:223], v[164:167], v[120:123]
	v_mfma_f32_16x16x32_bf16 v[108:111], v[212:215], v[176:179], v[108:111]
	v_mfma_f32_16x16x32_bf16 v[104:107], v[220:223], v[176:179], v[104:107]
	v_mfma_f32_16x16x32_bf16 v[92:95], v[212:215], v[196:199], v[92:95]
	v_mfma_f32_16x16x32_bf16 v[88:91], v[220:223], v[196:199], v[88:91]
	v_mfma_f32_16x16x32_bf16 v[76:79], v[212:215], v[204:207], v[76:79]
	v_mfma_f32_16x16x32_bf16 v[72:75], v[220:223], v[204:207], v[72:75]
	s_barrier
	s_mov_b32 m0, s27
	ds_read_b128 v[160:163], v146 offset:16384
	ds_read_b128 v[164:167], v146 offset:17408
	ds_read_b128 v[172:175], v146 offset:18432
	ds_read_b128 v[176:179], v146 offset:19456
	ds_read_b128 v[180:183], v146 offset:20480
	ds_read_b128 v[196:199], v146 offset:21504
	ds_read_b128 v[200:203], v146 offset:22528
	ds_read_b128 v[204:207], v146 offset:23552
	global_load_lds_dwordx4 v2, s[22:23]
	s_mov_b32 m0, s28
	s_add_u32 vcc_lo, s22, s52
	s_addc_u32 vcc_hi, s23, s53
	global_load_lds_dwordx4 v2, vcc
	s_barrier
	s_waitcnt lgkmcnt(0)
	v_mfma_f32_16x16x32_bf16 v[68:71], v[140:143], v[160:163], 0
	v_mfma_f32_16x16x32_bf16 v[64:67], v[152:155], v[160:163], 0
	v_mfma_f32_16x16x32_bf16 v[52:55], v[140:143], v[172:175], 0
	v_mfma_f32_16x16x32_bf16 v[48:51], v[152:155], v[172:175], 0
	v_mfma_f32_16x16x32_bf16 v[36:39], v[140:143], v[180:183], 0
	v_mfma_f32_16x16x32_bf16 v[32:35], v[152:155], v[180:183], 0
	v_mfma_f32_16x16x32_bf16 v[20:23], v[140:143], v[200:203], 0
	v_mfma_f32_16x16x32_bf16 v[16:19], v[152:155], v[200:203], 0
	v_mfma_f32_16x16x32_bf16 v[68:71], v[148:151], v[164:167], v[68:71]
	v_mfma_f32_16x16x32_bf16 v[64:67], v[156:159], v[164:167], v[64:67]
	v_mfma_f32_16x16x32_bf16 v[52:55], v[148:151], v[176:179], v[52:55]
	v_mfma_f32_16x16x32_bf16 v[48:51], v[156:159], v[176:179], v[48:51]
	v_mfma_f32_16x16x32_bf16 v[36:39], v[148:151], v[196:199], v[36:39]
	v_mfma_f32_16x16x32_bf16 v[32:35], v[156:159], v[196:199], v[32:35]
	v_mfma_f32_16x16x32_bf16 v[20:23], v[148:151], v[204:207], v[20:23]
	v_mfma_f32_16x16x32_bf16 v[16:19], v[156:159], v[204:207], v[16:19]
	s_barrier
; #define G_STAGE(bufoff, gbase, o0, h64) do { \
;         __builtin_amdgcn_global_load_lds((const unsigned*)((const char*)(gbase) + (o0)), (LAS unsigned*)(lds + (bufoff) + ldsw), 16, 0, 0); \
;         __builtin_amdgcn_global_load_lds((const unsigned*)((const char*)(gbase) + (h64) + (o0)), (LAS unsigned*)(lds + (bufoff) + ldsw + 8192), 16, 0, 0); } while (0)
; #define G_LDA(dst, b, h) do { _Pragma("unroll") for (int m = 0; m < 4; ++m) _Pragma("unroll") for (int k = 0; k < 2; ++k) dst[m][k] = *(const LAS bf16x8*)(lds + G_SA(b, h) + aoff + m * 2048 + k * 1024); } while (0)
; #define G_LDB(dst, b, h) do { _Pragma("unroll") for (int n = 0; n < 2; ++n) _Pragma("unroll") for (int k = 0; k < 2; ++k) dst[n][k] = *(const LAS bf16x8*)(lds + G_SB(b, h) + boff + n * 2048 + k * 1024); } while (0)
; #define G_WAIT_V(n) asm volatile("s_waitcnt vmcnt(" #n ")" ::: "memory")
; #define G_BAR __builtin_amdgcn_s_barrier()
;     ...
;         for (int t = 0; t < nt; t += 2) {
;             const bool last = (t == nt - 2);
;             const char* a1 = cA + (size_t)(t + 1) * ckA;
;             const char* a2 = last ? nA : cA + (size_t)(t + 2) * ckA; const char* b2 = last ? nB : cB + (size_t)(t + 2) * kB;
;             const char* a3 = a2 + ckA; const char* b3 = b2 + kB;
;             G_LDB(B0, 0, 0); G_SCHED; G_LDA(At, 0, 0); G_STAGE(G_SA(1, 1), a1 + chA, cA0, qA);
;             G_WAIT_L(8); G_BAR; G_WAIT_L(0); G_MMA(0, 0, At, B0); G_BAR; G_SCHED;
;             G_LDB(B1, 0, 1); G_STAGE(G_SB(0, 0), b2, cB0, qB);
;             G_BAR; G_WAIT_L(0); G_MMA(0, 1, At, B1); G_BAR;
;             G_LDA(At, 0, 1); G_STAGE(G_SA(0, 0), a2, cA0, qA);
;             G_BAR; G_WAIT_L(0); G_MMA(1, 0, At, B0); G_BAR; G_SCHED;
;             G_STAGE(G_SB(0, 1), b2 + chB, cB0, qB);
;             G_WAIT_V(6); G_BAR; G_MMA(1, 1, At, B1); G_BAR;
;             G_LDB(B0, 1, 0); G_SCHED; G_LDA(At, 1, 0); G_STAGE(G_SA(0, 1), a2 + chA, cA0, qA);
;             G_WAIT_L(8); G_BAR; G_WAIT_L(0); G_MMA(0, 0, At, B0); G_BAR; G_SCHED;
;             G_LDB(B1, 1, 1); G_STAGE(G_SB(1, 0), b3, cB0, qB);
;             G_BAR; G_WAIT_L(0); G_MMA(0, 1, At, B1); G_BAR;
;             G_LDA(At, 1, 1); G_STAGE(G_SA(1, 0), a3, cA0, qA);
;             G_BAR; G_WAIT_L(0); G_MMA(1, 0, At, B0); G_BAR; G_SCHED;
;             G_STAGE(G_SB(1, 1), b3 + chB, cB0, qB);
;             G_WAIT_V(6); G_BAR; G_MMA(1, 1, At, B1); G_BAR;
	s_add_i32 s4, s4, s26
	s_mov_b32 m0, s4
	s_add_u32 vcc_lo, s42, s0
	s_addc_u32 vcc_hi, s43, s1
	global_load_lds_dwordx4 v136, vcc
	s_add_i32 m0, s4, 0x2000
	s_add_u32 vcc_lo, s42, s54
	s_addc_u32 vcc_hi, s43, s55
	global_load_lds_dwordx4 v136, vcc
	s_waitcnt vmcnt(6)
	s_barrier
	v_mfma_f32_16x16x32_bf16 v[60:63], v[208:211], v[160:163], 0
	v_mfma_f32_16x16x32_bf16 v[56:59], v[216:219], v[160:163], 0
	v_mfma_f32_16x16x32_bf16 v[44:47], v[208:211], v[172:175], 0
	v_mfma_f32_16x16x32_bf16 v[40:43], v[216:219], v[172:175], 0
	v_mfma_f32_16x16x32_bf16 v[28:31], v[208:211], v[180:183], 0
	v_mfma_f32_16x16x32_bf16 v[24:27], v[216:219], v[180:183], 0
	v_mfma_f32_16x16x32_bf16 v[12:15], v[208:211], v[200:203], 0
	v_mfma_f32_16x16x32_bf16 v[8:11], v[216:219], v[200:203], 0
	v_mfma_f32_16x16x32_bf16 v[60:63], v[212:215], v[164:167], v[60:63]
	v_mfma_f32_16x16x32_bf16 v[56:59], v[220:223], v[164:167], v[56:59]
	v_mfma_f32_16x16x32_bf16 v[44:47], v[212:215], v[176:179], v[44:47]
	v_mfma_f32_16x16x32_bf16 v[40:43], v[220:223], v[176:179], v[40:43]
	v_mfma_f32_16x16x32_bf16 v[28:31], v[212:215], v[196:199], v[28:31]
	v_mfma_f32_16x16x32_bf16 v[24:27], v[220:223], v[196:199], v[24:27]
	v_mfma_f32_16x16x32_bf16 v[12:15], v[212:215], v[204:207], v[12:15]
	v_mfma_f32_16x16x32_bf16 v[8:11], v[220:223], v[204:207], v[8:11]
	s_barrier
	s_add_i32 s4, 0, 0x18000
	ds_read_b128 v[140:143], v255 offset:32768
	ds_read_b128 v[148:151], v255 offset:33792
	ds_read_b128 v[152:155], v255 offset:34816
	ds_read_b128 v[156:159], v255 offset:35840
	s_mov_b32 m0, s29
	ds_read_b128 v[160:163], v146 offset:32768
	ds_read_b128 v[164:167], v146 offset:33792
	ds_read_b128 v[172:175], v146 offset:34816
	ds_read_b128 v[176:179], v146 offset:35840
	ds_read_b128 v[180:183], v146 offset:36864
	ds_read_b128 v[196:199], v146 offset:37888
	ds_read_b128 v[200:203], v146 offset:38912
	ds_read_b128 v[204:207], v146 offset:39936
	s_add_u32 vcc_lo, s22, s0
	s_addc_u32 vcc_hi, s23, s1
	global_load_lds_dwordx4 v2, vcc
	s_mov_b32 m0, s30
	s_add_u32 vcc_lo, s22, s54
	s_addc_u32 vcc_hi, s23, s55
	global_load_lds_dwordx4 v2, vcc
	s_waitcnt lgkmcnt(8)
	s_barrier
	s_waitcnt lgkmcnt(0)
	v_mfma_f32_16x16x32_bf16 v[132:135], v[140:143], v[160:163], v[132:135]
	v_mfma_f32_16x16x32_bf16 v[128:131], v[152:155], v[160:163], v[128:131]
	v_mfma_f32_16x16x32_bf16 v[116:119], v[140:143], v[172:175], v[116:119]
	v_mfma_f32_16x16x32_bf16 v[112:115], v[152:155], v[172:175], v[112:115]
	v_mfma_f32_16x16x32_bf16 v[100:103], v[140:143], v[180:183], v[100:103]
	v_mfma_f32_16x16x32_bf16 v[96:99], v[152:155], v[180:183], v[96:99]
	v_mfma_f32_16x16x32_bf16 v[84:87], v[140:143], v[200:203], v[84:87]
	v_mfma_f32_16x16x32_bf16 v[80:83], v[152:155], v[200:203], v[80:83]
	v_mfma_f32_16x16x32_bf16 v[132:135], v[148:151], v[164:167], v[132:135]
	v_mfma_f32_16x16x32_bf16 v[128:131], v[156:159], v[164:167], v[128:131]
	v_mfma_f32_16x16x32_bf16 v[116:119], v[148:151], v[176:179], v[116:119]
	v_mfma_f32_16x16x32_bf16 v[112:115], v[156:159], v[176:179], v[112:115]
	v_mfma_f32_16x16x32_bf16 v[100:103], v[148:151], v[196:199], v[100:103]
	v_mfma_f32_16x16x32_bf16 v[96:99], v[156:159], v[196:199], v[96:99]
	v_mfma_f32_16x16x32_bf16 v[84:87], v[148:151], v[204:207], v[84:87]
	v_mfma_f32_16x16x32_bf16 v[80:83], v[156:159], v[204:207], v[80:83]
	s_barrier
	s_add_i32 s5, 0, 0x1c000
	s_add_i32 s4, s4, s26
	s_mov_b32 m0, s4
	ds_read_b128 v[208:211], v255 offset:49152
	ds_read_b128 v[212:215], v255 offset:50176
	ds_read_b128 v[216:219], v255 offset:51200
	ds_read_b128 v[220:223], v255 offset:52224
	s_add_u32 vcc_lo, s42, s46
	s_addc_u32 vcc_hi, s43, s47
	global_load_lds_dwordx4 v136, vcc
	s_add_i32 m0, s4, 0x2000
	s_add_u32 vcc_lo, s42, s58
	s_addc_u32 vcc_hi, s43, s59
	global_load_lds_dwordx4 v136, vcc
	s_barrier
	s_waitcnt lgkmcnt(0)
	v_mfma_f32_16x16x32_bf16 v[124:127], v[208:211], v[160:163], v[124:127]
	v_mfma_f32_16x16x32_bf16 v[120:123], v[216:219], v[160:163], v[120:123]
	v_mfma_f32_16x16x32_bf16 v[108:111], v[208:211], v[172:175], v[108:111]
	v_mfma_f32_16x16x32_bf16 v[104:107], v[216:219], v[172:175], v[104:107]
	v_mfma_f32_16x16x32_bf16 v[92:95], v[208:211], v[180:183], v[92:95]
	v_mfma_f32_16x16x32_bf16 v[88:91], v[216:219], v[180:183], v[88:91]
	v_mfma_f32_16x16x32_bf16 v[76:79], v[208:211], v[200:203], v[76:79]
	v_mfma_f32_16x16x32_bf16 v[72:75], v[216:219], v[200:203], v[72:75]
	v_mfma_f32_16x16x32_bf16 v[124:127], v[212:215], v[164:167], v[124:127]
	v_mfma_f32_16x16x32_bf16 v[120:123], v[220:223], v[164:167], v[120:123]
	v_mfma_f32_16x16x32_bf16 v[108:111], v[212:215], v[176:179], v[108:111]
	v_mfma_f32_16x16x32_bf16 v[104:107], v[220:223], v[176:179], v[104:107]
	v_mfma_f32_16x16x32_bf16 v[92:95], v[212:215], v[196:199], v[92:95]
	v_mfma_f32_16x16x32_bf16 v[88:91], v[220:223], v[196:199], v[88:91]
	v_mfma_f32_16x16x32_bf16 v[76:79], v[212:215], v[204:207], v[76:79]
	v_mfma_f32_16x16x32_bf16 v[72:75], v[220:223], v[204:207], v[72:75]
	s_barrier
	s_mov_b32 m0, s31
	ds_read_b128 v[160:163], v146 offset:49152
	ds_read_b128 v[164:167], v146 offset:50176
	ds_read_b128 v[172:175], v146 offset:51200
	ds_read_b128 v[176:179], v146 offset:52224
	ds_read_b128 v[180:183], v146 offset:53248
	ds_read_b128 v[196:199], v146 offset:54272
	ds_read_b128 v[200:203], v146 offset:55296
	ds_read_b128 v[204:207], v146 offset:56320
	s_add_u32 vcc_lo, s22, s46
	s_addc_u32 vcc_hi, s23, s47
	global_load_lds_dwordx4 v2, vcc
	s_mov_b32 m0, s33
	s_add_u32 vcc_lo, s22, s58
	s_addc_u32 vcc_hi, s23, s59
	global_load_lds_dwordx4 v2, vcc
	s_barrier
; #define G_STAGE(bufoff, gbase, o0, h64) do { \
;         __builtin_amdgcn_global_load_lds((const unsigned*)((const char*)(gbase) + (o0)), (LAS unsigned*)(lds + (bufoff) + ldsw), 16, 0, 0); \
;         __builtin_amdgcn_global_load_lds((const unsigned*)((const char*)(gbase) + (h64) + (o0)), (LAS unsigned*)(lds + (bufoff) + ldsw + 8192), 16, 0, 0); } while (0)
; #define G_LDA(dst, b, h) do { _Pragma("unroll") for (int m = 0; m < 4; ++m) _Pragma("unroll") for (int k = 0; k < 2; ++k) dst[m][k] = *(const LAS bf16x8*)(lds + G_SA(b, h) + aoff + m * 2048 + k * 1024); } while (0)
; #define G_LDB(dst, b, h) do { _Pragma("unroll") for (int n = 0; n < 2; ++n) _Pragma("unroll") for (int k = 0; k < 2; ++k) dst[n][k] = *(const LAS bf16x8*)(lds + G_SB(b, h) + boff + n * 2048 + k * 1024); } while (0)
; #define G_WAIT_V(n) asm volatile("s_waitcnt vmcnt(" #n ")" ::: "memory")
; #define G_BAR __builtin_amdgcn_s_barrier()
;     ...
;         for (int t = 0; t < nt; t += 2) {
;             const bool last = (t == nt - 2);
;             const char* a1 = cA + (size_t)(t + 1) * ckA;
;             const char* a2 = last ? nA : cA + (size_t)(t + 2) * ckA; const char* b2 = last ? nB : cB + (size_t)(t + 2) * kB;
;             const char* a3 = a2 + ckA; const char* b3 = b2 + kB;
;             G_LDB(B0, 0, 0); G_SCHED; G_LDA(At, 0, 0); G_STAGE(G_SA(1, 1), a1 + chA, cA0, qA);
;             G_WAIT_L(8); G_BAR; G_WAIT_L(0); G_MMA(0, 0, At, B0); G_BAR; G_SCHED;
;             G_LDB(B1, 0, 1); G_STAGE(G_SB(0, 0), b2, cB0, qB);
;             G_BAR; G_WAIT_L(0); G_MMA(0, 1, At, B1); G_BAR;
;             G_LDA(At, 0, 1); G_STAGE(G_SA(0, 0), a2, cA0, qA);
;             G_BAR; G_WAIT_L(0); G_MMA(1, 0, At, B0); G_BAR; G_SCHED;
;             G_STAGE(G_SB(0, 1), b2 + chB, cB0, qB);
;             G_WAIT_V(6); G_BAR; G_MMA(1, 1, At, B1); G_BAR;
;             G_LDB(B0, 1, 0); G_SCHED; G_LDA(At, 1, 0); G_STAGE(G_SA(0, 1), a2 + chA, cA0, qA);
;             G_WAIT_L(8); G_BAR; G_WAIT_L(0); G_MMA(0, 0, At, B0); G_BAR; G_SCHED;
;             G_LDB(B1, 1, 1); G_STAGE(G_SB(1, 0), b3, cB0, qB);
;             G_BAR; G_WAIT_L(0); G_MMA(0, 1, At, B1); G_BAR;
;             G_LDA(At, 1, 1); G_STAGE(G_SA(1, 0), a3, cA0, qA);
;             G_BAR; G_WAIT_L(0); G_MMA(1, 0, At, B0); G_BAR; G_SCHED;
;             G_STAGE(G_SB(1, 1), b3 + chB, cB0, qB);
;             G_WAIT_V(6); G_BAR; G_MMA(1, 1, At, B1); G_BAR;
	s_waitcnt lgkmcnt(0)
	v_mfma_f32_16x16x32_bf16 v[68:71], v[140:143], v[160:163], v[68:71]
	v_mfma_f32_16x16x32_bf16 v[64:67], v[152:155], v[160:163], v[64:67]
	v_mfma_f32_16x16x32_bf16 v[52:55], v[140:143], v[172:175], v[52:55]
	v_mfma_f32_16x16x32_bf16 v[48:51], v[152:155], v[172:175], v[48:51]
	v_mfma_f32_16x16x32_bf16 v[36:39], v[140:143], v[180:183], v[36:39]
	v_mfma_f32_16x16x32_bf16 v[32:35], v[152:155], v[180:183], v[32:35]
	v_mfma_f32_16x16x32_bf16 v[20:23], v[140:143], v[200:203], v[20:23]
	v_mfma_f32_16x16x32_bf16 v[16:19], v[152:155], v[200:203], v[16:19]
	v_mfma_f32_16x16x32_bf16 v[68:71], v[148:151], v[164:167], v[68:71]
	v_mfma_f32_16x16x32_bf16 v[64:67], v[156:159], v[164:167], v[64:67]
	v_mfma_f32_16x16x32_bf16 v[52:55], v[148:151], v[176:179], v[52:55]
	v_mfma_f32_16x16x32_bf16 v[48:51], v[156:159], v[176:179], v[48:51]
	v_mfma_f32_16x16x32_bf16 v[36:39], v[148:151], v[196:199], v[36:39]
	v_mfma_f32_16x16x32_bf16 v[32:35], v[156:159], v[196:199], v[32:35]
	v_mfma_f32_16x16x32_bf16 v[20:23], v[148:151], v[204:207], v[20:23]
	v_mfma_f32_16x16x32_bf16 v[16:19], v[156:159], v[204:207], v[16:19]
	s_barrier
	s_add_i32 s4, s5, s26
	s_mov_b32 m0, s4
	s_add_u32 vcc_lo, s42, s50
	s_addc_u32 vcc_hi, s43, s51
	global_load_lds_dwordx4 v136, vcc
	s_add_i32 m0, s4, 0x2000
	s_add_u32 vcc_lo, s42, s62
	s_addc_u32 vcc_hi, s43, s63
	global_load_lds_dwordx4 v136, vcc
	s_add_i32 s21, s21, 2
	s_add_u32 s6, s6, 0x100
	s_addc_u32 s7, s7, 0
	s_add_u32 s19, s19, 0x100
	s_addc_u32 s20, s20, 0
	s_cmp_gt_u32 s21, 5
	s_waitcnt vmcnt(6)
	s_barrier
	v_mfma_f32_16x16x32_bf16 v[60:63], v[208:211], v[160:163], v[60:63]
	v_mfma_f32_16x16x32_bf16 v[56:59], v[216:219], v[160:163], v[56:59]
	v_mfma_f32_16x16x32_bf16 v[44:47], v[208:211], v[172:175], v[44:47]
	v_mfma_f32_16x16x32_bf16 v[40:43], v[216:219], v[172:175], v[40:43]
	v_mfma_f32_16x16x32_bf16 v[28:31], v[208:211], v[180:183], v[28:31]
	v_mfma_f32_16x16x32_bf16 v[24:27], v[216:219], v[180:183], v[24:27]
	v_mfma_f32_16x16x32_bf16 v[12:15], v[208:211], v[200:203], v[12:15]
	v_mfma_f32_16x16x32_bf16 v[8:11], v[216:219], v[200:203], v[8:11]
	v_mfma_f32_16x16x32_bf16 v[60:63], v[212:215], v[164:167], v[60:63]
	v_mfma_f32_16x16x32_bf16 v[56:59], v[220:223], v[164:167], v[56:59]
	v_mfma_f32_16x16x32_bf16 v[44:47], v[212:215], v[176:179], v[44:47]
	v_mfma_f32_16x16x32_bf16 v[40:43], v[220:223], v[176:179], v[40:43]
	v_mfma_f32_16x16x32_bf16 v[28:31], v[212:215], v[196:199], v[28:31]
	v_mfma_f32_16x16x32_bf16 v[24:27], v[220:223], v[196:199], v[24:27]
	v_mfma_f32_16x16x32_bf16 v[12:15], v[212:215], v[204:207], v[12:15]
	v_mfma_f32_16x16x32_bf16 v[8:11], v[220:223], v[204:207], v[8:11]
	s_cbranch_scc0 .Ldb_SSM1_cont
	s_branch .Ldb_SSM1_xl
.LBB0_450:
	s_add_u32 s4, s6, 0xfffe0080
	s_addc_u32 s5, s7, -1
	s_add_i32 s41, 0, 0x10000
	ds_read_b128 v[140:143], v255 offset:0
	ds_read_b128 v[148:151], v255 offset:1024
	ds_read_b128 v[152:155], v255 offset:2048
	ds_read_b128 v[156:159], v255 offset:3072
	s_cmp_eq_u32 s21, 4
	s_cselect_b32 s23, s11, s5
	s_cselect_b32 s22, s10, s4
	s_cselect_b32 s43, s17, s20
	s_cselect_b32 s42, s16, s19
	s_add_i32 m0, s27, 0xc000
	ds_read_b128 v[160:163], v146
	ds_read_b128 v[164:167], v146 offset:1024
	ds_read_b128 v[172:175], v146 offset:2048
	ds_read_b128 v[176:179], v146 offset:3072
	ds_read_b128 v[180:183], v146 offset:4096
	ds_read_b128 v[196:199], v146 offset:5120
	ds_read_b128 v[200:203], v146 offset:6144
	ds_read_b128 v[204:207], v146 offset:7168
	global_load_lds_dwordx4 v138, s[6:7]
	s_add_i32 m0, s27, 0xe000
	s_add_u32 vcc_lo, s6, s52
	s_addc_u32 vcc_hi, s7, s53
	global_load_lds_dwordx4 v138, vcc
	s_waitcnt lgkmcnt(8)
	s_barrier
	s_waitcnt lgkmcnt(0)
	v_mfma_f32_16x16x32_bf16 v[132:135], v[140:143], v[160:163], v[132:135]
	v_mfma_f32_16x16x32_bf16 v[128:131], v[152:155], v[160:163], v[128:131]
	v_mfma_f32_16x16x32_bf16 v[116:119], v[140:143], v[172:175], v[116:119]
	v_mfma_f32_16x16x32_bf16 v[112:115], v[152:155], v[172:175], v[112:115]
	v_mfma_f32_16x16x32_bf16 v[100:103], v[140:143], v[180:183], v[100:103]
	v_mfma_f32_16x16x32_bf16 v[96:99], v[152:155], v[180:183], v[96:99]
	v_mfma_f32_16x16x32_bf16 v[84:87], v[140:143], v[200:203], v[84:87]
	v_mfma_f32_16x16x32_bf16 v[80:83], v[152:155], v[200:203], v[80:83]
	v_mfma_f32_16x16x32_bf16 v[132:135], v[148:151], v[164:167], v[132:135]
	v_mfma_f32_16x16x32_bf16 v[128:131], v[156:159], v[164:167], v[128:131]
	v_mfma_f32_16x16x32_bf16 v[116:119], v[148:151], v[176:179], v[116:119]
	v_mfma_f32_16x16x32_bf16 v[112:115], v[156:159], v[176:179], v[112:115]
	v_mfma_f32_16x16x32_bf16 v[100:103], v[148:151], v[196:199], v[100:103]
	v_mfma_f32_16x16x32_bf16 v[96:99], v[156:159], v[196:199], v[96:99]
	v_mfma_f32_16x16x32_bf16 v[84:87], v[148:151], v[204:207], v[84:87]
	v_mfma_f32_16x16x32_bf16 v[80:83], v[156:159], v[204:207], v[80:83]
	s_barrier
	s_add_i32 s4, 0, 0x14000
	s_add_i32 s5, s41, s26
	s_mov_b32 m0, s5
	ds_read_b128 v[208:211], v255 offset:16384
	ds_read_b128 v[212:215], v255 offset:17408
	ds_read_b128 v[216:219], v255 offset:18432
	ds_read_b128 v[220:223], v255 offset:19456
	global_load_lds_dwordx4 v136, s[42:43]
	s_add_i32 m0, s5, 0x2000
	s_add_u32 vcc_lo, s42, s52
	s_addc_u32 vcc_hi, s43, s53
	global_load_lds_dwordx4 v136, vcc
	s_barrier
; #define G_STAGE(bufoff, gbase, o0, h64) do { \
;         __builtin_amdgcn_global_load_lds((const unsigned*)((const char*)(gbase) + (o0)), (LAS unsigned*)(lds + (bufoff) + ldsw), 16, 0, 0); \
;         __builtin_amdgcn_global_load_lds((const unsigned*)((const char*)(gbase) + (h64) + (o0)), (LAS unsigned*)(lds + (bufoff) + ldsw + 8192), 16, 0, 0); } while (0)
; #define G_LDA(dst, b, h) do { _Pragma("unroll") for (int m = 0; m < 4; ++m) _Pragma("unroll") for (int k = 0; k < 2; ++k) dst[m][k] = *(const LAS bf16x8*)(lds + G_SA(b, h) + aoff + m * 2048 + k * 1024); } while (0)
; #define G_LDB(dst, b, h) do { _Pragma("unroll") for (int n = 0; n < 2; ++n) _Pragma("unroll") for (int k = 0; k < 2; ++k) dst[n][k] = *(const LAS bf16x8*)(lds + G_SB(b, h) + boff + n * 2048 + k * 1024); } while (0)
; #define G_WAIT_V(n) asm volatile("s_waitcnt vmcnt(" #n ")" ::: "memory")
; #define G_BAR __builtin_amdgcn_s_barrier()
;     ...
;         for (int t = 0; t < nt; t += 2) {
;             const bool last = (t == nt - 2);
;             const char* a1 = cA + (size_t)(t + 1) * ckA;
;             const char* a2 = last ? nA : cA + (size_t)(t + 2) * ckA; const char* b2 = last ? nB : cB + (size_t)(t + 2) * kB;
;             const char* a3 = a2 + ckA; const char* b3 = b2 + kB;
;             G_LDB(B0, 0, 0); G_SCHED; G_LDA(At, 0, 0); G_STAGE(G_SA(1, 1), a1 + chA, cA0, qA);
;             G_WAIT_L(8); G_BAR; G_WAIT_L(0); G_MMA(0, 0, At, B0); G_BAR; G_SCHED;
;             G_LDB(B1, 0, 1); G_STAGE(G_SB(0, 0), b2, cB0, qB);
;             G_BAR; G_WAIT_L(0); G_MMA(0, 1, At, B1); G_BAR;
;             G_LDA(At, 0, 1); G_STAGE(G_SA(0, 0), a2, cA0, qA);
;             G_BAR; G_WAIT_L(0); G_MMA(1, 0, At, B0); G_BAR; G_SCHED;
;             G_STAGE(G_SB(0, 1), b2 + chB, cB0, qB);
;             G_WAIT_V(6); G_BAR; G_MMA(1, 1, At, B1); G_BAR;
;             G_LDB(B0, 1, 0); G_SCHED; G_LDA(At, 1, 0); G_STAGE(G_SA(0, 1), a2 + chA, cA0, qA);
;             G_WAIT_L(8); G_BAR; G_WAIT_L(0); G_MMA(0, 0, At, B0); G_BAR; G_SCHED;
;             G_LDB(B1, 1, 1); G_STAGE(G_SB(1, 0), b3, cB0, qB);
;             G_BAR; G_WAIT_L(0); G_MMA(0, 1, At, B1); G_BAR;
;             G_LDA(At, 1, 1); G_STAGE(G_SA(1, 0), a3, cA0, qA);
;             G_BAR; G_WAIT_L(0); G_MMA(1, 0, At, B0); G_BAR; G_SCHED;
;             G_STAGE(G_SB(1, 1), b3 + chB, cB0, qB);
;             G_WAIT_V(6); G_BAR; G_MMA(1, 1, At, B1); G_BAR;
	s_waitcnt lgkmcnt(0)
	v_mfma_f32_16x16x32_bf16 v[124:127], v[208:211], v[160:163], v[124:127]
	v_mfma_f32_16x16x32_bf16 v[120:123], v[216:219], v[160:163], v[120:123]
	v_mfma_f32_16x16x32_bf16 v[108:111], v[208:211], v[172:175], v[108:111]
	v_mfma_f32_16x16x32_bf16 v[104:107], v[216:219], v[172:175], v[104:107]
	v_mfma_f32_16x16x32_bf16 v[92:95], v[208:211], v[180:183], v[92:95]
	v_mfma_f32_16x16x32_bf16 v[88:91], v[216:219], v[180:183], v[88:91]
	v_mfma_f32_16x16x32_bf16 v[76:79], v[208:211], v[200:203], v[76:79]
	v_mfma_f32_16x16x32_bf16 v[72:75], v[216:219], v[200:203], v[72:75]
	v_mfma_f32_16x16x32_bf16 v[124:127], v[212:215], v[164:167], v[124:127]
	v_mfma_f32_16x16x32_bf16 v[120:123], v[220:223], v[164:167], v[120:123]
	v_mfma_f32_16x16x32_bf16 v[108:111], v[212:215], v[176:179], v[108:111]
	v_mfma_f32_16x16x32_bf16 v[104:107], v[220:223], v[176:179], v[104:107]
	v_mfma_f32_16x16x32_bf16 v[92:95], v[212:215], v[196:199], v[92:95]
	v_mfma_f32_16x16x32_bf16 v[88:91], v[220:223], v[196:199], v[88:91]
	v_mfma_f32_16x16x32_bf16 v[76:79], v[212:215], v[204:207], v[76:79]
	v_mfma_f32_16x16x32_bf16 v[72:75], v[220:223], v[204:207], v[72:75]
	s_barrier
	s_mov_b32 m0, s27
	ds_read_b128 v[160:163], v146 offset:16384
	ds_read_b128 v[164:167], v146 offset:17408
	ds_read_b128 v[172:175], v146 offset:18432
	ds_read_b128 v[176:179], v146 offset:19456
	ds_read_b128 v[180:183], v146 offset:20480
	ds_read_b128 v[196:199], v146 offset:21504
	ds_read_b128 v[200:203], v146 offset:22528
	ds_read_b128 v[204:207], v146 offset:23552
	global_load_lds_dwordx4 v2, s[22:23]
	s_mov_b32 m0, s28
	s_add_u32 vcc_lo, s22, s52
	s_addc_u32 vcc_hi, s23, s53
	global_load_lds_dwordx4 v2, vcc
	s_barrier
	s_waitcnt lgkmcnt(0)
	v_mfma_f32_16x16x32_bf16 v[68:71], v[140:143], v[160:163], v[68:71]
	v_mfma_f32_16x16x32_bf16 v[64:67], v[152:155], v[160:163], v[64:67]
	v_mfma_f32_16x16x32_bf16 v[52:55], v[140:143], v[172:175], v[52:55]
	v_mfma_f32_16x16x32_bf16 v[48:51], v[152:155], v[172:175], v[48:51]
	v_mfma_f32_16x16x32_bf16 v[36:39], v[140:143], v[180:183], v[36:39]
	v_mfma_f32_16x16x32_bf16 v[32:35], v[152:155], v[180:183], v[32:35]
	v_mfma_f32_16x16x32_bf16 v[20:23], v[140:143], v[200:203], v[20:23]
	v_mfma_f32_16x16x32_bf16 v[16:19], v[152:155], v[200:203], v[16:19]
	v_mfma_f32_16x16x32_bf16 v[68:71], v[148:151], v[164:167], v[68:71]
	v_mfma_f32_16x16x32_bf16 v[64:67], v[156:159], v[164:167], v[64:67]
	v_mfma_f32_16x16x32_bf16 v[52:55], v[148:151], v[176:179], v[52:55]
	v_mfma_f32_16x16x32_bf16 v[48:51], v[156:159], v[176:179], v[48:51]
	v_mfma_f32_16x16x32_bf16 v[36:39], v[148:151], v[196:199], v[36:39]
	v_mfma_f32_16x16x32_bf16 v[32:35], v[156:159], v[196:199], v[32:35]
	v_mfma_f32_16x16x32_bf16 v[20:23], v[148:151], v[204:207], v[20:23]
	v_mfma_f32_16x16x32_bf16 v[16:19], v[156:159], v[204:207], v[16:19]
	s_barrier
	s_add_i32 s4, s4, s26
	s_mov_b32 m0, s4
	s_add_u32 vcc_lo, s42, s0
	s_addc_u32 vcc_hi, s43, s1
	global_load_lds_dwordx4 v136, vcc
	s_add_i32 m0, s4, 0x2000
	s_add_u32 vcc_lo, s42, s54
	s_addc_u32 vcc_hi, s43, s55
	global_load_lds_dwordx4 v136, vcc
	s_waitcnt vmcnt(6)
	s_barrier
	v_mfma_f32_16x16x32_bf16 v[60:63], v[208:211], v[160:163], v[60:63]
	v_mfma_f32_16x16x32_bf16 v[56:59], v[216:219], v[160:163], v[56:59]
	v_mfma_f32_16x16x32_bf16 v[44:47], v[208:211], v[172:175], v[44:47]
	v_mfma_f32_16x16x32_bf16 v[40:43], v[216:219], v[172:175], v[40:43]
	v_mfma_f32_16x16x32_bf16 v[28:31], v[208:211], v[180:183], v[28:31]
	v_mfma_f32_16x16x32_bf16 v[24:27], v[216:219], v[180:183], v[24:27]
	v_mfma_f32_16x16x32_bf16 v[12:15], v[208:211], v[200:203], v[12:15]
	v_mfma_f32_16x16x32_bf16 v[8:11], v[216:219], v[200:203], v[8:11]
	v_mfma_f32_16x16x32_bf16 v[60:63], v[212:215], v[164:167], v[60:63]
	v_mfma_f32_16x16x32_bf16 v[56:59], v[220:223], v[164:167], v[56:59]
	v_mfma_f32_16x16x32_bf16 v[44:47], v[212:215], v[176:179], v[44:47]
	v_mfma_f32_16x16x32_bf16 v[40:43], v[220:223], v[176:179], v[40:43]
	v_mfma_f32_16x16x32_bf16 v[28:31], v[212:215], v[196:199], v[28:31]
	v_mfma_f32_16x16x32_bf16 v[24:27], v[220:223], v[196:199], v[24:27]
	v_mfma_f32_16x16x32_bf16 v[12:15], v[212:215], v[204:207], v[12:15]
	v_mfma_f32_16x16x32_bf16 v[8:11], v[220:223], v[204:207], v[8:11]
	s_barrier
	s_add_i32 s4, 0, 0x18000
	ds_read_b128 v[140:143], v255 offset:32768
	ds_read_b128 v[148:151], v255 offset:33792
	ds_read_b128 v[152:155], v255 offset:34816
	ds_read_b128 v[156:159], v255 offset:35840
	s_mov_b32 m0, s29
	ds_read_b128 v[160:163], v146 offset:32768
	ds_read_b128 v[164:167], v146 offset:33792
	ds_read_b128 v[172:175], v146 offset:34816
	ds_read_b128 v[176:179], v146 offset:35840
	ds_read_b128 v[180:183], v146 offset:36864
	ds_read_b128 v[196:199], v146 offset:37888
	ds_read_b128 v[200:203], v146 offset:38912
	ds_read_b128 v[204:207], v146 offset:39936
	s_add_u32 vcc_lo, s22, s0
	s_addc_u32 vcc_hi, s23, s1
	global_load_lds_dwordx4 v2, vcc
	s_mov_b32 m0, s30
	s_add_u32 vcc_lo, s22, s54
	s_addc_u32 vcc_hi, s23, s55
	global_load_lds_dwordx4 v2, vcc
	s_waitcnt lgkmcnt(8)
	s_barrier
; #define G_STAGE(bufoff, gbase, o0, h64) do { \
;         __builtin_amdgcn_global_load_lds((const unsigned*)((const char*)(gbase) + (o0)), (LAS unsigned*)(lds + (bufoff) + ldsw), 16, 0, 0); \
;         __builtin_amdgcn_global_load_lds((const unsigned*)((const char*)(gbase) + (h64) + (o0)), (LAS unsigned*)(lds + (bufoff) + ldsw + 8192), 16, 0, 0); } while (0)
; #define G_LDA(dst, b, h) do { _Pragma("unroll") for (int m = 0; m < 4; ++m) _Pragma("unroll") for (int k = 0; k < 2; ++k) dst[m][k] = *(const LAS bf16x8*)(lds + G_SA(b, h) + aoff + m * 2048 + k * 1024); } while (0)
; #define G_LDB(dst, b, h) do { _Pragma("unroll") for (int n = 0; n < 2; ++n) _Pragma("unroll") for (int k = 0; k < 2; ++k) dst[n][k] = *(const LAS bf16x8*)(lds + G_SB(b, h) + boff + n * 2048 + k * 1024); } while (0)
; #define G_WAIT_V(n) asm volatile("s_waitcnt vmcnt(" #n ")" ::: "memory")
; #define G_BAR __builtin_amdgcn_s_barrier()
;     ...
;         for (int t = 0; t < nt; t += 2) {
;             const bool last = (t == nt - 2);
;             const char* a1 = cA + (size_t)(t + 1) * ckA;
;             const char* a2 = last ? nA : cA + (size_t)(t + 2) * ckA; const char* b2 = last ? nB : cB + (size_t)(t + 2) * kB;
;             const char* a3 = a2 + ckA; const char* b3 = b2 + kB;
;             G_LDB(B0, 0, 0); G_SCHED; G_LDA(At, 0, 0); G_STAGE(G_SA(1, 1), a1 + chA, cA0, qA);
;             G_WAIT_L(8); G_BAR; G_WAIT_L(0); G_MMA(0, 0, At, B0); G_BAR; G_SCHED;
;             G_LDB(B1, 0, 1); G_STAGE(G_SB(0, 0), b2, cB0, qB);
;             G_BAR; G_WAIT_L(0); G_MMA(0, 1, At, B1); G_BAR;
;             G_LDA(At, 0, 1); G_STAGE(G_SA(0, 0), a2, cA0, qA);
;             G_BAR; G_WAIT_L(0); G_MMA(1, 0, At, B0); G_BAR; G_SCHED;
;             G_STAGE(G_SB(0, 1), b2 + chB, cB0, qB);
;             G_WAIT_V(6); G_BAR; G_MMA(1, 1, At, B1); G_BAR;
;             G_LDB(B0, 1, 0); G_SCHED; G_LDA(At, 1, 0); G_STAGE(G_SA(0, 1), a2 + chA, cA0, qA);
;             G_WAIT_L(8); G_BAR; G_WAIT_L(0); G_MMA(0, 0, At, B0); G_BAR; G_SCHED;
;             G_LDB(B1, 1, 1); G_STAGE(G_SB(1, 0), b3, cB0, qB);
;             G_BAR; G_WAIT_L(0); G_MMA(0, 1, At, B1); G_BAR;
;             G_LDA(At, 1, 1); G_STAGE(G_SA(1, 0), a3, cA0, qA);
;             G_BAR; G_WAIT_L(0); G_MMA(1, 0, At, B0); G_BAR; G_SCHED;
;             G_STAGE(G_SB(1, 1), b3 + chB, cB0, qB);
;             G_WAIT_V(6); G_BAR; G_MMA(1, 1, At, B1); G_BAR;
;         }
	s_waitcnt lgkmcnt(0)
	v_mfma_f32_16x16x32_bf16 v[132:135], v[140:143], v[160:163], v[132:135]
	v_mfma_f32_16x16x32_bf16 v[128:131], v[152:155], v[160:163], v[128:131]
	v_mfma_f32_16x16x32_bf16 v[116:119], v[140:143], v[172:175], v[116:119]
	v_mfma_f32_16x16x32_bf16 v[112:115], v[152:155], v[172:175], v[112:115]
	v_mfma_f32_16x16x32_bf16 v[100:103], v[140:143], v[180:183], v[100:103]
	v_mfma_f32_16x16x32_bf16 v[96:99], v[152:155], v[180:183], v[96:99]
	v_mfma_f32_16x16x32_bf16 v[84:87], v[140:143], v[200:203], v[84:87]
	v_mfma_f32_16x16x32_bf16 v[80:83], v[152:155], v[200:203], v[80:83]
	v_mfma_f32_16x16x32_bf16 v[132:135], v[148:151], v[164:167], v[132:135]
	v_mfma_f32_16x16x32_bf16 v[128:131], v[156:159], v[164:167], v[128:131]
	v_mfma_f32_16x16x32_bf16 v[116:119], v[148:151], v[176:179], v[116:119]
	v_mfma_f32_16x16x32_bf16 v[112:115], v[156:159], v[176:179], v[112:115]
	v_mfma_f32_16x16x32_bf16 v[100:103], v[148:151], v[196:199], v[100:103]
	v_mfma_f32_16x16x32_bf16 v[96:99], v[156:159], v[196:199], v[96:99]
	v_mfma_f32_16x16x32_bf16 v[84:87], v[148:151], v[204:207], v[84:87]
	v_mfma_f32_16x16x32_bf16 v[80:83], v[156:159], v[204:207], v[80:83]
	s_barrier
	s_add_i32 s5, 0, 0x1c000
	s_add_i32 s4, s4, s26
	s_mov_b32 m0, s4
	ds_read_b128 v[208:211], v255 offset:49152
	ds_read_b128 v[212:215], v255 offset:50176
	ds_read_b128 v[216:219], v255 offset:51200
	ds_read_b128 v[220:223], v255 offset:52224
	s_add_u32 vcc_lo, s42, s46
	s_addc_u32 vcc_hi, s43, s47
	global_load_lds_dwordx4 v136, vcc
	s_add_i32 m0, s4, 0x2000
	s_add_u32 vcc_lo, s42, s58
	s_addc_u32 vcc_hi, s43, s59
	global_load_lds_dwordx4 v136, vcc
	s_barrier
	s_waitcnt lgkmcnt(0)
	v_mfma_f32_16x16x32_bf16 v[124:127], v[208:211], v[160:163], v[124:127]
	v_mfma_f32_16x16x32_bf16 v[120:123], v[216:219], v[160:163], v[120:123]
	v_mfma_f32_16x16x32_bf16 v[108:111], v[208:211], v[172:175], v[108:111]
	v_mfma_f32_16x16x32_bf16 v[104:107], v[216:219], v[172:175], v[104:107]
	v_mfma_f32_16x16x32_bf16 v[92:95], v[208:211], v[180:183], v[92:95]
	v_mfma_f32_16x16x32_bf16 v[88:91], v[216:219], v[180:183], v[88:91]
	v_mfma_f32_16x16x32_bf16 v[76:79], v[208:211], v[200:203], v[76:79]
	v_mfma_f32_16x16x32_bf16 v[72:75], v[216:219], v[200:203], v[72:75]
	v_mfma_f32_16x16x32_bf16 v[124:127], v[212:215], v[164:167], v[124:127]
	v_mfma_f32_16x16x32_bf16 v[120:123], v[220:223], v[164:167], v[120:123]
	v_mfma_f32_16x16x32_bf16 v[108:111], v[212:215], v[176:179], v[108:111]
	v_mfma_f32_16x16x32_bf16 v[104:107], v[220:223], v[176:179], v[104:107]
	v_mfma_f32_16x16x32_bf16 v[92:95], v[212:215], v[196:199], v[92:95]
	v_mfma_f32_16x16x32_bf16 v[88:91], v[220:223], v[196:199], v[88:91]
	v_mfma_f32_16x16x32_bf16 v[76:79], v[212:215], v[204:207], v[76:79]
	v_mfma_f32_16x16x32_bf16 v[72:75], v[220:223], v[204:207], v[72:75]
	s_barrier
	s_mov_b32 m0, s31
	ds_read_b128 v[160:163], v146 offset:49152
	ds_read_b128 v[164:167], v146 offset:50176
	ds_read_b128 v[172:175], v146 offset:51200
	ds_read_b128 v[176:179], v146 offset:52224
	ds_read_b128 v[180:183], v146 offset:53248
	ds_read_b128 v[196:199], v146 offset:54272
	ds_read_b128 v[200:203], v146 offset:55296
	ds_read_b128 v[204:207], v146 offset:56320
	s_add_u32 vcc_lo, s22, s46
	s_addc_u32 vcc_hi, s23, s47
	global_load_lds_dwordx4 v2, vcc
	s_mov_b32 m0, s33
	s_add_u32 vcc_lo, s22, s58
	s_addc_u32 vcc_hi, s23, s59
	global_load_lds_dwordx4 v2, vcc
	s_barrier
	s_waitcnt lgkmcnt(0)
	v_mfma_f32_16x16x32_bf16 v[68:71], v[140:143], v[160:163], v[68:71]
	v_mfma_f32_16x16x32_bf16 v[64:67], v[152:155], v[160:163], v[64:67]
	v_mfma_f32_16x16x32_bf16 v[52:55], v[140:143], v[172:175], v[52:55]
	v_mfma_f32_16x16x32_bf16 v[48:51], v[152:155], v[172:175], v[48:51]
	v_mfma_f32_16x16x32_bf16 v[36:39], v[140:143], v[180:183], v[36:39]
	v_mfma_f32_16x16x32_bf16 v[32:35], v[152:155], v[180:183], v[32:35]
	v_mfma_f32_16x16x32_bf16 v[20:23], v[140:143], v[200:203], v[20:23]
	v_mfma_f32_16x16x32_bf16 v[16:19], v[152:155], v[200:203], v[16:19]
	v_mfma_f32_16x16x32_bf16 v[68:71], v[148:151], v[164:167], v[68:71]
	v_mfma_f32_16x16x32_bf16 v[64:67], v[156:159], v[164:167], v[64:67]
	v_mfma_f32_16x16x32_bf16 v[52:55], v[148:151], v[176:179], v[52:55]
	v_mfma_f32_16x16x32_bf16 v[48:51], v[156:159], v[176:179], v[48:51]
	v_mfma_f32_16x16x32_bf16 v[36:39], v[148:151], v[196:199], v[36:39]
	v_mfma_f32_16x16x32_bf16 v[32:35], v[156:159], v[196:199], v[32:35]
	v_mfma_f32_16x16x32_bf16 v[20:23], v[148:151], v[204:207], v[20:23]
	v_mfma_f32_16x16x32_bf16 v[16:19], v[156:159], v[204:207], v[16:19]
	s_barrier
	s_add_i32 s4, s5, s26
	s_mov_b32 m0, s4
	s_add_u32 vcc_lo, s42, s50
	s_addc_u32 vcc_hi, s43, s51
	global_load_lds_dwordx4 v136, vcc
	s_add_i32 m0, s4, 0x2000
	s_add_u32 vcc_lo, s42, s62
	s_addc_u32 vcc_hi, s43, s63
	global_load_lds_dwordx4 v136, vcc
	s_add_i32 s21, s21, 2
	s_add_u32 s6, s6, 0x100
	s_addc_u32 s7, s7, 0
	s_add_u32 s19, s19, 0x100
	s_addc_u32 s20, s20, 0
	s_cmp_gt_u32 s21, 5
	s_waitcnt vmcnt(6)
	s_barrier
	v_mfma_f32_16x16x32_bf16 v[60:63], v[208:211], v[160:163], v[60:63]
	v_mfma_f32_16x16x32_bf16 v[56:59], v[216:219], v[160:163], v[56:59]
	v_mfma_f32_16x16x32_bf16 v[44:47], v[208:211], v[172:175], v[44:47]
	v_mfma_f32_16x16x32_bf16 v[40:43], v[216:219], v[172:175], v[40:43]
	v_mfma_f32_16x16x32_bf16 v[28:31], v[208:211], v[180:183], v[28:31]
	v_mfma_f32_16x16x32_bf16 v[24:27], v[216:219], v[180:183], v[24:27]
	v_mfma_f32_16x16x32_bf16 v[12:15], v[208:211], v[200:203], v[12:15]
	v_mfma_f32_16x16x32_bf16 v[8:11], v[216:219], v[200:203], v[8:11]
	v_mfma_f32_16x16x32_bf16 v[60:63], v[212:215], v[164:167], v[60:63]
	v_mfma_f32_16x16x32_bf16 v[56:59], v[220:223], v[164:167], v[56:59]
	v_mfma_f32_16x16x32_bf16 v[44:47], v[212:215], v[176:179], v[44:47]
	v_mfma_f32_16x16x32_bf16 v[40:43], v[220:223], v[176:179], v[40:43]
	v_mfma_f32_16x16x32_bf16 v[28:31], v[212:215], v[196:199], v[28:31]
	v_mfma_f32_16x16x32_bf16 v[24:27], v[220:223], v[196:199], v[24:27]
	v_mfma_f32_16x16x32_bf16 v[12:15], v[212:215], v[204:207], v[12:15]
	v_mfma_f32_16x16x32_bf16 v[8:11], v[220:223], v[204:207], v[8:11]
	s_cbranch_scc0 .Ldb_SSM1_cont

; #define G_STAGE(bufoff, gbase, o0, h64) do { \
;         __builtin_amdgcn_global_load_lds((const unsigned*)((const char*)(gbase) + (o0)), (LAS unsigned*)(lds + (bufoff) + ldsw), 16, 0, 0); \
;         __builtin_amdgcn_global_load_lds((const unsigned*)((const char*)(gbase) + (h64) + (o0)), (LAS unsigned*)(lds + (bufoff) + ldsw + 8192), 16, 0, 0); } while (0)
; #define G_LDA(dst, b, h) do { _Pragma("unroll") for (int m = 0; m < 4; ++m) _Pragma("unroll") for (int k = 0; k < 2; ++k) dst[m][k] = *(const LAS bf16x8*)(lds + G_SA(b, h) + aoff + m * 2048 + k * 1024); } while (0)
; #define G_WAIT_V(n) asm volatile("s_waitcnt vmcnt(" #n ")" ::: "memory")
; #define G_BAR __builtin_amdgcn_s_barrier()
;     ...
;     for (;;) {
;         const bool has_next = sched_next<PH, SUB>(E.ws, E.layer, ui + 1, nxt, E.x);
;         if (!has_next) nxt = cur;
;         const char* nA = nxt.A; const char* nB = nxt.B;
; #pragma unroll 1
;         for (int t = 0; t < nt; t += 2) {
;             const bool last = (t == nt - 2);
;             const char* a1 = cA + (size_t)(t + 1) * ckA;
;             const char* a2 = last ? nA : cA + (size_t)(t + 2) * ckA; const char* b2 = last ? nB : cB + (size_t)(t + 2) * kB;
;             const char* a3 = a2 + ckA; const char* b3 = b2 + kB;
;             G_LDB(B0, 0, 0); G_SCHED; G_LDA(At, 0, 0); G_STAGE(G_SA(1, 1), a1 + chA, cA0, qA);
;             G_WAIT_L(8); G_BAR; G_WAIT_L(0); G_MMA(0, 0, At, B0); G_BAR; G_SCHED;
;             G_LDB(B1, 0, 1); G_STAGE(G_SB(0, 0), b2, cB0, qB);
;             G_BAR; G_WAIT_L(0); G_MMA(0, 1, At, B1); G_BAR;
;             G_LDA(At, 0, 1); G_STAGE(G_SA(0, 0), a2, cA0, qA);
;             G_BAR; G_WAIT_L(0); G_MMA(1, 0, At, B0); G_BAR; G_SCHED;
;             G_STAGE(G_SB(0, 1), b2 + chB, cB0, qB);
;             G_WAIT_V(6); G_BAR; G_MMA(1, 1, At, B1); G_BAR;
;             G_LDB(B0, 1, 0); G_SCHED; G_LDA(At, 1, 0); G_STAGE(G_SA(0, 1), a2 + chA, cA0, qA);
;             G_WAIT_L(8); G_BAR; G_WAIT_L(0); G_MMA(0, 0, At, B0); G_BAR; G_SCHED;
;             G_LDB(B1, 1, 1); G_STAGE(G_SB(1, 0), b3, cB0, qB);
;             G_BAR; G_WAIT_L(0); G_MMA(0, 1, At, B1); G_BAR;
;             G_LDA(At, 1, 1); G_STAGE(G_SA(1, 0), a3, cA0, qA);
;             G_BAR; G_WAIT_L(0); G_MMA(1, 0, At, B0); G_BAR; G_SCHED;
;             G_STAGE(G_SB(1, 1), b3 + chB, cB0, qB);
;             G_WAIT_V(6); G_BAR; G_MMA(1, 1, At, B1); G_BAR;
.LBB0_742:
	s_add_u32 s36, s2, s30
	s_addc_u32 s37, s3, s31
	s_add_u32 s19, s36, 0x100
	s_addc_u32 s35, s37, 0
	s_and_b64 s[4:5], s[26:27], exec
	s_cselect_b32 s34, s12, s19
	s_cselect_b32 s35, s13, s35
	s_add_u32 s4, s20, s30
	s_addc_u32 s5, s21, s31
	s_add_u32 s19, s4, 0x100
	s_addc_u32 s30, s5, 0
	s_add_i32 s44, 0, 0x10000
	ds_read_b128 v[56:59], v255 offset:0
	ds_read_b128 v[60:63], v255 offset:1024
	ds_read_b128 v[144:147], v255 offset:2048
	ds_read_b128 v[148:151], v255 offset:3072
	s_and_b64 s[4:5], s[26:27], exec
	s_cselect_b32 s26, s16, s19
	s_cselect_b32 s27, s17, s30
	s_add_i32 s48, 0, 0x14000
	s_add_i32 s31, 0, 0x18000
	s_add_i32 s19, 0, 0x1c000
	s_add_i32 s49, s44, s38
	s_add_i32 s63, s48, s38
	s_add_i32 s30, s31, s38
	s_add_i32 s65, s19, s38
	s_add_i32 m0, s43, 0xc000
	s_add_i32 s45, s43, 0xe000
	s_add_i32 s66, s49, 0x2000
	s_add_i32 s62, s63, 0x2000
	s_add_i32 s67, s30, 0x2000
	s_add_i32 s64, s65, 0x2000
	s_mov_b64 s[4:5], 0x200080
	s_add_u32 vcc_lo, s36, s4
	s_addc_u32 vcc_hi, s37, s5
	s_mov_b64 s[4:5], 0x300080
	ds_read_b128 v[152:155], v184
	ds_read_b128 v[156:159], v184 offset:1024
	ds_read_b128 v[162:165], v184 offset:2048
	ds_read_b128 v[172:175], v184 offset:3072
	ds_read_b128 v[176:179], v184 offset:4096
	ds_read_b128 v[196:199], v184 offset:5120
	ds_read_b128 v[200:203], v184 offset:6144
	ds_read_b128 v[204:207], v184 offset:7168
	global_load_lds_dwordx4 v160, vcc
	s_mov_b32 m0, s45
	s_add_u32 vcc_lo, s36, s4
	s_addc_u32 vcc_hi, s37, s5
	global_load_lds_dwordx4 v160, vcc
	s_waitcnt lgkmcnt(8)
	s_cmp_eq_u32 s101, 1
	s_cbranch_scc1 .Ldb_SSM2_sk
	s_barrier
.Ldb_SSM2_sk:
	s_mov_b32 s101, 0
	s_waitcnt lgkmcnt(0)
	v_mfma_f32_16x16x32_bf16 v[140:143], v[56:59], v[152:155], v[140:143]
	v_mfma_f32_16x16x32_bf16 v[136:139], v[144:147], v[152:155], v[136:139]
	v_mfma_f32_16x16x32_bf16 v[124:127], v[56:59], v[162:165], v[124:127]
	v_mfma_f32_16x16x32_bf16 v[120:123], v[144:147], v[162:165], v[120:123]
	v_mfma_f32_16x16x32_bf16 v[108:111], v[56:59], v[176:179], v[108:111]
	v_mfma_f32_16x16x32_bf16 v[104:107], v[144:147], v[176:179], v[104:107]
	v_mfma_f32_16x16x32_bf16 v[92:95], v[56:59], v[200:203], v[92:95]
	v_mfma_f32_16x16x32_bf16 v[88:91], v[144:147], v[200:203], v[88:91]
	v_mfma_f32_16x16x32_bf16 v[140:143], v[60:63], v[156:159], v[140:143]
	v_mfma_f32_16x16x32_bf16 v[136:139], v[148:151], v[156:159], v[136:139]
	v_mfma_f32_16x16x32_bf16 v[124:127], v[60:63], v[172:175], v[124:127]
	v_mfma_f32_16x16x32_bf16 v[120:123], v[148:151], v[172:175], v[120:123]
	v_mfma_f32_16x16x32_bf16 v[108:111], v[60:63], v[196:199], v[108:111]
	v_mfma_f32_16x16x32_bf16 v[104:107], v[148:151], v[196:199], v[104:107]
	v_mfma_f32_16x16x32_bf16 v[92:95], v[60:63], v[204:207], v[92:95]
	v_mfma_f32_16x16x32_bf16 v[88:91], v[148:151], v[204:207], v[88:91]
	s_barrier
	s_mov_b32 m0, s49
	ds_read_b128 v[208:211], v255 offset:16384
	ds_read_b128 v[212:215], v255 offset:17408
	ds_read_b128 v[216:219], v255 offset:18432
	ds_read_b128 v[220:223], v255 offset:19456
	global_load_lds_dwordx4 v2, s[26:27]
	s_mov_b32 m0, s66
	s_add_u32 vcc_lo, s26, s92
	s_addc_u32 vcc_hi, s27, s93
	global_load_lds_dwordx4 v2, vcc
	s_barrier
	s_waitcnt lgkmcnt(0)
	v_mfma_f32_16x16x32_bf16 v[132:135], v[208:211], v[152:155], v[132:135]
	v_mfma_f32_16x16x32_bf16 v[128:131], v[216:219], v[152:155], v[128:131]
	v_mfma_f32_16x16x32_bf16 v[116:119], v[208:211], v[162:165], v[116:119]
	v_mfma_f32_16x16x32_bf16 v[112:115], v[216:219], v[162:165], v[112:115]
	v_mfma_f32_16x16x32_bf16 v[100:103], v[208:211], v[176:179], v[100:103]
	v_mfma_f32_16x16x32_bf16 v[96:99], v[216:219], v[176:179], v[96:99]
	v_mfma_f32_16x16x32_bf16 v[84:87], v[208:211], v[200:203], v[84:87]
	v_mfma_f32_16x16x32_bf16 v[80:83], v[216:219], v[200:203], v[80:83]
	v_mfma_f32_16x16x32_bf16 v[132:135], v[212:215], v[156:159], v[132:135]
	v_mfma_f32_16x16x32_bf16 v[128:131], v[220:223], v[156:159], v[128:131]
	v_mfma_f32_16x16x32_bf16 v[116:119], v[212:215], v[172:175], v[116:119]
	v_mfma_f32_16x16x32_bf16 v[112:115], v[220:223], v[172:175], v[112:115]
	v_mfma_f32_16x16x32_bf16 v[100:103], v[212:215], v[196:199], v[100:103]
	v_mfma_f32_16x16x32_bf16 v[96:99], v[220:223], v[196:199], v[96:99]
	v_mfma_f32_16x16x32_bf16 v[84:87], v[212:215], v[204:207], v[84:87]
	v_mfma_f32_16x16x32_bf16 v[80:83], v[220:223], v[204:207], v[80:83]
	s_barrier
	s_mov_b32 m0, s43
	ds_read_b128 v[152:155], v184 offset:16384
	ds_read_b128 v[156:159], v184 offset:17408
	ds_read_b128 v[162:165], v184 offset:18432
	ds_read_b128 v[172:175], v184 offset:19456
	ds_read_b128 v[176:179], v184 offset:20480
	ds_read_b128 v[196:199], v184 offset:21504
	ds_read_b128 v[200:203], v184 offset:22528
	ds_read_b128 v[204:207], v184 offset:23552
	global_load_lds_dwordx4 v160, s[34:35]
	s_mov_b32 m0, s50
	s_add_u32 vcc_lo, s34, s88
	s_addc_u32 vcc_hi, s35, s89
	global_load_lds_dwordx4 v160, vcc
	s_barrier
	s_waitcnt lgkmcnt(0)
	v_mfma_f32_16x16x32_bf16 v[76:79], v[56:59], v[152:155], v[76:79]
	v_mfma_f32_16x16x32_bf16 v[72:75], v[144:147], v[152:155], v[72:75]
	v_mfma_f32_16x16x32_bf16 v[52:55], v[56:59], v[162:165], v[52:55]
	v_mfma_f32_16x16x32_bf16 v[48:51], v[144:147], v[162:165], v[48:51]
	v_mfma_f32_16x16x32_bf16 v[36:39], v[56:59], v[176:179], v[36:39]
	v_mfma_f32_16x16x32_bf16 v[32:35], v[144:147], v[176:179], v[32:35]
	v_mfma_f32_16x16x32_bf16 v[20:23], v[56:59], v[200:203], v[20:23]
	v_mfma_f32_16x16x32_bf16 v[16:19], v[144:147], v[200:203], v[16:19]
	v_mfma_f32_16x16x32_bf16 v[76:79], v[60:63], v[156:159], v[76:79]
	v_mfma_f32_16x16x32_bf16 v[72:75], v[148:151], v[156:159], v[72:75]
	v_mfma_f32_16x16x32_bf16 v[52:55], v[60:63], v[172:175], v[52:55]
	v_mfma_f32_16x16x32_bf16 v[48:51], v[148:151], v[172:175], v[48:51]
	v_mfma_f32_16x16x32_bf16 v[36:39], v[60:63], v[196:199], v[36:39]
	v_mfma_f32_16x16x32_bf16 v[32:35], v[148:151], v[196:199], v[32:35]
	v_mfma_f32_16x16x32_bf16 v[20:23], v[60:63], v[204:207], v[20:23]
	v_mfma_f32_16x16x32_bf16 v[16:19], v[148:151], v[204:207], v[16:19]
	s_barrier
; #define G_STAGE(bufoff, gbase, o0, h64) do { \
;         __builtin_amdgcn_global_load_lds((const unsigned*)((const char*)(gbase) + (o0)), (LAS unsigned*)(lds + (bufoff) + ldsw), 16, 0, 0); \
;         __builtin_amdgcn_global_load_lds((const unsigned*)((const char*)(gbase) + (h64) + (o0)), (LAS unsigned*)(lds + (bufoff) + ldsw + 8192), 16, 0, 0); } while (0)
; #define G_LDA(dst, b, h) do { _Pragma("unroll") for (int m = 0; m < 4; ++m) _Pragma("unroll") for (int k = 0; k < 2; ++k) dst[m][k] = *(const LAS bf16x8*)(lds + G_SA(b, h) + aoff + m * 2048 + k * 1024); } while (0)
; #define G_LDB(dst, b, h) do { _Pragma("unroll") for (int n = 0; n < 2; ++n) _Pragma("unroll") for (int k = 0; k < 2; ++k) dst[n][k] = *(const LAS bf16x8*)(lds + G_SB(b, h) + boff + n * 2048 + k * 1024); } while (0)
; #define G_WAIT_V(n) asm volatile("s_waitcnt vmcnt(" #n ")" ::: "memory")
; #define G_BAR __builtin_amdgcn_s_barrier()
;     ...
;         for (int t = 0; t < nt; t += 2) {
;             const bool last = (t == nt - 2);
;             const char* a1 = cA + (size_t)(t + 1) * ckA;
;             const char* a2 = last ? nA : cA + (size_t)(t + 2) * ckA; const char* b2 = last ? nB : cB + (size_t)(t + 2) * kB;
;             const char* a3 = a2 + ckA; const char* b3 = b2 + kB;
;             G_LDB(B0, 0, 0); G_SCHED; G_LDA(At, 0, 0); G_STAGE(G_SA(1, 1), a1 + chA, cA0, qA);
;             G_WAIT_L(8); G_BAR; G_WAIT_L(0); G_MMA(0, 0, At, B0); G_BAR; G_SCHED;
;             G_LDB(B1, 0, 1); G_STAGE(G_SB(0, 0), b2, cB0, qB);
;             G_BAR; G_WAIT_L(0); G_MMA(0, 1, At, B1); G_BAR;
;             G_LDA(At, 0, 1); G_STAGE(G_SA(0, 0), a2, cA0, qA);
;             G_BAR; G_WAIT_L(0); G_MMA(1, 0, At, B0); G_BAR; G_SCHED;
;             G_STAGE(G_SB(0, 1), b2 + chB, cB0, qB);
;             G_WAIT_V(6); G_BAR; G_MMA(1, 1, At, B1); G_BAR;
;             G_LDB(B0, 1, 0); G_SCHED; G_LDA(At, 1, 0); G_STAGE(G_SA(0, 1), a2 + chA, cA0, qA);
;             G_WAIT_L(8); G_BAR; G_WAIT_L(0); G_MMA(0, 0, At, B0); G_BAR; G_SCHED;
;             G_LDB(B1, 1, 1); G_STAGE(G_SB(1, 0), b3, cB0, qB);
;             G_BAR; G_WAIT_L(0); G_MMA(0, 1, At, B1); G_BAR;
;             G_LDA(At, 1, 1); G_STAGE(G_SA(1, 0), a3, cA0, qA);
;             G_BAR; G_WAIT_L(0); G_MMA(1, 0, At, B0); G_BAR; G_SCHED;
;             G_STAGE(G_SB(1, 1), b3 + chB, cB0, qB);
;             G_WAIT_V(6); G_BAR; G_MMA(1, 1, At, B1); G_BAR;
	s_mov_b32 m0, s63
	s_add_u32 vcc_lo, s26, s82
	s_addc_u32 vcc_hi, s27, s83
	global_load_lds_dwordx4 v2, vcc
	s_mov_b32 m0, s62
	s_add_u32 vcc_lo, s26, s94
	s_addc_u32 vcc_hi, s27, s95
	global_load_lds_dwordx4 v2, vcc
	s_waitcnt vmcnt(6)
	s_barrier
	v_mfma_f32_16x16x32_bf16 v[44:47], v[208:211], v[162:165], v[44:47]
	v_mfma_f32_16x16x32_bf16 v[40:43], v[216:219], v[162:165], v[40:43]
	v_mfma_f32_16x16x32_bf16 v[28:31], v[208:211], v[176:179], v[28:31]
	v_mfma_f32_16x16x32_bf16 v[24:27], v[216:219], v[176:179], v[24:27]
	v_mfma_f32_16x16x32_bf16 v[12:15], v[208:211], v[200:203], v[12:15]
	v_mfma_f32_16x16x32_bf16 v[8:11], v[216:219], v[200:203], v[8:11]
	v_mfma_f32_16x16x32_bf16 v[56:59], v[208:211], v[152:155], v[68:71]
	v_mfma_f32_16x16x32_bf16 v[60:63], v[216:219], v[152:155], v[64:67]
	v_mfma_f32_16x16x32_bf16 v[44:47], v[212:215], v[172:175], v[44:47]
	v_mfma_f32_16x16x32_bf16 v[40:43], v[220:223], v[172:175], v[40:43]
	v_mfma_f32_16x16x32_bf16 v[28:31], v[212:215], v[196:199], v[28:31]
	v_mfma_f32_16x16x32_bf16 v[24:27], v[220:223], v[196:199], v[24:27]
	v_mfma_f32_16x16x32_bf16 v[12:15], v[212:215], v[204:207], v[12:15]
	v_mfma_f32_16x16x32_bf16 v[8:11], v[220:223], v[204:207], v[8:11]
	v_mfma_f32_16x16x32_bf16 v[56:59], v[212:215], v[156:159], v[56:59]
	v_mfma_f32_16x16x32_bf16 v[60:63], v[220:223], v[156:159], v[60:63]
	s_barrier
	ds_read_b128 v[64:67], v255 offset:32768
	ds_read_b128 v[68:71], v255 offset:33792
	ds_read_b128 v[144:147], v255 offset:34816
	ds_read_b128 v[148:151], v255 offset:35840
	s_mov_b32 m0, s51
	ds_read_b128 v[152:155], v184 offset:32768
	ds_read_b128 v[156:159], v184 offset:33792
	ds_read_b128 v[162:165], v184 offset:34816
	ds_read_b128 v[172:175], v184 offset:35840
	ds_read_b128 v[176:179], v184 offset:36864
	ds_read_b128 v[196:199], v184 offset:37888
	ds_read_b128 v[200:203], v184 offset:38912
	ds_read_b128 v[204:207], v184 offset:39936
	s_add_u32 vcc_lo, s34, s86
	s_addc_u32 vcc_hi, s35, s87
	global_load_lds_dwordx4 v160, vcc
	s_mov_b32 m0, s52
	s_add_u32 vcc_lo, s34, s96
	s_addc_u32 vcc_hi, s35, s97
	global_load_lds_dwordx4 v160, vcc
	s_waitcnt lgkmcnt(8)
	s_barrier
	s_waitcnt lgkmcnt(0)
	v_mfma_f32_16x16x32_bf16 v[140:143], v[64:67], v[152:155], v[140:143]
	v_mfma_f32_16x16x32_bf16 v[136:139], v[144:147], v[152:155], v[136:139]
	v_mfma_f32_16x16x32_bf16 v[124:127], v[64:67], v[162:165], v[124:127]
	v_mfma_f32_16x16x32_bf16 v[120:123], v[144:147], v[162:165], v[120:123]
	v_mfma_f32_16x16x32_bf16 v[108:111], v[64:67], v[176:179], v[108:111]
	v_mfma_f32_16x16x32_bf16 v[104:107], v[144:147], v[176:179], v[104:107]
	v_mfma_f32_16x16x32_bf16 v[92:95], v[64:67], v[200:203], v[92:95]
	v_mfma_f32_16x16x32_bf16 v[88:91], v[144:147], v[200:203], v[88:91]
	v_mfma_f32_16x16x32_bf16 v[140:143], v[68:71], v[156:159], v[140:143]
	v_mfma_f32_16x16x32_bf16 v[136:139], v[148:151], v[156:159], v[136:139]
	v_mfma_f32_16x16x32_bf16 v[124:127], v[68:71], v[172:175], v[124:127]
	v_mfma_f32_16x16x32_bf16 v[120:123], v[148:151], v[172:175], v[120:123]
	v_mfma_f32_16x16x32_bf16 v[108:111], v[68:71], v[196:199], v[108:111]
	v_mfma_f32_16x16x32_bf16 v[104:107], v[148:151], v[196:199], v[104:107]
	v_mfma_f32_16x16x32_bf16 v[92:95], v[68:71], v[204:207], v[92:95]
	v_mfma_f32_16x16x32_bf16 v[88:91], v[148:151], v[204:207], v[88:91]
	s_barrier
	s_mov_b32 m0, s30
	ds_read_b128 v[208:211], v255 offset:49152
	ds_read_b128 v[212:215], v255 offset:50176
	ds_read_b128 v[216:219], v255 offset:51200
	ds_read_b128 v[220:223], v255 offset:52224
	s_add_u32 vcc_lo, s26, s46
	s_addc_u32 vcc_hi, s27, s47
	global_load_lds_dwordx4 v2, vcc
	s_mov_b32 m0, s67
	s_add_u32 vcc_lo, s26, s70
	s_addc_u32 vcc_hi, s27, s71
	global_load_lds_dwordx4 v2, vcc
	s_barrier
; #define G_STAGE(bufoff, gbase, o0, h64) do { \
;         __builtin_amdgcn_global_load_lds((const unsigned*)((const char*)(gbase) + (o0)), (LAS unsigned*)(lds + (bufoff) + ldsw), 16, 0, 0); \
;         __builtin_amdgcn_global_load_lds((const unsigned*)((const char*)(gbase) + (h64) + (o0)), (LAS unsigned*)(lds + (bufoff) + ldsw + 8192), 16, 0, 0); } while (0)
; #define G_LDA(dst, b, h) do { _Pragma("unroll") for (int m = 0; m < 4; ++m) _Pragma("unroll") for (int k = 0; k < 2; ++k) dst[m][k] = *(const LAS bf16x8*)(lds + G_SA(b, h) + aoff + m * 2048 + k * 1024); } while (0)
; #define G_LDB(dst, b, h) do { _Pragma("unroll") for (int n = 0; n < 2; ++n) _Pragma("unroll") for (int k = 0; k < 2; ++k) dst[n][k] = *(const LAS bf16x8*)(lds + G_SB(b, h) + boff + n * 2048 + k * 1024); } while (0)
; #define G_BAR __builtin_amdgcn_s_barrier()
;     ...
;         for (int t = 0; t < nt; t += 2) {
;             const bool last = (t == nt - 2);
;             const char* a1 = cA + (size_t)(t + 1) * ckA;
;             const char* a2 = last ? nA : cA + (size_t)(t + 2) * ckA; const char* b2 = last ? nB : cB + (size_t)(t + 2) * kB;
;             const char* a3 = a2 + ckA; const char* b3 = b2 + kB;
;             G_LDB(B0, 0, 0); G_SCHED; G_LDA(At, 0, 0); G_STAGE(G_SA(1, 1), a1 + chA, cA0, qA);
;             G_WAIT_L(8); G_BAR; G_WAIT_L(0); G_MMA(0, 0, At, B0); G_BAR; G_SCHED;
;             G_LDB(B1, 0, 1); G_STAGE(G_SB(0, 0), b2, cB0, qB);
;             G_BAR; G_WAIT_L(0); G_MMA(0, 1, At, B1); G_BAR;
;             G_LDA(At, 0, 1); G_STAGE(G_SA(0, 0), a2, cA0, qA);
;             G_BAR; G_WAIT_L(0); G_MMA(1, 0, At, B0); G_BAR; G_SCHED;
;             G_STAGE(G_SB(0, 1), b2 + chB, cB0, qB);
;             G_WAIT_V(6); G_BAR; G_MMA(1, 1, At, B1); G_BAR;
;             G_LDB(B0, 1, 0); G_SCHED; G_LDA(At, 1, 0); G_STAGE(G_SA(0, 1), a2 + chA, cA0, qA);
;             G_WAIT_L(8); G_BAR; G_WAIT_L(0); G_MMA(0, 0, At, B0); G_BAR; G_SCHED;
;             G_LDB(B1, 1, 1); G_STAGE(G_SB(1, 0), b3, cB0, qB);
;             G_BAR; G_WAIT_L(0); G_MMA(0, 1, At, B1); G_BAR;
;             G_LDA(At, 1, 1); G_STAGE(G_SA(1, 0), a3, cA0, qA);
;             G_BAR; G_WAIT_L(0); G_MMA(1, 0, At, B0); G_BAR; G_SCHED;
;             G_STAGE(G_SB(1, 1), b3 + chB, cB0, qB);
;             G_WAIT_V(6); G_BAR; G_MMA(1, 1, At, B1); G_BAR;
;         }
;         E.template run<cs.kind>(acc, cur, tid);
;         if (!has_next) break;
	s_waitcnt lgkmcnt(0)
	v_mfma_f32_16x16x32_bf16 v[132:135], v[208:211], v[152:155], v[132:135]
	v_mfma_f32_16x16x32_bf16 v[128:131], v[216:219], v[152:155], v[128:131]
	v_mfma_f32_16x16x32_bf16 v[116:119], v[208:211], v[162:165], v[116:119]
	v_mfma_f32_16x16x32_bf16 v[112:115], v[216:219], v[162:165], v[112:115]
	v_mfma_f32_16x16x32_bf16 v[100:103], v[208:211], v[176:179], v[100:103]
	v_mfma_f32_16x16x32_bf16 v[96:99], v[216:219], v[176:179], v[96:99]
	v_mfma_f32_16x16x32_bf16 v[84:87], v[208:211], v[200:203], v[84:87]
	v_mfma_f32_16x16x32_bf16 v[80:83], v[216:219], v[200:203], v[80:83]
	v_mfma_f32_16x16x32_bf16 v[132:135], v[212:215], v[156:159], v[132:135]
	v_mfma_f32_16x16x32_bf16 v[128:131], v[220:223], v[156:159], v[128:131]
	v_mfma_f32_16x16x32_bf16 v[116:119], v[212:215], v[172:175], v[116:119]
	v_mfma_f32_16x16x32_bf16 v[112:115], v[220:223], v[172:175], v[112:115]
	v_mfma_f32_16x16x32_bf16 v[100:103], v[212:215], v[196:199], v[100:103]
	v_mfma_f32_16x16x32_bf16 v[96:99], v[220:223], v[196:199], v[96:99]
	v_mfma_f32_16x16x32_bf16 v[84:87], v[212:215], v[204:207], v[84:87]
	v_mfma_f32_16x16x32_bf16 v[80:83], v[220:223], v[204:207], v[80:83]
	s_barrier
	s_mov_b32 m0, s53
	ds_read_b128 v[152:155], v184 offset:49152
	ds_read_b128 v[156:159], v184 offset:50176
	ds_read_b128 v[162:165], v184 offset:51200
	ds_read_b128 v[172:175], v184 offset:52224
	ds_read_b128 v[176:179], v184 offset:53248
	ds_read_b128 v[196:199], v184 offset:54272
	ds_read_b128 v[200:203], v184 offset:55296
	ds_read_b128 v[204:207], v184 offset:56320
	s_add_u32 vcc_lo, s34, s46
	s_addc_u32 vcc_hi, s35, s47
	global_load_lds_dwordx4 v160, vcc
	s_mov_b32 m0, s54
	s_add_u32 vcc_lo, s34, s68
	s_addc_u32 vcc_hi, s35, s69
	global_load_lds_dwordx4 v160, vcc
	s_barrier
	s_waitcnt lgkmcnt(0)
	v_mfma_f32_16x16x32_bf16 v[76:79], v[64:67], v[152:155], v[76:79]
	v_mfma_f32_16x16x32_bf16 v[72:75], v[144:147], v[152:155], v[72:75]
	v_mfma_f32_16x16x32_bf16 v[52:55], v[64:67], v[162:165], v[52:55]
	v_mfma_f32_16x16x32_bf16 v[48:51], v[144:147], v[162:165], v[48:51]
	v_mfma_f32_16x16x32_bf16 v[36:39], v[64:67], v[176:179], v[36:39]
	v_mfma_f32_16x16x32_bf16 v[32:35], v[144:147], v[176:179], v[32:35]
	v_mfma_f32_16x16x32_bf16 v[20:23], v[64:67], v[200:203], v[20:23]
	v_mfma_f32_16x16x32_bf16 v[16:19], v[144:147], v[200:203], v[16:19]
	v_mfma_f32_16x16x32_bf16 v[76:79], v[68:71], v[156:159], v[76:79]
	v_mfma_f32_16x16x32_bf16 v[72:75], v[148:151], v[156:159], v[72:75]
	v_mfma_f32_16x16x32_bf16 v[52:55], v[68:71], v[172:175], v[52:55]
	v_mfma_f32_16x16x32_bf16 v[48:51], v[148:151], v[172:175], v[48:51]
	v_mfma_f32_16x16x32_bf16 v[36:39], v[68:71], v[196:199], v[36:39]
	v_mfma_f32_16x16x32_bf16 v[32:35], v[148:151], v[196:199], v[32:35]
	v_mfma_f32_16x16x32_bf16 v[20:23], v[68:71], v[204:207], v[20:23]
	v_mfma_f32_16x16x32_bf16 v[16:19], v[148:151], v[204:207], v[16:19]
	s_barrier
	s_mov_b32 m0, s65
	s_add_u32 vcc_lo, s26, s84
	s_addc_u32 vcc_hi, s27, s85
	global_load_lds_dwordx4 v2, vcc
	s_mov_b32 m0, s64
	s_add_u32 vcc_lo, s26, s28
	s_addc_u32 vcc_hi, s27, s29
	global_load_lds_dwordx4 v2, vcc
	s_waitcnt vmcnt(6)
	s_barrier
	v_mfma_f32_16x16x32_bf16 v[56:59], v[208:211], v[152:155], v[56:59]
	v_mfma_f32_16x16x32_bf16 v[68:71], v[212:215], v[156:159], v[56:59]
	v_mfma_f32_16x16x32_bf16 v[56:59], v[216:219], v[152:155], v[60:63]
	v_mfma_f32_16x16x32_bf16 v[44:47], v[208:211], v[162:165], v[44:47]
	v_mfma_f32_16x16x32_bf16 v[40:43], v[216:219], v[162:165], v[40:43]
	v_mfma_f32_16x16x32_bf16 v[28:31], v[208:211], v[176:179], v[28:31]
	v_mfma_f32_16x16x32_bf16 v[24:27], v[216:219], v[176:179], v[24:27]
	v_mfma_f32_16x16x32_bf16 v[12:15], v[208:211], v[200:203], v[12:15]
	v_mfma_f32_16x16x32_bf16 v[8:11], v[216:219], v[200:203], v[8:11]
	v_mfma_f32_16x16x32_bf16 v[64:67], v[220:223], v[156:159], v[56:59]
	v_mfma_f32_16x16x32_bf16 v[44:47], v[212:215], v[172:175], v[44:47]
	v_mfma_f32_16x16x32_bf16 v[40:43], v[220:223], v[172:175], v[40:43]
	v_mfma_f32_16x16x32_bf16 v[28:31], v[212:215], v[196:199], v[28:31]
	v_mfma_f32_16x16x32_bf16 v[24:27], v[220:223], v[196:199], v[24:27]
	v_mfma_f32_16x16x32_bf16 v[12:15], v[212:215], v[204:207], v[12:15]
	v_mfma_f32_16x16x32_bf16 v[8:11], v[220:223], v[204:207], v[8:11]
	s_andn2_b64 vcc, exec, s[24:25]
	s_mov_b64 s[26:27], -1
	s_mov_b64 s[24:25], 0
	s_mov_b64 s[30:31], 0x100
	s_cbranch_vccz .Ldb_SSM2_cont
	v_readfirstlane_b32 s101, v186
	s_cmpk_gt_u32 s101, 0xff
	s_cbranch_scc1 .Ldb_SSM2_young
	s_barrier
	s_mov_b32 s101, 1
	s_branch .Ldb_SSM2_exit

; #define G_STAGE(bufoff, gbase, o0, h64) do { \
;         __builtin_amdgcn_global_load_lds((const unsigned*)((const char*)(gbase) + (o0)), (LAS unsigned*)(lds + (bufoff) + ldsw), 16, 0, 0); \
;         __builtin_amdgcn_global_load_lds((const unsigned*)((const char*)(gbase) + (h64) + (o0)), (LAS unsigned*)(lds + (bufoff) + ldsw + 8192), 16, 0, 0); } while (0)
; #define G_LDA(dst, b, h) do { _Pragma("unroll") for (int m = 0; m < 4; ++m) _Pragma("unroll") for (int k = 0; k < 2; ++k) dst[m][k] = *(const LAS bf16x8*)(lds + G_SA(b, h) + aoff + m * 2048 + k * 1024); } while (0)
; #define G_WAIT_V(n) asm volatile("s_waitcnt vmcnt(" #n ")" ::: "memory")
; #define G_BAR __builtin_amdgcn_s_barrier()
;     ...
;     for (;;) {
;         const bool has_next = sched_next<PH, SUB>(E.ws, E.layer, ui + 1, nxt, E.x);
;         if (!has_next) nxt = cur;
;         const char* nA = nxt.A; const char* nB = nxt.B;
; #pragma unroll 1
;         for (int t = 0; t < nt; t += 2) {
;             const bool last = (t == nt - 2);
;             const char* a1 = cA + (size_t)(t + 1) * ckA;
;             const char* a2 = last ? nA : cA + (size_t)(t + 2) * ckA; const char* b2 = last ? nB : cB + (size_t)(t + 2) * kB;
;             const char* a3 = a2 + ckA; const char* b3 = b2 + kB;
;             G_LDB(B0, 0, 0); G_SCHED; G_LDA(At, 0, 0); G_STAGE(G_SA(1, 1), a1 + chA, cA0, qA);
;             G_WAIT_L(8); G_BAR; G_WAIT_L(0); G_MMA(0, 0, At, B0); G_BAR; G_SCHED;
;             G_LDB(B1, 0, 1); G_STAGE(G_SB(0, 0), b2, cB0, qB);
;             G_BAR; G_WAIT_L(0); G_MMA(0, 1, At, B1); G_BAR;
;             G_LDA(At, 0, 1); G_STAGE(G_SA(0, 0), a2, cA0, qA);
;             G_BAR; G_WAIT_L(0); G_MMA(1, 0, At, B0); G_BAR; G_SCHED;
;             G_STAGE(G_SB(0, 1), b2 + chB, cB0, qB);
;             G_WAIT_V(6); G_BAR; G_MMA(1, 1, At, B1); G_BAR;
;             G_LDB(B0, 1, 0); G_SCHED; G_LDA(At, 1, 0); G_STAGE(G_SA(0, 1), a2 + chA, cA0, qA);
;             G_WAIT_L(8); G_BAR; G_WAIT_L(0); G_MMA(0, 0, At, B0); G_BAR; G_SCHED;
;             G_LDB(B1, 1, 1); G_STAGE(G_SB(1, 0), b3, cB0, qB);
;             G_BAR; G_WAIT_L(0); G_MMA(0, 1, At, B1); G_BAR;
;             G_LDA(At, 1, 1); G_STAGE(G_SA(1, 0), a3, cA0, qA);
;             G_BAR; G_WAIT_L(0); G_MMA(1, 0, At, B0); G_BAR; G_SCHED;
;             G_STAGE(G_SB(1, 1), b3 + chB, cB0, qB);
;             G_WAIT_V(6); G_BAR; G_MMA(1, 1, At, B1); G_BAR;
.LBB0_803:
	s_add_u32 s13, s18, 0x100
	s_addc_u32 s18, s19, 0
	s_add_u32 s2, s2, 0x800000
	s_addc_u32 s3, s3, 0
	s_mov_b32 s19, -2
	s_mov_b64 s[42:43], 0x20080
	s_mov_b64 s[50:51], 0x10000
	s_mov_b64 s[52:53], 0x30000
	s_mov_b64 s[54:55], 0x10080
	s_mov_b64 s[58:59], 0x30080
	s_mov_b64 s[62:63], 0x400000
	s_cmp_eq_u32 s101, 2
	s_cselect_b32 s101, 0, s101
	s_setprio 0
	v_add_u32_e32 v255, 0x10000, v196
	s_add_i32 s40, 0, 0x10000
	ds_read_b128 v[112:115], v255 offset:0
	ds_read_b128 v[124:127], v255 offset:1024
	ds_read_b128 v[136:139], v255 offset:2048
	ds_read_b128 v[148:151], v255 offset:3072
	s_cmp_eq_u32 s19, 4
	s_cselect_b32 s5, s15, s3
	s_cselect_b32 s4, s14, s2
	s_cselect_b32 s37, s17, s18
	s_cselect_b32 s36, s16, s13
	s_mov_b32 s38, 0xffc01000
	s_mov_b32 s39, -1
	s_add_u32 vcc_lo, s2, s38
	s_addc_u32 vcc_hi, s3, s39
	s_mov_b32 s38, 0xffc01800
	s_add_i32 m0, s24, 0xc000
	s_mov_b32 s39, -1
	ds_read_b128 v[152:155], v197
	ds_read_b128 v[156:159], v197 offset:1024
	ds_read_b128 v[160:163], v197 offset:2048
	ds_read_b128 v[172:175], v197 offset:3072
	ds_read_b128 v[176:179], v197 offset:4096
	ds_read_b128 v[180:183], v197 offset:5120
	ds_read_b128 v[198:201], v197 offset:6144
	ds_read_b128 v[202:205], v197 offset:7168
	global_load_lds_dwordx4 v166, vcc
	s_add_i32 m0, s24, 0xe000
	s_add_u32 vcc_lo, s2, s38
	s_addc_u32 vcc_hi, s3, s39
	global_load_lds_dwordx4 v166, vcc
	s_waitcnt lgkmcnt(8)
	s_cmp_eq_u32 s101, 1
	s_cbranch_scc1 .Ldb_GLU_skp
	s_barrier
.Ldb_GLU_skp:
	s_mov_b32 s101, 0
	s_waitcnt lgkmcnt(0)
	v_mfma_f32_16x16x32_bf16 v[144:147], v[112:115], v[152:155], 0
	v_mfma_f32_16x16x32_bf16 v[140:143], v[136:139], v[152:155], 0
	v_mfma_f32_16x16x32_bf16 v[120:123], v[112:115], v[160:163], 0
	v_mfma_f32_16x16x32_bf16 v[116:119], v[136:139], v[160:163], 0
	v_mfma_f32_16x16x32_bf16 v[100:103], v[112:115], v[176:179], 0
	v_mfma_f32_16x16x32_bf16 v[96:99], v[136:139], v[176:179], 0
	v_mfma_f32_16x16x32_bf16 v[84:87], v[112:115], v[198:201], 0
	v_mfma_f32_16x16x32_bf16 v[80:83], v[136:139], v[198:201], 0
	v_mfma_f32_16x16x32_bf16 v[144:147], v[124:127], v[156:159], v[144:147]
	v_mfma_f32_16x16x32_bf16 v[140:143], v[148:151], v[156:159], v[140:143]
	v_mfma_f32_16x16x32_bf16 v[120:123], v[124:127], v[172:175], v[120:123]
	v_mfma_f32_16x16x32_bf16 v[116:119], v[148:151], v[172:175], v[116:119]
	v_mfma_f32_16x16x32_bf16 v[100:103], v[124:127], v[180:183], v[100:103]
	v_mfma_f32_16x16x32_bf16 v[96:99], v[148:151], v[180:183], v[96:99]
	v_mfma_f32_16x16x32_bf16 v[84:87], v[124:127], v[202:205], v[84:87]
	v_mfma_f32_16x16x32_bf16 v[80:83], v[148:151], v[202:205], v[80:83]
	s_barrier
	s_add_i32 s38, 0, 0x14000
	s_add_i32 s100, s40, s21
	s_mov_b32 m0, s100
	ds_read_b128 v[206:209], v255 offset:16384
	ds_read_b128 v[210:213], v255 offset:17408
	ds_read_b128 v[214:217], v255 offset:18432
	ds_read_b128 v[218:221], v255 offset:19456
	global_load_lds_dwordx4 v2, s[36:37]
	s_add_i32 m0, s100, 0x2000
	s_add_u32 vcc_lo, s36, s50
	s_addc_u32 vcc_hi, s37, s51
	global_load_lds_dwordx4 v2, vcc
	s_barrier
	s_waitcnt lgkmcnt(0)
	v_mfma_f32_16x16x32_bf16 v[132:135], v[206:209], v[152:155], 0
	v_mfma_f32_16x16x32_bf16 v[128:131], v[214:217], v[152:155], 0
	v_mfma_f32_16x16x32_bf16 v[108:111], v[206:209], v[160:163], 0
	v_mfma_f32_16x16x32_bf16 v[104:107], v[214:217], v[160:163], 0
	v_mfma_f32_16x16x32_bf16 v[92:95], v[206:209], v[176:179], 0
	v_mfma_f32_16x16x32_bf16 v[88:91], v[214:217], v[176:179], 0
	v_mfma_f32_16x16x32_bf16 v[76:79], v[206:209], v[198:201], 0
	v_mfma_f32_16x16x32_bf16 v[72:75], v[214:217], v[198:201], 0
	v_mfma_f32_16x16x32_bf16 v[132:135], v[210:213], v[156:159], v[132:135]
	v_mfma_f32_16x16x32_bf16 v[128:131], v[218:221], v[156:159], v[128:131]
	v_mfma_f32_16x16x32_bf16 v[108:111], v[210:213], v[172:175], v[108:111]
	v_mfma_f32_16x16x32_bf16 v[104:107], v[218:221], v[172:175], v[104:107]
	v_mfma_f32_16x16x32_bf16 v[92:95], v[210:213], v[180:183], v[92:95]
	v_mfma_f32_16x16x32_bf16 v[88:91], v[218:221], v[180:183], v[88:91]
	v_mfma_f32_16x16x32_bf16 v[76:79], v[210:213], v[202:205], v[76:79]
	v_mfma_f32_16x16x32_bf16 v[72:75], v[218:221], v[202:205], v[72:75]
	s_barrier
	s_mov_b32 m0, s24
	v_lshl_add_u64 v[222:223], s[4:5], 0, v[164:165]
	ds_read_b128 v[152:155], v197 offset:16384
	ds_read_b128 v[156:159], v197 offset:17408
	ds_read_b128 v[160:163], v197 offset:18432
	ds_read_b128 v[172:175], v197 offset:19456
	ds_read_b128 v[176:179], v197 offset:20480
	ds_read_b128 v[180:183], v197 offset:21504
	ds_read_b128 v[198:201], v197 offset:22528
	ds_read_b128 v[202:205], v197 offset:23552
	global_load_lds_dwordx4 v164, s[4:5]
	s_mov_b32 m0, s25
	s_add_u32 vcc_lo, s4, s70
	s_addc_u32 vcc_hi, s5, s71
	global_load_lds_dwordx4 v164, vcc
	s_barrier
	s_waitcnt lgkmcnt(0)
	v_mfma_f32_16x16x32_bf16 v[68:71], v[112:115], v[152:155], 0
	v_mfma_f32_16x16x32_bf16 v[64:67], v[136:139], v[152:155], 0
	v_mfma_f32_16x16x32_bf16 v[52:55], v[112:115], v[160:163], 0
	v_mfma_f32_16x16x32_bf16 v[48:51], v[136:139], v[160:163], 0
	v_mfma_f32_16x16x32_bf16 v[36:39], v[112:115], v[176:179], 0
	v_mfma_f32_16x16x32_bf16 v[32:35], v[136:139], v[176:179], 0
	v_mfma_f32_16x16x32_bf16 v[20:23], v[112:115], v[198:201], 0
	v_mfma_f32_16x16x32_bf16 v[16:19], v[136:139], v[198:201], 0
	v_mfma_f32_16x16x32_bf16 v[68:71], v[124:127], v[156:159], v[68:71]
	v_mfma_f32_16x16x32_bf16 v[64:67], v[148:151], v[156:159], v[64:67]
	v_mfma_f32_16x16x32_bf16 v[52:55], v[124:127], v[172:175], v[52:55]
	v_mfma_f32_16x16x32_bf16 v[48:51], v[148:151], v[172:175], v[48:51]
	v_mfma_f32_16x16x32_bf16 v[36:39], v[124:127], v[180:183], v[36:39]
	v_mfma_f32_16x16x32_bf16 v[32:35], v[148:151], v[180:183], v[32:35]
	v_mfma_f32_16x16x32_bf16 v[20:23], v[124:127], v[202:205], v[20:23]
	v_mfma_f32_16x16x32_bf16 v[16:19], v[148:151], v[202:205], v[16:19]
	s_barrier
; #define G_STAGE(bufoff, gbase, o0, h64) do { \
;         __builtin_amdgcn_global_load_lds((const unsigned*)((const char*)(gbase) + (o0)), (LAS unsigned*)(lds + (bufoff) + ldsw), 16, 0, 0); \
;         __builtin_amdgcn_global_load_lds((const unsigned*)((const char*)(gbase) + (h64) + (o0)), (LAS unsigned*)(lds + (bufoff) + ldsw + 8192), 16, 0, 0); } while (0)
; #define G_LDA(dst, b, h) do { _Pragma("unroll") for (int m = 0; m < 4; ++m) _Pragma("unroll") for (int k = 0; k < 2; ++k) dst[m][k] = *(const LAS bf16x8*)(lds + G_SA(b, h) + aoff + m * 2048 + k * 1024); } while (0)
; #define G_LDB(dst, b, h) do { _Pragma("unroll") for (int n = 0; n < 2; ++n) _Pragma("unroll") for (int k = 0; k < 2; ++k) dst[n][k] = *(const LAS bf16x8*)(lds + G_SB(b, h) + boff + n * 2048 + k * 1024); } while (0)
; #define G_WAIT_V(n) asm volatile("s_waitcnt vmcnt(" #n ")" ::: "memory")
; #define G_BAR __builtin_amdgcn_s_barrier()
;     ...
;         for (int t = 0; t < nt; t += 2) {
;             const bool last = (t == nt - 2);
;             const char* a1 = cA + (size_t)(t + 1) * ckA;
;             const char* a2 = last ? nA : cA + (size_t)(t + 2) * ckA; const char* b2 = last ? nB : cB + (size_t)(t + 2) * kB;
;             const char* a3 = a2 + ckA; const char* b3 = b2 + kB;
;             G_LDB(B0, 0, 0); G_SCHED; G_LDA(At, 0, 0); G_STAGE(G_SA(1, 1), a1 + chA, cA0, qA);
;             G_WAIT_L(8); G_BAR; G_WAIT_L(0); G_MMA(0, 0, At, B0); G_BAR; G_SCHED;
;             G_LDB(B1, 0, 1); G_STAGE(G_SB(0, 0), b2, cB0, qB);
;             G_BAR; G_WAIT_L(0); G_MMA(0, 1, At, B1); G_BAR;
;             G_LDA(At, 0, 1); G_STAGE(G_SA(0, 0), a2, cA0, qA);
;             G_BAR; G_WAIT_L(0); G_MMA(1, 0, At, B0); G_BAR; G_SCHED;
;             G_STAGE(G_SB(0, 1), b2 + chB, cB0, qB);
;             G_WAIT_V(6); G_BAR; G_MMA(1, 1, At, B1); G_BAR;
;             G_LDB(B0, 1, 0); G_SCHED; G_LDA(At, 1, 0); G_STAGE(G_SA(0, 1), a2 + chA, cA0, qA);
;             G_WAIT_L(8); G_BAR; G_WAIT_L(0); G_MMA(0, 0, At, B0); G_BAR; G_SCHED;
;             G_LDB(B1, 1, 1); G_STAGE(G_SB(1, 0), b3, cB0, qB);
;             G_BAR; G_WAIT_L(0); G_MMA(0, 1, At, B1); G_BAR;
;             G_LDA(At, 1, 1); G_STAGE(G_SA(1, 0), a3, cA0, qA);
;             G_BAR; G_WAIT_L(0); G_MMA(1, 0, At, B0); G_BAR; G_SCHED;
;             G_STAGE(G_SB(1, 1), b3 + chB, cB0, qB);
;             G_WAIT_V(6); G_BAR; G_MMA(1, 1, At, B1); G_BAR;
	s_add_i32 s100, s38, s21
	s_mov_b32 m0, s100
	s_add_u32 vcc_lo, s36, s0
	s_addc_u32 vcc_hi, s37, s1
	global_load_lds_dwordx4 v2, vcc
	s_add_i32 m0, s100, 0x2000
	s_add_u32 vcc_lo, s36, s52
	s_addc_u32 vcc_hi, s37, s53
	global_load_lds_dwordx4 v2, vcc
	s_waitcnt vmcnt(6)
	s_barrier
	v_mfma_f32_16x16x32_bf16 v[60:63], v[206:209], v[152:155], 0
	v_mfma_f32_16x16x32_bf16 v[56:59], v[214:217], v[152:155], 0
	v_mfma_f32_16x16x32_bf16 v[44:47], v[206:209], v[160:163], 0
	v_mfma_f32_16x16x32_bf16 v[40:43], v[214:217], v[160:163], 0
	v_mfma_f32_16x16x32_bf16 v[28:31], v[206:209], v[176:179], 0
	v_mfma_f32_16x16x32_bf16 v[24:27], v[214:217], v[176:179], 0
	v_mfma_f32_16x16x32_bf16 v[12:15], v[206:209], v[198:201], 0
	v_mfma_f32_16x16x32_bf16 v[8:11], v[214:217], v[198:201], 0
	v_mfma_f32_16x16x32_bf16 v[60:63], v[210:213], v[156:159], v[60:63]
	v_mfma_f32_16x16x32_bf16 v[56:59], v[218:221], v[156:159], v[56:59]
	v_mfma_f32_16x16x32_bf16 v[44:47], v[210:213], v[172:175], v[44:47]
	v_mfma_f32_16x16x32_bf16 v[40:43], v[218:221], v[172:175], v[40:43]
	v_mfma_f32_16x16x32_bf16 v[28:31], v[210:213], v[180:183], v[28:31]
	v_mfma_f32_16x16x32_bf16 v[24:27], v[218:221], v[180:183], v[24:27]
	v_mfma_f32_16x16x32_bf16 v[12:15], v[210:213], v[202:205], v[12:15]
	v_mfma_f32_16x16x32_bf16 v[8:11], v[218:221], v[202:205], v[8:11]
	s_barrier
	s_add_i32 s100, 0, 0x18000
	ds_read_b128 v[112:115], v255 offset:32768
	ds_read_b128 v[124:127], v255 offset:33792
	ds_read_b128 v[136:139], v255 offset:34816
	ds_read_b128 v[148:151], v255 offset:35840
	s_mov_b32 m0, s26
	ds_read_b128 v[152:155], v197 offset:32768
	ds_read_b128 v[156:159], v197 offset:33792
	ds_read_b128 v[160:163], v197 offset:34816
	ds_read_b128 v[172:175], v197 offset:35840
	ds_read_b128 v[176:179], v197 offset:36864
	ds_read_b128 v[180:183], v197 offset:37888
	ds_read_b128 v[198:201], v197 offset:38912
	ds_read_b128 v[202:205], v197 offset:39936
	s_add_u32 vcc_lo, s4, s80
	s_addc_u32 vcc_hi, s5, s81
	global_load_lds_dwordx4 v164, vcc
	s_mov_b32 m0, s27
	s_add_u32 vcc_lo, s4, s82
	s_addc_u32 vcc_hi, s5, s83
	global_load_lds_dwordx4 v164, vcc
	s_waitcnt lgkmcnt(8)
	s_barrier
	s_waitcnt lgkmcnt(0)
	v_mfma_f32_16x16x32_bf16 v[144:147], v[112:115], v[152:155], v[144:147]
	v_mfma_f32_16x16x32_bf16 v[140:143], v[136:139], v[152:155], v[140:143]
	v_mfma_f32_16x16x32_bf16 v[120:123], v[112:115], v[160:163], v[120:123]
	v_mfma_f32_16x16x32_bf16 v[116:119], v[136:139], v[160:163], v[116:119]
	v_mfma_f32_16x16x32_bf16 v[100:103], v[112:115], v[176:179], v[100:103]
	v_mfma_f32_16x16x32_bf16 v[96:99], v[136:139], v[176:179], v[96:99]
	v_mfma_f32_16x16x32_bf16 v[84:87], v[112:115], v[198:201], v[84:87]
	v_mfma_f32_16x16x32_bf16 v[80:83], v[136:139], v[198:201], v[80:83]
	v_mfma_f32_16x16x32_bf16 v[144:147], v[124:127], v[156:159], v[144:147]
	v_mfma_f32_16x16x32_bf16 v[140:143], v[148:151], v[156:159], v[140:143]
	v_mfma_f32_16x16x32_bf16 v[120:123], v[124:127], v[172:175], v[120:123]
	v_mfma_f32_16x16x32_bf16 v[116:119], v[148:151], v[172:175], v[116:119]
	v_mfma_f32_16x16x32_bf16 v[100:103], v[124:127], v[180:183], v[100:103]
	v_mfma_f32_16x16x32_bf16 v[96:99], v[148:151], v[180:183], v[96:99]
	v_mfma_f32_16x16x32_bf16 v[84:87], v[124:127], v[202:205], v[84:87]
	v_mfma_f32_16x16x32_bf16 v[80:83], v[148:151], v[202:205], v[80:83]
	s_barrier
	s_add_i32 s5, 0, 0x1c000
	s_add_i32 s4, s100, s21
	s_mov_b32 m0, s4
	ds_read_b128 v[206:209], v255 offset:49152
	ds_read_b128 v[210:213], v255 offset:50176
	ds_read_b128 v[214:217], v255 offset:51200
	ds_read_b128 v[218:221], v255 offset:52224
	s_add_u32 vcc_lo, s36, s46
	s_addc_u32 vcc_hi, s37, s47
	global_load_lds_dwordx4 v2, vcc
	s_add_i32 m0, s4, 0x2000
	s_add_u32 vcc_lo, s36, s54
	s_addc_u32 vcc_hi, s37, s55
	global_load_lds_dwordx4 v2, vcc
	s_barrier
	s_waitcnt lgkmcnt(0)
	v_mfma_f32_16x16x32_bf16 v[132:135], v[206:209], v[152:155], v[132:135]
	v_mfma_f32_16x16x32_bf16 v[128:131], v[214:217], v[152:155], v[128:131]
	v_mfma_f32_16x16x32_bf16 v[108:111], v[206:209], v[160:163], v[108:111]
	v_mfma_f32_16x16x32_bf16 v[104:107], v[214:217], v[160:163], v[104:107]
	v_mfma_f32_16x16x32_bf16 v[92:95], v[206:209], v[176:179], v[92:95]
	v_mfma_f32_16x16x32_bf16 v[88:91], v[214:217], v[176:179], v[88:91]
	v_mfma_f32_16x16x32_bf16 v[76:79], v[206:209], v[198:201], v[76:79]
	v_mfma_f32_16x16x32_bf16 v[72:75], v[214:217], v[198:201], v[72:75]
	v_mfma_f32_16x16x32_bf16 v[132:135], v[210:213], v[156:159], v[132:135]
	v_mfma_f32_16x16x32_bf16 v[128:131], v[218:221], v[156:159], v[128:131]
	v_mfma_f32_16x16x32_bf16 v[108:111], v[210:213], v[172:175], v[108:111]
	v_mfma_f32_16x16x32_bf16 v[104:107], v[218:221], v[172:175], v[104:107]
	v_mfma_f32_16x16x32_bf16 v[92:95], v[210:213], v[180:183], v[92:95]
	v_mfma_f32_16x16x32_bf16 v[88:91], v[218:221], v[180:183], v[88:91]
	v_mfma_f32_16x16x32_bf16 v[76:79], v[210:213], v[202:205], v[76:79]
	v_mfma_f32_16x16x32_bf16 v[72:75], v[218:221], v[202:205], v[72:75]
	s_barrier
	s_mov_b32 m0, s29
	v_lshl_add_u64 v[224:225], v[222:223], 0, s[62:63]
	ds_read_b128 v[152:155], v197 offset:49152
	ds_read_b128 v[156:159], v197 offset:50176
	ds_read_b128 v[160:163], v197 offset:51200
	ds_read_b128 v[172:175], v197 offset:52224
	ds_read_b128 v[176:179], v197 offset:53248
	ds_read_b128 v[180:183], v197 offset:54272
	ds_read_b128 v[198:201], v197 offset:55296
	ds_read_b128 v[202:205], v197 offset:56320
	global_load_lds_dwordx4 v[224:225], off
	v_lshl_add_u64 v[222:223], v[222:223], 0, s[84:85]
	s_mov_b32 m0, s30
	s_nop 0
	global_load_lds_dwordx4 v[222:223], off
	s_barrier
; #define G_STAGE(bufoff, gbase, o0, h64) do { \
;         __builtin_amdgcn_global_load_lds((const unsigned*)((const char*)(gbase) + (o0)), (LAS unsigned*)(lds + (bufoff) + ldsw), 16, 0, 0); \
;         __builtin_amdgcn_global_load_lds((const unsigned*)((const char*)(gbase) + (h64) + (o0)), (LAS unsigned*)(lds + (bufoff) + ldsw + 8192), 16, 0, 0); } while (0)
; #define G_LDA(dst, b, h) do { _Pragma("unroll") for (int m = 0; m < 4; ++m) _Pragma("unroll") for (int k = 0; k < 2; ++k) dst[m][k] = *(const LAS bf16x8*)(lds + G_SA(b, h) + aoff + m * 2048 + k * 1024); } while (0)
; #define G_LDB(dst, b, h) do { _Pragma("unroll") for (int n = 0; n < 2; ++n) _Pragma("unroll") for (int k = 0; k < 2; ++k) dst[n][k] = *(const LAS bf16x8*)(lds + G_SB(b, h) + boff + n * 2048 + k * 1024); } while (0)
; #define G_WAIT_V(n) asm volatile("s_waitcnt vmcnt(" #n ")" ::: "memory")
; #define G_BAR __builtin_amdgcn_s_barrier()
;     ...
;         for (int t = 0; t < nt; t += 2) {
;             const bool last = (t == nt - 2);
;             const char* a1 = cA + (size_t)(t + 1) * ckA;
;             const char* a2 = last ? nA : cA + (size_t)(t + 2) * ckA; const char* b2 = last ? nB : cB + (size_t)(t + 2) * kB;
;             const char* a3 = a2 + ckA; const char* b3 = b2 + kB;
;             G_LDB(B0, 0, 0); G_SCHED; G_LDA(At, 0, 0); G_STAGE(G_SA(1, 1), a1 + chA, cA0, qA);
;             G_WAIT_L(8); G_BAR; G_WAIT_L(0); G_MMA(0, 0, At, B0); G_BAR; G_SCHED;
;             G_LDB(B1, 0, 1); G_STAGE(G_SB(0, 0), b2, cB0, qB);
;             G_BAR; G_WAIT_L(0); G_MMA(0, 1, At, B1); G_BAR;
;             G_LDA(At, 0, 1); G_STAGE(G_SA(0, 0), a2, cA0, qA);
;             G_BAR; G_WAIT_L(0); G_MMA(1, 0, At, B0); G_BAR; G_SCHED;
;             G_STAGE(G_SB(0, 1), b2 + chB, cB0, qB);
;             G_WAIT_V(6); G_BAR; G_MMA(1, 1, At, B1); G_BAR;
;             G_LDB(B0, 1, 0); G_SCHED; G_LDA(At, 1, 0); G_STAGE(G_SA(0, 1), a2 + chA, cA0, qA);
;             G_WAIT_L(8); G_BAR; G_WAIT_L(0); G_MMA(0, 0, At, B0); G_BAR; G_SCHED;
;             G_LDB(B1, 1, 1); G_STAGE(G_SB(1, 0), b3, cB0, qB);
;             G_BAR; G_WAIT_L(0); G_MMA(0, 1, At, B1); G_BAR;
;             G_LDA(At, 1, 1); G_STAGE(G_SA(1, 0), a3, cA0, qA);
;             G_BAR; G_WAIT_L(0); G_MMA(1, 0, At, B0); G_BAR; G_SCHED;
;             G_STAGE(G_SB(1, 1), b3 + chB, cB0, qB);
;             G_WAIT_V(6); G_BAR; G_MMA(1, 1, At, B1); G_BAR;
	s_waitcnt lgkmcnt(0)
	v_mfma_f32_16x16x32_bf16 v[68:71], v[112:115], v[152:155], v[68:71]
	v_mfma_f32_16x16x32_bf16 v[64:67], v[136:139], v[152:155], v[64:67]
	v_mfma_f32_16x16x32_bf16 v[52:55], v[112:115], v[160:163], v[52:55]
	v_mfma_f32_16x16x32_bf16 v[48:51], v[136:139], v[160:163], v[48:51]
	v_mfma_f32_16x16x32_bf16 v[36:39], v[112:115], v[176:179], v[36:39]
	v_mfma_f32_16x16x32_bf16 v[32:35], v[136:139], v[176:179], v[32:35]
	v_mfma_f32_16x16x32_bf16 v[20:23], v[112:115], v[198:201], v[20:23]
	v_mfma_f32_16x16x32_bf16 v[16:19], v[136:139], v[198:201], v[16:19]
	v_mfma_f32_16x16x32_bf16 v[68:71], v[124:127], v[156:159], v[68:71]
	v_mfma_f32_16x16x32_bf16 v[64:67], v[148:151], v[156:159], v[64:67]
	v_mfma_f32_16x16x32_bf16 v[52:55], v[124:127], v[172:175], v[52:55]
	v_mfma_f32_16x16x32_bf16 v[48:51], v[148:151], v[172:175], v[48:51]
	v_mfma_f32_16x16x32_bf16 v[36:39], v[124:127], v[180:183], v[36:39]
	v_mfma_f32_16x16x32_bf16 v[32:35], v[148:151], v[180:183], v[32:35]
	v_mfma_f32_16x16x32_bf16 v[20:23], v[124:127], v[202:205], v[20:23]
	v_mfma_f32_16x16x32_bf16 v[16:19], v[148:151], v[202:205], v[16:19]
	s_barrier
	s_add_i32 s4, s5, s21
	s_mov_b32 m0, s4
	s_add_u32 vcc_lo, s36, s42
	s_addc_u32 vcc_hi, s37, s43
	global_load_lds_dwordx4 v2, vcc
	s_add_i32 m0, s4, 0x2000
	s_add_u32 vcc_lo, s36, s58
	s_addc_u32 vcc_hi, s37, s59
	global_load_lds_dwordx4 v2, vcc
	s_add_i32 s19, s19, 2
	s_add_u32 s13, s13, 0x100
	s_addc_u32 s18, s18, 0
	s_add_u32 s2, s2, 0x800000
	s_addc_u32 s3, s3, 0
	s_cmp_gt_u32 s19, 5
	s_waitcnt vmcnt(6)
	s_barrier
	v_mfma_f32_16x16x32_bf16 v[60:63], v[206:209], v[152:155], v[60:63]
	v_mfma_f32_16x16x32_bf16 v[56:59], v[214:217], v[152:155], v[56:59]
	v_mfma_f32_16x16x32_bf16 v[44:47], v[206:209], v[160:163], v[44:47]
	v_mfma_f32_16x16x32_bf16 v[40:43], v[214:217], v[160:163], v[40:43]
	v_mfma_f32_16x16x32_bf16 v[28:31], v[206:209], v[176:179], v[28:31]
	v_mfma_f32_16x16x32_bf16 v[24:27], v[214:217], v[176:179], v[24:27]
	v_mfma_f32_16x16x32_bf16 v[12:15], v[206:209], v[198:201], v[12:15]
	v_mfma_f32_16x16x32_bf16 v[8:11], v[214:217], v[198:201], v[8:11]
	v_mfma_f32_16x16x32_bf16 v[60:63], v[210:213], v[156:159], v[60:63]
	v_mfma_f32_16x16x32_bf16 v[56:59], v[218:221], v[156:159], v[56:59]
	v_mfma_f32_16x16x32_bf16 v[44:47], v[210:213], v[172:175], v[44:47]
	v_mfma_f32_16x16x32_bf16 v[40:43], v[218:221], v[172:175], v[40:43]
	v_mfma_f32_16x16x32_bf16 v[28:31], v[210:213], v[180:183], v[28:31]
	v_mfma_f32_16x16x32_bf16 v[24:27], v[218:221], v[180:183], v[24:27]
	v_mfma_f32_16x16x32_bf16 v[12:15], v[210:213], v[202:205], v[12:15]
	v_mfma_f32_16x16x32_bf16 v[8:11], v[218:221], v[202:205], v[8:11]
	s_cbranch_scc0 .Ldb_GLU_cont
	s_branch .Ldb_GLU_xl
.LBB0_804:
	s_add_i32 s40, 0, 0x10000
	ds_read_b128 v[112:115], v255 offset:0
	ds_read_b128 v[124:127], v255 offset:1024
	ds_read_b128 v[136:139], v255 offset:2048
	ds_read_b128 v[148:151], v255 offset:3072
	s_cmp_eq_u32 s19, 4
	s_cselect_b32 s5, s15, s3
	s_cselect_b32 s4, s14, s2
	s_cselect_b32 s37, s17, s18
	s_cselect_b32 s36, s16, s13
	s_mov_b32 s38, 0xffc01000
	s_mov_b32 s39, -1
	s_add_u32 vcc_lo, s2, s38
	s_addc_u32 vcc_hi, s3, s39
	s_mov_b32 s38, 0xffc01800
	s_add_i32 m0, s24, 0xc000
	s_mov_b32 s39, -1
	ds_read_b128 v[152:155], v197
	ds_read_b128 v[156:159], v197 offset:1024
	ds_read_b128 v[160:163], v197 offset:2048
	ds_read_b128 v[172:175], v197 offset:3072
	ds_read_b128 v[176:179], v197 offset:4096
	ds_read_b128 v[180:183], v197 offset:5120
	ds_read_b128 v[198:201], v197 offset:6144
	ds_read_b128 v[202:205], v197 offset:7168
	global_load_lds_dwordx4 v166, vcc
	s_add_i32 m0, s24, 0xe000
	s_add_u32 vcc_lo, s2, s38
	s_addc_u32 vcc_hi, s3, s39
	global_load_lds_dwordx4 v166, vcc
	s_waitcnt lgkmcnt(8)
	s_barrier
	s_waitcnt lgkmcnt(0)
	v_mfma_f32_16x16x32_bf16 v[144:147], v[112:115], v[152:155], v[144:147]
	v_mfma_f32_16x16x32_bf16 v[140:143], v[136:139], v[152:155], v[140:143]
	v_mfma_f32_16x16x32_bf16 v[120:123], v[112:115], v[160:163], v[120:123]
	v_mfma_f32_16x16x32_bf16 v[116:119], v[136:139], v[160:163], v[116:119]
	v_mfma_f32_16x16x32_bf16 v[100:103], v[112:115], v[176:179], v[100:103]
	v_mfma_f32_16x16x32_bf16 v[96:99], v[136:139], v[176:179], v[96:99]
	v_mfma_f32_16x16x32_bf16 v[84:87], v[112:115], v[198:201], v[84:87]
	v_mfma_f32_16x16x32_bf16 v[80:83], v[136:139], v[198:201], v[80:83]
	v_mfma_f32_16x16x32_bf16 v[144:147], v[124:127], v[156:159], v[144:147]
	v_mfma_f32_16x16x32_bf16 v[140:143], v[148:151], v[156:159], v[140:143]
	v_mfma_f32_16x16x32_bf16 v[120:123], v[124:127], v[172:175], v[120:123]
	v_mfma_f32_16x16x32_bf16 v[116:119], v[148:151], v[172:175], v[116:119]
	v_mfma_f32_16x16x32_bf16 v[100:103], v[124:127], v[180:183], v[100:103]
	v_mfma_f32_16x16x32_bf16 v[96:99], v[148:151], v[180:183], v[96:99]
	v_mfma_f32_16x16x32_bf16 v[84:87], v[124:127], v[202:205], v[84:87]
	v_mfma_f32_16x16x32_bf16 v[80:83], v[148:151], v[202:205], v[80:83]
	s_barrier
	s_add_i32 s38, 0, 0x14000
	s_add_i32 s100, s40, s21
	s_mov_b32 m0, s100
	ds_read_b128 v[206:209], v255 offset:16384
	ds_read_b128 v[210:213], v255 offset:17408
	ds_read_b128 v[214:217], v255 offset:18432
	ds_read_b128 v[218:221], v255 offset:19456
	global_load_lds_dwordx4 v2, s[36:37]
	s_add_i32 m0, s100, 0x2000
	s_add_u32 vcc_lo, s36, s50
	s_addc_u32 vcc_hi, s37, s51
	global_load_lds_dwordx4 v2, vcc
	s_barrier
; #define G_STAGE(bufoff, gbase, o0, h64) do { \
;         __builtin_amdgcn_global_load_lds((const unsigned*)((const char*)(gbase) + (o0)), (LAS unsigned*)(lds + (bufoff) + ldsw), 16, 0, 0); \
;         __builtin_amdgcn_global_load_lds((const unsigned*)((const char*)(gbase) + (h64) + (o0)), (LAS unsigned*)(lds + (bufoff) + ldsw + 8192), 16, 0, 0); } while (0)
; #define G_LDA(dst, b, h) do { _Pragma("unroll") for (int m = 0; m < 4; ++m) _Pragma("unroll") for (int k = 0; k < 2; ++k) dst[m][k] = *(const LAS bf16x8*)(lds + G_SA(b, h) + aoff + m * 2048 + k * 1024); } while (0)
; #define G_LDB(dst, b, h) do { _Pragma("unroll") for (int n = 0; n < 2; ++n) _Pragma("unroll") for (int k = 0; k < 2; ++k) dst[n][k] = *(const LAS bf16x8*)(lds + G_SB(b, h) + boff + n * 2048 + k * 1024); } while (0)
; #define G_WAIT_V(n) asm volatile("s_waitcnt vmcnt(" #n ")" ::: "memory")
; #define G_BAR __builtin_amdgcn_s_barrier()
;     ...
;         for (int t = 0; t < nt; t += 2) {
;             const bool last = (t == nt - 2);
;             const char* a1 = cA + (size_t)(t + 1) * ckA;
;             const char* a2 = last ? nA : cA + (size_t)(t + 2) * ckA; const char* b2 = last ? nB : cB + (size_t)(t + 2) * kB;
;             const char* a3 = a2 + ckA; const char* b3 = b2 + kB;
;             G_LDB(B0, 0, 0); G_SCHED; G_LDA(At, 0, 0); G_STAGE(G_SA(1, 1), a1 + chA, cA0, qA);
;             G_WAIT_L(8); G_BAR; G_WAIT_L(0); G_MMA(0, 0, At, B0); G_BAR; G_SCHED;
;             G_LDB(B1, 0, 1); G_STAGE(G_SB(0, 0), b2, cB0, qB);
;             G_BAR; G_WAIT_L(0); G_MMA(0, 1, At, B1); G_BAR;
;             G_LDA(At, 0, 1); G_STAGE(G_SA(0, 0), a2, cA0, qA);
;             G_BAR; G_WAIT_L(0); G_MMA(1, 0, At, B0); G_BAR; G_SCHED;
;             G_STAGE(G_SB(0, 1), b2 + chB, cB0, qB);
;             G_WAIT_V(6); G_BAR; G_MMA(1, 1, At, B1); G_BAR;
;             G_LDB(B0, 1, 0); G_SCHED; G_LDA(At, 1, 0); G_STAGE(G_SA(0, 1), a2 + chA, cA0, qA);
;             G_WAIT_L(8); G_BAR; G_WAIT_L(0); G_MMA(0, 0, At, B0); G_BAR; G_SCHED;
;             G_LDB(B1, 1, 1); G_STAGE(G_SB(1, 0), b3, cB0, qB);
;             G_BAR; G_WAIT_L(0); G_MMA(0, 1, At, B1); G_BAR;
;             G_LDA(At, 1, 1); G_STAGE(G_SA(1, 0), a3, cA0, qA);
;             G_BAR; G_WAIT_L(0); G_MMA(1, 0, At, B0); G_BAR; G_SCHED;
;             G_STAGE(G_SB(1, 1), b3 + chB, cB0, qB);
;             G_WAIT_V(6); G_BAR; G_MMA(1, 1, At, B1); G_BAR;
	s_waitcnt lgkmcnt(0)
	v_mfma_f32_16x16x32_bf16 v[132:135], v[206:209], v[152:155], v[132:135]
	v_mfma_f32_16x16x32_bf16 v[128:131], v[214:217], v[152:155], v[128:131]
	v_mfma_f32_16x16x32_bf16 v[108:111], v[206:209], v[160:163], v[108:111]
	v_mfma_f32_16x16x32_bf16 v[104:107], v[214:217], v[160:163], v[104:107]
	v_mfma_f32_16x16x32_bf16 v[92:95], v[206:209], v[176:179], v[92:95]
	v_mfma_f32_16x16x32_bf16 v[88:91], v[214:217], v[176:179], v[88:91]
	v_mfma_f32_16x16x32_bf16 v[76:79], v[206:209], v[198:201], v[76:79]
	v_mfma_f32_16x16x32_bf16 v[72:75], v[214:217], v[198:201], v[72:75]
	v_mfma_f32_16x16x32_bf16 v[132:135], v[210:213], v[156:159], v[132:135]
	v_mfma_f32_16x16x32_bf16 v[128:131], v[218:221], v[156:159], v[128:131]
	v_mfma_f32_16x16x32_bf16 v[108:111], v[210:213], v[172:175], v[108:111]
	v_mfma_f32_16x16x32_bf16 v[104:107], v[218:221], v[172:175], v[104:107]
	v_mfma_f32_16x16x32_bf16 v[92:95], v[210:213], v[180:183], v[92:95]
	v_mfma_f32_16x16x32_bf16 v[88:91], v[218:221], v[180:183], v[88:91]
	v_mfma_f32_16x16x32_bf16 v[76:79], v[210:213], v[202:205], v[76:79]
	v_mfma_f32_16x16x32_bf16 v[72:75], v[218:221], v[202:205], v[72:75]
	s_barrier
	s_mov_b32 m0, s24
	v_lshl_add_u64 v[222:223], s[4:5], 0, v[164:165]
	ds_read_b128 v[152:155], v197 offset:16384
	ds_read_b128 v[156:159], v197 offset:17408
	ds_read_b128 v[160:163], v197 offset:18432
	ds_read_b128 v[172:175], v197 offset:19456
	ds_read_b128 v[176:179], v197 offset:20480
	ds_read_b128 v[180:183], v197 offset:21504
	ds_read_b128 v[198:201], v197 offset:22528
	ds_read_b128 v[202:205], v197 offset:23552
	global_load_lds_dwordx4 v164, s[4:5]
	s_mov_b32 m0, s25
	s_add_u32 vcc_lo, s4, s70
	s_addc_u32 vcc_hi, s5, s71
	global_load_lds_dwordx4 v164, vcc
	s_barrier
	s_waitcnt lgkmcnt(0)
	v_mfma_f32_16x16x32_bf16 v[68:71], v[112:115], v[152:155], v[68:71]
	v_mfma_f32_16x16x32_bf16 v[64:67], v[136:139], v[152:155], v[64:67]
	v_mfma_f32_16x16x32_bf16 v[52:55], v[112:115], v[160:163], v[52:55]
	v_mfma_f32_16x16x32_bf16 v[48:51], v[136:139], v[160:163], v[48:51]
	v_mfma_f32_16x16x32_bf16 v[36:39], v[112:115], v[176:179], v[36:39]
	v_mfma_f32_16x16x32_bf16 v[32:35], v[136:139], v[176:179], v[32:35]
	v_mfma_f32_16x16x32_bf16 v[20:23], v[112:115], v[198:201], v[20:23]
	v_mfma_f32_16x16x32_bf16 v[16:19], v[136:139], v[198:201], v[16:19]
	v_mfma_f32_16x16x32_bf16 v[68:71], v[124:127], v[156:159], v[68:71]
	v_mfma_f32_16x16x32_bf16 v[64:67], v[148:151], v[156:159], v[64:67]
	v_mfma_f32_16x16x32_bf16 v[52:55], v[124:127], v[172:175], v[52:55]
	v_mfma_f32_16x16x32_bf16 v[48:51], v[148:151], v[172:175], v[48:51]
	v_mfma_f32_16x16x32_bf16 v[36:39], v[124:127], v[180:183], v[36:39]
	v_mfma_f32_16x16x32_bf16 v[32:35], v[148:151], v[180:183], v[32:35]
	v_mfma_f32_16x16x32_bf16 v[20:23], v[124:127], v[202:205], v[20:23]
	v_mfma_f32_16x16x32_bf16 v[16:19], v[148:151], v[202:205], v[16:19]
	s_barrier
	s_add_i32 s100, s38, s21
	s_mov_b32 m0, s100
	s_add_u32 vcc_lo, s36, s0
	s_addc_u32 vcc_hi, s37, s1
	global_load_lds_dwordx4 v2, vcc
	s_add_i32 m0, s100, 0x2000
	s_add_u32 vcc_lo, s36, s52
	s_addc_u32 vcc_hi, s37, s53
	global_load_lds_dwordx4 v2, vcc
	s_waitcnt vmcnt(6)
	s_barrier
	v_mfma_f32_16x16x32_bf16 v[60:63], v[206:209], v[152:155], v[60:63]
	v_mfma_f32_16x16x32_bf16 v[56:59], v[214:217], v[152:155], v[56:59]
	v_mfma_f32_16x16x32_bf16 v[44:47], v[206:209], v[160:163], v[44:47]
	v_mfma_f32_16x16x32_bf16 v[40:43], v[214:217], v[160:163], v[40:43]
	v_mfma_f32_16x16x32_bf16 v[28:31], v[206:209], v[176:179], v[28:31]
	v_mfma_f32_16x16x32_bf16 v[24:27], v[214:217], v[176:179], v[24:27]
	v_mfma_f32_16x16x32_bf16 v[12:15], v[206:209], v[198:201], v[12:15]
	v_mfma_f32_16x16x32_bf16 v[8:11], v[214:217], v[198:201], v[8:11]
	v_mfma_f32_16x16x32_bf16 v[60:63], v[210:213], v[156:159], v[60:63]
	v_mfma_f32_16x16x32_bf16 v[56:59], v[218:221], v[156:159], v[56:59]
	v_mfma_f32_16x16x32_bf16 v[44:47], v[210:213], v[172:175], v[44:47]
	v_mfma_f32_16x16x32_bf16 v[40:43], v[218:221], v[172:175], v[40:43]
	v_mfma_f32_16x16x32_bf16 v[28:31], v[210:213], v[180:183], v[28:31]
	v_mfma_f32_16x16x32_bf16 v[24:27], v[218:221], v[180:183], v[24:27]
	v_mfma_f32_16x16x32_bf16 v[12:15], v[210:213], v[202:205], v[12:15]
	v_mfma_f32_16x16x32_bf16 v[8:11], v[218:221], v[202:205], v[8:11]
	s_barrier
	s_add_i32 s100, 0, 0x18000
	ds_read_b128 v[112:115], v255 offset:32768
	ds_read_b128 v[124:127], v255 offset:33792
	ds_read_b128 v[136:139], v255 offset:34816
	ds_read_b128 v[148:151], v255 offset:35840
	s_mov_b32 m0, s26
	ds_read_b128 v[152:155], v197 offset:32768
	ds_read_b128 v[156:159], v197 offset:33792
	ds_read_b128 v[160:163], v197 offset:34816
	ds_read_b128 v[172:175], v197 offset:35840
	ds_read_b128 v[176:179], v197 offset:36864
	ds_read_b128 v[180:183], v197 offset:37888
	ds_read_b128 v[198:201], v197 offset:38912
	ds_read_b128 v[202:205], v197 offset:39936
	s_add_u32 vcc_lo, s4, s80
	s_addc_u32 vcc_hi, s5, s81
	global_load_lds_dwordx4 v164, vcc
	s_mov_b32 m0, s27
	s_add_u32 vcc_lo, s4, s82
	s_addc_u32 vcc_hi, s5, s83
	global_load_lds_dwordx4 v164, vcc
	s_waitcnt lgkmcnt(8)
	s_barrier
; #define G_STAGE(bufoff, gbase, o0, h64) do { \
;         __builtin_amdgcn_global_load_lds((const unsigned*)((const char*)(gbase) + (o0)), (LAS unsigned*)(lds + (bufoff) + ldsw), 16, 0, 0); \
;         __builtin_amdgcn_global_load_lds((const unsigned*)((const char*)(gbase) + (h64) + (o0)), (LAS unsigned*)(lds + (bufoff) + ldsw + 8192), 16, 0, 0); } while (0)
; #define G_LDA(dst, b, h) do { _Pragma("unroll") for (int m = 0; m < 4; ++m) _Pragma("unroll") for (int k = 0; k < 2; ++k) dst[m][k] = *(const LAS bf16x8*)(lds + G_SA(b, h) + aoff + m * 2048 + k * 1024); } while (0)
; #define G_LDB(dst, b, h) do { _Pragma("unroll") for (int n = 0; n < 2; ++n) _Pragma("unroll") for (int k = 0; k < 2; ++k) dst[n][k] = *(const LAS bf16x8*)(lds + G_SB(b, h) + boff + n * 2048 + k * 1024); } while (0)
; #define G_WAIT_V(n) asm volatile("s_waitcnt vmcnt(" #n ")" ::: "memory")
; #define G_BAR __builtin_amdgcn_s_barrier()
;     ...
;         for (int t = 0; t < nt; t += 2) {
;             const bool last = (t == nt - 2);
;             const char* a1 = cA + (size_t)(t + 1) * ckA;
;             const char* a2 = last ? nA : cA + (size_t)(t + 2) * ckA; const char* b2 = last ? nB : cB + (size_t)(t + 2) * kB;
;             const char* a3 = a2 + ckA; const char* b3 = b2 + kB;
;             G_LDB(B0, 0, 0); G_SCHED; G_LDA(At, 0, 0); G_STAGE(G_SA(1, 1), a1 + chA, cA0, qA);
;             G_WAIT_L(8); G_BAR; G_WAIT_L(0); G_MMA(0, 0, At, B0); G_BAR; G_SCHED;
;             G_LDB(B1, 0, 1); G_STAGE(G_SB(0, 0), b2, cB0, qB);
;             G_BAR; G_WAIT_L(0); G_MMA(0, 1, At, B1); G_BAR;
;             G_LDA(At, 0, 1); G_STAGE(G_SA(0, 0), a2, cA0, qA);
;             G_BAR; G_WAIT_L(0); G_MMA(1, 0, At, B0); G_BAR; G_SCHED;
;             G_STAGE(G_SB(0, 1), b2 + chB, cB0, qB);
;             G_WAIT_V(6); G_BAR; G_MMA(1, 1, At, B1); G_BAR;
;             G_LDB(B0, 1, 0); G_SCHED; G_LDA(At, 1, 0); G_STAGE(G_SA(0, 1), a2 + chA, cA0, qA);
;             G_WAIT_L(8); G_BAR; G_WAIT_L(0); G_MMA(0, 0, At, B0); G_BAR; G_SCHED;
;             G_LDB(B1, 1, 1); G_STAGE(G_SB(1, 0), b3, cB0, qB);
;             G_BAR; G_WAIT_L(0); G_MMA(0, 1, At, B1); G_BAR;
;             G_LDA(At, 1, 1); G_STAGE(G_SA(1, 0), a3, cA0, qA);
;             G_BAR; G_WAIT_L(0); G_MMA(1, 0, At, B0); G_BAR; G_SCHED;
;             G_STAGE(G_SB(1, 1), b3 + chB, cB0, qB);
;             G_WAIT_V(6); G_BAR; G_MMA(1, 1, At, B1); G_BAR;
;         }
	s_waitcnt lgkmcnt(0)
	v_mfma_f32_16x16x32_bf16 v[144:147], v[112:115], v[152:155], v[144:147]
	v_mfma_f32_16x16x32_bf16 v[140:143], v[136:139], v[152:155], v[140:143]
	v_mfma_f32_16x16x32_bf16 v[120:123], v[112:115], v[160:163], v[120:123]
	v_mfma_f32_16x16x32_bf16 v[116:119], v[136:139], v[160:163], v[116:119]
	v_mfma_f32_16x16x32_bf16 v[100:103], v[112:115], v[176:179], v[100:103]
	v_mfma_f32_16x16x32_bf16 v[96:99], v[136:139], v[176:179], v[96:99]
	v_mfma_f32_16x16x32_bf16 v[84:87], v[112:115], v[198:201], v[84:87]
	v_mfma_f32_16x16x32_bf16 v[80:83], v[136:139], v[198:201], v[80:83]
	v_mfma_f32_16x16x32_bf16 v[144:147], v[124:127], v[156:159], v[144:147]
	v_mfma_f32_16x16x32_bf16 v[140:143], v[148:151], v[156:159], v[140:143]
	v_mfma_f32_16x16x32_bf16 v[120:123], v[124:127], v[172:175], v[120:123]
	v_mfma_f32_16x16x32_bf16 v[116:119], v[148:151], v[172:175], v[116:119]
	v_mfma_f32_16x16x32_bf16 v[100:103], v[124:127], v[180:183], v[100:103]
	v_mfma_f32_16x16x32_bf16 v[96:99], v[148:151], v[180:183], v[96:99]
	v_mfma_f32_16x16x32_bf16 v[84:87], v[124:127], v[202:205], v[84:87]
	v_mfma_f32_16x16x32_bf16 v[80:83], v[148:151], v[202:205], v[80:83]
	s_barrier
	s_add_i32 s5, 0, 0x1c000
	s_add_i32 s4, s100, s21
	s_mov_b32 m0, s4
	ds_read_b128 v[206:209], v255 offset:49152
	ds_read_b128 v[210:213], v255 offset:50176
	ds_read_b128 v[214:217], v255 offset:51200
	ds_read_b128 v[218:221], v255 offset:52224
	s_add_u32 vcc_lo, s36, s46
	s_addc_u32 vcc_hi, s37, s47
	global_load_lds_dwordx4 v2, vcc
	s_add_i32 m0, s4, 0x2000
	s_add_u32 vcc_lo, s36, s54
	s_addc_u32 vcc_hi, s37, s55
	global_load_lds_dwordx4 v2, vcc
	s_barrier
	s_waitcnt lgkmcnt(0)
	v_mfma_f32_16x16x32_bf16 v[132:135], v[206:209], v[152:155], v[132:135]
	v_mfma_f32_16x16x32_bf16 v[128:131], v[214:217], v[152:155], v[128:131]
	v_mfma_f32_16x16x32_bf16 v[108:111], v[206:209], v[160:163], v[108:111]
	v_mfma_f32_16x16x32_bf16 v[104:107], v[214:217], v[160:163], v[104:107]
	v_mfma_f32_16x16x32_bf16 v[92:95], v[206:209], v[176:179], v[92:95]
	v_mfma_f32_16x16x32_bf16 v[88:91], v[214:217], v[176:179], v[88:91]
	v_mfma_f32_16x16x32_bf16 v[76:79], v[206:209], v[198:201], v[76:79]
	v_mfma_f32_16x16x32_bf16 v[72:75], v[214:217], v[198:201], v[72:75]
	v_mfma_f32_16x16x32_bf16 v[132:135], v[210:213], v[156:159], v[132:135]
	v_mfma_f32_16x16x32_bf16 v[128:131], v[218:221], v[156:159], v[128:131]
	v_mfma_f32_16x16x32_bf16 v[108:111], v[210:213], v[172:175], v[108:111]
	v_mfma_f32_16x16x32_bf16 v[104:107], v[218:221], v[172:175], v[104:107]
	v_mfma_f32_16x16x32_bf16 v[92:95], v[210:213], v[180:183], v[92:95]
	v_mfma_f32_16x16x32_bf16 v[88:91], v[218:221], v[180:183], v[88:91]
	v_mfma_f32_16x16x32_bf16 v[76:79], v[210:213], v[202:205], v[76:79]
	v_mfma_f32_16x16x32_bf16 v[72:75], v[218:221], v[202:205], v[72:75]
	s_barrier
	s_mov_b32 m0, s29
	v_lshl_add_u64 v[224:225], v[222:223], 0, s[62:63]
	ds_read_b128 v[152:155], v197 offset:49152
	ds_read_b128 v[156:159], v197 offset:50176
	ds_read_b128 v[160:163], v197 offset:51200
	ds_read_b128 v[172:175], v197 offset:52224
	ds_read_b128 v[176:179], v197 offset:53248
	ds_read_b128 v[180:183], v197 offset:54272
	ds_read_b128 v[198:201], v197 offset:55296
	ds_read_b128 v[202:205], v197 offset:56320
	global_load_lds_dwordx4 v[224:225], off
	v_lshl_add_u64 v[222:223], v[222:223], 0, s[84:85]
	s_mov_b32 m0, s30
	s_nop 0
	global_load_lds_dwordx4 v[222:223], off
	s_barrier
	s_waitcnt lgkmcnt(0)
	v_mfma_f32_16x16x32_bf16 v[68:71], v[112:115], v[152:155], v[68:71]
	v_mfma_f32_16x16x32_bf16 v[64:67], v[136:139], v[152:155], v[64:67]
	v_mfma_f32_16x16x32_bf16 v[52:55], v[112:115], v[160:163], v[52:55]
	v_mfma_f32_16x16x32_bf16 v[48:51], v[136:139], v[160:163], v[48:51]
	v_mfma_f32_16x16x32_bf16 v[36:39], v[112:115], v[176:179], v[36:39]
	v_mfma_f32_16x16x32_bf16 v[32:35], v[136:139], v[176:179], v[32:35]
	v_mfma_f32_16x16x32_bf16 v[20:23], v[112:115], v[198:201], v[20:23]
	v_mfma_f32_16x16x32_bf16 v[16:19], v[136:139], v[198:201], v[16:19]
	v_mfma_f32_16x16x32_bf16 v[68:71], v[124:127], v[156:159], v[68:71]
	v_mfma_f32_16x16x32_bf16 v[64:67], v[148:151], v[156:159], v[64:67]
	v_mfma_f32_16x16x32_bf16 v[52:55], v[124:127], v[172:175], v[52:55]
	v_mfma_f32_16x16x32_bf16 v[48:51], v[148:151], v[172:175], v[48:51]
	v_mfma_f32_16x16x32_bf16 v[36:39], v[124:127], v[180:183], v[36:39]
	v_mfma_f32_16x16x32_bf16 v[32:35], v[148:151], v[180:183], v[32:35]
	v_mfma_f32_16x16x32_bf16 v[20:23], v[124:127], v[202:205], v[20:23]
	v_mfma_f32_16x16x32_bf16 v[16:19], v[148:151], v[202:205], v[16:19]
	s_barrier
	s_add_i32 s4, s5, s21
	s_mov_b32 m0, s4
	s_add_u32 vcc_lo, s36, s42
	s_addc_u32 vcc_hi, s37, s43
	global_load_lds_dwordx4 v2, vcc
	s_add_i32 m0, s4, 0x2000
	s_add_u32 vcc_lo, s36, s58
	s_addc_u32 vcc_hi, s37, s59
	global_load_lds_dwordx4 v2, vcc
	s_add_i32 s19, s19, 2
	s_add_u32 s13, s13, 0x100
	s_addc_u32 s18, s18, 0
	s_add_u32 s2, s2, 0x800000
	s_addc_u32 s3, s3, 0
	s_cmp_gt_u32 s19, 5
	s_waitcnt vmcnt(6)
	s_barrier
	v_mfma_f32_16x16x32_bf16 v[60:63], v[206:209], v[152:155], v[60:63]
	v_mfma_f32_16x16x32_bf16 v[56:59], v[214:217], v[152:155], v[56:59]
	v_mfma_f32_16x16x32_bf16 v[44:47], v[206:209], v[160:163], v[44:47]
	v_mfma_f32_16x16x32_bf16 v[40:43], v[214:217], v[160:163], v[40:43]
	v_mfma_f32_16x16x32_bf16 v[28:31], v[206:209], v[176:179], v[28:31]
	v_mfma_f32_16x16x32_bf16 v[24:27], v[214:217], v[176:179], v[24:27]
	v_mfma_f32_16x16x32_bf16 v[12:15], v[206:209], v[198:201], v[12:15]
	v_mfma_f32_16x16x32_bf16 v[8:11], v[214:217], v[198:201], v[8:11]
	v_mfma_f32_16x16x32_bf16 v[60:63], v[210:213], v[156:159], v[60:63]
	v_mfma_f32_16x16x32_bf16 v[56:59], v[218:221], v[156:159], v[56:59]
	v_mfma_f32_16x16x32_bf16 v[44:47], v[210:213], v[172:175], v[44:47]
	v_mfma_f32_16x16x32_bf16 v[40:43], v[218:221], v[172:175], v[40:43]
	v_mfma_f32_16x16x32_bf16 v[28:31], v[210:213], v[180:183], v[28:31]
	v_mfma_f32_16x16x32_bf16 v[24:27], v[218:221], v[180:183], v[24:27]
	v_mfma_f32_16x16x32_bf16 v[12:15], v[210:213], v[202:205], v[12:15]
	v_mfma_f32_16x16x32_bf16 v[8:11], v[218:221], v[202:205], v[8:11]
	s_cbranch_scc0 .Ldb_GLU_cont

; #define G_STAGE(bufoff, gbase, o0, h64) do { \
;         __builtin_amdgcn_global_load_lds((const unsigned*)((const char*)(gbase) + (o0)), (LAS unsigned*)(lds + (bufoff) + ldsw), 16, 0, 0); \
;         __builtin_amdgcn_global_load_lds((const unsigned*)((const char*)(gbase) + (h64) + (o0)), (LAS unsigned*)(lds + (bufoff) + ldsw + 8192), 16, 0, 0); } while (0)
; #define G_LDA(dst, b, h) do { _Pragma("unroll") for (int m = 0; m < 4; ++m) _Pragma("unroll") for (int k = 0; k < 2; ++k) dst[m][k] = *(const LAS bf16x8*)(lds + G_SA(b, h) + aoff + m * 2048 + k * 1024); } while (0)
; #define G_WAIT_V(n) asm volatile("s_waitcnt vmcnt(" #n ")" ::: "memory")
; #define G_BAR __builtin_amdgcn_s_barrier()
;     ...
;     for (;;) {
;         const bool has_next = sched_next<PH, SUB>(E.ws, E.layer, ui + 1, nxt, E.x);
;         if (!has_next) nxt = cur;
;         const char* nA = nxt.A; const char* nB = nxt.B;
; #pragma unroll 1
;         for (int t = 0; t < nt; t += 2) {
;             const bool last = (t == nt - 2);
;             const char* a1 = cA + (size_t)(t + 1) * ckA;
;             const char* a2 = last ? nA : cA + (size_t)(t + 2) * ckA; const char* b2 = last ? nB : cB + (size_t)(t + 2) * kB;
;             const char* a3 = a2 + ckA; const char* b3 = b2 + kB;
;             G_LDB(B0, 0, 0); G_SCHED; G_LDA(At, 0, 0); G_STAGE(G_SA(1, 1), a1 + chA, cA0, qA);
;             G_WAIT_L(8); G_BAR; G_WAIT_L(0); G_MMA(0, 0, At, B0); G_BAR; G_SCHED;
;             G_LDB(B1, 0, 1); G_STAGE(G_SB(0, 0), b2, cB0, qB);
;             G_BAR; G_WAIT_L(0); G_MMA(0, 1, At, B1); G_BAR;
;             G_LDA(At, 0, 1); G_STAGE(G_SA(0, 0), a2, cA0, qA);
;             G_BAR; G_WAIT_L(0); G_MMA(1, 0, At, B0); G_BAR; G_SCHED;
;             G_STAGE(G_SB(0, 1), b2 + chB, cB0, qB);
;             G_WAIT_V(6); G_BAR; G_MMA(1, 1, At, B1); G_BAR;
;             G_LDB(B0, 1, 0); G_SCHED; G_LDA(At, 1, 0); G_STAGE(G_SA(0, 1), a2 + chA, cA0, qA);
;             G_WAIT_L(8); G_BAR; G_WAIT_L(0); G_MMA(0, 0, At, B0); G_BAR; G_SCHED;
;             G_LDB(B1, 1, 1); G_STAGE(G_SB(1, 0), b3, cB0, qB);
;             G_BAR; G_WAIT_L(0); G_MMA(0, 1, At, B1); G_BAR;
;             G_LDA(At, 1, 1); G_STAGE(G_SA(1, 0), a3, cA0, qA);
;             G_BAR; G_WAIT_L(0); G_MMA(1, 0, At, B0); G_BAR; G_SCHED;
;             G_STAGE(G_SB(1, 1), b3 + chB, cB0, qB);
;             G_WAIT_V(6); G_BAR; G_MMA(1, 1, At, B1); G_BAR;
.LBB0_871:
	s_add_u32 s2, s2, 0xb0080
	s_addc_u32 s3, s3, 0
	s_add_u32 s37, s12, 0x100
	s_addc_u32 s38, s13, 0
	s_mov_b32 s39, -2
	s_mov_b64 s[42:43], 0x20080
	s_mov_b64 s[50:51], 0x10000
	s_mov_b64 s[52:53], 0x30000
	s_mov_b64 s[54:55], 0x10080
	s_mov_b64 s[58:59], 0x30080
	s_cmp_eq_u32 s101, 2
	s_cselect_b32 s101, 0, s101
	s_setprio 0
	v_add_u32_e32 v239, 0x10000, v159
	s_add_u32 s4, s2, 0xfff50080
	s_addc_u32 s5, s3, -1
	s_add_i32 s40, 0, 0x10000
	ds_read_b128 v[144:147], v239 offset:0
	ds_read_b128 v[148:151], v239 offset:1024
	ds_read_b128 v[136:139], v239 offset:2048
	ds_read_b128 v[140:143], v239 offset:3072
	s_cmp_eq_u32 s39, 4
	s_cselect_b32 s13, s9, s5
	s_cselect_b32 s12, s8, s4
	s_cselect_b32 s15, s11, s38
	s_cselect_b32 s14, s10, s37
	s_add_i32 m0, s22, 0xc000
	ds_read_b128 v[160:163], v236
	ds_read_b128 v[164:167], v236 offset:1024
	ds_read_b128 v[176:179], v236 offset:2048
	ds_read_b128 v[180:183], v236 offset:3072
	ds_read_b128 v[196:199], v236 offset:4096
	ds_read_b128 v[200:203], v236 offset:5120
	ds_read_b128 v[204:207], v236 offset:6144
	ds_read_b128 v[208:211], v236 offset:7168
	global_load_lds_dwordx4 v152, s[2:3]
	s_add_i32 m0, s22, 0xe000
	s_add_u32 vcc_lo, s2, s86
	s_addc_u32 vcc_hi, s3, s87
	global_load_lds_dwordx4 v152, vcc
	s_waitcnt lgkmcnt(8)
	s_cmp_eq_u32 s101, 1
	s_cbranch_scc1 .Ldb_MG0_skp
	s_barrier
.Ldb_MG0_skp:
	s_mov_b32 s101, 0
	s_waitcnt lgkmcnt(0)
	v_mfma_f32_16x16x128_f8f6f4 v[128:131], v[144:151], v[160:167], 0
	v_mfma_f32_16x16x128_f8f6f4 v[132:135], v[136:143], v[160:167], 0
	v_mfma_f32_16x16x128_f8f6f4 v[112:115], v[144:151], v[176:183], 0
	v_mfma_f32_16x16x128_f8f6f4 v[116:119], v[136:143], v[176:183], 0
	v_mfma_f32_16x16x128_f8f6f4 v[96:99], v[144:151], v[196:203], 0
	v_mfma_f32_16x16x128_f8f6f4 v[100:103], v[136:143], v[196:203], 0
	v_mfma_f32_16x16x128_f8f6f4 v[80:83], v[144:151], v[204:211], 0
	v_mfma_f32_16x16x128_f8f6f4 v[84:87], v[136:143], v[204:211], 0
	s_barrier
	s_add_i32 s4, 0, 0x14000
	s_add_i32 s5, s40, s17
	ds_read_b128 v[212:215], v239 offset:16384
	ds_read_b128 v[216:219], v239 offset:17408
	ds_read_b128 v[220:223], v239 offset:18432
	ds_read_b128 v[224:227], v239 offset:19456
	s_mov_b32 m0, s5
	global_load_lds_dwordx4 v0, s[14:15]
	s_add_i32 m0, s5, 0x2000
	s_add_u32 vcc_lo, s14, s50
	s_addc_u32 vcc_hi, s15, s51
	global_load_lds_dwordx4 v0, vcc
	s_barrier
	s_waitcnt lgkmcnt(0)
	v_mfma_f32_16x16x128_f8f6f4 v[124:127], v[212:219], v[160:167], 0
	v_mfma_f32_16x16x128_f8f6f4 v[120:123], v[220:227], v[160:167], 0
	v_mfma_f32_16x16x128_f8f6f4 v[108:111], v[212:219], v[176:183], 0
	v_mfma_f32_16x16x128_f8f6f4 v[104:107], v[220:227], v[176:183], 0
	v_mfma_f32_16x16x128_f8f6f4 v[92:95], v[212:219], v[196:203], 0
	v_mfma_f32_16x16x128_f8f6f4 v[88:91], v[220:227], v[196:203], 0
	v_mfma_f32_16x16x128_f8f6f4 v[76:79], v[212:219], v[204:211], 0
	v_mfma_f32_16x16x128_f8f6f4 v[72:75], v[220:227], v[204:211], 0
	s_barrier
	s_mov_b32 m0, s22
	ds_read_b128 v[160:163], v236 offset:16384
	ds_read_b128 v[164:167], v236 offset:17408
	ds_read_b128 v[176:179], v236 offset:18432
	ds_read_b128 v[180:183], v236 offset:19456
	ds_read_b128 v[196:199], v236 offset:20480
	ds_read_b128 v[200:203], v236 offset:21504
	ds_read_b128 v[204:207], v236 offset:22528
	ds_read_b128 v[208:211], v236 offset:23552
	global_load_lds_dwordx4 v2, s[12:13]
	s_mov_b32 m0, s23
	s_add_u32 vcc_lo, s12, s86
	s_addc_u32 vcc_hi, s13, s87
	global_load_lds_dwordx4 v2, vcc
	s_barrier
	s_waitcnt lgkmcnt(0)
	v_mfma_f32_16x16x128_f8f6f4 v[64:67], v[144:151], v[160:167], 0
	v_mfma_f32_16x16x128_f8f6f4 v[68:71], v[136:143], v[160:167], 0
	v_mfma_f32_16x16x128_f8f6f4 v[48:51], v[144:151], v[176:183], 0
	v_mfma_f32_16x16x128_f8f6f4 v[52:55], v[136:143], v[176:183], 0
	v_mfma_f32_16x16x128_f8f6f4 v[32:35], v[144:151], v[196:203], 0
	v_mfma_f32_16x16x128_f8f6f4 v[36:39], v[136:143], v[196:203], 0
	v_mfma_f32_16x16x128_f8f6f4 v[20:23], v[144:151], v[204:211], 0
	v_mfma_f32_16x16x128_f8f6f4 v[16:19], v[136:143], v[204:211], 0
	s_barrier
	s_add_i32 s4, s4, s17
	s_mov_b32 m0, s4
	s_add_u32 vcc_lo, s14, s0
	s_addc_u32 vcc_hi, s15, s1
	global_load_lds_dwordx4 v0, vcc
	s_add_i32 m0, s4, 0x2000
	s_add_u32 vcc_lo, s14, s52
	s_addc_u32 vcc_hi, s15, s53
	global_load_lds_dwordx4 v0, vcc
	s_waitcnt vmcnt(6)
	s_barrier
	v_mfma_f32_16x16x128_f8f6f4 v[60:63], v[212:219], v[160:167], 0
	v_mfma_f32_16x16x128_f8f6f4 v[56:59], v[220:227], v[160:167], 0
	v_mfma_f32_16x16x128_f8f6f4 v[44:47], v[212:219], v[176:183], 0
	v_mfma_f32_16x16x128_f8f6f4 v[40:43], v[220:227], v[176:183], 0
	v_mfma_f32_16x16x128_f8f6f4 v[28:31], v[212:219], v[196:203], 0
	v_mfma_f32_16x16x128_f8f6f4 v[24:27], v[220:227], v[196:203], 0
	v_mfma_f32_16x16x128_f8f6f4 v[12:15], v[212:219], v[204:211], 0
	v_mfma_f32_16x16x128_f8f6f4 v[8:11], v[220:227], v[204:211], 0
	s_barrier
	s_add_i32 s4, 0, 0x18000
	ds_read_b128 v[144:147], v239 offset:32768
	ds_read_b128 v[148:151], v239 offset:33792
	ds_read_b128 v[136:139], v239 offset:34816
	ds_read_b128 v[140:143], v239 offset:35840
	s_mov_b32 m0, s24
	ds_read_b128 v[160:163], v236 offset:32768
	ds_read_b128 v[164:167], v236 offset:33792
	ds_read_b128 v[176:179], v236 offset:34816
	ds_read_b128 v[180:183], v236 offset:35840
	ds_read_b128 v[196:199], v236 offset:36864
	ds_read_b128 v[200:203], v236 offset:37888
	ds_read_b128 v[204:207], v236 offset:38912
	ds_read_b128 v[208:211], v236 offset:39936
	s_add_u32 vcc_lo, s12, s88
	s_addc_u32 vcc_hi, s13, s89
	global_load_lds_dwordx4 v2, vcc
	s_mov_b32 m0, s25
	s_add_u32 vcc_lo, s12, s64
	s_addc_u32 vcc_hi, s13, s65
	global_load_lds_dwordx4 v2, vcc
	s_waitcnt lgkmcnt(8)
	s_barrier
; #define G_STAGE(bufoff, gbase, o0, h64) do { \
;         __builtin_amdgcn_global_load_lds((const unsigned*)((const char*)(gbase) + (o0)), (LAS unsigned*)(lds + (bufoff) + ldsw), 16, 0, 0); \
;         __builtin_amdgcn_global_load_lds((const unsigned*)((const char*)(gbase) + (h64) + (o0)), (LAS unsigned*)(lds + (bufoff) + ldsw + 8192), 16, 0, 0); } while (0)
; #define G_LDA(dst, b, h) do { _Pragma("unroll") for (int m = 0; m < 4; ++m) _Pragma("unroll") for (int k = 0; k < 2; ++k) dst[m][k] = *(const LAS bf16x8*)(lds + G_SA(b, h) + aoff + m * 2048 + k * 1024); } while (0)
; #define G_LDB(dst, b, h) do { _Pragma("unroll") for (int n = 0; n < 2; ++n) _Pragma("unroll") for (int k = 0; k < 2; ++k) dst[n][k] = *(const LAS bf16x8*)(lds + G_SB(b, h) + boff + n * 2048 + k * 1024); } while (0)
; #define G_WAIT_V(n) asm volatile("s_waitcnt vmcnt(" #n ")" ::: "memory")
; #define G_BAR __builtin_amdgcn_s_barrier()
;     ...
;         for (int t = 0; t < nt; t += 2) {
;             const bool last = (t == nt - 2);
;             const char* a1 = cA + (size_t)(t + 1) * ckA;
;             const char* a2 = last ? nA : cA + (size_t)(t + 2) * ckA; const char* b2 = last ? nB : cB + (size_t)(t + 2) * kB;
;             const char* a3 = a2 + ckA; const char* b3 = b2 + kB;
;             G_LDB(B0, 0, 0); G_SCHED; G_LDA(At, 0, 0); G_STAGE(G_SA(1, 1), a1 + chA, cA0, qA);
;             G_WAIT_L(8); G_BAR; G_WAIT_L(0); G_MMA(0, 0, At, B0); G_BAR; G_SCHED;
;             G_LDB(B1, 0, 1); G_STAGE(G_SB(0, 0), b2, cB0, qB);
;             G_BAR; G_WAIT_L(0); G_MMA(0, 1, At, B1); G_BAR;
;             G_LDA(At, 0, 1); G_STAGE(G_SA(0, 0), a2, cA0, qA);
;             G_BAR; G_WAIT_L(0); G_MMA(1, 0, At, B0); G_BAR; G_SCHED;
;             G_STAGE(G_SB(0, 1), b2 + chB, cB0, qB);
;             G_WAIT_V(6); G_BAR; G_MMA(1, 1, At, B1); G_BAR;
;             G_LDB(B0, 1, 0); G_SCHED; G_LDA(At, 1, 0); G_STAGE(G_SA(0, 1), a2 + chA, cA0, qA);
;             G_WAIT_L(8); G_BAR; G_WAIT_L(0); G_MMA(0, 0, At, B0); G_BAR; G_SCHED;
;             G_LDB(B1, 1, 1); G_STAGE(G_SB(1, 0), b3, cB0, qB);
;             G_BAR; G_WAIT_L(0); G_MMA(0, 1, At, B1); G_BAR;
;             G_LDA(At, 1, 1); G_STAGE(G_SA(1, 0), a3, cA0, qA);
;             G_BAR; G_WAIT_L(0); G_MMA(1, 0, At, B0); G_BAR; G_SCHED;
;             G_STAGE(G_SB(1, 1), b3 + chB, cB0, qB);
;             G_WAIT_V(6); G_BAR; G_MMA(1, 1, At, B1); G_BAR;
	s_waitcnt lgkmcnt(0)
	v_mfma_f32_16x16x128_f8f6f4 v[128:131], v[144:151], v[160:167], v[128:131]
	v_mfma_f32_16x16x128_f8f6f4 v[132:135], v[136:143], v[160:167], v[132:135]
	v_mfma_f32_16x16x128_f8f6f4 v[112:115], v[144:151], v[176:183], v[112:115]
	v_mfma_f32_16x16x128_f8f6f4 v[116:119], v[136:143], v[176:183], v[116:119]
	v_mfma_f32_16x16x128_f8f6f4 v[96:99], v[144:151], v[196:203], v[96:99]
	v_mfma_f32_16x16x128_f8f6f4 v[100:103], v[136:143], v[196:203], v[100:103]
	v_mfma_f32_16x16x128_f8f6f4 v[80:83], v[144:151], v[204:211], v[80:83]
	v_mfma_f32_16x16x128_f8f6f4 v[84:87], v[136:143], v[204:211], v[84:87]
	s_barrier
	s_add_i32 s5, 0, 0x1c000
	s_add_i32 s4, s4, s17
	s_mov_b32 m0, s4
	ds_read_b128 v[212:215], v239 offset:49152
	ds_read_b128 v[216:219], v239 offset:50176
	ds_read_b128 v[220:223], v239 offset:51200
	ds_read_b128 v[224:227], v239 offset:52224
	s_add_u32 vcc_lo, s14, s46
	s_addc_u32 vcc_hi, s15, s47
	global_load_lds_dwordx4 v0, vcc
	s_add_i32 m0, s4, 0x2000
	s_add_u32 vcc_lo, s14, s54
	s_addc_u32 vcc_hi, s15, s55
	global_load_lds_dwordx4 v0, vcc
	s_barrier
	s_waitcnt lgkmcnt(0)
	v_mfma_f32_16x16x128_f8f6f4 v[124:127], v[212:219], v[160:167], v[124:127]
	v_mfma_f32_16x16x128_f8f6f4 v[120:123], v[220:227], v[160:167], v[120:123]
	v_mfma_f32_16x16x128_f8f6f4 v[108:111], v[212:219], v[176:183], v[108:111]
	v_mfma_f32_16x16x128_f8f6f4 v[104:107], v[220:227], v[176:183], v[104:107]
	v_mfma_f32_16x16x128_f8f6f4 v[92:95], v[212:219], v[196:203], v[92:95]
	v_mfma_f32_16x16x128_f8f6f4 v[88:91], v[220:227], v[196:203], v[88:91]
	v_mfma_f32_16x16x128_f8f6f4 v[76:79], v[212:219], v[204:211], v[76:79]
	v_mfma_f32_16x16x128_f8f6f4 v[72:75], v[220:227], v[204:211], v[72:75]
	s_barrier
	s_mov_b32 m0, s26
	ds_read_b128 v[160:163], v236 offset:49152
	ds_read_b128 v[164:167], v236 offset:50176
	ds_read_b128 v[176:179], v236 offset:51200
	ds_read_b128 v[180:183], v236 offset:52224
	ds_read_b128 v[196:199], v236 offset:53248
	ds_read_b128 v[200:203], v236 offset:54272
	ds_read_b128 v[204:207], v236 offset:55296
	ds_read_b128 v[208:211], v236 offset:56320
	s_add_u32 vcc_lo, s12, s46
	s_addc_u32 vcc_hi, s13, s47
	global_load_lds_dwordx4 v2, vcc
	s_mov_b32 m0, s27
	s_add_u32 vcc_lo, s12, s66
	s_addc_u32 vcc_hi, s13, s67
	global_load_lds_dwordx4 v2, vcc
	s_barrier
	s_waitcnt lgkmcnt(0)
	v_mfma_f32_16x16x128_f8f6f4 v[64:67], v[144:151], v[160:167], v[64:67]
	v_mfma_f32_16x16x128_f8f6f4 v[68:71], v[136:143], v[160:167], v[68:71]
	v_mfma_f32_16x16x128_f8f6f4 v[48:51], v[144:151], v[176:183], v[48:51]
	v_mfma_f32_16x16x128_f8f6f4 v[52:55], v[136:143], v[176:183], v[52:55]
	v_mfma_f32_16x16x128_f8f6f4 v[32:35], v[144:151], v[196:203], v[32:35]
	v_mfma_f32_16x16x128_f8f6f4 v[36:39], v[136:143], v[196:203], v[36:39]
	v_mfma_f32_16x16x128_f8f6f4 v[20:23], v[144:151], v[204:211], v[20:23]
	v_mfma_f32_16x16x128_f8f6f4 v[16:19], v[136:143], v[204:211], v[16:19]
	s_barrier
	s_add_i32 s4, s5, s17
	s_mov_b32 m0, s4
	s_add_u32 vcc_lo, s14, s42
	s_addc_u32 vcc_hi, s15, s43
	global_load_lds_dwordx4 v0, vcc
	s_add_i32 m0, s4, 0x2000
	s_add_u32 vcc_lo, s14, s58
	s_addc_u32 vcc_hi, s15, s59
	global_load_lds_dwordx4 v0, vcc
	s_add_i32 s39, s39, 2
	s_add_u32 s2, s2, 0x100
	s_addc_u32 s3, s3, 0
	s_add_u32 s37, s37, 0x100
	s_addc_u32 s38, s38, 0
	s_cmp_gt_u32 s39, 5
	s_waitcnt vmcnt(6)
	s_barrier
	v_mfma_f32_16x16x128_f8f6f4 v[60:63], v[212:219], v[160:167], v[60:63]
	v_mfma_f32_16x16x128_f8f6f4 v[56:59], v[220:227], v[160:167], v[56:59]
	v_mfma_f32_16x16x128_f8f6f4 v[44:47], v[212:219], v[176:183], v[44:47]
	v_mfma_f32_16x16x128_f8f6f4 v[40:43], v[220:227], v[176:183], v[40:43]
	v_mfma_f32_16x16x128_f8f6f4 v[28:31], v[212:219], v[196:203], v[28:31]
	v_mfma_f32_16x16x128_f8f6f4 v[24:27], v[220:227], v[196:203], v[24:27]
	v_mfma_f32_16x16x128_f8f6f4 v[12:15], v[212:219], v[204:211], v[12:15]
	v_mfma_f32_16x16x128_f8f6f4 v[8:11], v[220:227], v[204:211], v[8:11]
	s_cbranch_scc0 .Ldb_MG0_cont
	s_branch .Ldb_MG0_xl
.LBB0_872:
	s_add_u32 s4, s2, 0xfff50080
	s_addc_u32 s5, s3, -1
	s_add_i32 s40, 0, 0x10000
	ds_read_b128 v[144:147], v239 offset:0
	ds_read_b128 v[148:151], v239 offset:1024
	ds_read_b128 v[136:139], v239 offset:2048
	ds_read_b128 v[140:143], v239 offset:3072
	s_cmp_eq_u32 s39, 4
	s_cselect_b32 s13, s9, s5
	s_cselect_b32 s12, s8, s4
	s_cselect_b32 s15, s11, s38
	s_cselect_b32 s14, s10, s37
	s_add_i32 m0, s22, 0xc000
	ds_read_b128 v[160:163], v236
	ds_read_b128 v[164:167], v236 offset:1024
	ds_read_b128 v[176:179], v236 offset:2048
	ds_read_b128 v[180:183], v236 offset:3072
	ds_read_b128 v[196:199], v236 offset:4096
	ds_read_b128 v[200:203], v236 offset:5120
	ds_read_b128 v[204:207], v236 offset:6144
	ds_read_b128 v[208:211], v236 offset:7168
	global_load_lds_dwordx4 v152, s[2:3]
	s_add_i32 m0, s22, 0xe000
	s_add_u32 vcc_lo, s2, s86
	s_addc_u32 vcc_hi, s3, s87
	global_load_lds_dwordx4 v152, vcc
	s_waitcnt lgkmcnt(8)
	s_barrier
	s_waitcnt lgkmcnt(0)
	v_mfma_f32_16x16x128_f8f6f4 v[128:131], v[144:151], v[160:167], v[128:131]
	v_mfma_f32_16x16x128_f8f6f4 v[132:135], v[136:143], v[160:167], v[132:135]
	v_mfma_f32_16x16x128_f8f6f4 v[112:115], v[144:151], v[176:183], v[112:115]
	v_mfma_f32_16x16x128_f8f6f4 v[116:119], v[136:143], v[176:183], v[116:119]
	v_mfma_f32_16x16x128_f8f6f4 v[96:99], v[144:151], v[196:203], v[96:99]
	v_mfma_f32_16x16x128_f8f6f4 v[100:103], v[136:143], v[196:203], v[100:103]
	v_mfma_f32_16x16x128_f8f6f4 v[80:83], v[144:151], v[204:211], v[80:83]
	v_mfma_f32_16x16x128_f8f6f4 v[84:87], v[136:143], v[204:211], v[84:87]
	s_barrier
; #define G_STAGE(bufoff, gbase, o0, h64) do { \
;         __builtin_amdgcn_global_load_lds((const unsigned*)((const char*)(gbase) + (o0)), (LAS unsigned*)(lds + (bufoff) + ldsw), 16, 0, 0); \
;         __builtin_amdgcn_global_load_lds((const unsigned*)((const char*)(gbase) + (h64) + (o0)), (LAS unsigned*)(lds + (bufoff) + ldsw + 8192), 16, 0, 0); } while (0)
; #define G_LDA(dst, b, h) do { _Pragma("unroll") for (int m = 0; m < 4; ++m) _Pragma("unroll") for (int k = 0; k < 2; ++k) dst[m][k] = *(const LAS bf16x8*)(lds + G_SA(b, h) + aoff + m * 2048 + k * 1024); } while (0)
; #define G_LDB(dst, b, h) do { _Pragma("unroll") for (int n = 0; n < 2; ++n) _Pragma("unroll") for (int k = 0; k < 2; ++k) dst[n][k] = *(const LAS bf16x8*)(lds + G_SB(b, h) + boff + n * 2048 + k * 1024); } while (0)
; #define G_WAIT_V(n) asm volatile("s_waitcnt vmcnt(" #n ")" ::: "memory")
; #define G_BAR __builtin_amdgcn_s_barrier()
;     ...
;         for (int t = 0; t < nt; t += 2) {
;             const bool last = (t == nt - 2);
;             const char* a1 = cA + (size_t)(t + 1) * ckA;
;             const char* a2 = last ? nA : cA + (size_t)(t + 2) * ckA; const char* b2 = last ? nB : cB + (size_t)(t + 2) * kB;
;             const char* a3 = a2 + ckA; const char* b3 = b2 + kB;
;             G_LDB(B0, 0, 0); G_SCHED; G_LDA(At, 0, 0); G_STAGE(G_SA(1, 1), a1 + chA, cA0, qA);
;             G_WAIT_L(8); G_BAR; G_WAIT_L(0); G_MMA(0, 0, At, B0); G_BAR; G_SCHED;
;             G_LDB(B1, 0, 1); G_STAGE(G_SB(0, 0), b2, cB0, qB);
;             G_BAR; G_WAIT_L(0); G_MMA(0, 1, At, B1); G_BAR;
;             G_LDA(At, 0, 1); G_STAGE(G_SA(0, 0), a2, cA0, qA);
;             G_BAR; G_WAIT_L(0); G_MMA(1, 0, At, B0); G_BAR; G_SCHED;
;             G_STAGE(G_SB(0, 1), b2 + chB, cB0, qB);
;             G_WAIT_V(6); G_BAR; G_MMA(1, 1, At, B1); G_BAR;
;             G_LDB(B0, 1, 0); G_SCHED; G_LDA(At, 1, 0); G_STAGE(G_SA(0, 1), a2 + chA, cA0, qA);
;             G_WAIT_L(8); G_BAR; G_WAIT_L(0); G_MMA(0, 0, At, B0); G_BAR; G_SCHED;
;             G_LDB(B1, 1, 1); G_STAGE(G_SB(1, 0), b3, cB0, qB);
;             G_BAR; G_WAIT_L(0); G_MMA(0, 1, At, B1); G_BAR;
;             G_LDA(At, 1, 1); G_STAGE(G_SA(1, 0), a3, cA0, qA);
;             G_BAR; G_WAIT_L(0); G_MMA(1, 0, At, B0); G_BAR; G_SCHED;
;             G_STAGE(G_SB(1, 1), b3 + chB, cB0, qB);
;             G_WAIT_V(6); G_BAR; G_MMA(1, 1, At, B1); G_BAR;
	s_add_i32 s4, 0, 0x14000
	s_add_i32 s5, s40, s17
	ds_read_b128 v[212:215], v239 offset:16384
	ds_read_b128 v[216:219], v239 offset:17408
	ds_read_b128 v[220:223], v239 offset:18432
	ds_read_b128 v[224:227], v239 offset:19456
	s_mov_b32 m0, s5
	global_load_lds_dwordx4 v0, s[14:15]
	s_add_i32 m0, s5, 0x2000
	s_add_u32 vcc_lo, s14, s50
	s_addc_u32 vcc_hi, s15, s51
	global_load_lds_dwordx4 v0, vcc
	s_barrier
	s_waitcnt lgkmcnt(0)
	v_mfma_f32_16x16x128_f8f6f4 v[124:127], v[212:219], v[160:167], v[124:127]
	v_mfma_f32_16x16x128_f8f6f4 v[120:123], v[220:227], v[160:167], v[120:123]
	v_mfma_f32_16x16x128_f8f6f4 v[108:111], v[212:219], v[176:183], v[108:111]
	v_mfma_f32_16x16x128_f8f6f4 v[104:107], v[220:227], v[176:183], v[104:107]
	v_mfma_f32_16x16x128_f8f6f4 v[92:95], v[212:219], v[196:203], v[92:95]
	v_mfma_f32_16x16x128_f8f6f4 v[88:91], v[220:227], v[196:203], v[88:91]
	v_mfma_f32_16x16x128_f8f6f4 v[76:79], v[212:219], v[204:211], v[76:79]
	v_mfma_f32_16x16x128_f8f6f4 v[72:75], v[220:227], v[204:211], v[72:75]
	s_barrier
	s_mov_b32 m0, s22
	ds_read_b128 v[160:163], v236 offset:16384
	ds_read_b128 v[164:167], v236 offset:17408
	ds_read_b128 v[176:179], v236 offset:18432
	ds_read_b128 v[180:183], v236 offset:19456
	ds_read_b128 v[196:199], v236 offset:20480
	ds_read_b128 v[200:203], v236 offset:21504
	ds_read_b128 v[204:207], v236 offset:22528
	ds_read_b128 v[208:211], v236 offset:23552
	global_load_lds_dwordx4 v2, s[12:13]
	s_mov_b32 m0, s23
	s_add_u32 vcc_lo, s12, s86
	s_addc_u32 vcc_hi, s13, s87
	global_load_lds_dwordx4 v2, vcc
	s_barrier
	s_waitcnt lgkmcnt(0)
	v_mfma_f32_16x16x128_f8f6f4 v[64:67], v[144:151], v[160:167], v[64:67]
	v_mfma_f32_16x16x128_f8f6f4 v[68:71], v[136:143], v[160:167], v[68:71]
	v_mfma_f32_16x16x128_f8f6f4 v[48:51], v[144:151], v[176:183], v[48:51]
	v_mfma_f32_16x16x128_f8f6f4 v[52:55], v[136:143], v[176:183], v[52:55]
	v_mfma_f32_16x16x128_f8f6f4 v[32:35], v[144:151], v[196:203], v[32:35]
	v_mfma_f32_16x16x128_f8f6f4 v[36:39], v[136:143], v[196:203], v[36:39]
	v_mfma_f32_16x16x128_f8f6f4 v[20:23], v[144:151], v[204:211], v[20:23]
	v_mfma_f32_16x16x128_f8f6f4 v[16:19], v[136:143], v[204:211], v[16:19]
	s_barrier
	s_add_i32 s4, s4, s17
	s_mov_b32 m0, s4
	s_add_u32 vcc_lo, s14, s0
	s_addc_u32 vcc_hi, s15, s1
	global_load_lds_dwordx4 v0, vcc
	s_add_i32 m0, s4, 0x2000
	s_add_u32 vcc_lo, s14, s52
	s_addc_u32 vcc_hi, s15, s53
	global_load_lds_dwordx4 v0, vcc
	s_waitcnt vmcnt(6)
	s_barrier
	v_mfma_f32_16x16x128_f8f6f4 v[60:63], v[212:219], v[160:167], v[60:63]
	v_mfma_f32_16x16x128_f8f6f4 v[56:59], v[220:227], v[160:167], v[56:59]
	v_mfma_f32_16x16x128_f8f6f4 v[44:47], v[212:219], v[176:183], v[44:47]
	v_mfma_f32_16x16x128_f8f6f4 v[40:43], v[220:227], v[176:183], v[40:43]
	v_mfma_f32_16x16x128_f8f6f4 v[28:31], v[212:219], v[196:203], v[28:31]
	v_mfma_f32_16x16x128_f8f6f4 v[24:27], v[220:227], v[196:203], v[24:27]
	v_mfma_f32_16x16x128_f8f6f4 v[12:15], v[212:219], v[204:211], v[12:15]
	v_mfma_f32_16x16x128_f8f6f4 v[8:11], v[220:227], v[204:211], v[8:11]
	s_barrier
	s_add_i32 s4, 0, 0x18000
	ds_read_b128 v[144:147], v239 offset:32768
	ds_read_b128 v[148:151], v239 offset:33792
	ds_read_b128 v[136:139], v239 offset:34816
	ds_read_b128 v[140:143], v239 offset:35840
	s_mov_b32 m0, s24
	ds_read_b128 v[160:163], v236 offset:32768
	ds_read_b128 v[164:167], v236 offset:33792
	ds_read_b128 v[176:179], v236 offset:34816
	ds_read_b128 v[180:183], v236 offset:35840
	ds_read_b128 v[196:199], v236 offset:36864
	ds_read_b128 v[200:203], v236 offset:37888
	ds_read_b128 v[204:207], v236 offset:38912
	ds_read_b128 v[208:211], v236 offset:39936
	s_add_u32 vcc_lo, s12, s88
	s_addc_u32 vcc_hi, s13, s89
	global_load_lds_dwordx4 v2, vcc
	s_mov_b32 m0, s25
	s_add_u32 vcc_lo, s12, s64
	s_addc_u32 vcc_hi, s13, s65
	global_load_lds_dwordx4 v2, vcc
	s_waitcnt lgkmcnt(8)
	s_barrier
; #define G_STAGE(bufoff, gbase, o0, h64) do { \
;         __builtin_amdgcn_global_load_lds((const unsigned*)((const char*)(gbase) + (o0)), (LAS unsigned*)(lds + (bufoff) + ldsw), 16, 0, 0); \
;         __builtin_amdgcn_global_load_lds((const unsigned*)((const char*)(gbase) + (h64) + (o0)), (LAS unsigned*)(lds + (bufoff) + ldsw + 8192), 16, 0, 0); } while (0)
; #define G_LDA(dst, b, h) do { _Pragma("unroll") for (int m = 0; m < 4; ++m) _Pragma("unroll") for (int k = 0; k < 2; ++k) dst[m][k] = *(const LAS bf16x8*)(lds + G_SA(b, h) + aoff + m * 2048 + k * 1024); } while (0)
; #define G_LDB(dst, b, h) do { _Pragma("unroll") for (int n = 0; n < 2; ++n) _Pragma("unroll") for (int k = 0; k < 2; ++k) dst[n][k] = *(const LAS bf16x8*)(lds + G_SB(b, h) + boff + n * 2048 + k * 1024); } while (0)
; #define G_WAIT_V(n) asm volatile("s_waitcnt vmcnt(" #n ")" ::: "memory")
; #define G_BAR __builtin_amdgcn_s_barrier()
;     ...
;         for (int t = 0; t < nt; t += 2) {
;             const bool last = (t == nt - 2);
;             const char* a1 = cA + (size_t)(t + 1) * ckA;
;             const char* a2 = last ? nA : cA + (size_t)(t + 2) * ckA; const char* b2 = last ? nB : cB + (size_t)(t + 2) * kB;
;             const char* a3 = a2 + ckA; const char* b3 = b2 + kB;
;             G_LDB(B0, 0, 0); G_SCHED; G_LDA(At, 0, 0); G_STAGE(G_SA(1, 1), a1 + chA, cA0, qA);
;             G_WAIT_L(8); G_BAR; G_WAIT_L(0); G_MMA(0, 0, At, B0); G_BAR; G_SCHED;
;             G_LDB(B1, 0, 1); G_STAGE(G_SB(0, 0), b2, cB0, qB);
;             G_BAR; G_WAIT_L(0); G_MMA(0, 1, At, B1); G_BAR;
;             G_LDA(At, 0, 1); G_STAGE(G_SA(0, 0), a2, cA0, qA);
;             G_BAR; G_WAIT_L(0); G_MMA(1, 0, At, B0); G_BAR; G_SCHED;
;             G_STAGE(G_SB(0, 1), b2 + chB, cB0, qB);
;             G_WAIT_V(6); G_BAR; G_MMA(1, 1, At, B1); G_BAR;
;             G_LDB(B0, 1, 0); G_SCHED; G_LDA(At, 1, 0); G_STAGE(G_SA(0, 1), a2 + chA, cA0, qA);
;             G_WAIT_L(8); G_BAR; G_WAIT_L(0); G_MMA(0, 0, At, B0); G_BAR; G_SCHED;
;             G_LDB(B1, 1, 1); G_STAGE(G_SB(1, 0), b3, cB0, qB);
;             G_BAR; G_WAIT_L(0); G_MMA(0, 1, At, B1); G_BAR;
;             G_LDA(At, 1, 1); G_STAGE(G_SA(1, 0), a3, cA0, qA);
;             G_BAR; G_WAIT_L(0); G_MMA(1, 0, At, B0); G_BAR; G_SCHED;
;             G_STAGE(G_SB(1, 1), b3 + chB, cB0, qB);
;             G_WAIT_V(6); G_BAR; G_MMA(1, 1, At, B1); G_BAR;
;         }
	s_waitcnt lgkmcnt(0)
	v_mfma_f32_16x16x128_f8f6f4 v[128:131], v[144:151], v[160:167], v[128:131]
	v_mfma_f32_16x16x128_f8f6f4 v[132:135], v[136:143], v[160:167], v[132:135]
	v_mfma_f32_16x16x128_f8f6f4 v[112:115], v[144:151], v[176:183], v[112:115]
	v_mfma_f32_16x16x128_f8f6f4 v[116:119], v[136:143], v[176:183], v[116:119]
	v_mfma_f32_16x16x128_f8f6f4 v[96:99], v[144:151], v[196:203], v[96:99]
	v_mfma_f32_16x16x128_f8f6f4 v[100:103], v[136:143], v[196:203], v[100:103]
	v_mfma_f32_16x16x128_f8f6f4 v[80:83], v[144:151], v[204:211], v[80:83]
	v_mfma_f32_16x16x128_f8f6f4 v[84:87], v[136:143], v[204:211], v[84:87]
	s_barrier
	s_add_i32 s5, 0, 0x1c000
	s_add_i32 s4, s4, s17
	s_mov_b32 m0, s4
	ds_read_b128 v[212:215], v239 offset:49152
	ds_read_b128 v[216:219], v239 offset:50176
	ds_read_b128 v[220:223], v239 offset:51200
	ds_read_b128 v[224:227], v239 offset:52224
	s_add_u32 vcc_lo, s14, s46
	s_addc_u32 vcc_hi, s15, s47
	global_load_lds_dwordx4 v0, vcc
	s_add_i32 m0, s4, 0x2000
	s_add_u32 vcc_lo, s14, s54
	s_addc_u32 vcc_hi, s15, s55
	global_load_lds_dwordx4 v0, vcc
	s_barrier
	s_waitcnt lgkmcnt(0)
	v_mfma_f32_16x16x128_f8f6f4 v[124:127], v[212:219], v[160:167], v[124:127]
	v_mfma_f32_16x16x128_f8f6f4 v[120:123], v[220:227], v[160:167], v[120:123]
	v_mfma_f32_16x16x128_f8f6f4 v[108:111], v[212:219], v[176:183], v[108:111]
	v_mfma_f32_16x16x128_f8f6f4 v[104:107], v[220:227], v[176:183], v[104:107]
	v_mfma_f32_16x16x128_f8f6f4 v[92:95], v[212:219], v[196:203], v[92:95]
	v_mfma_f32_16x16x128_f8f6f4 v[88:91], v[220:227], v[196:203], v[88:91]
	v_mfma_f32_16x16x128_f8f6f4 v[76:79], v[212:219], v[204:211], v[76:79]
	v_mfma_f32_16x16x128_f8f6f4 v[72:75], v[220:227], v[204:211], v[72:75]
	s_barrier
	s_mov_b32 m0, s26
	ds_read_b128 v[160:163], v236 offset:49152
	ds_read_b128 v[164:167], v236 offset:50176
	ds_read_b128 v[176:179], v236 offset:51200
	ds_read_b128 v[180:183], v236 offset:52224
	ds_read_b128 v[196:199], v236 offset:53248
	ds_read_b128 v[200:203], v236 offset:54272
	ds_read_b128 v[204:207], v236 offset:55296
	ds_read_b128 v[208:211], v236 offset:56320
	s_add_u32 vcc_lo, s12, s46
	s_addc_u32 vcc_hi, s13, s47
	global_load_lds_dwordx4 v2, vcc
	s_mov_b32 m0, s27
	s_add_u32 vcc_lo, s12, s66
	s_addc_u32 vcc_hi, s13, s67
	global_load_lds_dwordx4 v2, vcc
	s_barrier
	s_waitcnt lgkmcnt(0)
	v_mfma_f32_16x16x128_f8f6f4 v[64:67], v[144:151], v[160:167], v[64:67]
	v_mfma_f32_16x16x128_f8f6f4 v[68:71], v[136:143], v[160:167], v[68:71]
	v_mfma_f32_16x16x128_f8f6f4 v[48:51], v[144:151], v[176:183], v[48:51]
	v_mfma_f32_16x16x128_f8f6f4 v[52:55], v[136:143], v[176:183], v[52:55]
	v_mfma_f32_16x16x128_f8f6f4 v[32:35], v[144:151], v[196:203], v[32:35]
	v_mfma_f32_16x16x128_f8f6f4 v[36:39], v[136:143], v[196:203], v[36:39]
	v_mfma_f32_16x16x128_f8f6f4 v[20:23], v[144:151], v[204:211], v[20:23]
	v_mfma_f32_16x16x128_f8f6f4 v[16:19], v[136:143], v[204:211], v[16:19]
	s_barrier
	s_add_i32 s4, s5, s17
	s_mov_b32 m0, s4
	s_add_u32 vcc_lo, s14, s42
	s_addc_u32 vcc_hi, s15, s43
	global_load_lds_dwordx4 v0, vcc
	s_add_i32 m0, s4, 0x2000
	s_add_u32 vcc_lo, s14, s58
	s_addc_u32 vcc_hi, s15, s59
	global_load_lds_dwordx4 v0, vcc
	s_add_i32 s39, s39, 2
	s_add_u32 s2, s2, 0x100
	s_addc_u32 s3, s3, 0
	s_add_u32 s37, s37, 0x100
	s_addc_u32 s38, s38, 0
	s_cmp_gt_u32 s39, 5
	s_waitcnt vmcnt(6)
	s_barrier
	v_mfma_f32_16x16x128_f8f6f4 v[60:63], v[212:219], v[160:167], v[60:63]
	v_mfma_f32_16x16x128_f8f6f4 v[56:59], v[220:227], v[160:167], v[56:59]
	v_mfma_f32_16x16x128_f8f6f4 v[44:47], v[212:219], v[176:183], v[44:47]
	v_mfma_f32_16x16x128_f8f6f4 v[40:43], v[220:227], v[176:183], v[40:43]
	v_mfma_f32_16x16x128_f8f6f4 v[28:31], v[212:219], v[196:203], v[28:31]
	v_mfma_f32_16x16x128_f8f6f4 v[24:27], v[220:227], v[196:203], v[24:27]
	v_mfma_f32_16x16x128_f8f6f4 v[12:15], v[212:219], v[204:211], v[12:15]
	v_mfma_f32_16x16x128_f8f6f4 v[8:11], v[220:227], v[204:211], v[8:11]
	s_cbranch_scc0 .Ldb_MG0_cont

; #define G_STAGE(bufoff, gbase, o0, h64) do { \
;         __builtin_amdgcn_global_load_lds((const unsigned*)((const char*)(gbase) + (o0)), (LAS unsigned*)(lds + (bufoff) + ldsw), 16, 0, 0); \
;         __builtin_amdgcn_global_load_lds((const unsigned*)((const char*)(gbase) + (h64) + (o0)), (LAS unsigned*)(lds + (bufoff) + ldsw + 8192), 16, 0, 0); } while (0)
; #define G_LDA(dst, b, h) do { _Pragma("unroll") for (int m = 0; m < 4; ++m) _Pragma("unroll") for (int k = 0; k < 2; ++k) dst[m][k] = *(const LAS bf16x8*)(lds + G_SA(b, h) + aoff + m * 2048 + k * 1024); } while (0)
; #define G_LDB(dst, b, h) do { _Pragma("unroll") for (int n = 0; n < 2; ++n) _Pragma("unroll") for (int k = 0; k < 2; ++k) dst[n][k] = *(const LAS bf16x8*)(lds + G_SB(b, h) + boff + n * 2048 + k * 1024); } while (0)
; #define G_WAIT_V(n) asm volatile("s_waitcnt vmcnt(" #n ")" ::: "memory")
; #define G_BAR __builtin_amdgcn_s_barrier()
;     ...
;         for (int t = 0; t < nt; t += 2) {
;             const bool last = (t == nt - 2);
;             const char* a1 = cA + (size_t)(t + 1) * ckA;
;             const char* a2 = last ? nA : cA + (size_t)(t + 2) * ckA; const char* b2 = last ? nB : cB + (size_t)(t + 2) * kB;
;             const char* a3 = a2 + ckA; const char* b3 = b2 + kB;
;             G_LDB(B0, 0, 0); G_SCHED; G_LDA(At, 0, 0); G_STAGE(G_SA(1, 1), a1 + chA, cA0, qA);
;             G_WAIT_L(8); G_BAR; G_WAIT_L(0); G_MMA(0, 0, At, B0); G_BAR; G_SCHED;
;             G_LDB(B1, 0, 1); G_STAGE(G_SB(0, 0), b2, cB0, qB);
;             G_BAR; G_WAIT_L(0); G_MMA(0, 1, At, B1); G_BAR;
;             G_LDA(At, 0, 1); G_STAGE(G_SA(0, 0), a2, cA0, qA);
;             G_BAR; G_WAIT_L(0); G_MMA(1, 0, At, B0); G_BAR; G_SCHED;
;             G_STAGE(G_SB(0, 1), b2 + chB, cB0, qB);
;             G_WAIT_V(6); G_BAR; G_MMA(1, 1, At, B1); G_BAR;
;             G_LDB(B0, 1, 0); G_SCHED; G_LDA(At, 1, 0); G_STAGE(G_SA(0, 1), a2 + chA, cA0, qA);
;             G_WAIT_L(8); G_BAR; G_WAIT_L(0); G_MMA(0, 0, At, B0); G_BAR; G_SCHED;
;             G_LDB(B1, 1, 1); G_STAGE(G_SB(1, 0), b3, cB0, qB);
;             G_BAR; G_WAIT_L(0); G_MMA(0, 1, At, B1); G_BAR;
;             G_LDA(At, 1, 1); G_STAGE(G_SA(1, 0), a3, cA0, qA);
;             G_BAR; G_WAIT_L(0); G_MMA(1, 0, At, B0); G_BAR; G_SCHED;
;             G_STAGE(G_SB(1, 1), b3 + chB, cB0, qB);
;             G_WAIT_V(6); G_BAR; G_MMA(1, 1, At, B1); G_BAR;
.LBB0_890:
	s_add_u32 s4, s6, 0xfff50080
	s_addc_u32 s5, s7, -1
	s_add_i32 s19, 0, 0x10000
	ds_read_b128 v[136:139], v239 offset:0
	ds_read_b128 v[140:143], v239 offset:1024
	ds_read_b128 v[144:147], v239 offset:2048
	ds_read_b128 v[148:151], v239 offset:3072
	s_cmp_eq_u32 s18, 4
	s_cselect_b32 s45, s15, s9
	s_cselect_b32 s44, s14, s8
	s_cselect_b32 s5, s13, s5
	s_cselect_b32 s4, s12, s4
	s_add_i32 m0, s22, 0xc000
	ds_read_b128 v[158:161], v176
	ds_read_b128 v[162:165], v176 offset:1024
	ds_read_b128 v[178:181], v176 offset:2048
	ds_read_b128 v[182:185], v176 offset:3072
	ds_read_b128 v[196:199], v176 offset:4096
	ds_read_b128 v[200:203], v176 offset:5120
	ds_read_b128 v[204:207], v176 offset:6144
	ds_read_b128 v[208:211], v176 offset:7168
	global_load_lds_dwordx4 v156, s[6:7]
	s_add_i32 m0, s22, 0xe000
	s_add_u32 vcc_lo, s6, s86
	s_addc_u32 vcc_hi, s7, s87
	global_load_lds_dwordx4 v156, vcc
	s_waitcnt lgkmcnt(8)
	s_cmp_eq_u32 s101, 1
	s_cbranch_scc1 .Ldb_MG1_sk
	s_barrier
.Ldb_MG1_sk:
	s_mov_b32 s101, 0
	s_waitcnt lgkmcnt(0)
	v_mfma_f32_16x16x32_bf16 v[104:107], v[136:139], v[158:161], v[104:107]
	v_mfma_f32_16x16x32_bf16 v[108:111], v[144:147], v[158:161], v[108:111]
	v_mfma_f32_16x16x32_bf16 v[132:135], v[136:139], v[178:181], v[132:135]
	v_mfma_f32_16x16x32_bf16 v[128:131], v[144:147], v[178:181], v[128:131]
	v_mfma_f32_16x16x32_bf16 v[124:127], v[136:139], v[196:199], v[124:127]
	v_mfma_f32_16x16x32_bf16 v[120:123], v[144:147], v[196:199], v[120:123]
	v_mfma_f32_16x16x32_bf16 v[116:119], v[136:139], v[204:207], v[116:119]
	v_mfma_f32_16x16x32_bf16 v[112:115], v[144:147], v[204:207], v[112:115]
	v_mfma_f32_16x16x32_bf16 v[104:107], v[140:143], v[162:165], v[104:107]
	v_mfma_f32_16x16x32_bf16 v[108:111], v[148:151], v[162:165], v[108:111]
	v_mfma_f32_16x16x32_bf16 v[132:135], v[140:143], v[182:185], v[132:135]
	v_mfma_f32_16x16x32_bf16 v[128:131], v[148:151], v[182:185], v[128:131]
	v_mfma_f32_16x16x32_bf16 v[124:127], v[140:143], v[200:203], v[124:127]
	v_mfma_f32_16x16x32_bf16 v[120:123], v[148:151], v[200:203], v[120:123]
	v_mfma_f32_16x16x32_bf16 v[116:119], v[140:143], v[208:211], v[116:119]
	v_mfma_f32_16x16x32_bf16 v[112:115], v[148:151], v[208:211], v[112:115]
	s_barrier
	s_add_i32 s43, 0, 0x14000
	s_add_i32 s19, s19, s21
	v_lshl_add_u64 v[2:3], s[44:45], 0, v[154:155]
	s_mov_b64 vcc, s[44:45]
	s_mov_b64 s[44:45], 0x10000
	s_mov_b32 m0, s19
	ds_read_b128 v[212:215], v239 offset:16384
	ds_read_b128 v[216:219], v239 offset:17408
	ds_read_b128 v[220:223], v239 offset:18432
	ds_read_b128 v[224:227], v239 offset:19456
	global_load_lds_dwordx4 v154, vcc
	v_lshl_add_u64 v[166:167], v[2:3], 0, s[44:45]
	s_add_i32 m0, s19, 0x2000
	s_nop 0
	global_load_lds_dwordx4 v[166:167], off
	s_barrier
	s_waitcnt lgkmcnt(0)
	v_mfma_f32_16x16x32_bf16 v[100:103], v[212:215], v[158:161], v[100:103]
	v_mfma_f32_16x16x32_bf16 v[96:99], v[220:223], v[158:161], v[96:99]
	v_mfma_f32_16x16x32_bf16 v[92:95], v[212:215], v[178:181], v[92:95]
	v_mfma_f32_16x16x32_bf16 v[88:91], v[220:223], v[178:181], v[88:91]
	v_mfma_f32_16x16x32_bf16 v[84:87], v[212:215], v[196:199], v[84:87]
	v_mfma_f32_16x16x32_bf16 v[80:83], v[220:223], v[196:199], v[80:83]
	v_mfma_f32_16x16x32_bf16 v[76:79], v[212:215], v[204:207], v[76:79]
	v_mfma_f32_16x16x32_bf16 v[72:75], v[220:223], v[204:207], v[72:75]
	v_mfma_f32_16x16x32_bf16 v[100:103], v[216:219], v[162:165], v[100:103]
	v_mfma_f32_16x16x32_bf16 v[96:99], v[224:227], v[162:165], v[96:99]
	v_mfma_f32_16x16x32_bf16 v[92:95], v[216:219], v[182:185], v[92:95]
	v_mfma_f32_16x16x32_bf16 v[88:91], v[224:227], v[182:185], v[88:91]
	v_mfma_f32_16x16x32_bf16 v[84:87], v[216:219], v[200:203], v[84:87]
	v_mfma_f32_16x16x32_bf16 v[80:83], v[224:227], v[200:203], v[80:83]
	v_mfma_f32_16x16x32_bf16 v[76:79], v[216:219], v[208:211], v[76:79]
	v_mfma_f32_16x16x32_bf16 v[72:75], v[224:227], v[208:211], v[72:75]
	s_barrier
	s_mov_b32 m0, s22
	v_lshl_add_u64 v[166:167], s[4:5], 0, v[152:153]
	ds_read_b128 v[158:161], v176 offset:16384
	ds_read_b128 v[162:165], v176 offset:17408
	ds_read_b128 v[178:181], v176 offset:18432
	ds_read_b128 v[182:185], v176 offset:19456
	ds_read_b128 v[196:199], v176 offset:20480
	ds_read_b128 v[200:203], v176 offset:21504
	ds_read_b128 v[204:207], v176 offset:22528
	ds_read_b128 v[208:211], v176 offset:23552
	global_load_lds_dwordx4 v152, s[4:5]
	s_mov_b32 m0, s23
	s_add_u32 vcc_lo, s4, s86
	s_addc_u32 vcc_hi, s5, s87
	global_load_lds_dwordx4 v152, vcc
	s_barrier
	s_waitcnt lgkmcnt(0)
	v_mfma_f32_16x16x32_bf16 v[68:71], v[136:139], v[158:161], v[68:71]
	v_mfma_f32_16x16x32_bf16 v[64:67], v[144:147], v[158:161], v[64:67]
	v_mfma_f32_16x16x32_bf16 v[60:63], v[136:139], v[178:181], v[60:63]
	v_mfma_f32_16x16x32_bf16 v[56:59], v[144:147], v[178:181], v[56:59]
	v_mfma_f32_16x16x32_bf16 v[52:55], v[136:139], v[196:199], v[52:55]
	v_mfma_f32_16x16x32_bf16 v[48:51], v[144:147], v[196:199], v[48:51]
	v_mfma_f32_16x16x32_bf16 v[44:47], v[136:139], v[204:207], v[44:47]
	v_mfma_f32_16x16x32_bf16 v[40:43], v[144:147], v[204:207], v[40:43]
	v_mfma_f32_16x16x32_bf16 v[68:71], v[140:143], v[162:165], v[68:71]
	v_mfma_f32_16x16x32_bf16 v[64:67], v[148:151], v[162:165], v[64:67]
	v_mfma_f32_16x16x32_bf16 v[60:63], v[140:143], v[182:185], v[60:63]
	v_mfma_f32_16x16x32_bf16 v[56:59], v[148:151], v[182:185], v[56:59]
	v_mfma_f32_16x16x32_bf16 v[52:55], v[140:143], v[200:203], v[52:55]
	v_mfma_f32_16x16x32_bf16 v[48:51], v[148:151], v[200:203], v[48:51]
	v_mfma_f32_16x16x32_bf16 v[44:47], v[140:143], v[208:211], v[44:47]
	v_mfma_f32_16x16x32_bf16 v[40:43], v[148:151], v[208:211], v[40:43]
	s_barrier
; #define G_STAGE(bufoff, gbase, o0, h64) do { \
;         __builtin_amdgcn_global_load_lds((const unsigned*)((const char*)(gbase) + (o0)), (LAS unsigned*)(lds + (bufoff) + ldsw), 16, 0, 0); \
;         __builtin_amdgcn_global_load_lds((const unsigned*)((const char*)(gbase) + (h64) + (o0)), (LAS unsigned*)(lds + (bufoff) + ldsw + 8192), 16, 0, 0); } while (0)
; #define G_LDA(dst, b, h) do { _Pragma("unroll") for (int m = 0; m < 4; ++m) _Pragma("unroll") for (int k = 0; k < 2; ++k) dst[m][k] = *(const LAS bf16x8*)(lds + G_SA(b, h) + aoff + m * 2048 + k * 1024); } while (0)
; #define G_LDB(dst, b, h) do { _Pragma("unroll") for (int n = 0; n < 2; ++n) _Pragma("unroll") for (int k = 0; k < 2; ++k) dst[n][k] = *(const LAS bf16x8*)(lds + G_SB(b, h) + boff + n * 2048 + k * 1024); } while (0)
; #define G_WAIT_V(n) asm volatile("s_waitcnt vmcnt(" #n ")" ::: "memory")
; #define G_BAR __builtin_amdgcn_s_barrier()
;     ...
;         for (int t = 0; t < nt; t += 2) {
;             const bool last = (t == nt - 2);
;             const char* a1 = cA + (size_t)(t + 1) * ckA;
;             const char* a2 = last ? nA : cA + (size_t)(t + 2) * ckA; const char* b2 = last ? nB : cB + (size_t)(t + 2) * kB;
;             const char* a3 = a2 + ckA; const char* b3 = b2 + kB;
;             G_LDB(B0, 0, 0); G_SCHED; G_LDA(At, 0, 0); G_STAGE(G_SA(1, 1), a1 + chA, cA0, qA);
;             G_WAIT_L(8); G_BAR; G_WAIT_L(0); G_MMA(0, 0, At, B0); G_BAR; G_SCHED;
;             G_LDB(B1, 0, 1); G_STAGE(G_SB(0, 0), b2, cB0, qB);
;             G_BAR; G_WAIT_L(0); G_MMA(0, 1, At, B1); G_BAR;
;             G_LDA(At, 0, 1); G_STAGE(G_SA(0, 0), a2, cA0, qA);
;             G_BAR; G_WAIT_L(0); G_MMA(1, 0, At, B0); G_BAR; G_SCHED;
;             G_STAGE(G_SB(0, 1), b2 + chB, cB0, qB);
;             G_WAIT_V(6); G_BAR; G_MMA(1, 1, At, B1); G_BAR;
;             G_LDB(B0, 1, 0); G_SCHED; G_LDA(At, 1, 0); G_STAGE(G_SA(0, 1), a2 + chA, cA0, qA);
;             G_WAIT_L(8); G_BAR; G_WAIT_L(0); G_MMA(0, 0, At, B0); G_BAR; G_SCHED;
;             G_LDB(B1, 1, 1); G_STAGE(G_SB(1, 0), b3, cB0, qB);
;             G_BAR; G_WAIT_L(0); G_MMA(0, 1, At, B1); G_BAR;
;             G_LDA(At, 1, 1); G_STAGE(G_SA(1, 0), a3, cA0, qA);
;             G_BAR; G_WAIT_L(0); G_MMA(1, 0, At, B0); G_BAR; G_SCHED;
;             G_STAGE(G_SB(1, 1), b3 + chB, cB0, qB);
;             G_WAIT_V(6); G_BAR; G_MMA(1, 1, At, B1); G_BAR;
	s_add_i32 s4, s43, s21
	v_lshl_add_u64 v[136:137], v[2:3], 0, s[0:1]
	s_mov_b32 m0, s4
	s_nop 0
	global_load_lds_dwordx4 v[136:137], off
	v_lshl_add_u64 v[136:137], v[2:3], 0, s[52:53]
	s_add_i32 m0, s4, 0x2000
	s_nop 0
	global_load_lds_dwordx4 v[136:137], off
	s_waitcnt vmcnt(6)
	s_barrier
	v_mfma_f32_16x16x32_bf16 v[36:39], v[212:215], v[158:161], v[36:39]
	v_mfma_f32_16x16x32_bf16 v[32:35], v[220:223], v[158:161], v[32:35]
	v_mfma_f32_16x16x32_bf16 v[28:31], v[212:215], v[178:181], v[28:31]
	v_mfma_f32_16x16x32_bf16 v[24:27], v[220:223], v[178:181], v[24:27]
	v_mfma_f32_16x16x32_bf16 v[20:23], v[212:215], v[196:199], v[20:23]
	v_mfma_f32_16x16x32_bf16 v[16:19], v[220:223], v[196:199], v[16:19]
	v_mfma_f32_16x16x32_bf16 v[12:15], v[212:215], v[204:207], v[12:15]
	v_mfma_f32_16x16x32_bf16 v[8:11], v[220:223], v[204:207], v[8:11]
	v_mfma_f32_16x16x32_bf16 v[36:39], v[216:219], v[162:165], v[36:39]
	v_mfma_f32_16x16x32_bf16 v[32:35], v[224:227], v[162:165], v[32:35]
	v_mfma_f32_16x16x32_bf16 v[28:31], v[216:219], v[182:185], v[28:31]
	v_mfma_f32_16x16x32_bf16 v[24:27], v[224:227], v[182:185], v[24:27]
	v_mfma_f32_16x16x32_bf16 v[20:23], v[216:219], v[200:203], v[20:23]
	v_mfma_f32_16x16x32_bf16 v[16:19], v[224:227], v[200:203], v[16:19]
	v_mfma_f32_16x16x32_bf16 v[12:15], v[216:219], v[208:211], v[12:15]
	v_mfma_f32_16x16x32_bf16 v[8:11], v[224:227], v[208:211], v[8:11]
	s_barrier
	s_add_i32 s4, 0, 0x18000
	ds_read_b128 v[136:139], v239 offset:32768
	ds_read_b128 v[140:143], v239 offset:33792
	ds_read_b128 v[144:147], v239 offset:34816
	ds_read_b128 v[148:151], v239 offset:35840
	s_mov_b32 m0, s24
	v_lshl_add_u64 v[172:173], v[166:167], 0, s[88:89]
	ds_read_b128 v[158:161], v176 offset:32768
	ds_read_b128 v[162:165], v176 offset:33792
	ds_read_b128 v[178:181], v176 offset:34816
	ds_read_b128 v[182:185], v176 offset:35840
	ds_read_b128 v[196:199], v176 offset:36864
	ds_read_b128 v[200:203], v176 offset:37888
	ds_read_b128 v[204:207], v176 offset:38912
	ds_read_b128 v[208:211], v176 offset:39936
	global_load_lds_dwordx4 v[172:173], off
	v_lshl_add_u64 v[172:173], v[166:167], 0, s[64:65]
	s_mov_b32 m0, s25
	s_nop 0
	global_load_lds_dwordx4 v[172:173], off
	s_waitcnt lgkmcnt(8)
	s_barrier
	s_waitcnt lgkmcnt(0)
	v_mfma_f32_16x16x32_bf16 v[104:107], v[136:139], v[158:161], v[104:107]
	v_mfma_f32_16x16x32_bf16 v[108:111], v[144:147], v[158:161], v[108:111]
	v_mfma_f32_16x16x32_bf16 v[132:135], v[136:139], v[178:181], v[132:135]
	v_mfma_f32_16x16x32_bf16 v[128:131], v[144:147], v[178:181], v[128:131]
	v_mfma_f32_16x16x32_bf16 v[124:127], v[136:139], v[196:199], v[124:127]
	v_mfma_f32_16x16x32_bf16 v[120:123], v[144:147], v[196:199], v[120:123]
	v_mfma_f32_16x16x32_bf16 v[116:119], v[136:139], v[204:207], v[116:119]
	v_mfma_f32_16x16x32_bf16 v[112:115], v[144:147], v[204:207], v[112:115]
	v_mfma_f32_16x16x32_bf16 v[104:107], v[140:143], v[162:165], v[104:107]
	v_mfma_f32_16x16x32_bf16 v[108:111], v[148:151], v[162:165], v[108:111]
	v_mfma_f32_16x16x32_bf16 v[132:135], v[140:143], v[182:185], v[132:135]
	v_mfma_f32_16x16x32_bf16 v[128:131], v[148:151], v[182:185], v[128:131]
	v_mfma_f32_16x16x32_bf16 v[124:127], v[140:143], v[200:203], v[124:127]
	v_mfma_f32_16x16x32_bf16 v[120:123], v[148:151], v[200:203], v[120:123]
	v_mfma_f32_16x16x32_bf16 v[116:119], v[140:143], v[208:211], v[116:119]
	v_mfma_f32_16x16x32_bf16 v[112:115], v[148:151], v[208:211], v[112:115]
	s_barrier
	s_add_i32 s5, 0, 0x1c000
	s_add_i32 s4, s4, s21
	v_lshl_add_u64 v[172:173], v[2:3], 0, s[46:47]
	s_mov_b32 m0, s4
	ds_read_b128 v[212:215], v239 offset:49152
	ds_read_b128 v[216:219], v239 offset:50176
	ds_read_b128 v[220:223], v239 offset:51200
	ds_read_b128 v[224:227], v239 offset:52224
	global_load_lds_dwordx4 v[172:173], off
	v_lshl_add_u64 v[172:173], v[2:3], 0, s[54:55]
	s_add_i32 m0, s4, 0x2000
	s_nop 0
	global_load_lds_dwordx4 v[172:173], off
	s_barrier
	s_waitcnt lgkmcnt(0)
	v_mfma_f32_16x16x32_bf16 v[100:103], v[212:215], v[158:161], v[100:103]
	v_mfma_f32_16x16x32_bf16 v[96:99], v[220:223], v[158:161], v[96:99]
	v_mfma_f32_16x16x32_bf16 v[92:95], v[212:215], v[178:181], v[92:95]
	v_mfma_f32_16x16x32_bf16 v[88:91], v[220:223], v[178:181], v[88:91]
	v_mfma_f32_16x16x32_bf16 v[84:87], v[212:215], v[196:199], v[84:87]
	v_mfma_f32_16x16x32_bf16 v[80:83], v[220:223], v[196:199], v[80:83]
	v_mfma_f32_16x16x32_bf16 v[76:79], v[212:215], v[204:207], v[76:79]
	v_mfma_f32_16x16x32_bf16 v[72:75], v[220:223], v[204:207], v[72:75]
	v_mfma_f32_16x16x32_bf16 v[100:103], v[216:219], v[162:165], v[100:103]
	v_mfma_f32_16x16x32_bf16 v[96:99], v[224:227], v[162:165], v[96:99]
	v_mfma_f32_16x16x32_bf16 v[92:95], v[216:219], v[182:185], v[92:95]
	v_mfma_f32_16x16x32_bf16 v[88:91], v[224:227], v[182:185], v[88:91]
	v_mfma_f32_16x16x32_bf16 v[84:87], v[216:219], v[200:203], v[84:87]
	v_mfma_f32_16x16x32_bf16 v[80:83], v[224:227], v[200:203], v[80:83]
	v_mfma_f32_16x16x32_bf16 v[76:79], v[216:219], v[208:211], v[76:79]
	v_mfma_f32_16x16x32_bf16 v[72:75], v[224:227], v[208:211], v[72:75]
	s_barrier
	s_mov_b32 m0, s26
	v_lshl_add_u64 v[172:173], v[166:167], 0, s[46:47]
	ds_read_b128 v[158:161], v176 offset:49152
	ds_read_b128 v[162:165], v176 offset:50176
	ds_read_b128 v[178:181], v176 offset:51200
	ds_read_b128 v[182:185], v176 offset:52224
	ds_read_b128 v[196:199], v176 offset:53248
	ds_read_b128 v[200:203], v176 offset:54272
	ds_read_b128 v[204:207], v176 offset:55296
	ds_read_b128 v[208:211], v176 offset:56320
	global_load_lds_dwordx4 v[172:173], off
	v_lshl_add_u64 v[166:167], v[166:167], 0, s[66:67]
	s_mov_b32 m0, s27
	s_nop 0
	global_load_lds_dwordx4 v[166:167], off
	s_barrier
	s_waitcnt lgkmcnt(0)
	v_mfma_f32_16x16x32_bf16 v[68:71], v[136:139], v[158:161], v[68:71]
	v_mfma_f32_16x16x32_bf16 v[64:67], v[144:147], v[158:161], v[64:67]
	v_mfma_f32_16x16x32_bf16 v[60:63], v[136:139], v[178:181], v[60:63]
	v_mfma_f32_16x16x32_bf16 v[56:59], v[144:147], v[178:181], v[56:59]
	v_mfma_f32_16x16x32_bf16 v[52:55], v[136:139], v[196:199], v[52:55]
	v_mfma_f32_16x16x32_bf16 v[48:51], v[144:147], v[196:199], v[48:51]
	v_mfma_f32_16x16x32_bf16 v[44:47], v[136:139], v[204:207], v[44:47]
	v_mfma_f32_16x16x32_bf16 v[40:43], v[144:147], v[204:207], v[40:43]
	v_mfma_f32_16x16x32_bf16 v[68:71], v[140:143], v[162:165], v[68:71]
	v_mfma_f32_16x16x32_bf16 v[64:67], v[148:151], v[162:165], v[64:67]
	v_mfma_f32_16x16x32_bf16 v[60:63], v[140:143], v[182:185], v[60:63]
	v_mfma_f32_16x16x32_bf16 v[56:59], v[148:151], v[182:185], v[56:59]
	v_mfma_f32_16x16x32_bf16 v[52:55], v[140:143], v[200:203], v[52:55]
	v_mfma_f32_16x16x32_bf16 v[48:51], v[148:151], v[200:203], v[48:51]
	v_mfma_f32_16x16x32_bf16 v[44:47], v[140:143], v[208:211], v[44:47]
	v_mfma_f32_16x16x32_bf16 v[40:43], v[148:151], v[208:211], v[40:43]
	s_barrier
	s_add_i32 s4, s5, s21
	v_lshl_add_u64 v[136:137], v[2:3], 0, s[50:51]
	s_mov_b32 m0, s4
	v_lshl_add_u64 v[2:3], v[2:3], 0, s[58:59]
	global_load_lds_dwordx4 v[136:137], off
	s_add_i32 m0, s4, 0x2000
	s_nop 0
	global_load_lds_dwordx4 v[2:3], off
	s_add_i32 s18, s18, 2
	s_add_u32 s6, s6, 0x100
	s_addc_u32 s7, s7, 0
	s_add_u32 s8, s8, 0x100
	s_addc_u32 s9, s9, 0
	s_cmp_gt_u32 s18, 5
	s_waitcnt vmcnt(6)
	s_barrier
	v_mfma_f32_16x16x32_bf16 v[36:39], v[212:215], v[158:161], v[36:39]
	v_mfma_f32_16x16x32_bf16 v[32:35], v[220:223], v[158:161], v[32:35]
	v_mfma_f32_16x16x32_bf16 v[28:31], v[212:215], v[178:181], v[28:31]
	v_mfma_f32_16x16x32_bf16 v[24:27], v[220:223], v[178:181], v[24:27]
	v_mfma_f32_16x16x32_bf16 v[20:23], v[212:215], v[196:199], v[20:23]
	v_mfma_f32_16x16x32_bf16 v[16:19], v[220:223], v[196:199], v[16:19]
	v_mfma_f32_16x16x32_bf16 v[12:15], v[212:215], v[204:207], v[12:15]
	v_mfma_f32_16x16x32_bf16 v[8:11], v[220:223], v[204:207], v[8:11]
	v_mfma_f32_16x16x32_bf16 v[36:39], v[216:219], v[162:165], v[36:39]
	v_mfma_f32_16x16x32_bf16 v[32:35], v[224:227], v[162:165], v[32:35]
	v_mfma_f32_16x16x32_bf16 v[28:31], v[216:219], v[182:185], v[28:31]
	v_mfma_f32_16x16x32_bf16 v[24:27], v[224:227], v[182:185], v[24:27]
	v_mfma_f32_16x16x32_bf16 v[20:23], v[216:219], v[200:203], v[20:23]
	v_mfma_f32_16x16x32_bf16 v[16:19], v[224:227], v[200:203], v[16:19]
	v_mfma_f32_16x16x32_bf16 v[12:15], v[216:219], v[208:211], v[12:15]
	v_mfma_f32_16x16x32_bf16 v[8:11], v[224:227], v[208:211], v[8:11]
	s_cbranch_scc0 .Ldb_MG1_cont
	v_readfirstlane_b32 s101, v186
	s_cmpk_gt_u32 s101, 0xff
	s_cbranch_scc1 .Ldb_MG1_young
	s_barrier
	s_mov_b32 s101, 1
	s_branch .Ldb_MG1_exit

.LBB0_1036:
	s_add_u32 s2, s2, 0x40080
	s_addc_u32 s3, s3, 0
	s_add_u32 s6, s6, 0x100
	s_waitcnt lgkmcnt(0)
	s_addc_u32 s7, s7, 0
	s_mov_b32 s15, -2
	s_mov_b64 s[42:43], 0x40000
	s_mov_b64 s[50:51], 0x60000
	s_mov_b64 s[52:53], 0x20080
	s_mov_b64 s[54:55], 0x40080
	s_mov_b64 s[58:59], 0x60080
	s_cmp_eq_u32 s101, 2
	s_cselect_b32 s101, 0, s101
	s_setprio 0
	v_add_u32_e32 v255, 0x10000, v181
	s_add_u32 s4, s2, 0xfffc0080
	s_addc_u32 s5, s3, -1
	s_add_i32 s33, 0, 0x10000
	ds_read_b128 v[136:139], v255 offset:0
	ds_read_b128 v[140:143], v255 offset:1024
	ds_read_b128 v[144:147], v255 offset:2048
	ds_read_b128 v[148:151], v255 offset:3072
	s_cmp_eq_u32 s15, 12
	s_cselect_b32 s5, s17, s5
	s_cselect_b32 s4, s16, s4
	s_cselect_b32 s21, s19, s7
	s_cselect_b32 s20, s18, s6
	s_add_i32 m0, s24, 0xc000
	ds_read_b128 v[152:155], v182
	ds_read_b128 v[156:159], v182 offset:1024
	ds_read_b128 v[160:163], v182 offset:2048
	ds_read_b128 v[172:175], v182 offset:3072
	ds_read_b128 v[176:179], v182 offset:4096
	ds_read_b128 v[196:199], v182 offset:5120
	ds_read_b128 v[200:203], v182 offset:6144
	ds_read_b128 v[204:207], v182 offset:7168
	global_load_lds_dwordx4 v166, s[2:3]
	s_add_i32 m0, s24, 0xe000
	s_add_u32 vcc_lo, s2, s0
	s_addc_u32 vcc_hi, s3, s1
	global_load_lds_dwordx4 v166, vcc
	s_waitcnt lgkmcnt(8)
	s_cmp_eq_u32 s101, 1
	s_cbranch_scc1 .Ldb_WOUT_skp
	s_barrier
.Ldb_WOUT_skp:
	s_mov_b32 s101, 0
	s_waitcnt lgkmcnt(0)
	v_mfma_f32_16x16x32_bf16 v[132:135], v[136:139], v[152:155], 0
	v_mfma_f32_16x16x32_bf16 v[128:131], v[144:147], v[152:155], 0
	v_mfma_f32_16x16x32_bf16 v[116:119], v[136:139], v[160:163], 0
	v_mfma_f32_16x16x32_bf16 v[112:115], v[144:147], v[160:163], 0
	v_mfma_f32_16x16x32_bf16 v[100:103], v[136:139], v[176:179], 0
	v_mfma_f32_16x16x32_bf16 v[96:99], v[144:147], v[176:179], 0
	v_mfma_f32_16x16x32_bf16 v[84:87], v[136:139], v[200:203], 0
	v_mfma_f32_16x16x32_bf16 v[80:83], v[144:147], v[200:203], 0
	v_mfma_f32_16x16x32_bf16 v[132:135], v[140:143], v[156:159], v[132:135]
	v_mfma_f32_16x16x32_bf16 v[128:131], v[148:151], v[156:159], v[128:131]
	v_mfma_f32_16x16x32_bf16 v[116:119], v[140:143], v[172:175], v[116:119]
	v_mfma_f32_16x16x32_bf16 v[112:115], v[148:151], v[172:175], v[112:115]
	v_mfma_f32_16x16x32_bf16 v[100:103], v[140:143], v[196:199], v[100:103]
	v_mfma_f32_16x16x32_bf16 v[96:99], v[148:151], v[196:199], v[96:99]
	v_mfma_f32_16x16x32_bf16 v[84:87], v[140:143], v[204:207], v[84:87]
	v_mfma_f32_16x16x32_bf16 v[80:83], v[148:151], v[204:207], v[80:83]
	s_barrier
	s_add_i32 s41, 0, 0x14000
	s_add_i32 s100, s33, s23
	s_mov_b32 m0, s100
	ds_read_b128 v[208:211], v255 offset:16384
	ds_read_b128 v[212:215], v255 offset:17408
	ds_read_b128 v[216:219], v255 offset:18432
	ds_read_b128 v[220:223], v255 offset:19456
	global_load_lds_dwordx4 v164, s[20:21]
	s_add_i32 m0, s100, 0x2000
	s_add_u32 vcc_lo, s20, s0
	s_addc_u32 vcc_hi, s21, s1
	global_load_lds_dwordx4 v164, vcc
	s_barrier
	s_waitcnt lgkmcnt(0)
	v_mfma_f32_16x16x32_bf16 v[124:127], v[208:211], v[152:155], 0
	v_mfma_f32_16x16x32_bf16 v[120:123], v[216:219], v[152:155], 0
	v_mfma_f32_16x16x32_bf16 v[108:111], v[208:211], v[160:163], 0
	v_mfma_f32_16x16x32_bf16 v[104:107], v[216:219], v[160:163], 0
	v_mfma_f32_16x16x32_bf16 v[92:95], v[208:211], v[176:179], 0
	v_mfma_f32_16x16x32_bf16 v[88:91], v[216:219], v[176:179], 0
	v_mfma_f32_16x16x32_bf16 v[76:79], v[208:211], v[200:203], 0
	v_mfma_f32_16x16x32_bf16 v[72:75], v[216:219], v[200:203], 0
	v_mfma_f32_16x16x32_bf16 v[124:127], v[212:215], v[156:159], v[124:127]
	v_mfma_f32_16x16x32_bf16 v[120:123], v[220:223], v[156:159], v[120:123]
	v_mfma_f32_16x16x32_bf16 v[108:111], v[212:215], v[172:175], v[108:111]
	v_mfma_f32_16x16x32_bf16 v[104:107], v[220:223], v[172:175], v[104:107]
	v_mfma_f32_16x16x32_bf16 v[92:95], v[212:215], v[196:199], v[92:95]
	v_mfma_f32_16x16x32_bf16 v[88:91], v[220:223], v[196:199], v[88:91]
	v_mfma_f32_16x16x32_bf16 v[76:79], v[212:215], v[204:207], v[76:79]
	v_mfma_f32_16x16x32_bf16 v[72:75], v[220:223], v[204:207], v[72:75]
	s_barrier
	s_mov_b32 m0, s24
	v_lshl_add_u64 v[224:225], s[4:5], 0, v[2:3]
	ds_read_b128 v[152:155], v182 offset:16384
	ds_read_b128 v[156:159], v182 offset:17408
	ds_read_b128 v[160:163], v182 offset:18432
	ds_read_b128 v[172:175], v182 offset:19456
	ds_read_b128 v[176:179], v182 offset:20480
	ds_read_b128 v[196:199], v182 offset:21504
	ds_read_b128 v[200:203], v182 offset:22528
	ds_read_b128 v[204:207], v182 offset:23552
	global_load_lds_dwordx4 v2, s[4:5]
	s_mov_b32 m0, s25
	s_add_u32 vcc_lo, s4, s0
	s_addc_u32 vcc_hi, s5, s1
	global_load_lds_dwordx4 v2, vcc
	s_barrier
	s_waitcnt lgkmcnt(0)
	v_mfma_f32_16x16x32_bf16 v[68:71], v[136:139], v[152:155], 0
	v_mfma_f32_16x16x32_bf16 v[64:67], v[144:147], v[152:155], 0
	v_mfma_f32_16x16x32_bf16 v[52:55], v[136:139], v[160:163], 0
	v_mfma_f32_16x16x32_bf16 v[48:51], v[144:147], v[160:163], 0
	v_mfma_f32_16x16x32_bf16 v[36:39], v[136:139], v[176:179], 0
	v_mfma_f32_16x16x32_bf16 v[32:35], v[144:147], v[176:179], 0
	v_mfma_f32_16x16x32_bf16 v[20:23], v[136:139], v[200:203], 0
	v_mfma_f32_16x16x32_bf16 v[16:19], v[144:147], v[200:203], 0
	v_mfma_f32_16x16x32_bf16 v[68:71], v[140:143], v[156:159], v[68:71]
	v_mfma_f32_16x16x32_bf16 v[64:67], v[148:151], v[156:159], v[64:67]
	v_mfma_f32_16x16x32_bf16 v[52:55], v[140:143], v[172:175], v[52:55]
	v_mfma_f32_16x16x32_bf16 v[48:51], v[148:151], v[172:175], v[48:51]
	v_mfma_f32_16x16x32_bf16 v[36:39], v[140:143], v[196:199], v[36:39]
	v_mfma_f32_16x16x32_bf16 v[32:35], v[148:151], v[196:199], v[32:35]
	v_mfma_f32_16x16x32_bf16 v[20:23], v[140:143], v[204:207], v[20:23]
	v_mfma_f32_16x16x32_bf16 v[16:19], v[148:151], v[204:207], v[16:19]
	s_barrier
	s_add_i32 s100, s41, s23
	s_mov_b32 m0, s100
	s_add_u32 vcc_lo, s20, s42
	s_addc_u32 vcc_hi, s21, s43
	global_load_lds_dwordx4 v164, vcc
	s_add_i32 m0, s100, 0x2000
	s_add_u32 vcc_lo, s20, s50
	s_addc_u32 vcc_hi, s21, s51
	global_load_lds_dwordx4 v164, vcc
	s_waitcnt vmcnt(6)
	s_barrier
	v_mfma_f32_16x16x32_bf16 v[60:63], v[208:211], v[152:155], 0
	v_mfma_f32_16x16x32_bf16 v[56:59], v[216:219], v[152:155], 0
	v_mfma_f32_16x16x32_bf16 v[44:47], v[208:211], v[160:163], 0
	v_mfma_f32_16x16x32_bf16 v[40:43], v[216:219], v[160:163], 0
	v_mfma_f32_16x16x32_bf16 v[28:31], v[208:211], v[176:179], 0
	v_mfma_f32_16x16x32_bf16 v[24:27], v[216:219], v[176:179], 0
	v_mfma_f32_16x16x32_bf16 v[12:15], v[208:211], v[200:203], 0
	v_mfma_f32_16x16x32_bf16 v[8:11], v[216:219], v[200:203], 0
	v_mfma_f32_16x16x32_bf16 v[60:63], v[212:215], v[156:159], v[60:63]
	v_mfma_f32_16x16x32_bf16 v[56:59], v[220:223], v[156:159], v[56:59]
	v_mfma_f32_16x16x32_bf16 v[44:47], v[212:215], v[172:175], v[44:47]
	v_mfma_f32_16x16x32_bf16 v[40:43], v[220:223], v[172:175], v[40:43]
	v_mfma_f32_16x16x32_bf16 v[28:31], v[212:215], v[196:199], v[28:31]
	v_mfma_f32_16x16x32_bf16 v[24:27], v[220:223], v[196:199], v[24:27]
	v_mfma_f32_16x16x32_bf16 v[12:15], v[212:215], v[204:207], v[12:15]
	v_mfma_f32_16x16x32_bf16 v[8:11], v[220:223], v[204:207], v[8:11]
	s_barrier
	s_add_i32 s100, 0, 0x18000
	ds_read_b128 v[136:139], v255 offset:32768
	ds_read_b128 v[140:143], v255 offset:33792
	ds_read_b128 v[144:147], v255 offset:34816
	ds_read_b128 v[148:151], v255 offset:35840
	s_mov_b32 m0, s26
	ds_read_b128 v[152:155], v182 offset:32768
	ds_read_b128 v[156:159], v182 offset:33792
	ds_read_b128 v[160:163], v182 offset:34816
	ds_read_b128 v[172:175], v182 offset:35840
	ds_read_b128 v[176:179], v182 offset:36864
	ds_read_b128 v[196:199], v182 offset:37888
	ds_read_b128 v[200:203], v182 offset:38912
	ds_read_b128 v[204:207], v182 offset:39936
	s_add_u32 vcc_lo, s4, s42
	s_addc_u32 vcc_hi, s5, s43
	global_load_lds_dwordx4 v2, vcc
	s_mov_b32 m0, s27
	s_add_u32 vcc_lo, s4, s50
	s_addc_u32 vcc_hi, s5, s51
	global_load_lds_dwordx4 v2, vcc
	s_waitcnt lgkmcnt(8)
	s_barrier
	s_waitcnt lgkmcnt(0)
	v_mfma_f32_16x16x32_bf16 v[132:135], v[136:139], v[152:155], v[132:135]
	v_mfma_f32_16x16x32_bf16 v[128:131], v[144:147], v[152:155], v[128:131]
	v_mfma_f32_16x16x32_bf16 v[116:119], v[136:139], v[160:163], v[116:119]
	v_mfma_f32_16x16x32_bf16 v[112:115], v[144:147], v[160:163], v[112:115]
	v_mfma_f32_16x16x32_bf16 v[100:103], v[136:139], v[176:179], v[100:103]
	v_mfma_f32_16x16x32_bf16 v[96:99], v[144:147], v[176:179], v[96:99]
	v_mfma_f32_16x16x32_bf16 v[84:87], v[136:139], v[200:203], v[84:87]
	v_mfma_f32_16x16x32_bf16 v[80:83], v[144:147], v[200:203], v[80:83]
	v_mfma_f32_16x16x32_bf16 v[132:135], v[140:143], v[156:159], v[132:135]
	v_mfma_f32_16x16x32_bf16 v[128:131], v[148:151], v[156:159], v[128:131]
	v_mfma_f32_16x16x32_bf16 v[116:119], v[140:143], v[172:175], v[116:119]
	v_mfma_f32_16x16x32_bf16 v[112:115], v[148:151], v[172:175], v[112:115]
	v_mfma_f32_16x16x32_bf16 v[100:103], v[140:143], v[196:199], v[100:103]
	v_mfma_f32_16x16x32_bf16 v[96:99], v[148:151], v[196:199], v[96:99]
	v_mfma_f32_16x16x32_bf16 v[84:87], v[140:143], v[204:207], v[84:87]
	v_mfma_f32_16x16x32_bf16 v[80:83], v[148:151], v[204:207], v[80:83]
	s_barrier
	s_add_i32 s5, 0, 0x1c000
	s_add_i32 s4, s100, s23
	s_mov_b32 m0, s4
	ds_read_b128 v[208:211], v255 offset:49152
	ds_read_b128 v[212:215], v255 offset:50176
	ds_read_b128 v[216:219], v255 offset:51200
	ds_read_b128 v[220:223], v255 offset:52224
	s_add_u32 vcc_lo, s20, s46
	s_addc_u32 vcc_hi, s21, s47
	global_load_lds_dwordx4 v164, vcc
	s_add_i32 m0, s4, 0x2000
	s_add_u32 vcc_lo, s20, s52
	s_addc_u32 vcc_hi, s21, s53
	global_load_lds_dwordx4 v164, vcc
	s_barrier
	s_waitcnt lgkmcnt(0)
	v_mfma_f32_16x16x32_bf16 v[124:127], v[208:211], v[152:155], v[124:127]
	v_mfma_f32_16x16x32_bf16 v[120:123], v[216:219], v[152:155], v[120:123]
	v_mfma_f32_16x16x32_bf16 v[108:111], v[208:211], v[160:163], v[108:111]
	v_mfma_f32_16x16x32_bf16 v[104:107], v[216:219], v[160:163], v[104:107]
	v_mfma_f32_16x16x32_bf16 v[92:95], v[208:211], v[176:179], v[92:95]
	v_mfma_f32_16x16x32_bf16 v[88:91], v[216:219], v[176:179], v[88:91]
	v_mfma_f32_16x16x32_bf16 v[76:79], v[208:211], v[200:203], v[76:79]
	v_mfma_f32_16x16x32_bf16 v[72:75], v[216:219], v[200:203], v[72:75]
	v_mfma_f32_16x16x32_bf16 v[124:127], v[212:215], v[156:159], v[124:127]
	v_mfma_f32_16x16x32_bf16 v[120:123], v[220:223], v[156:159], v[120:123]
	v_mfma_f32_16x16x32_bf16 v[108:111], v[212:215], v[172:175], v[108:111]
	v_mfma_f32_16x16x32_bf16 v[104:107], v[220:223], v[172:175], v[104:107]
	v_mfma_f32_16x16x32_bf16 v[92:95], v[212:215], v[196:199], v[92:95]
	v_mfma_f32_16x16x32_bf16 v[88:91], v[220:223], v[196:199], v[88:91]
	v_mfma_f32_16x16x32_bf16 v[76:79], v[212:215], v[204:207], v[76:79]
	v_mfma_f32_16x16x32_bf16 v[72:75], v[220:223], v[204:207], v[72:75]
	s_barrier
	s_mov_b32 m0, s29
	v_lshl_add_u64 v[226:227], v[224:225], 0, s[46:47]
	ds_read_b128 v[152:155], v182 offset:49152
	ds_read_b128 v[156:159], v182 offset:50176
	ds_read_b128 v[160:163], v182 offset:51200
	ds_read_b128 v[172:175], v182 offset:52224
	ds_read_b128 v[176:179], v182 offset:53248
	ds_read_b128 v[196:199], v182 offset:54272
	ds_read_b128 v[200:203], v182 offset:55296
	ds_read_b128 v[204:207], v182 offset:56320
	global_load_lds_dwordx4 v[226:227], off
	v_lshl_add_u64 v[224:225], v[224:225], 0, s[52:53]
	s_mov_b32 m0, s30
	s_nop 0
	global_load_lds_dwordx4 v[224:225], off
	s_barrier
	s_waitcnt lgkmcnt(0)
	v_mfma_f32_16x16x32_bf16 v[68:71], v[136:139], v[152:155], v[68:71]
	v_mfma_f32_16x16x32_bf16 v[64:67], v[144:147], v[152:155], v[64:67]
	v_mfma_f32_16x16x32_bf16 v[52:55], v[136:139], v[160:163], v[52:55]
	v_mfma_f32_16x16x32_bf16 v[48:51], v[144:147], v[160:163], v[48:51]
	v_mfma_f32_16x16x32_bf16 v[36:39], v[136:139], v[176:179], v[36:39]
	v_mfma_f32_16x16x32_bf16 v[32:35], v[144:147], v[176:179], v[32:35]
	v_mfma_f32_16x16x32_bf16 v[20:23], v[136:139], v[200:203], v[20:23]
	v_mfma_f32_16x16x32_bf16 v[16:19], v[144:147], v[200:203], v[16:19]
	v_mfma_f32_16x16x32_bf16 v[68:71], v[140:143], v[156:159], v[68:71]
	v_mfma_f32_16x16x32_bf16 v[64:67], v[148:151], v[156:159], v[64:67]
	v_mfma_f32_16x16x32_bf16 v[52:55], v[140:143], v[172:175], v[52:55]
	v_mfma_f32_16x16x32_bf16 v[48:51], v[148:151], v[172:175], v[48:51]
	v_mfma_f32_16x16x32_bf16 v[36:39], v[140:143], v[196:199], v[36:39]
	v_mfma_f32_16x16x32_bf16 v[32:35], v[148:151], v[196:199], v[32:35]
	v_mfma_f32_16x16x32_bf16 v[20:23], v[140:143], v[204:207], v[20:23]
	v_mfma_f32_16x16x32_bf16 v[16:19], v[148:151], v[204:207], v[16:19]
	s_barrier
	s_add_i32 s4, s5, s23
	s_mov_b32 m0, s4
	s_add_u32 vcc_lo, s20, s54
	s_addc_u32 vcc_hi, s21, s55
	global_load_lds_dwordx4 v164, vcc
	s_add_i32 m0, s4, 0x2000
	s_add_u32 vcc_lo, s20, s58
	s_addc_u32 vcc_hi, s21, s59
	global_load_lds_dwordx4 v164, vcc
	s_add_i32 s15, s15, 2
	s_add_u32 s2, s2, 0x100
	s_addc_u32 s3, s3, 0
	s_add_u32 s6, s6, 0x100
	s_addc_u32 s7, s7, 0
	s_cmp_gt_u32 s15, 13
	s_waitcnt vmcnt(6)
	s_barrier
	v_mfma_f32_16x16x32_bf16 v[60:63], v[208:211], v[152:155], v[60:63]
	v_mfma_f32_16x16x32_bf16 v[56:59], v[216:219], v[152:155], v[56:59]
	v_mfma_f32_16x16x32_bf16 v[44:47], v[208:211], v[160:163], v[44:47]
	v_mfma_f32_16x16x32_bf16 v[40:43], v[216:219], v[160:163], v[40:43]
	v_mfma_f32_16x16x32_bf16 v[28:31], v[208:211], v[176:179], v[28:31]
	v_mfma_f32_16x16x32_bf16 v[24:27], v[216:219], v[176:179], v[24:27]
	v_mfma_f32_16x16x32_bf16 v[12:15], v[208:211], v[200:203], v[12:15]
	v_mfma_f32_16x16x32_bf16 v[8:11], v[216:219], v[200:203], v[8:11]
	v_mfma_f32_16x16x32_bf16 v[60:63], v[212:215], v[156:159], v[60:63]
	v_mfma_f32_16x16x32_bf16 v[56:59], v[220:223], v[156:159], v[56:59]
	v_mfma_f32_16x16x32_bf16 v[44:47], v[212:215], v[172:175], v[44:47]
	v_mfma_f32_16x16x32_bf16 v[40:43], v[220:223], v[172:175], v[40:43]
	v_mfma_f32_16x16x32_bf16 v[28:31], v[212:215], v[196:199], v[28:31]
	v_mfma_f32_16x16x32_bf16 v[24:27], v[220:223], v[196:199], v[24:27]
	v_mfma_f32_16x16x32_bf16 v[12:15], v[212:215], v[204:207], v[12:15]
	v_mfma_f32_16x16x32_bf16 v[8:11], v[220:223], v[204:207], v[8:11]
	s_cbranch_scc0 .Ldb_WOUT_cont
	s_branch .Ldb_WOUT_xl
.LBB0_1037:
	s_add_u32 s4, s2, 0xfffc0080
	s_addc_u32 s5, s3, -1
	s_add_i32 s33, 0, 0x10000
	ds_read_b128 v[136:139], v255 offset:0
	ds_read_b128 v[140:143], v255 offset:1024
	ds_read_b128 v[144:147], v255 offset:2048
	ds_read_b128 v[148:151], v255 offset:3072
	s_cmp_eq_u32 s15, 12
	s_cselect_b32 s5, s17, s5
	s_cselect_b32 s4, s16, s4
	s_cselect_b32 s21, s19, s7
	s_cselect_b32 s20, s18, s6
	s_add_i32 m0, s24, 0xc000
	ds_read_b128 v[152:155], v182
	ds_read_b128 v[156:159], v182 offset:1024
	ds_read_b128 v[160:163], v182 offset:2048
	ds_read_b128 v[172:175], v182 offset:3072
	ds_read_b128 v[176:179], v182 offset:4096
	ds_read_b128 v[196:199], v182 offset:5120
	ds_read_b128 v[200:203], v182 offset:6144
	ds_read_b128 v[204:207], v182 offset:7168
	global_load_lds_dwordx4 v166, s[2:3]
	s_add_i32 m0, s24, 0xe000
	s_add_u32 vcc_lo, s2, s0
	s_addc_u32 vcc_hi, s3, s1
	global_load_lds_dwordx4 v166, vcc
	s_waitcnt lgkmcnt(8)
	s_barrier
	s_waitcnt lgkmcnt(0)
	v_mfma_f32_16x16x32_bf16 v[132:135], v[136:139], v[152:155], v[132:135]
	v_mfma_f32_16x16x32_bf16 v[128:131], v[144:147], v[152:155], v[128:131]
	v_mfma_f32_16x16x32_bf16 v[116:119], v[136:139], v[160:163], v[116:119]
	v_mfma_f32_16x16x32_bf16 v[112:115], v[144:147], v[160:163], v[112:115]
	v_mfma_f32_16x16x32_bf16 v[100:103], v[136:139], v[176:179], v[100:103]
	v_mfma_f32_16x16x32_bf16 v[96:99], v[144:147], v[176:179], v[96:99]
	v_mfma_f32_16x16x32_bf16 v[84:87], v[136:139], v[200:203], v[84:87]
	v_mfma_f32_16x16x32_bf16 v[80:83], v[144:147], v[200:203], v[80:83]
	v_mfma_f32_16x16x32_bf16 v[132:135], v[140:143], v[156:159], v[132:135]
	v_mfma_f32_16x16x32_bf16 v[128:131], v[148:151], v[156:159], v[128:131]
	v_mfma_f32_16x16x32_bf16 v[116:119], v[140:143], v[172:175], v[116:119]
	v_mfma_f32_16x16x32_bf16 v[112:115], v[148:151], v[172:175], v[112:115]
	v_mfma_f32_16x16x32_bf16 v[100:103], v[140:143], v[196:199], v[100:103]
	v_mfma_f32_16x16x32_bf16 v[96:99], v[148:151], v[196:199], v[96:99]
	v_mfma_f32_16x16x32_bf16 v[84:87], v[140:143], v[204:207], v[84:87]
	v_mfma_f32_16x16x32_bf16 v[80:83], v[148:151], v[204:207], v[80:83]
	s_barrier
	s_add_i32 s41, 0, 0x14000
	s_add_i32 s100, s33, s23
	s_mov_b32 m0, s100
	ds_read_b128 v[208:211], v255 offset:16384
	ds_read_b128 v[212:215], v255 offset:17408
	ds_read_b128 v[216:219], v255 offset:18432
	ds_read_b128 v[220:223], v255 offset:19456
	global_load_lds_dwordx4 v164, s[20:21]
	s_add_i32 m0, s100, 0x2000
	s_add_u32 vcc_lo, s20, s0
	s_addc_u32 vcc_hi, s21, s1
	global_load_lds_dwordx4 v164, vcc
	s_barrier
	s_waitcnt lgkmcnt(0)
	v_mfma_f32_16x16x32_bf16 v[124:127], v[208:211], v[152:155], v[124:127]
	v_mfma_f32_16x16x32_bf16 v[120:123], v[216:219], v[152:155], v[120:123]
	v_mfma_f32_16x16x32_bf16 v[108:111], v[208:211], v[160:163], v[108:111]
	v_mfma_f32_16x16x32_bf16 v[104:107], v[216:219], v[160:163], v[104:107]
	v_mfma_f32_16x16x32_bf16 v[92:95], v[208:211], v[176:179], v[92:95]
	v_mfma_f32_16x16x32_bf16 v[88:91], v[216:219], v[176:179], v[88:91]
	v_mfma_f32_16x16x32_bf16 v[76:79], v[208:211], v[200:203], v[76:79]
	v_mfma_f32_16x16x32_bf16 v[72:75], v[216:219], v[200:203], v[72:75]
	v_mfma_f32_16x16x32_bf16 v[124:127], v[212:215], v[156:159], v[124:127]
	v_mfma_f32_16x16x32_bf16 v[120:123], v[220:223], v[156:159], v[120:123]
	v_mfma_f32_16x16x32_bf16 v[108:111], v[212:215], v[172:175], v[108:111]
	v_mfma_f32_16x16x32_bf16 v[104:107], v[220:223], v[172:175], v[104:107]
	v_mfma_f32_16x16x32_bf16 v[92:95], v[212:215], v[196:199], v[92:95]
	v_mfma_f32_16x16x32_bf16 v[88:91], v[220:223], v[196:199], v[88:91]
	v_mfma_f32_16x16x32_bf16 v[76:79], v[212:215], v[204:207], v[76:79]
	v_mfma_f32_16x16x32_bf16 v[72:75], v[220:223], v[204:207], v[72:75]
	s_barrier
	s_mov_b32 m0, s24
	v_lshl_add_u64 v[224:225], s[4:5], 0, v[2:3]
	ds_read_b128 v[152:155], v182 offset:16384
	ds_read_b128 v[156:159], v182 offset:17408
	ds_read_b128 v[160:163], v182 offset:18432
	ds_read_b128 v[172:175], v182 offset:19456
	ds_read_b128 v[176:179], v182 offset:20480
	ds_read_b128 v[196:199], v182 offset:21504
	ds_read_b128 v[200:203], v182 offset:22528
	ds_read_b128 v[204:207], v182 offset:23552
	global_load_lds_dwordx4 v2, s[4:5]
	s_mov_b32 m0, s25
	s_add_u32 vcc_lo, s4, s0
	s_addc_u32 vcc_hi, s5, s1
	global_load_lds_dwordx4 v2, vcc
	s_barrier
	s_waitcnt lgkmcnt(0)
	v_mfma_f32_16x16x32_bf16 v[68:71], v[136:139], v[152:155], v[68:71]
	v_mfma_f32_16x16x32_bf16 v[64:67], v[144:147], v[152:155], v[64:67]
	v_mfma_f32_16x16x32_bf16 v[52:55], v[136:139], v[160:163], v[52:55]
	v_mfma_f32_16x16x32_bf16 v[48:51], v[144:147], v[160:163], v[48:51]
	v_mfma_f32_16x16x32_bf16 v[36:39], v[136:139], v[176:179], v[36:39]
	v_mfma_f32_16x16x32_bf16 v[32:35], v[144:147], v[176:179], v[32:35]
	v_mfma_f32_16x16x32_bf16 v[20:23], v[136:139], v[200:203], v[20:23]
	v_mfma_f32_16x16x32_bf16 v[16:19], v[144:147], v[200:203], v[16:19]
	v_mfma_f32_16x16x32_bf16 v[68:71], v[140:143], v[156:159], v[68:71]
	v_mfma_f32_16x16x32_bf16 v[64:67], v[148:151], v[156:159], v[64:67]
	v_mfma_f32_16x16x32_bf16 v[52:55], v[140:143], v[172:175], v[52:55]
	v_mfma_f32_16x16x32_bf16 v[48:51], v[148:151], v[172:175], v[48:51]
	v_mfma_f32_16x16x32_bf16 v[36:39], v[140:143], v[196:199], v[36:39]
	v_mfma_f32_16x16x32_bf16 v[32:35], v[148:151], v[196:199], v[32:35]
	v_mfma_f32_16x16x32_bf16 v[20:23], v[140:143], v[204:207], v[20:23]
	v_mfma_f32_16x16x32_bf16 v[16:19], v[148:151], v[204:207], v[16:19]
	s_barrier
	s_add_i32 s100, s41, s23
	s_mov_b32 m0, s100
	s_add_u32 vcc_lo, s20, s42
	s_addc_u32 vcc_hi, s21, s43
	global_load_lds_dwordx4 v164, vcc
	s_add_i32 m0, s100, 0x2000
	s_add_u32 vcc_lo, s20, s50
	s_addc_u32 vcc_hi, s21, s51
	global_load_lds_dwordx4 v164, vcc
	s_waitcnt vmcnt(6)
	s_barrier
	v_mfma_f32_16x16x32_bf16 v[60:63], v[208:211], v[152:155], v[60:63]
	v_mfma_f32_16x16x32_bf16 v[56:59], v[216:219], v[152:155], v[56:59]
	v_mfma_f32_16x16x32_bf16 v[44:47], v[208:211], v[160:163], v[44:47]
	v_mfma_f32_16x16x32_bf16 v[40:43], v[216:219], v[160:163], v[40:43]
	v_mfma_f32_16x16x32_bf16 v[28:31], v[208:211], v[176:179], v[28:31]
	v_mfma_f32_16x16x32_bf16 v[24:27], v[216:219], v[176:179], v[24:27]
	v_mfma_f32_16x16x32_bf16 v[12:15], v[208:211], v[200:203], v[12:15]
	v_mfma_f32_16x16x32_bf16 v[8:11], v[216:219], v[200:203], v[8:11]
	v_mfma_f32_16x16x32_bf16 v[60:63], v[212:215], v[156:159], v[60:63]
	v_mfma_f32_16x16x32_bf16 v[56:59], v[220:223], v[156:159], v[56:59]
	v_mfma_f32_16x16x32_bf16 v[44:47], v[212:215], v[172:175], v[44:47]
	v_mfma_f32_16x16x32_bf16 v[40:43], v[220:223], v[172:175], v[40:43]
	v_mfma_f32_16x16x32_bf16 v[28:31], v[212:215], v[196:199], v[28:31]
	v_mfma_f32_16x16x32_bf16 v[24:27], v[220:223], v[196:199], v[24:27]
	v_mfma_f32_16x16x32_bf16 v[12:15], v[212:215], v[204:207], v[12:15]
	v_mfma_f32_16x16x32_bf16 v[8:11], v[220:223], v[204:207], v[8:11]
	s_barrier
	s_add_i32 s100, 0, 0x18000
	ds_read_b128 v[136:139], v255 offset:32768
	ds_read_b128 v[140:143], v255 offset:33792
	ds_read_b128 v[144:147], v255 offset:34816
	ds_read_b128 v[148:151], v255 offset:35840
	s_mov_b32 m0, s26
	ds_read_b128 v[152:155], v182 offset:32768
	ds_read_b128 v[156:159], v182 offset:33792
	ds_read_b128 v[160:163], v182 offset:34816
	ds_read_b128 v[172:175], v182 offset:35840
	ds_read_b128 v[176:179], v182 offset:36864
	ds_read_b128 v[196:199], v182 offset:37888
	ds_read_b128 v[200:203], v182 offset:38912
	ds_read_b128 v[204:207], v182 offset:39936
	s_add_u32 vcc_lo, s4, s42
	s_addc_u32 vcc_hi, s5, s43
	global_load_lds_dwordx4 v2, vcc
	s_mov_b32 m0, s27
	s_add_u32 vcc_lo, s4, s50
	s_addc_u32 vcc_hi, s5, s51
	global_load_lds_dwordx4 v2, vcc
	s_waitcnt lgkmcnt(8)
	s_barrier
	s_waitcnt lgkmcnt(0)
	v_mfma_f32_16x16x32_bf16 v[132:135], v[136:139], v[152:155], v[132:135]
	v_mfma_f32_16x16x32_bf16 v[128:131], v[144:147], v[152:155], v[128:131]
	v_mfma_f32_16x16x32_bf16 v[116:119], v[136:139], v[160:163], v[116:119]
	v_mfma_f32_16x16x32_bf16 v[112:115], v[144:147], v[160:163], v[112:115]
	v_mfma_f32_16x16x32_bf16 v[100:103], v[136:139], v[176:179], v[100:103]
	v_mfma_f32_16x16x32_bf16 v[96:99], v[144:147], v[176:179], v[96:99]
	v_mfma_f32_16x16x32_bf16 v[84:87], v[136:139], v[200:203], v[84:87]
	v_mfma_f32_16x16x32_bf16 v[80:83], v[144:147], v[200:203], v[80:83]
	v_mfma_f32_16x16x32_bf16 v[132:135], v[140:143], v[156:159], v[132:135]
	v_mfma_f32_16x16x32_bf16 v[128:131], v[148:151], v[156:159], v[128:131]
	v_mfma_f32_16x16x32_bf16 v[116:119], v[140:143], v[172:175], v[116:119]
	v_mfma_f32_16x16x32_bf16 v[112:115], v[148:151], v[172:175], v[112:115]
	v_mfma_f32_16x16x32_bf16 v[100:103], v[140:143], v[196:199], v[100:103]
	v_mfma_f32_16x16x32_bf16 v[96:99], v[148:151], v[196:199], v[96:99]
	v_mfma_f32_16x16x32_bf16 v[84:87], v[140:143], v[204:207], v[84:87]
	v_mfma_f32_16x16x32_bf16 v[80:83], v[148:151], v[204:207], v[80:83]
	s_barrier
	s_add_i32 s5, 0, 0x1c000
	s_add_i32 s4, s100, s23
	s_mov_b32 m0, s4
	ds_read_b128 v[208:211], v255 offset:49152
	ds_read_b128 v[212:215], v255 offset:50176
	ds_read_b128 v[216:219], v255 offset:51200
	ds_read_b128 v[220:223], v255 offset:52224
	s_add_u32 vcc_lo, s20, s46
	s_addc_u32 vcc_hi, s21, s47
	global_load_lds_dwordx4 v164, vcc
	s_add_i32 m0, s4, 0x2000
	s_add_u32 vcc_lo, s20, s52
	s_addc_u32 vcc_hi, s21, s53
	global_load_lds_dwordx4 v164, vcc
	s_barrier
	s_waitcnt lgkmcnt(0)
	v_mfma_f32_16x16x32_bf16 v[124:127], v[208:211], v[152:155], v[124:127]
	v_mfma_f32_16x16x32_bf16 v[120:123], v[216:219], v[152:155], v[120:123]
	v_mfma_f32_16x16x32_bf16 v[108:111], v[208:211], v[160:163], v[108:111]
	v_mfma_f32_16x16x32_bf16 v[104:107], v[216:219], v[160:163], v[104:107]
	v_mfma_f32_16x16x32_bf16 v[92:95], v[208:211], v[176:179], v[92:95]
	v_mfma_f32_16x16x32_bf16 v[88:91], v[216:219], v[176:179], v[88:91]
	v_mfma_f32_16x16x32_bf16 v[76:79], v[208:211], v[200:203], v[76:79]
	v_mfma_f32_16x16x32_bf16 v[72:75], v[216:219], v[200:203], v[72:75]
	v_mfma_f32_16x16x32_bf16 v[124:127], v[212:215], v[156:159], v[124:127]
	v_mfma_f32_16x16x32_bf16 v[120:123], v[220:223], v[156:159], v[120:123]
	v_mfma_f32_16x16x32_bf16 v[108:111], v[212:215], v[172:175], v[108:111]
	v_mfma_f32_16x16x32_bf16 v[104:107], v[220:223], v[172:175], v[104:107]
	v_mfma_f32_16x16x32_bf16 v[92:95], v[212:215], v[196:199], v[92:95]
	v_mfma_f32_16x16x32_bf16 v[88:91], v[220:223], v[196:199], v[88:91]
	v_mfma_f32_16x16x32_bf16 v[76:79], v[212:215], v[204:207], v[76:79]
	v_mfma_f32_16x16x32_bf16 v[72:75], v[220:223], v[204:207], v[72:75]
	s_barrier
	s_mov_b32 m0, s29
	v_lshl_add_u64 v[226:227], v[224:225], 0, s[46:47]
	ds_read_b128 v[152:155], v182 offset:49152
	ds_read_b128 v[156:159], v182 offset:50176
	ds_read_b128 v[160:163], v182 offset:51200
	ds_read_b128 v[172:175], v182 offset:52224
	ds_read_b128 v[176:179], v182 offset:53248
	ds_read_b128 v[196:199], v182 offset:54272
	ds_read_b128 v[200:203], v182 offset:55296
	ds_read_b128 v[204:207], v182 offset:56320
	global_load_lds_dwordx4 v[226:227], off
	v_lshl_add_u64 v[224:225], v[224:225], 0, s[52:53]
	s_mov_b32 m0, s30
	s_nop 0
	global_load_lds_dwordx4 v[224:225], off
	s_barrier
	s_waitcnt lgkmcnt(0)
	v_mfma_f32_16x16x32_bf16 v[68:71], v[136:139], v[152:155], v[68:71]
	v_mfma_f32_16x16x32_bf16 v[64:67], v[144:147], v[152:155], v[64:67]
	v_mfma_f32_16x16x32_bf16 v[52:55], v[136:139], v[160:163], v[52:55]
	v_mfma_f32_16x16x32_bf16 v[48:51], v[144:147], v[160:163], v[48:51]
	v_mfma_f32_16x16x32_bf16 v[36:39], v[136:139], v[176:179], v[36:39]
	v_mfma_f32_16x16x32_bf16 v[32:35], v[144:147], v[176:179], v[32:35]
	v_mfma_f32_16x16x32_bf16 v[20:23], v[136:139], v[200:203], v[20:23]
	v_mfma_f32_16x16x32_bf16 v[16:19], v[144:147], v[200:203], v[16:19]
	v_mfma_f32_16x16x32_bf16 v[68:71], v[140:143], v[156:159], v[68:71]
	v_mfma_f32_16x16x32_bf16 v[64:67], v[148:151], v[156:159], v[64:67]
	v_mfma_f32_16x16x32_bf16 v[52:55], v[140:143], v[172:175], v[52:55]
	v_mfma_f32_16x16x32_bf16 v[48:51], v[148:151], v[172:175], v[48:51]
	v_mfma_f32_16x16x32_bf16 v[36:39], v[140:143], v[196:199], v[36:39]
	v_mfma_f32_16x16x32_bf16 v[32:35], v[148:151], v[196:199], v[32:35]
	v_mfma_f32_16x16x32_bf16 v[20:23], v[140:143], v[204:207], v[20:23]
	v_mfma_f32_16x16x32_bf16 v[16:19], v[148:151], v[204:207], v[16:19]
	s_barrier
	s_add_i32 s4, s5, s23
	s_mov_b32 m0, s4
	s_add_u32 vcc_lo, s20, s54
	s_addc_u32 vcc_hi, s21, s55
	global_load_lds_dwordx4 v164, vcc
	s_add_i32 m0, s4, 0x2000
	s_add_u32 vcc_lo, s20, s58
	s_addc_u32 vcc_hi, s21, s59
	global_load_lds_dwordx4 v164, vcc
	s_add_i32 s15, s15, 2
	s_add_u32 s2, s2, 0x100
	s_addc_u32 s3, s3, 0
	s_add_u32 s6, s6, 0x100
	s_addc_u32 s7, s7, 0
	s_cmp_gt_u32 s15, 13
	s_waitcnt vmcnt(6)
	s_barrier
	v_mfma_f32_16x16x32_bf16 v[60:63], v[208:211], v[152:155], v[60:63]
	v_mfma_f32_16x16x32_bf16 v[56:59], v[216:219], v[152:155], v[56:59]
	v_mfma_f32_16x16x32_bf16 v[44:47], v[208:211], v[160:163], v[44:47]
	v_mfma_f32_16x16x32_bf16 v[40:43], v[216:219], v[160:163], v[40:43]
	v_mfma_f32_16x16x32_bf16 v[28:31], v[208:211], v[176:179], v[28:31]
	v_mfma_f32_16x16x32_bf16 v[24:27], v[216:219], v[176:179], v[24:27]
	v_mfma_f32_16x16x32_bf16 v[12:15], v[208:211], v[200:203], v[12:15]
	v_mfma_f32_16x16x32_bf16 v[8:11], v[216:219], v[200:203], v[8:11]
	v_mfma_f32_16x16x32_bf16 v[60:63], v[212:215], v[156:159], v[60:63]
	v_mfma_f32_16x16x32_bf16 v[56:59], v[220:223], v[156:159], v[56:59]
	v_mfma_f32_16x16x32_bf16 v[44:47], v[212:215], v[172:175], v[44:47]
	v_mfma_f32_16x16x32_bf16 v[40:43], v[220:223], v[172:175], v[40:43]
	v_mfma_f32_16x16x32_bf16 v[28:31], v[212:215], v[196:199], v[28:31]
	v_mfma_f32_16x16x32_bf16 v[24:27], v[220:223], v[196:199], v[24:27]
	v_mfma_f32_16x16x32_bf16 v[12:15], v[212:215], v[204:207], v[12:15]
	v_mfma_f32_16x16x32_bf16 v[8:11], v[220:223], v[204:207], v[8:11]
	s_cbranch_scc0 .Ldb_WOUT_cont

.LBB0_1119:
	s_add_u32 s2, s16, 0x40080
	s_addc_u32 s3, s17, 0
	s_add_u32 s16, s18, 0x100
	s_addc_u32 s17, s19, 0
	s_mov_b32 s18, -2
	s_mov_b64 s[42:43], 0x40000
	s_mov_b64 s[50:51], 0x60000
	s_mov_b64 s[52:53], 0x20080
	s_mov_b64 s[54:55], 0x40080
	s_mov_b64 s[58:59], 0x60080
	s_cmp_eq_u32 s101, 2
	s_cselect_b32 s101, 0, s101
	s_setprio 0
	v_add_u32_e32 v235, 0x10000, v149
	s_add_u32 s4, s2, 0xfffc0080
	s_addc_u32 s5, s3, -1
	s_add_i32 s19, 0, 0x10000
	ds_read_b128 v[140:143], v235 offset:0
	ds_read_b128 v[144:147], v235 offset:1024
	ds_read_b128 v[152:155], v235 offset:2048
	ds_read_b128 v[156:159], v235 offset:3072
	s_cmp_eq_u32 s18, 12
	s_cselect_b32 s5, s13, s5
	s_cselect_b32 s4, s12, s4
	s_cselect_b32 s41, s15, s17
	s_cselect_b32 s40, s14, s16
	s_add_i32 m0, s26, 0xc000
	ds_read_b128 v[160:163], v150
	ds_read_b128 v[164:167], v150 offset:1024
	ds_read_b128 v[172:175], v150 offset:2048
	ds_read_b128 v[176:179], v150 offset:3072
	ds_read_b128 v[180:183], v150 offset:4096
	ds_read_b128 v[196:199], v150 offset:5120
	ds_read_b128 v[200:203], v150 offset:6144
	ds_read_b128 v[204:207], v150 offset:7168
	global_load_lds_dwordx4 v138, s[2:3]
	s_add_i32 m0, s26, 0xe000
	s_add_u32 vcc_lo, s2, s0
	s_addc_u32 vcc_hi, s3, s1
	global_load_lds_dwordx4 v138, vcc
	s_waitcnt lgkmcnt(8)
	s_cmp_eq_u32 s101, 1
	s_cbranch_scc1 .Ldb_FFI_skp
	s_barrier
.Ldb_FFI_skp:
	s_mov_b32 s101, 0
	s_waitcnt lgkmcnt(0)
	v_mfma_f32_16x16x32_bf16 v[132:135], v[140:143], v[160:163], 0
	v_mfma_f32_16x16x32_bf16 v[124:127], v[152:155], v[160:163], 0
	v_mfma_f32_16x16x32_bf16 v[116:119], v[140:143], v[172:175], 0
	v_mfma_f32_16x16x32_bf16 v[108:111], v[152:155], v[172:175], 0
	v_mfma_f32_16x16x32_bf16 v[100:103], v[140:143], v[180:183], 0
	v_mfma_f32_16x16x32_bf16 v[92:95], v[152:155], v[180:183], 0
	v_mfma_f32_16x16x32_bf16 v[84:87], v[140:143], v[200:203], 0
	v_mfma_f32_16x16x32_bf16 v[76:79], v[152:155], v[200:203], 0
	v_mfma_f32_16x16x32_bf16 v[132:135], v[144:147], v[164:167], v[132:135]
	v_mfma_f32_16x16x32_bf16 v[124:127], v[156:159], v[164:167], v[124:127]
	v_mfma_f32_16x16x32_bf16 v[116:119], v[144:147], v[176:179], v[116:119]
	v_mfma_f32_16x16x32_bf16 v[108:111], v[156:159], v[176:179], v[108:111]
	v_mfma_f32_16x16x32_bf16 v[100:103], v[144:147], v[196:199], v[100:103]
	v_mfma_f32_16x16x32_bf16 v[92:95], v[156:159], v[196:199], v[92:95]
	v_mfma_f32_16x16x32_bf16 v[84:87], v[144:147], v[204:207], v[84:87]
	v_mfma_f32_16x16x32_bf16 v[76:79], v[156:159], v[204:207], v[76:79]
	s_barrier
	s_add_i32 s39, 0, 0x14000
	s_add_i32 s19, s19, s21
	s_mov_b32 m0, s19
	ds_read_b128 v[208:211], v235 offset:16384
	ds_read_b128 v[212:215], v235 offset:17408
	ds_read_b128 v[216:219], v235 offset:18432
	ds_read_b128 v[220:223], v235 offset:19456
	global_load_lds_dwordx4 v2, s[40:41]
	s_add_i32 m0, s19, 0x2000
	s_add_u32 vcc_lo, s40, s0
	s_addc_u32 vcc_hi, s41, s1
	global_load_lds_dwordx4 v2, vcc
	s_barrier
	s_waitcnt lgkmcnt(0)
	v_mfma_f32_16x16x32_bf16 v[128:131], v[208:211], v[160:163], 0
	v_mfma_f32_16x16x32_bf16 v[120:123], v[216:219], v[160:163], 0
	v_mfma_f32_16x16x32_bf16 v[112:115], v[208:211], v[172:175], 0
	v_mfma_f32_16x16x32_bf16 v[104:107], v[216:219], v[172:175], 0
	v_mfma_f32_16x16x32_bf16 v[96:99], v[208:211], v[180:183], 0
	v_mfma_f32_16x16x32_bf16 v[88:91], v[216:219], v[180:183], 0
	v_mfma_f32_16x16x32_bf16 v[80:83], v[208:211], v[200:203], 0
	v_mfma_f32_16x16x32_bf16 v[72:75], v[216:219], v[200:203], 0
	v_mfma_f32_16x16x32_bf16 v[128:131], v[212:215], v[164:167], v[128:131]
	v_mfma_f32_16x16x32_bf16 v[120:123], v[220:223], v[164:167], v[120:123]
	v_mfma_f32_16x16x32_bf16 v[112:115], v[212:215], v[176:179], v[112:115]
	v_mfma_f32_16x16x32_bf16 v[104:107], v[220:223], v[176:179], v[104:107]
	v_mfma_f32_16x16x32_bf16 v[96:99], v[212:215], v[196:199], v[96:99]
	v_mfma_f32_16x16x32_bf16 v[88:91], v[220:223], v[196:199], v[88:91]
	v_mfma_f32_16x16x32_bf16 v[80:83], v[212:215], v[204:207], v[80:83]
	v_mfma_f32_16x16x32_bf16 v[72:75], v[220:223], v[204:207], v[72:75]
	s_barrier
	s_mov_b32 m0, s26
	v_lshl_add_u64 v[224:225], s[4:5], 0, v[136:137]
	ds_read_b128 v[160:163], v150 offset:16384
	ds_read_b128 v[164:167], v150 offset:17408
	ds_read_b128 v[172:175], v150 offset:18432
	ds_read_b128 v[176:179], v150 offset:19456
	ds_read_b128 v[180:183], v150 offset:20480
	ds_read_b128 v[196:199], v150 offset:21504
	ds_read_b128 v[200:203], v150 offset:22528
	ds_read_b128 v[204:207], v150 offset:23552
	global_load_lds_dwordx4 v136, s[4:5]
	s_mov_b32 m0, s27
	s_add_u32 vcc_lo, s4, s0
	s_addc_u32 vcc_hi, s5, s1
	global_load_lds_dwordx4 v136, vcc
	s_barrier
	s_waitcnt lgkmcnt(0)
	v_mfma_f32_16x16x32_bf16 v[68:71], v[140:143], v[160:163], 0
	v_mfma_f32_16x16x32_bf16 v[60:63], v[152:155], v[160:163], 0
	v_mfma_f32_16x16x32_bf16 v[52:55], v[140:143], v[172:175], 0
	v_mfma_f32_16x16x32_bf16 v[44:47], v[152:155], v[172:175], 0
	v_mfma_f32_16x16x32_bf16 v[36:39], v[140:143], v[180:183], 0
	v_mfma_f32_16x16x32_bf16 v[28:31], v[152:155], v[180:183], 0
	v_mfma_f32_16x16x32_bf16 v[20:23], v[140:143], v[200:203], 0
	v_mfma_f32_16x16x32_bf16 v[12:15], v[152:155], v[200:203], 0
	v_mfma_f32_16x16x32_bf16 v[68:71], v[144:147], v[164:167], v[68:71]
	v_mfma_f32_16x16x32_bf16 v[60:63], v[156:159], v[164:167], v[60:63]
	v_mfma_f32_16x16x32_bf16 v[52:55], v[144:147], v[176:179], v[52:55]
	v_mfma_f32_16x16x32_bf16 v[44:47], v[156:159], v[176:179], v[44:47]
	v_mfma_f32_16x16x32_bf16 v[36:39], v[144:147], v[196:199], v[36:39]
	v_mfma_f32_16x16x32_bf16 v[28:31], v[156:159], v[196:199], v[28:31]
	v_mfma_f32_16x16x32_bf16 v[20:23], v[144:147], v[204:207], v[20:23]
	v_mfma_f32_16x16x32_bf16 v[12:15], v[156:159], v[204:207], v[12:15]
	s_barrier
	s_add_i32 s100, s39, s21
	s_mov_b32 m0, s100
	s_add_u32 vcc_lo, s40, s42
	s_addc_u32 vcc_hi, s41, s43
	global_load_lds_dwordx4 v2, vcc
	s_add_i32 m0, s100, 0x2000
	s_add_u32 vcc_lo, s40, s50
	s_addc_u32 vcc_hi, s41, s51
	global_load_lds_dwordx4 v2, vcc
	s_waitcnt vmcnt(6)
	s_barrier
	v_mfma_f32_16x16x32_bf16 v[64:67], v[208:211], v[160:163], 0
	v_mfma_f32_16x16x32_bf16 v[56:59], v[216:219], v[160:163], 0
	v_mfma_f32_16x16x32_bf16 v[48:51], v[208:211], v[172:175], 0
	v_mfma_f32_16x16x32_bf16 v[40:43], v[216:219], v[172:175], 0
	v_mfma_f32_16x16x32_bf16 v[32:35], v[208:211], v[180:183], 0
	v_mfma_f32_16x16x32_bf16 v[24:27], v[216:219], v[180:183], 0
	v_mfma_f32_16x16x32_bf16 v[16:19], v[208:211], v[200:203], 0
	v_mfma_f32_16x16x32_bf16 v[8:11], v[216:219], v[200:203], 0
	v_mfma_f32_16x16x32_bf16 v[64:67], v[212:215], v[164:167], v[64:67]
	v_mfma_f32_16x16x32_bf16 v[56:59], v[220:223], v[164:167], v[56:59]
	v_mfma_f32_16x16x32_bf16 v[48:51], v[212:215], v[176:179], v[48:51]
	v_mfma_f32_16x16x32_bf16 v[40:43], v[220:223], v[176:179], v[40:43]
	v_mfma_f32_16x16x32_bf16 v[32:35], v[212:215], v[196:199], v[32:35]
	v_mfma_f32_16x16x32_bf16 v[24:27], v[220:223], v[196:199], v[24:27]
	v_mfma_f32_16x16x32_bf16 v[16:19], v[212:215], v[204:207], v[16:19]
	v_mfma_f32_16x16x32_bf16 v[8:11], v[220:223], v[204:207], v[8:11]
	s_barrier
	s_add_i32 s100, 0, 0x18000
	ds_read_b128 v[140:143], v235 offset:32768
	ds_read_b128 v[144:147], v235 offset:33792
	ds_read_b128 v[152:155], v235 offset:34816
	ds_read_b128 v[156:159], v235 offset:35840
	s_mov_b32 m0, s29
	ds_read_b128 v[160:163], v150 offset:32768
	ds_read_b128 v[164:167], v150 offset:33792
	ds_read_b128 v[172:175], v150 offset:34816
	ds_read_b128 v[176:179], v150 offset:35840
	ds_read_b128 v[180:183], v150 offset:36864
	ds_read_b128 v[196:199], v150 offset:37888
	ds_read_b128 v[200:203], v150 offset:38912
	ds_read_b128 v[204:207], v150 offset:39936
	s_add_u32 vcc_lo, s4, s42
	s_addc_u32 vcc_hi, s5, s43
	global_load_lds_dwordx4 v136, vcc
	s_mov_b32 m0, s30
	s_add_u32 vcc_lo, s4, s50
	s_addc_u32 vcc_hi, s5, s51
	global_load_lds_dwordx4 v136, vcc
	s_waitcnt lgkmcnt(8)
	s_barrier
	s_waitcnt lgkmcnt(0)
	v_mfma_f32_16x16x32_bf16 v[132:135], v[140:143], v[160:163], v[132:135]
	v_mfma_f32_16x16x32_bf16 v[124:127], v[152:155], v[160:163], v[124:127]
	v_mfma_f32_16x16x32_bf16 v[116:119], v[140:143], v[172:175], v[116:119]
	v_mfma_f32_16x16x32_bf16 v[108:111], v[152:155], v[172:175], v[108:111]
	v_mfma_f32_16x16x32_bf16 v[100:103], v[140:143], v[180:183], v[100:103]
	v_mfma_f32_16x16x32_bf16 v[92:95], v[152:155], v[180:183], v[92:95]
	v_mfma_f32_16x16x32_bf16 v[84:87], v[140:143], v[200:203], v[84:87]
	v_mfma_f32_16x16x32_bf16 v[76:79], v[152:155], v[200:203], v[76:79]
	v_mfma_f32_16x16x32_bf16 v[132:135], v[144:147], v[164:167], v[132:135]
	v_mfma_f32_16x16x32_bf16 v[124:127], v[156:159], v[164:167], v[124:127]
	v_mfma_f32_16x16x32_bf16 v[116:119], v[144:147], v[176:179], v[116:119]
	v_mfma_f32_16x16x32_bf16 v[108:111], v[156:159], v[176:179], v[108:111]
	v_mfma_f32_16x16x32_bf16 v[100:103], v[144:147], v[196:199], v[100:103]
	v_mfma_f32_16x16x32_bf16 v[92:95], v[156:159], v[196:199], v[92:95]
	v_mfma_f32_16x16x32_bf16 v[84:87], v[144:147], v[204:207], v[84:87]
	v_mfma_f32_16x16x32_bf16 v[76:79], v[156:159], v[204:207], v[76:79]
	s_barrier
	s_add_i32 s5, 0, 0x1c000
	s_add_i32 s4, s100, s21
	s_mov_b32 m0, s4
	ds_read_b128 v[208:211], v235 offset:49152
	ds_read_b128 v[212:215], v235 offset:50176
	ds_read_b128 v[216:219], v235 offset:51200
	ds_read_b128 v[220:223], v235 offset:52224
	s_add_u32 vcc_lo, s40, s46
	s_addc_u32 vcc_hi, s41, s47
	global_load_lds_dwordx4 v2, vcc
	s_add_i32 m0, s4, 0x2000
	s_add_u32 vcc_lo, s40, s52
	s_addc_u32 vcc_hi, s41, s53
	global_load_lds_dwordx4 v2, vcc
	s_barrier
	s_waitcnt lgkmcnt(0)
	v_mfma_f32_16x16x32_bf16 v[128:131], v[208:211], v[160:163], v[128:131]
	v_mfma_f32_16x16x32_bf16 v[120:123], v[216:219], v[160:163], v[120:123]
	v_mfma_f32_16x16x32_bf16 v[112:115], v[208:211], v[172:175], v[112:115]
	v_mfma_f32_16x16x32_bf16 v[104:107], v[216:219], v[172:175], v[104:107]
	v_mfma_f32_16x16x32_bf16 v[96:99], v[208:211], v[180:183], v[96:99]
	v_mfma_f32_16x16x32_bf16 v[88:91], v[216:219], v[180:183], v[88:91]
	v_mfma_f32_16x16x32_bf16 v[80:83], v[208:211], v[200:203], v[80:83]
	v_mfma_f32_16x16x32_bf16 v[72:75], v[216:219], v[200:203], v[72:75]
	v_mfma_f32_16x16x32_bf16 v[128:131], v[212:215], v[164:167], v[128:131]
	v_mfma_f32_16x16x32_bf16 v[120:123], v[220:223], v[164:167], v[120:123]
	v_mfma_f32_16x16x32_bf16 v[112:115], v[212:215], v[176:179], v[112:115]
	v_mfma_f32_16x16x32_bf16 v[104:107], v[220:223], v[176:179], v[104:107]
	v_mfma_f32_16x16x32_bf16 v[96:99], v[212:215], v[196:199], v[96:99]
	v_mfma_f32_16x16x32_bf16 v[88:91], v[220:223], v[196:199], v[88:91]
	v_mfma_f32_16x16x32_bf16 v[80:83], v[212:215], v[204:207], v[80:83]
	v_mfma_f32_16x16x32_bf16 v[72:75], v[220:223], v[204:207], v[72:75]
	s_barrier
	s_mov_b32 m0, s31
	v_lshl_add_u64 v[226:227], v[224:225], 0, s[46:47]
	ds_read_b128 v[160:163], v150 offset:49152
	ds_read_b128 v[164:167], v150 offset:50176
	ds_read_b128 v[172:175], v150 offset:51200
	ds_read_b128 v[176:179], v150 offset:52224
	ds_read_b128 v[180:183], v150 offset:53248
	ds_read_b128 v[196:199], v150 offset:54272
	ds_read_b128 v[200:203], v150 offset:55296
	ds_read_b128 v[204:207], v150 offset:56320
	global_load_lds_dwordx4 v[226:227], off
	v_lshl_add_u64 v[224:225], v[224:225], 0, s[52:53]
	s_mov_b32 m0, s34
	s_nop 0
	global_load_lds_dwordx4 v[224:225], off
	s_barrier
	s_waitcnt lgkmcnt(0)
	v_mfma_f32_16x16x32_bf16 v[68:71], v[140:143], v[160:163], v[68:71]
	v_mfma_f32_16x16x32_bf16 v[60:63], v[152:155], v[160:163], v[60:63]
	v_mfma_f32_16x16x32_bf16 v[52:55], v[140:143], v[172:175], v[52:55]
	v_mfma_f32_16x16x32_bf16 v[44:47], v[152:155], v[172:175], v[44:47]
	v_mfma_f32_16x16x32_bf16 v[36:39], v[140:143], v[180:183], v[36:39]
	v_mfma_f32_16x16x32_bf16 v[28:31], v[152:155], v[180:183], v[28:31]
	v_mfma_f32_16x16x32_bf16 v[20:23], v[140:143], v[200:203], v[20:23]
	v_mfma_f32_16x16x32_bf16 v[12:15], v[152:155], v[200:203], v[12:15]
	v_mfma_f32_16x16x32_bf16 v[68:71], v[144:147], v[164:167], v[68:71]
	v_mfma_f32_16x16x32_bf16 v[60:63], v[156:159], v[164:167], v[60:63]
	v_mfma_f32_16x16x32_bf16 v[52:55], v[144:147], v[176:179], v[52:55]
	v_mfma_f32_16x16x32_bf16 v[44:47], v[156:159], v[176:179], v[44:47]
	v_mfma_f32_16x16x32_bf16 v[36:39], v[144:147], v[196:199], v[36:39]
	v_mfma_f32_16x16x32_bf16 v[28:31], v[156:159], v[196:199], v[28:31]
	v_mfma_f32_16x16x32_bf16 v[20:23], v[144:147], v[204:207], v[20:23]
	v_mfma_f32_16x16x32_bf16 v[12:15], v[156:159], v[204:207], v[12:15]
	s_barrier
	s_add_i32 s4, s5, s21
	s_mov_b32 m0, s4
	s_add_u32 vcc_lo, s40, s54
	s_addc_u32 vcc_hi, s41, s55
	global_load_lds_dwordx4 v2, vcc
	s_add_i32 m0, s4, 0x2000
	s_add_u32 vcc_lo, s40, s58
	s_addc_u32 vcc_hi, s41, s59
	global_load_lds_dwordx4 v2, vcc
	s_add_i32 s18, s18, 2
	s_add_u32 s2, s2, 0x100
	s_addc_u32 s3, s3, 0
	s_add_u32 s16, s16, 0x100
	s_addc_u32 s17, s17, 0
	s_cmp_gt_u32 s18, 13
	s_waitcnt vmcnt(6)
	s_barrier
	v_mfma_f32_16x16x32_bf16 v[64:67], v[208:211], v[160:163], v[64:67]
	v_mfma_f32_16x16x32_bf16 v[56:59], v[216:219], v[160:163], v[56:59]
	v_mfma_f32_16x16x32_bf16 v[48:51], v[208:211], v[172:175], v[48:51]
	v_mfma_f32_16x16x32_bf16 v[40:43], v[216:219], v[172:175], v[40:43]
	v_mfma_f32_16x16x32_bf16 v[32:35], v[208:211], v[180:183], v[32:35]
	v_mfma_f32_16x16x32_bf16 v[24:27], v[216:219], v[180:183], v[24:27]
	v_mfma_f32_16x16x32_bf16 v[16:19], v[208:211], v[200:203], v[16:19]
	v_mfma_f32_16x16x32_bf16 v[8:11], v[216:219], v[200:203], v[8:11]
	v_mfma_f32_16x16x32_bf16 v[64:67], v[212:215], v[164:167], v[64:67]
	v_mfma_f32_16x16x32_bf16 v[56:59], v[220:223], v[164:167], v[56:59]
	v_mfma_f32_16x16x32_bf16 v[48:51], v[212:215], v[176:179], v[48:51]
	v_mfma_f32_16x16x32_bf16 v[40:43], v[220:223], v[176:179], v[40:43]
	v_mfma_f32_16x16x32_bf16 v[32:35], v[212:215], v[196:199], v[32:35]
	v_mfma_f32_16x16x32_bf16 v[24:27], v[220:223], v[196:199], v[24:27]
	v_mfma_f32_16x16x32_bf16 v[16:19], v[212:215], v[204:207], v[16:19]
	v_mfma_f32_16x16x32_bf16 v[8:11], v[220:223], v[204:207], v[8:11]
	s_cbranch_scc0 .Ldb_FFI_cont
	s_branch .Ldb_FFI_xl
.LBB0_1120:
	s_add_u32 s4, s2, 0xfffc0080
	s_addc_u32 s5, s3, -1
	s_add_i32 s19, 0, 0x10000
	ds_read_b128 v[140:143], v235 offset:0
	ds_read_b128 v[144:147], v235 offset:1024
	ds_read_b128 v[152:155], v235 offset:2048
	ds_read_b128 v[156:159], v235 offset:3072
	s_cmp_eq_u32 s18, 12
	s_cselect_b32 s5, s13, s5
	s_cselect_b32 s4, s12, s4
	s_cselect_b32 s41, s15, s17
	s_cselect_b32 s40, s14, s16
	s_add_i32 m0, s26, 0xc000
	ds_read_b128 v[160:163], v150
	ds_read_b128 v[164:167], v150 offset:1024
	ds_read_b128 v[172:175], v150 offset:2048
	ds_read_b128 v[176:179], v150 offset:3072
	ds_read_b128 v[180:183], v150 offset:4096
	ds_read_b128 v[196:199], v150 offset:5120
	ds_read_b128 v[200:203], v150 offset:6144
	ds_read_b128 v[204:207], v150 offset:7168
	global_load_lds_dwordx4 v138, s[2:3]
	s_add_i32 m0, s26, 0xe000
	s_add_u32 vcc_lo, s2, s0
	s_addc_u32 vcc_hi, s3, s1
	global_load_lds_dwordx4 v138, vcc
	s_waitcnt lgkmcnt(8)
	s_barrier
	s_waitcnt lgkmcnt(0)
	v_mfma_f32_16x16x32_bf16 v[132:135], v[140:143], v[160:163], v[132:135]
	v_mfma_f32_16x16x32_bf16 v[124:127], v[152:155], v[160:163], v[124:127]
	v_mfma_f32_16x16x32_bf16 v[116:119], v[140:143], v[172:175], v[116:119]
	v_mfma_f32_16x16x32_bf16 v[108:111], v[152:155], v[172:175], v[108:111]
	v_mfma_f32_16x16x32_bf16 v[100:103], v[140:143], v[180:183], v[100:103]
	v_mfma_f32_16x16x32_bf16 v[92:95], v[152:155], v[180:183], v[92:95]
	v_mfma_f32_16x16x32_bf16 v[84:87], v[140:143], v[200:203], v[84:87]
	v_mfma_f32_16x16x32_bf16 v[76:79], v[152:155], v[200:203], v[76:79]
	v_mfma_f32_16x16x32_bf16 v[132:135], v[144:147], v[164:167], v[132:135]
	v_mfma_f32_16x16x32_bf16 v[124:127], v[156:159], v[164:167], v[124:127]
	v_mfma_f32_16x16x32_bf16 v[116:119], v[144:147], v[176:179], v[116:119]
	v_mfma_f32_16x16x32_bf16 v[108:111], v[156:159], v[176:179], v[108:111]
	v_mfma_f32_16x16x32_bf16 v[100:103], v[144:147], v[196:199], v[100:103]
	v_mfma_f32_16x16x32_bf16 v[92:95], v[156:159], v[196:199], v[92:95]
	v_mfma_f32_16x16x32_bf16 v[84:87], v[144:147], v[204:207], v[84:87]
	v_mfma_f32_16x16x32_bf16 v[76:79], v[156:159], v[204:207], v[76:79]
	s_barrier
	s_add_i32 s39, 0, 0x14000
	s_add_i32 s19, s19, s21
	s_mov_b32 m0, s19
	ds_read_b128 v[208:211], v235 offset:16384
	ds_read_b128 v[212:215], v235 offset:17408
	ds_read_b128 v[216:219], v235 offset:18432
	ds_read_b128 v[220:223], v235 offset:19456
	global_load_lds_dwordx4 v2, s[40:41]
	s_add_i32 m0, s19, 0x2000
	s_add_u32 vcc_lo, s40, s0
	s_addc_u32 vcc_hi, s41, s1
	global_load_lds_dwordx4 v2, vcc
	s_barrier
	s_waitcnt lgkmcnt(0)
	v_mfma_f32_16x16x32_bf16 v[128:131], v[208:211], v[160:163], v[128:131]
	v_mfma_f32_16x16x32_bf16 v[120:123], v[216:219], v[160:163], v[120:123]
	v_mfma_f32_16x16x32_bf16 v[112:115], v[208:211], v[172:175], v[112:115]
	v_mfma_f32_16x16x32_bf16 v[104:107], v[216:219], v[172:175], v[104:107]
	v_mfma_f32_16x16x32_bf16 v[96:99], v[208:211], v[180:183], v[96:99]
	v_mfma_f32_16x16x32_bf16 v[88:91], v[216:219], v[180:183], v[88:91]
	v_mfma_f32_16x16x32_bf16 v[80:83], v[208:211], v[200:203], v[80:83]
	v_mfma_f32_16x16x32_bf16 v[72:75], v[216:219], v[200:203], v[72:75]
	v_mfma_f32_16x16x32_bf16 v[128:131], v[212:215], v[164:167], v[128:131]
	v_mfma_f32_16x16x32_bf16 v[120:123], v[220:223], v[164:167], v[120:123]
	v_mfma_f32_16x16x32_bf16 v[112:115], v[212:215], v[176:179], v[112:115]
	v_mfma_f32_16x16x32_bf16 v[104:107], v[220:223], v[176:179], v[104:107]
	v_mfma_f32_16x16x32_bf16 v[96:99], v[212:215], v[196:199], v[96:99]
	v_mfma_f32_16x16x32_bf16 v[88:91], v[220:223], v[196:199], v[88:91]
	v_mfma_f32_16x16x32_bf16 v[80:83], v[212:215], v[204:207], v[80:83]
	v_mfma_f32_16x16x32_bf16 v[72:75], v[220:223], v[204:207], v[72:75]
	s_barrier
	s_mov_b32 m0, s26
	v_lshl_add_u64 v[224:225], s[4:5], 0, v[136:137]
	ds_read_b128 v[160:163], v150 offset:16384
	ds_read_b128 v[164:167], v150 offset:17408
	ds_read_b128 v[172:175], v150 offset:18432
	ds_read_b128 v[176:179], v150 offset:19456
	ds_read_b128 v[180:183], v150 offset:20480
	ds_read_b128 v[196:199], v150 offset:21504
	ds_read_b128 v[200:203], v150 offset:22528
	ds_read_b128 v[204:207], v150 offset:23552
	global_load_lds_dwordx4 v136, s[4:5]
	s_mov_b32 m0, s27
	s_add_u32 vcc_lo, s4, s0
	s_addc_u32 vcc_hi, s5, s1
	global_load_lds_dwordx4 v136, vcc
	s_barrier
	s_waitcnt lgkmcnt(0)
	v_mfma_f32_16x16x32_bf16 v[68:71], v[140:143], v[160:163], v[68:71]
	v_mfma_f32_16x16x32_bf16 v[60:63], v[152:155], v[160:163], v[60:63]
	v_mfma_f32_16x16x32_bf16 v[52:55], v[140:143], v[172:175], v[52:55]
	v_mfma_f32_16x16x32_bf16 v[44:47], v[152:155], v[172:175], v[44:47]
	v_mfma_f32_16x16x32_bf16 v[36:39], v[140:143], v[180:183], v[36:39]
	v_mfma_f32_16x16x32_bf16 v[28:31], v[152:155], v[180:183], v[28:31]
	v_mfma_f32_16x16x32_bf16 v[20:23], v[140:143], v[200:203], v[20:23]
	v_mfma_f32_16x16x32_bf16 v[12:15], v[152:155], v[200:203], v[12:15]
	v_mfma_f32_16x16x32_bf16 v[68:71], v[144:147], v[164:167], v[68:71]
	v_mfma_f32_16x16x32_bf16 v[60:63], v[156:159], v[164:167], v[60:63]
	v_mfma_f32_16x16x32_bf16 v[52:55], v[144:147], v[176:179], v[52:55]
	v_mfma_f32_16x16x32_bf16 v[44:47], v[156:159], v[176:179], v[44:47]
	v_mfma_f32_16x16x32_bf16 v[36:39], v[144:147], v[196:199], v[36:39]
	v_mfma_f32_16x16x32_bf16 v[28:31], v[156:159], v[196:199], v[28:31]
	v_mfma_f32_16x16x32_bf16 v[20:23], v[144:147], v[204:207], v[20:23]
	v_mfma_f32_16x16x32_bf16 v[12:15], v[156:159], v[204:207], v[12:15]
	s_barrier
	s_add_i32 s100, s39, s21
	s_mov_b32 m0, s100
	s_add_u32 vcc_lo, s40, s42
	s_addc_u32 vcc_hi, s41, s43
	global_load_lds_dwordx4 v2, vcc
	s_add_i32 m0, s100, 0x2000
	s_add_u32 vcc_lo, s40, s50
	s_addc_u32 vcc_hi, s41, s51
	global_load_lds_dwordx4 v2, vcc
	s_waitcnt vmcnt(6)
	s_barrier
	v_mfma_f32_16x16x32_bf16 v[64:67], v[208:211], v[160:163], v[64:67]
	v_mfma_f32_16x16x32_bf16 v[56:59], v[216:219], v[160:163], v[56:59]
	v_mfma_f32_16x16x32_bf16 v[48:51], v[208:211], v[172:175], v[48:51]
	v_mfma_f32_16x16x32_bf16 v[40:43], v[216:219], v[172:175], v[40:43]
	v_mfma_f32_16x16x32_bf16 v[32:35], v[208:211], v[180:183], v[32:35]
	v_mfma_f32_16x16x32_bf16 v[24:27], v[216:219], v[180:183], v[24:27]
	v_mfma_f32_16x16x32_bf16 v[16:19], v[208:211], v[200:203], v[16:19]
	v_mfma_f32_16x16x32_bf16 v[8:11], v[216:219], v[200:203], v[8:11]
	v_mfma_f32_16x16x32_bf16 v[64:67], v[212:215], v[164:167], v[64:67]
	v_mfma_f32_16x16x32_bf16 v[56:59], v[220:223], v[164:167], v[56:59]
	v_mfma_f32_16x16x32_bf16 v[48:51], v[212:215], v[176:179], v[48:51]
	v_mfma_f32_16x16x32_bf16 v[40:43], v[220:223], v[176:179], v[40:43]
	v_mfma_f32_16x16x32_bf16 v[32:35], v[212:215], v[196:199], v[32:35]
	v_mfma_f32_16x16x32_bf16 v[24:27], v[220:223], v[196:199], v[24:27]
	v_mfma_f32_16x16x32_bf16 v[16:19], v[212:215], v[204:207], v[16:19]
	v_mfma_f32_16x16x32_bf16 v[8:11], v[220:223], v[204:207], v[8:11]
	s_barrier
	s_add_i32 s100, 0, 0x18000
	ds_read_b128 v[140:143], v235 offset:32768
	ds_read_b128 v[144:147], v235 offset:33792
	ds_read_b128 v[152:155], v235 offset:34816
	ds_read_b128 v[156:159], v235 offset:35840
	s_mov_b32 m0, s29
	ds_read_b128 v[160:163], v150 offset:32768
	ds_read_b128 v[164:167], v150 offset:33792
	ds_read_b128 v[172:175], v150 offset:34816
	ds_read_b128 v[176:179], v150 offset:35840
	ds_read_b128 v[180:183], v150 offset:36864
	ds_read_b128 v[196:199], v150 offset:37888
	ds_read_b128 v[200:203], v150 offset:38912
	ds_read_b128 v[204:207], v150 offset:39936
	s_add_u32 vcc_lo, s4, s42
	s_addc_u32 vcc_hi, s5, s43
	global_load_lds_dwordx4 v136, vcc
	s_mov_b32 m0, s30
	s_add_u32 vcc_lo, s4, s50
	s_addc_u32 vcc_hi, s5, s51
	global_load_lds_dwordx4 v136, vcc
	s_waitcnt lgkmcnt(8)
	s_barrier
	s_waitcnt lgkmcnt(0)
	v_mfma_f32_16x16x32_bf16 v[132:135], v[140:143], v[160:163], v[132:135]
	v_mfma_f32_16x16x32_bf16 v[124:127], v[152:155], v[160:163], v[124:127]
	v_mfma_f32_16x16x32_bf16 v[116:119], v[140:143], v[172:175], v[116:119]
	v_mfma_f32_16x16x32_bf16 v[108:111], v[152:155], v[172:175], v[108:111]
	v_mfma_f32_16x16x32_bf16 v[100:103], v[140:143], v[180:183], v[100:103]
	v_mfma_f32_16x16x32_bf16 v[92:95], v[152:155], v[180:183], v[92:95]
	v_mfma_f32_16x16x32_bf16 v[84:87], v[140:143], v[200:203], v[84:87]
	v_mfma_f32_16x16x32_bf16 v[76:79], v[152:155], v[200:203], v[76:79]
	v_mfma_f32_16x16x32_bf16 v[132:135], v[144:147], v[164:167], v[132:135]
	v_mfma_f32_16x16x32_bf16 v[124:127], v[156:159], v[164:167], v[124:127]
	v_mfma_f32_16x16x32_bf16 v[116:119], v[144:147], v[176:179], v[116:119]
	v_mfma_f32_16x16x32_bf16 v[108:111], v[156:159], v[176:179], v[108:111]
	v_mfma_f32_16x16x32_bf16 v[100:103], v[144:147], v[196:199], v[100:103]
	v_mfma_f32_16x16x32_bf16 v[92:95], v[156:159], v[196:199], v[92:95]
	v_mfma_f32_16x16x32_bf16 v[84:87], v[144:147], v[204:207], v[84:87]
	v_mfma_f32_16x16x32_bf16 v[76:79], v[156:159], v[204:207], v[76:79]
	s_barrier
	s_add_i32 s5, 0, 0x1c000
	s_add_i32 s4, s100, s21
	s_mov_b32 m0, s4
	ds_read_b128 v[208:211], v235 offset:49152
	ds_read_b128 v[212:215], v235 offset:50176
	ds_read_b128 v[216:219], v235 offset:51200
	ds_read_b128 v[220:223], v235 offset:52224
	s_add_u32 vcc_lo, s40, s46
	s_addc_u32 vcc_hi, s41, s47
	global_load_lds_dwordx4 v2, vcc
	s_add_i32 m0, s4, 0x2000
	s_add_u32 vcc_lo, s40, s52
	s_addc_u32 vcc_hi, s41, s53
	global_load_lds_dwordx4 v2, vcc
	s_barrier
	s_waitcnt lgkmcnt(0)
	v_mfma_f32_16x16x32_bf16 v[128:131], v[208:211], v[160:163], v[128:131]
	v_mfma_f32_16x16x32_bf16 v[120:123], v[216:219], v[160:163], v[120:123]
	v_mfma_f32_16x16x32_bf16 v[112:115], v[208:211], v[172:175], v[112:115]
	v_mfma_f32_16x16x32_bf16 v[104:107], v[216:219], v[172:175], v[104:107]
	v_mfma_f32_16x16x32_bf16 v[96:99], v[208:211], v[180:183], v[96:99]
	v_mfma_f32_16x16x32_bf16 v[88:91], v[216:219], v[180:183], v[88:91]
	v_mfma_f32_16x16x32_bf16 v[80:83], v[208:211], v[200:203], v[80:83]
	v_mfma_f32_16x16x32_bf16 v[72:75], v[216:219], v[200:203], v[72:75]
	v_mfma_f32_16x16x32_bf16 v[128:131], v[212:215], v[164:167], v[128:131]
	v_mfma_f32_16x16x32_bf16 v[120:123], v[220:223], v[164:167], v[120:123]
	v_mfma_f32_16x16x32_bf16 v[112:115], v[212:215], v[176:179], v[112:115]
	v_mfma_f32_16x16x32_bf16 v[104:107], v[220:223], v[176:179], v[104:107]
	v_mfma_f32_16x16x32_bf16 v[96:99], v[212:215], v[196:199], v[96:99]
	v_mfma_f32_16x16x32_bf16 v[88:91], v[220:223], v[196:199], v[88:91]
	v_mfma_f32_16x16x32_bf16 v[80:83], v[212:215], v[204:207], v[80:83]
	v_mfma_f32_16x16x32_bf16 v[72:75], v[220:223], v[204:207], v[72:75]
	s_barrier
	s_mov_b32 m0, s31
	v_lshl_add_u64 v[226:227], v[224:225], 0, s[46:47]
	ds_read_b128 v[160:163], v150 offset:49152
	ds_read_b128 v[164:167], v150 offset:50176
	ds_read_b128 v[172:175], v150 offset:51200
	ds_read_b128 v[176:179], v150 offset:52224
	ds_read_b128 v[180:183], v150 offset:53248
	ds_read_b128 v[196:199], v150 offset:54272
	ds_read_b128 v[200:203], v150 offset:55296
	ds_read_b128 v[204:207], v150 offset:56320
	global_load_lds_dwordx4 v[226:227], off
	v_lshl_add_u64 v[224:225], v[224:225], 0, s[52:53]
	s_mov_b32 m0, s34
	s_nop 0
	global_load_lds_dwordx4 v[224:225], off
	s_barrier
	s_waitcnt lgkmcnt(0)
	v_mfma_f32_16x16x32_bf16 v[68:71], v[140:143], v[160:163], v[68:71]
	v_mfma_f32_16x16x32_bf16 v[60:63], v[152:155], v[160:163], v[60:63]
	v_mfma_f32_16x16x32_bf16 v[52:55], v[140:143], v[172:175], v[52:55]
	v_mfma_f32_16x16x32_bf16 v[44:47], v[152:155], v[172:175], v[44:47]
	v_mfma_f32_16x16x32_bf16 v[36:39], v[140:143], v[180:183], v[36:39]
	v_mfma_f32_16x16x32_bf16 v[28:31], v[152:155], v[180:183], v[28:31]
	v_mfma_f32_16x16x32_bf16 v[20:23], v[140:143], v[200:203], v[20:23]
	v_mfma_f32_16x16x32_bf16 v[12:15], v[152:155], v[200:203], v[12:15]
	v_mfma_f32_16x16x32_bf16 v[68:71], v[144:147], v[164:167], v[68:71]
	v_mfma_f32_16x16x32_bf16 v[60:63], v[156:159], v[164:167], v[60:63]
	v_mfma_f32_16x16x32_bf16 v[52:55], v[144:147], v[176:179], v[52:55]
	v_mfma_f32_16x16x32_bf16 v[44:47], v[156:159], v[176:179], v[44:47]
	v_mfma_f32_16x16x32_bf16 v[36:39], v[144:147], v[196:199], v[36:39]
	v_mfma_f32_16x16x32_bf16 v[28:31], v[156:159], v[196:199], v[28:31]
	v_mfma_f32_16x16x32_bf16 v[20:23], v[144:147], v[204:207], v[20:23]
	v_mfma_f32_16x16x32_bf16 v[12:15], v[156:159], v[204:207], v[12:15]
	s_barrier
	s_add_i32 s4, s5, s21
	s_mov_b32 m0, s4
	s_add_u32 vcc_lo, s40, s54
	s_addc_u32 vcc_hi, s41, s55
	global_load_lds_dwordx4 v2, vcc
	s_add_i32 m0, s4, 0x2000
	s_add_u32 vcc_lo, s40, s58
	s_addc_u32 vcc_hi, s41, s59
	global_load_lds_dwordx4 v2, vcc
	s_add_i32 s18, s18, 2
	s_add_u32 s2, s2, 0x100
	s_addc_u32 s3, s3, 0
	s_add_u32 s16, s16, 0x100
	s_addc_u32 s17, s17, 0
	s_cmp_gt_u32 s18, 13
	s_waitcnt vmcnt(6)
	s_barrier
	v_mfma_f32_16x16x32_bf16 v[64:67], v[208:211], v[160:163], v[64:67]
	v_mfma_f32_16x16x32_bf16 v[56:59], v[216:219], v[160:163], v[56:59]
	v_mfma_f32_16x16x32_bf16 v[48:51], v[208:211], v[172:175], v[48:51]
	v_mfma_f32_16x16x32_bf16 v[40:43], v[216:219], v[172:175], v[40:43]
	v_mfma_f32_16x16x32_bf16 v[32:35], v[208:211], v[180:183], v[32:35]
	v_mfma_f32_16x16x32_bf16 v[24:27], v[216:219], v[180:183], v[24:27]
	v_mfma_f32_16x16x32_bf16 v[16:19], v[208:211], v[200:203], v[16:19]
	v_mfma_f32_16x16x32_bf16 v[8:11], v[216:219], v[200:203], v[8:11]
	v_mfma_f32_16x16x32_bf16 v[64:67], v[212:215], v[164:167], v[64:67]
	v_mfma_f32_16x16x32_bf16 v[56:59], v[220:223], v[164:167], v[56:59]
	v_mfma_f32_16x16x32_bf16 v[48:51], v[212:215], v[176:179], v[48:51]
	v_mfma_f32_16x16x32_bf16 v[40:43], v[220:223], v[176:179], v[40:43]
	v_mfma_f32_16x16x32_bf16 v[32:35], v[212:215], v[196:199], v[32:35]
	v_mfma_f32_16x16x32_bf16 v[24:27], v[220:223], v[196:199], v[24:27]
	v_mfma_f32_16x16x32_bf16 v[16:19], v[212:215], v[204:207], v[16:19]
	v_mfma_f32_16x16x32_bf16 v[8:11], v[220:223], v[204:207], v[8:11]
	s_cbranch_scc0 .Ldb_FFI_cont

.LBB0_1184:
	s_add_u32 s2, s2, 0xb0080
	s_addc_u32 s3, s3, 0
	s_add_u32 s6, s6, 0x100
	s_waitcnt lgkmcnt(0)
	s_addc_u32 s7, s7, 0
	s_mov_b32 s21, -2
	s_mov_b64 s[52:53], 0xb0080
	s_mov_b64 s[54:55], 0x108080
	s_cmp_eq_u32 s101, 2
	s_cselect_b32 s101, 0, s101
	s_setprio 0
	v_add_u32_e32 v255, 0x10000, v185
	s_add_u32 s4, s2, 0xfff50080
	s_addc_u32 s5, s3, -1
	s_add_i32 s33, 0, 0x10000
	ds_read_b128 v[136:139], v255 offset:0
	ds_read_b128 v[140:143], v255 offset:1024
	ds_read_b128 v[144:147], v255 offset:2048
	ds_read_b128 v[148:151], v255 offset:3072
	s_cmp_eq_u32 s21, 40
	s_cselect_b32 s5, s17, s5
	s_cselect_b32 s4, s16, s4
	s_cselect_b32 s23, s19, s7
	s_cselect_b32 s22, s18, s6
	s_add_i32 m0, s26, 0xc000
	ds_read_b128 v[152:155], v195
	ds_read_b128 v[156:159], v195 offset:1024
	ds_read_b128 v[160:163], v195 offset:2048
	ds_read_b128 v[164:167], v195 offset:3072
	ds_read_b128 v[176:179], v195 offset:4096
	ds_read_b128 v[180:183], v195 offset:5120
	ds_read_b128 v[196:199], v195 offset:6144
	ds_read_b128 v[200:203], v195 offset:7168
	global_load_lds_dwordx4 v174, s[2:3]
	s_add_i32 m0, s26, 0xe000
	s_add_u32 vcc_lo, s2, s86
	s_addc_u32 vcc_hi, s3, s87
	global_load_lds_dwordx4 v174, vcc
	s_waitcnt lgkmcnt(8)
	s_cmp_eq_u32 s101, 1
	s_cbranch_scc1 .Ldb_FFO_skp
	s_barrier
.Ldb_FFO_skp:
	s_mov_b32 s101, 0
	s_waitcnt lgkmcnt(0)
	v_mfma_f32_16x16x32_bf16 v[132:135], v[136:139], v[152:155], 0
	v_mfma_f32_16x16x32_bf16 v[128:131], v[144:147], v[152:155], 0
	v_mfma_f32_16x16x32_bf16 v[116:119], v[136:139], v[160:163], 0
	v_mfma_f32_16x16x32_bf16 v[112:115], v[144:147], v[160:163], 0
	v_mfma_f32_16x16x32_bf16 v[100:103], v[136:139], v[176:179], 0
	v_mfma_f32_16x16x32_bf16 v[96:99], v[144:147], v[176:179], 0
	v_mfma_f32_16x16x32_bf16 v[84:87], v[136:139], v[196:199], 0
	v_mfma_f32_16x16x32_bf16 v[80:83], v[144:147], v[196:199], 0
	v_mfma_f32_16x16x32_bf16 v[132:135], v[140:143], v[156:159], v[132:135]
	v_mfma_f32_16x16x32_bf16 v[128:131], v[148:151], v[156:159], v[128:131]
	v_mfma_f32_16x16x32_bf16 v[116:119], v[140:143], v[164:167], v[116:119]
	v_mfma_f32_16x16x32_bf16 v[112:115], v[148:151], v[164:167], v[112:115]
	v_mfma_f32_16x16x32_bf16 v[100:103], v[140:143], v[180:183], v[100:103]
	v_mfma_f32_16x16x32_bf16 v[96:99], v[148:151], v[180:183], v[96:99]
	v_mfma_f32_16x16x32_bf16 v[84:87], v[140:143], v[200:203], v[84:87]
	v_mfma_f32_16x16x32_bf16 v[80:83], v[148:151], v[200:203], v[80:83]
	s_barrier
	s_add_i32 s44, 0, 0x14000
	s_add_i32 s100, s33, s25
	s_mov_b32 m0, s100
	ds_read_b128 v[204:207], v255 offset:16384
	ds_read_b128 v[208:211], v255 offset:17408
	ds_read_b128 v[212:215], v255 offset:18432
	ds_read_b128 v[216:219], v255 offset:19456
	global_load_lds_dwordx4 v172, s[22:23]
	s_add_i32 m0, s100, 0x2000
	s_add_u32 vcc_lo, s22, s86
	s_addc_u32 vcc_hi, s23, s87
	global_load_lds_dwordx4 v172, vcc
	s_barrier
	s_waitcnt lgkmcnt(0)
	v_mfma_f32_16x16x32_bf16 v[124:127], v[204:207], v[152:155], 0
	v_mfma_f32_16x16x32_bf16 v[120:123], v[212:215], v[152:155], 0
	v_mfma_f32_16x16x32_bf16 v[108:111], v[204:207], v[160:163], 0
	v_mfma_f32_16x16x32_bf16 v[104:107], v[212:215], v[160:163], 0
	v_mfma_f32_16x16x32_bf16 v[92:95], v[204:207], v[176:179], 0
	v_mfma_f32_16x16x32_bf16 v[88:91], v[212:215], v[176:179], 0
	v_mfma_f32_16x16x32_bf16 v[76:79], v[204:207], v[196:199], 0
	v_mfma_f32_16x16x32_bf16 v[72:75], v[212:215], v[196:199], 0
	v_mfma_f32_16x16x32_bf16 v[124:127], v[208:211], v[156:159], v[124:127]
	v_mfma_f32_16x16x32_bf16 v[120:123], v[216:219], v[156:159], v[120:123]
	v_mfma_f32_16x16x32_bf16 v[108:111], v[208:211], v[164:167], v[108:111]
	v_mfma_f32_16x16x32_bf16 v[104:107], v[216:219], v[164:167], v[104:107]
	v_mfma_f32_16x16x32_bf16 v[92:95], v[208:211], v[180:183], v[92:95]
	v_mfma_f32_16x16x32_bf16 v[88:91], v[216:219], v[180:183], v[88:91]
	v_mfma_f32_16x16x32_bf16 v[76:79], v[208:211], v[200:203], v[76:79]
	v_mfma_f32_16x16x32_bf16 v[72:75], v[216:219], v[200:203], v[72:75]
	s_barrier
	s_mov_b32 m0, s26
	v_lshl_add_u64 v[222:223], s[4:5], 0, v[2:3]
	ds_read_b128 v[152:155], v195 offset:16384
	ds_read_b128 v[156:159], v195 offset:17408
	ds_read_b128 v[160:163], v195 offset:18432
	ds_read_b128 v[164:167], v195 offset:19456
	ds_read_b128 v[176:179], v195 offset:20480
	ds_read_b128 v[180:183], v195 offset:21504
	ds_read_b128 v[196:199], v195 offset:22528
	ds_read_b128 v[200:203], v195 offset:23552
	global_load_lds_dwordx4 v2, s[4:5]
	s_mov_b32 m0, s27
	s_add_u32 vcc_lo, s4, s86
	s_addc_u32 vcc_hi, s5, s87
	global_load_lds_dwordx4 v2, vcc
	s_barrier
	s_waitcnt lgkmcnt(0)
	v_mfma_f32_16x16x32_bf16 v[68:71], v[136:139], v[152:155], 0
	v_mfma_f32_16x16x32_bf16 v[64:67], v[144:147], v[152:155], 0
	v_mfma_f32_16x16x32_bf16 v[52:55], v[136:139], v[160:163], 0
	v_mfma_f32_16x16x32_bf16 v[48:51], v[144:147], v[160:163], 0
	v_mfma_f32_16x16x32_bf16 v[36:39], v[136:139], v[176:179], 0
	v_mfma_f32_16x16x32_bf16 v[32:35], v[144:147], v[176:179], 0
	v_mfma_f32_16x16x32_bf16 v[20:23], v[136:139], v[196:199], 0
	v_mfma_f32_16x16x32_bf16 v[16:19], v[144:147], v[196:199], 0
	v_mfma_f32_16x16x32_bf16 v[68:71], v[140:143], v[156:159], v[68:71]
	v_mfma_f32_16x16x32_bf16 v[64:67], v[148:151], v[156:159], v[64:67]
	v_mfma_f32_16x16x32_bf16 v[52:55], v[140:143], v[164:167], v[52:55]
	v_mfma_f32_16x16x32_bf16 v[48:51], v[148:151], v[164:167], v[48:51]
	v_mfma_f32_16x16x32_bf16 v[36:39], v[140:143], v[180:183], v[36:39]
	v_mfma_f32_16x16x32_bf16 v[32:35], v[148:151], v[180:183], v[32:35]
	v_mfma_f32_16x16x32_bf16 v[20:23], v[140:143], v[200:203], v[20:23]
	v_mfma_f32_16x16x32_bf16 v[16:19], v[148:151], v[200:203], v[16:19]
	s_barrier
	s_add_i32 s100, s44, s25
	s_mov_b32 m0, s100
	s_add_u32 vcc_lo, s22, s88
	s_addc_u32 vcc_hi, s23, s89
	global_load_lds_dwordx4 v172, vcc
	s_add_i32 m0, s100, 0x2000
	s_add_u32 vcc_lo, s22, s64
	s_addc_u32 vcc_hi, s23, s65
	global_load_lds_dwordx4 v172, vcc
	s_waitcnt vmcnt(6)
	s_barrier
	v_mfma_f32_16x16x32_bf16 v[60:63], v[204:207], v[152:155], 0
	v_mfma_f32_16x16x32_bf16 v[56:59], v[212:215], v[152:155], 0
	v_mfma_f32_16x16x32_bf16 v[44:47], v[204:207], v[160:163], 0
	v_mfma_f32_16x16x32_bf16 v[40:43], v[212:215], v[160:163], 0
	v_mfma_f32_16x16x32_bf16 v[28:31], v[204:207], v[176:179], 0
	v_mfma_f32_16x16x32_bf16 v[24:27], v[212:215], v[176:179], 0
	v_mfma_f32_16x16x32_bf16 v[12:15], v[204:207], v[196:199], 0
	v_mfma_f32_16x16x32_bf16 v[8:11], v[212:215], v[196:199], 0
	v_mfma_f32_16x16x32_bf16 v[60:63], v[208:211], v[156:159], v[60:63]
	v_mfma_f32_16x16x32_bf16 v[56:59], v[216:219], v[156:159], v[56:59]
	v_mfma_f32_16x16x32_bf16 v[44:47], v[208:211], v[164:167], v[44:47]
	v_mfma_f32_16x16x32_bf16 v[40:43], v[216:219], v[164:167], v[40:43]
	v_mfma_f32_16x16x32_bf16 v[28:31], v[208:211], v[180:183], v[28:31]
	v_mfma_f32_16x16x32_bf16 v[24:27], v[216:219], v[180:183], v[24:27]
	v_mfma_f32_16x16x32_bf16 v[12:15], v[208:211], v[200:203], v[12:15]
	v_mfma_f32_16x16x32_bf16 v[8:11], v[216:219], v[200:203], v[8:11]
	s_barrier
	s_add_i32 s100, 0, 0x18000
	ds_read_b128 v[136:139], v255 offset:32768
	ds_read_b128 v[140:143], v255 offset:33792
	ds_read_b128 v[144:147], v255 offset:34816
	ds_read_b128 v[148:151], v255 offset:35840
	s_mov_b32 m0, s29
	ds_read_b128 v[152:155], v195 offset:32768
	ds_read_b128 v[156:159], v195 offset:33792
	ds_read_b128 v[160:163], v195 offset:34816
	ds_read_b128 v[164:167], v195 offset:35840
	ds_read_b128 v[176:179], v195 offset:36864
	ds_read_b128 v[180:183], v195 offset:37888
	ds_read_b128 v[196:199], v195 offset:38912
	ds_read_b128 v[200:203], v195 offset:39936
	s_add_u32 vcc_lo, s4, s88
	s_addc_u32 vcc_hi, s5, s89
	global_load_lds_dwordx4 v2, vcc
	s_mov_b32 m0, s30
	s_add_u32 vcc_lo, s4, s64
	s_addc_u32 vcc_hi, s5, s65
	global_load_lds_dwordx4 v2, vcc
	s_waitcnt lgkmcnt(8)
	s_barrier
	s_waitcnt lgkmcnt(0)
	v_mfma_f32_16x16x32_bf16 v[132:135], v[136:139], v[152:155], v[132:135]
	v_mfma_f32_16x16x32_bf16 v[128:131], v[144:147], v[152:155], v[128:131]
	v_mfma_f32_16x16x32_bf16 v[116:119], v[136:139], v[160:163], v[116:119]
	v_mfma_f32_16x16x32_bf16 v[112:115], v[144:147], v[160:163], v[112:115]
	v_mfma_f32_16x16x32_bf16 v[100:103], v[136:139], v[176:179], v[100:103]
	v_mfma_f32_16x16x32_bf16 v[96:99], v[144:147], v[176:179], v[96:99]
	v_mfma_f32_16x16x32_bf16 v[84:87], v[136:139], v[196:199], v[84:87]
	v_mfma_f32_16x16x32_bf16 v[80:83], v[144:147], v[196:199], v[80:83]
	v_mfma_f32_16x16x32_bf16 v[132:135], v[140:143], v[156:159], v[132:135]
	v_mfma_f32_16x16x32_bf16 v[128:131], v[148:151], v[156:159], v[128:131]
	v_mfma_f32_16x16x32_bf16 v[116:119], v[140:143], v[164:167], v[116:119]
	v_mfma_f32_16x16x32_bf16 v[112:115], v[148:151], v[164:167], v[112:115]
	v_mfma_f32_16x16x32_bf16 v[100:103], v[140:143], v[180:183], v[100:103]
	v_mfma_f32_16x16x32_bf16 v[96:99], v[148:151], v[180:183], v[96:99]
	v_mfma_f32_16x16x32_bf16 v[84:87], v[140:143], v[200:203], v[84:87]
	v_mfma_f32_16x16x32_bf16 v[80:83], v[148:151], v[200:203], v[80:83]
	s_barrier
	s_add_i32 s5, 0, 0x1c000
	s_add_i32 s4, s100, s25
	s_mov_b32 m0, s4
	ds_read_b128 v[204:207], v255 offset:49152
	ds_read_b128 v[208:211], v255 offset:50176
	ds_read_b128 v[212:215], v255 offset:51200
	ds_read_b128 v[216:219], v255 offset:52224
	s_add_u32 vcc_lo, s22, s46
	s_addc_u32 vcc_hi, s23, s47
	global_load_lds_dwordx4 v172, vcc
	s_add_i32 m0, s4, 0x2000
	s_add_u32 vcc_lo, s22, s66
	s_addc_u32 vcc_hi, s23, s67
	global_load_lds_dwordx4 v172, vcc
	s_barrier
	s_waitcnt lgkmcnt(0)
	v_mfma_f32_16x16x32_bf16 v[124:127], v[204:207], v[152:155], v[124:127]
	v_mfma_f32_16x16x32_bf16 v[120:123], v[212:215], v[152:155], v[120:123]
	v_mfma_f32_16x16x32_bf16 v[108:111], v[204:207], v[160:163], v[108:111]
	v_mfma_f32_16x16x32_bf16 v[104:107], v[212:215], v[160:163], v[104:107]
	v_mfma_f32_16x16x32_bf16 v[92:95], v[204:207], v[176:179], v[92:95]
	v_mfma_f32_16x16x32_bf16 v[88:91], v[212:215], v[176:179], v[88:91]
	v_mfma_f32_16x16x32_bf16 v[76:79], v[204:207], v[196:199], v[76:79]
	v_mfma_f32_16x16x32_bf16 v[72:75], v[212:215], v[196:199], v[72:75]
	v_mfma_f32_16x16x32_bf16 v[124:127], v[208:211], v[156:159], v[124:127]
	v_mfma_f32_16x16x32_bf16 v[120:123], v[216:219], v[156:159], v[120:123]
	v_mfma_f32_16x16x32_bf16 v[108:111], v[208:211], v[164:167], v[108:111]
	v_mfma_f32_16x16x32_bf16 v[104:107], v[216:219], v[164:167], v[104:107]
	v_mfma_f32_16x16x32_bf16 v[92:95], v[208:211], v[180:183], v[92:95]
	v_mfma_f32_16x16x32_bf16 v[88:91], v[216:219], v[180:183], v[88:91]
	v_mfma_f32_16x16x32_bf16 v[76:79], v[208:211], v[200:203], v[76:79]
	v_mfma_f32_16x16x32_bf16 v[72:75], v[216:219], v[200:203], v[72:75]
	s_barrier
	s_mov_b32 m0, s31
	v_lshl_add_u64 v[224:225], v[222:223], 0, s[46:47]
	ds_read_b128 v[152:155], v195 offset:49152
	ds_read_b128 v[156:159], v195 offset:50176
	ds_read_b128 v[160:163], v195 offset:51200
	ds_read_b128 v[164:167], v195 offset:52224
	ds_read_b128 v[176:179], v195 offset:53248
	ds_read_b128 v[180:183], v195 offset:54272
	ds_read_b128 v[196:199], v195 offset:55296
	ds_read_b128 v[200:203], v195 offset:56320
	global_load_lds_dwordx4 v[224:225], off
	v_lshl_add_u64 v[222:223], v[222:223], 0, s[66:67]
	s_mov_b32 m0, s34
	s_nop 0
	global_load_lds_dwordx4 v[222:223], off
	s_barrier
	s_waitcnt lgkmcnt(0)
	v_mfma_f32_16x16x32_bf16 v[68:71], v[136:139], v[152:155], v[68:71]
	v_mfma_f32_16x16x32_bf16 v[64:67], v[144:147], v[152:155], v[64:67]
	v_mfma_f32_16x16x32_bf16 v[52:55], v[136:139], v[160:163], v[52:55]
	v_mfma_f32_16x16x32_bf16 v[48:51], v[144:147], v[160:163], v[48:51]
	v_mfma_f32_16x16x32_bf16 v[36:39], v[136:139], v[176:179], v[36:39]
	v_mfma_f32_16x16x32_bf16 v[32:35], v[144:147], v[176:179], v[32:35]
	v_mfma_f32_16x16x32_bf16 v[20:23], v[136:139], v[196:199], v[20:23]
	v_mfma_f32_16x16x32_bf16 v[16:19], v[144:147], v[196:199], v[16:19]
	v_mfma_f32_16x16x32_bf16 v[68:71], v[140:143], v[156:159], v[68:71]
	v_mfma_f32_16x16x32_bf16 v[64:67], v[148:151], v[156:159], v[64:67]
	v_mfma_f32_16x16x32_bf16 v[52:55], v[140:143], v[164:167], v[52:55]
	v_mfma_f32_16x16x32_bf16 v[48:51], v[148:151], v[164:167], v[48:51]
	v_mfma_f32_16x16x32_bf16 v[36:39], v[140:143], v[180:183], v[36:39]
	v_mfma_f32_16x16x32_bf16 v[32:35], v[148:151], v[180:183], v[32:35]
	v_mfma_f32_16x16x32_bf16 v[20:23], v[140:143], v[200:203], v[20:23]
	v_mfma_f32_16x16x32_bf16 v[16:19], v[148:151], v[200:203], v[16:19]
	s_barrier
	s_add_i32 s4, s5, s25
	s_mov_b32 m0, s4
	s_add_u32 vcc_lo, s22, s52
	s_addc_u32 vcc_hi, s23, s53
	global_load_lds_dwordx4 v172, vcc
	s_add_i32 m0, s4, 0x2000
	s_add_u32 vcc_lo, s22, s54
	s_addc_u32 vcc_hi, s23, s55
	global_load_lds_dwordx4 v172, vcc
	s_add_i32 s21, s21, 2
	s_add_u32 s2, s2, 0x100
	s_addc_u32 s3, s3, 0
	s_add_u32 s6, s6, 0x100
	s_addc_u32 s7, s7, 0
	s_cmp_gt_u32 s21, 41
	s_waitcnt vmcnt(6)
	s_barrier
	v_mfma_f32_16x16x32_bf16 v[60:63], v[204:207], v[152:155], v[60:63]
	v_mfma_f32_16x16x32_bf16 v[56:59], v[212:215], v[152:155], v[56:59]
	v_mfma_f32_16x16x32_bf16 v[44:47], v[204:207], v[160:163], v[44:47]
	v_mfma_f32_16x16x32_bf16 v[40:43], v[212:215], v[160:163], v[40:43]
	v_mfma_f32_16x16x32_bf16 v[28:31], v[204:207], v[176:179], v[28:31]
	v_mfma_f32_16x16x32_bf16 v[24:27], v[212:215], v[176:179], v[24:27]
	v_mfma_f32_16x16x32_bf16 v[12:15], v[204:207], v[196:199], v[12:15]
	v_mfma_f32_16x16x32_bf16 v[8:11], v[212:215], v[196:199], v[8:11]
	v_mfma_f32_16x16x32_bf16 v[60:63], v[208:211], v[156:159], v[60:63]
	v_mfma_f32_16x16x32_bf16 v[56:59], v[216:219], v[156:159], v[56:59]
	v_mfma_f32_16x16x32_bf16 v[44:47], v[208:211], v[164:167], v[44:47]
	v_mfma_f32_16x16x32_bf16 v[40:43], v[216:219], v[164:167], v[40:43]
	v_mfma_f32_16x16x32_bf16 v[28:31], v[208:211], v[180:183], v[28:31]
	v_mfma_f32_16x16x32_bf16 v[24:27], v[216:219], v[180:183], v[24:27]
	v_mfma_f32_16x16x32_bf16 v[12:15], v[208:211], v[200:203], v[12:15]
	v_mfma_f32_16x16x32_bf16 v[8:11], v[216:219], v[200:203], v[8:11]
	s_cbranch_scc0 .Ldb_FFO_cont
	s_branch .Ldb_FFO_xl
.LBB0_1185:
	s_add_u32 s4, s2, 0xfff50080
	s_addc_u32 s5, s3, -1
	s_add_i32 s33, 0, 0x10000
	ds_read_b128 v[136:139], v255 offset:0
	ds_read_b128 v[140:143], v255 offset:1024
	ds_read_b128 v[144:147], v255 offset:2048
	ds_read_b128 v[148:151], v255 offset:3072
	s_cmp_eq_u32 s21, 40
	s_cselect_b32 s5, s17, s5
	s_cselect_b32 s4, s16, s4
	s_cselect_b32 s23, s19, s7
	s_cselect_b32 s22, s18, s6
	s_add_i32 m0, s26, 0xc000
	ds_read_b128 v[152:155], v195
	ds_read_b128 v[156:159], v195 offset:1024
	ds_read_b128 v[160:163], v195 offset:2048
	ds_read_b128 v[164:167], v195 offset:3072
	ds_read_b128 v[176:179], v195 offset:4096
	ds_read_b128 v[180:183], v195 offset:5120
	ds_read_b128 v[196:199], v195 offset:6144
	ds_read_b128 v[200:203], v195 offset:7168
	global_load_lds_dwordx4 v174, s[2:3]
	s_add_i32 m0, s26, 0xe000
	s_add_u32 vcc_lo, s2, s86
	s_addc_u32 vcc_hi, s3, s87
	global_load_lds_dwordx4 v174, vcc
	s_waitcnt lgkmcnt(8)
	s_barrier
	s_waitcnt lgkmcnt(0)
	v_mfma_f32_16x16x32_bf16 v[132:135], v[136:139], v[152:155], v[132:135]
	v_mfma_f32_16x16x32_bf16 v[128:131], v[144:147], v[152:155], v[128:131]
	v_mfma_f32_16x16x32_bf16 v[116:119], v[136:139], v[160:163], v[116:119]
	v_mfma_f32_16x16x32_bf16 v[112:115], v[144:147], v[160:163], v[112:115]
	v_mfma_f32_16x16x32_bf16 v[100:103], v[136:139], v[176:179], v[100:103]
	v_mfma_f32_16x16x32_bf16 v[96:99], v[144:147], v[176:179], v[96:99]
	v_mfma_f32_16x16x32_bf16 v[84:87], v[136:139], v[196:199], v[84:87]
	v_mfma_f32_16x16x32_bf16 v[80:83], v[144:147], v[196:199], v[80:83]
	v_mfma_f32_16x16x32_bf16 v[132:135], v[140:143], v[156:159], v[132:135]
	v_mfma_f32_16x16x32_bf16 v[128:131], v[148:151], v[156:159], v[128:131]
	v_mfma_f32_16x16x32_bf16 v[116:119], v[140:143], v[164:167], v[116:119]
	v_mfma_f32_16x16x32_bf16 v[112:115], v[148:151], v[164:167], v[112:115]
	v_mfma_f32_16x16x32_bf16 v[100:103], v[140:143], v[180:183], v[100:103]
	v_mfma_f32_16x16x32_bf16 v[96:99], v[148:151], v[180:183], v[96:99]
	v_mfma_f32_16x16x32_bf16 v[84:87], v[140:143], v[200:203], v[84:87]
	v_mfma_f32_16x16x32_bf16 v[80:83], v[148:151], v[200:203], v[80:83]
	s_barrier
	s_add_i32 s44, 0, 0x14000
	s_add_i32 s100, s33, s25
	s_mov_b32 m0, s100
	ds_read_b128 v[204:207], v255 offset:16384
	ds_read_b128 v[208:211], v255 offset:17408
	ds_read_b128 v[212:215], v255 offset:18432
	ds_read_b128 v[216:219], v255 offset:19456
	global_load_lds_dwordx4 v172, s[22:23]
	s_add_i32 m0, s100, 0x2000
	s_add_u32 vcc_lo, s22, s86
	s_addc_u32 vcc_hi, s23, s87
	global_load_lds_dwordx4 v172, vcc
	s_barrier
	s_waitcnt lgkmcnt(0)
	v_mfma_f32_16x16x32_bf16 v[124:127], v[204:207], v[152:155], v[124:127]
	v_mfma_f32_16x16x32_bf16 v[120:123], v[212:215], v[152:155], v[120:123]
	v_mfma_f32_16x16x32_bf16 v[108:111], v[204:207], v[160:163], v[108:111]
	v_mfma_f32_16x16x32_bf16 v[104:107], v[212:215], v[160:163], v[104:107]
	v_mfma_f32_16x16x32_bf16 v[92:95], v[204:207], v[176:179], v[92:95]
	v_mfma_f32_16x16x32_bf16 v[88:91], v[212:215], v[176:179], v[88:91]
	v_mfma_f32_16x16x32_bf16 v[76:79], v[204:207], v[196:199], v[76:79]
	v_mfma_f32_16x16x32_bf16 v[72:75], v[212:215], v[196:199], v[72:75]
	v_mfma_f32_16x16x32_bf16 v[124:127], v[208:211], v[156:159], v[124:127]
	v_mfma_f32_16x16x32_bf16 v[120:123], v[216:219], v[156:159], v[120:123]
	v_mfma_f32_16x16x32_bf16 v[108:111], v[208:211], v[164:167], v[108:111]
	v_mfma_f32_16x16x32_bf16 v[104:107], v[216:219], v[164:167], v[104:107]
	v_mfma_f32_16x16x32_bf16 v[92:95], v[208:211], v[180:183], v[92:95]
	v_mfma_f32_16x16x32_bf16 v[88:91], v[216:219], v[180:183], v[88:91]
	v_mfma_f32_16x16x32_bf16 v[76:79], v[208:211], v[200:203], v[76:79]
	v_mfma_f32_16x16x32_bf16 v[72:75], v[216:219], v[200:203], v[72:75]
	s_barrier
	s_mov_b32 m0, s26
	v_lshl_add_u64 v[222:223], s[4:5], 0, v[2:3]
	ds_read_b128 v[152:155], v195 offset:16384
	ds_read_b128 v[156:159], v195 offset:17408
	ds_read_b128 v[160:163], v195 offset:18432
	ds_read_b128 v[164:167], v195 offset:19456
	ds_read_b128 v[176:179], v195 offset:20480
	ds_read_b128 v[180:183], v195 offset:21504
	ds_read_b128 v[196:199], v195 offset:22528
	ds_read_b128 v[200:203], v195 offset:23552
	global_load_lds_dwordx4 v2, s[4:5]
	s_mov_b32 m0, s27
	s_add_u32 vcc_lo, s4, s86
	s_addc_u32 vcc_hi, s5, s87
	global_load_lds_dwordx4 v2, vcc
	s_barrier
	s_waitcnt lgkmcnt(0)
	v_mfma_f32_16x16x32_bf16 v[68:71], v[136:139], v[152:155], v[68:71]
	v_mfma_f32_16x16x32_bf16 v[64:67], v[144:147], v[152:155], v[64:67]
	v_mfma_f32_16x16x32_bf16 v[52:55], v[136:139], v[160:163], v[52:55]
	v_mfma_f32_16x16x32_bf16 v[48:51], v[144:147], v[160:163], v[48:51]
	v_mfma_f32_16x16x32_bf16 v[36:39], v[136:139], v[176:179], v[36:39]
	v_mfma_f32_16x16x32_bf16 v[32:35], v[144:147], v[176:179], v[32:35]
	v_mfma_f32_16x16x32_bf16 v[20:23], v[136:139], v[196:199], v[20:23]
	v_mfma_f32_16x16x32_bf16 v[16:19], v[144:147], v[196:199], v[16:19]
	v_mfma_f32_16x16x32_bf16 v[68:71], v[140:143], v[156:159], v[68:71]
	v_mfma_f32_16x16x32_bf16 v[64:67], v[148:151], v[156:159], v[64:67]
	v_mfma_f32_16x16x32_bf16 v[52:55], v[140:143], v[164:167], v[52:55]
	v_mfma_f32_16x16x32_bf16 v[48:51], v[148:151], v[164:167], v[48:51]
	v_mfma_f32_16x16x32_bf16 v[36:39], v[140:143], v[180:183], v[36:39]
	v_mfma_f32_16x16x32_bf16 v[32:35], v[148:151], v[180:183], v[32:35]
	v_mfma_f32_16x16x32_bf16 v[20:23], v[140:143], v[200:203], v[20:23]
	v_mfma_f32_16x16x32_bf16 v[16:19], v[148:151], v[200:203], v[16:19]
	s_barrier
	s_add_i32 s100, s44, s25
	s_mov_b32 m0, s100
	s_add_u32 vcc_lo, s22, s88
	s_addc_u32 vcc_hi, s23, s89
	global_load_lds_dwordx4 v172, vcc
	s_add_i32 m0, s100, 0x2000
	s_add_u32 vcc_lo, s22, s64
	s_addc_u32 vcc_hi, s23, s65
	global_load_lds_dwordx4 v172, vcc
	s_waitcnt vmcnt(6)
	s_barrier
	v_mfma_f32_16x16x32_bf16 v[60:63], v[204:207], v[152:155], v[60:63]
	v_mfma_f32_16x16x32_bf16 v[56:59], v[212:215], v[152:155], v[56:59]
	v_mfma_f32_16x16x32_bf16 v[44:47], v[204:207], v[160:163], v[44:47]
	v_mfma_f32_16x16x32_bf16 v[40:43], v[212:215], v[160:163], v[40:43]
	v_mfma_f32_16x16x32_bf16 v[28:31], v[204:207], v[176:179], v[28:31]
	v_mfma_f32_16x16x32_bf16 v[24:27], v[212:215], v[176:179], v[24:27]
	v_mfma_f32_16x16x32_bf16 v[12:15], v[204:207], v[196:199], v[12:15]
	v_mfma_f32_16x16x32_bf16 v[8:11], v[212:215], v[196:199], v[8:11]
	v_mfma_f32_16x16x32_bf16 v[60:63], v[208:211], v[156:159], v[60:63]
	v_mfma_f32_16x16x32_bf16 v[56:59], v[216:219], v[156:159], v[56:59]
	v_mfma_f32_16x16x32_bf16 v[44:47], v[208:211], v[164:167], v[44:47]
	v_mfma_f32_16x16x32_bf16 v[40:43], v[216:219], v[164:167], v[40:43]
	v_mfma_f32_16x16x32_bf16 v[28:31], v[208:211], v[180:183], v[28:31]
	v_mfma_f32_16x16x32_bf16 v[24:27], v[216:219], v[180:183], v[24:27]
	v_mfma_f32_16x16x32_bf16 v[12:15], v[208:211], v[200:203], v[12:15]
	v_mfma_f32_16x16x32_bf16 v[8:11], v[216:219], v[200:203], v[8:11]
	s_barrier
	s_add_i32 s100, 0, 0x18000
	ds_read_b128 v[136:139], v255 offset:32768
	ds_read_b128 v[140:143], v255 offset:33792
	ds_read_b128 v[144:147], v255 offset:34816
	ds_read_b128 v[148:151], v255 offset:35840
	s_mov_b32 m0, s29
	ds_read_b128 v[152:155], v195 offset:32768
	ds_read_b128 v[156:159], v195 offset:33792
	ds_read_b128 v[160:163], v195 offset:34816
	ds_read_b128 v[164:167], v195 offset:35840
	ds_read_b128 v[176:179], v195 offset:36864
	ds_read_b128 v[180:183], v195 offset:37888
	ds_read_b128 v[196:199], v195 offset:38912
	ds_read_b128 v[200:203], v195 offset:39936
	s_add_u32 vcc_lo, s4, s88
	s_addc_u32 vcc_hi, s5, s89
	global_load_lds_dwordx4 v2, vcc
	s_mov_b32 m0, s30
	s_add_u32 vcc_lo, s4, s64
	s_addc_u32 vcc_hi, s5, s65
	global_load_lds_dwordx4 v2, vcc
	s_waitcnt lgkmcnt(8)
	s_barrier
	s_waitcnt lgkmcnt(0)
	v_mfma_f32_16x16x32_bf16 v[132:135], v[136:139], v[152:155], v[132:135]
	v_mfma_f32_16x16x32_bf16 v[128:131], v[144:147], v[152:155], v[128:131]
	v_mfma_f32_16x16x32_bf16 v[116:119], v[136:139], v[160:163], v[116:119]
	v_mfma_f32_16x16x32_bf16 v[112:115], v[144:147], v[160:163], v[112:115]
	v_mfma_f32_16x16x32_bf16 v[100:103], v[136:139], v[176:179], v[100:103]
	v_mfma_f32_16x16x32_bf16 v[96:99], v[144:147], v[176:179], v[96:99]
	v_mfma_f32_16x16x32_bf16 v[84:87], v[136:139], v[196:199], v[84:87]
	v_mfma_f32_16x16x32_bf16 v[80:83], v[144:147], v[196:199], v[80:83]
	v_mfma_f32_16x16x32_bf16 v[132:135], v[140:143], v[156:159], v[132:135]
	v_mfma_f32_16x16x32_bf16 v[128:131], v[148:151], v[156:159], v[128:131]
	v_mfma_f32_16x16x32_bf16 v[116:119], v[140:143], v[164:167], v[116:119]
	v_mfma_f32_16x16x32_bf16 v[112:115], v[148:151], v[164:167], v[112:115]
	v_mfma_f32_16x16x32_bf16 v[100:103], v[140:143], v[180:183], v[100:103]
	v_mfma_f32_16x16x32_bf16 v[96:99], v[148:151], v[180:183], v[96:99]
	v_mfma_f32_16x16x32_bf16 v[84:87], v[140:143], v[200:203], v[84:87]
	v_mfma_f32_16x16x32_bf16 v[80:83], v[148:151], v[200:203], v[80:83]
	s_barrier
	s_add_i32 s5, 0, 0x1c000
	s_add_i32 s4, s100, s25
	s_mov_b32 m0, s4
	ds_read_b128 v[204:207], v255 offset:49152
	ds_read_b128 v[208:211], v255 offset:50176
	ds_read_b128 v[212:215], v255 offset:51200
	ds_read_b128 v[216:219], v255 offset:52224
	s_add_u32 vcc_lo, s22, s46
	s_addc_u32 vcc_hi, s23, s47
	global_load_lds_dwordx4 v172, vcc
	s_add_i32 m0, s4, 0x2000
	s_add_u32 vcc_lo, s22, s66
	s_addc_u32 vcc_hi, s23, s67
	global_load_lds_dwordx4 v172, vcc
	s_barrier
	s_waitcnt lgkmcnt(0)
	v_mfma_f32_16x16x32_bf16 v[124:127], v[204:207], v[152:155], v[124:127]
	v_mfma_f32_16x16x32_bf16 v[120:123], v[212:215], v[152:155], v[120:123]
	v_mfma_f32_16x16x32_bf16 v[108:111], v[204:207], v[160:163], v[108:111]
	v_mfma_f32_16x16x32_bf16 v[104:107], v[212:215], v[160:163], v[104:107]
	v_mfma_f32_16x16x32_bf16 v[92:95], v[204:207], v[176:179], v[92:95]
	v_mfma_f32_16x16x32_bf16 v[88:91], v[212:215], v[176:179], v[88:91]
	v_mfma_f32_16x16x32_bf16 v[76:79], v[204:207], v[196:199], v[76:79]
	v_mfma_f32_16x16x32_bf16 v[72:75], v[212:215], v[196:199], v[72:75]
	v_mfma_f32_16x16x32_bf16 v[124:127], v[208:211], v[156:159], v[124:127]
	v_mfma_f32_16x16x32_bf16 v[120:123], v[216:219], v[156:159], v[120:123]
	v_mfma_f32_16x16x32_bf16 v[108:111], v[208:211], v[164:167], v[108:111]
	v_mfma_f32_16x16x32_bf16 v[104:107], v[216:219], v[164:167], v[104:107]
	v_mfma_f32_16x16x32_bf16 v[92:95], v[208:211], v[180:183], v[92:95]
	v_mfma_f32_16x16x32_bf16 v[88:91], v[216:219], v[180:183], v[88:91]
	v_mfma_f32_16x16x32_bf16 v[76:79], v[208:211], v[200:203], v[76:79]
	v_mfma_f32_16x16x32_bf16 v[72:75], v[216:219], v[200:203], v[72:75]
	s_barrier
	s_mov_b32 m0, s31
	v_lshl_add_u64 v[224:225], v[222:223], 0, s[46:47]
	ds_read_b128 v[152:155], v195 offset:49152
	ds_read_b128 v[156:159], v195 offset:50176
	ds_read_b128 v[160:163], v195 offset:51200
	ds_read_b128 v[164:167], v195 offset:52224
	ds_read_b128 v[176:179], v195 offset:53248
	ds_read_b128 v[180:183], v195 offset:54272
	ds_read_b128 v[196:199], v195 offset:55296
	ds_read_b128 v[200:203], v195 offset:56320
	global_load_lds_dwordx4 v[224:225], off
	v_lshl_add_u64 v[222:223], v[222:223], 0, s[66:67]
	s_mov_b32 m0, s34
	s_nop 0
	global_load_lds_dwordx4 v[222:223], off
	s_barrier
	s_waitcnt lgkmcnt(0)
	v_mfma_f32_16x16x32_bf16 v[68:71], v[136:139], v[152:155], v[68:71]
	v_mfma_f32_16x16x32_bf16 v[64:67], v[144:147], v[152:155], v[64:67]
	v_mfma_f32_16x16x32_bf16 v[52:55], v[136:139], v[160:163], v[52:55]
	v_mfma_f32_16x16x32_bf16 v[48:51], v[144:147], v[160:163], v[48:51]
	v_mfma_f32_16x16x32_bf16 v[36:39], v[136:139], v[176:179], v[36:39]
	v_mfma_f32_16x16x32_bf16 v[32:35], v[144:147], v[176:179], v[32:35]
	v_mfma_f32_16x16x32_bf16 v[20:23], v[136:139], v[196:199], v[20:23]
	v_mfma_f32_16x16x32_bf16 v[16:19], v[144:147], v[196:199], v[16:19]
	v_mfma_f32_16x16x32_bf16 v[68:71], v[140:143], v[156:159], v[68:71]
	v_mfma_f32_16x16x32_bf16 v[64:67], v[148:151], v[156:159], v[64:67]
	v_mfma_f32_16x16x32_bf16 v[52:55], v[140:143], v[164:167], v[52:55]
	v_mfma_f32_16x16x32_bf16 v[48:51], v[148:151], v[164:167], v[48:51]
	v_mfma_f32_16x16x32_bf16 v[36:39], v[140:143], v[180:183], v[36:39]
	v_mfma_f32_16x16x32_bf16 v[32:35], v[148:151], v[180:183], v[32:35]
	v_mfma_f32_16x16x32_bf16 v[20:23], v[140:143], v[200:203], v[20:23]
	v_mfma_f32_16x16x32_bf16 v[16:19], v[148:151], v[200:203], v[16:19]
	s_barrier
	s_add_i32 s4, s5, s25
	s_mov_b32 m0, s4
	s_add_u32 vcc_lo, s22, s52
	s_addc_u32 vcc_hi, s23, s53
	global_load_lds_dwordx4 v172, vcc
	s_add_i32 m0, s4, 0x2000
	s_add_u32 vcc_lo, s22, s54
	s_addc_u32 vcc_hi, s23, s55
	global_load_lds_dwordx4 v172, vcc
	s_add_i32 s21, s21, 2
	s_add_u32 s2, s2, 0x100
	s_addc_u32 s3, s3, 0
	s_add_u32 s6, s6, 0x100
	s_addc_u32 s7, s7, 0
	s_cmp_gt_u32 s21, 41
	s_waitcnt vmcnt(6)
	s_barrier
	v_mfma_f32_16x16x32_bf16 v[60:63], v[204:207], v[152:155], v[60:63]
	v_mfma_f32_16x16x32_bf16 v[56:59], v[212:215], v[152:155], v[56:59]
	v_mfma_f32_16x16x32_bf16 v[44:47], v[204:207], v[160:163], v[44:47]
	v_mfma_f32_16x16x32_bf16 v[40:43], v[212:215], v[160:163], v[40:43]
	v_mfma_f32_16x16x32_bf16 v[28:31], v[204:207], v[176:179], v[28:31]
	v_mfma_f32_16x16x32_bf16 v[24:27], v[212:215], v[176:179], v[24:27]
	v_mfma_f32_16x16x32_bf16 v[12:15], v[204:207], v[196:199], v[12:15]
	v_mfma_f32_16x16x32_bf16 v[8:11], v[212:215], v[196:199], v[8:11]
	v_mfma_f32_16x16x32_bf16 v[60:63], v[208:211], v[156:159], v[60:63]
	v_mfma_f32_16x16x32_bf16 v[56:59], v[216:219], v[156:159], v[56:59]
	v_mfma_f32_16x16x32_bf16 v[44:47], v[208:211], v[164:167], v[44:47]
	v_mfma_f32_16x16x32_bf16 v[40:43], v[216:219], v[164:167], v[40:43]
	v_mfma_f32_16x16x32_bf16 v[28:31], v[208:211], v[180:183], v[28:31]
	v_mfma_f32_16x16x32_bf16 v[24:27], v[216:219], v[180:183], v[24:27]
	v_mfma_f32_16x16x32_bf16 v[12:15], v[208:211], v[200:203], v[12:15]
	v_mfma_f32_16x16x32_bf16 v[8:11], v[216:219], v[200:203], v[8:11]
	s_cbranch_scc0 .Ldb_FFO_cont

.LBB0_1259:
	s_mov_b64 s[18:19], 0
	s_mov_b64 s[14:15], -1
	s_mov_b64 s[16:17], 0
	s_mov_b64 s[58:59], 0x10000
	s_cmp_eq_u32 s101, 2
	s_cselect_b32 s101, 0, s101
	s_setprio 0
	v_add_u32_e32 v255, 0x10000, v137
	s_add_u32 s22, s10, s18
	s_addc_u32 s23, s11, s19
	s_add_u32 s20, s22, 0x100
	s_addc_u32 s21, s23, 0
	s_and_b64 s[4:5], s[16:17], exec
	s_cselect_b32 s20, s6, s20
	s_cselect_b32 s21, s7, s21
	s_add_u32 s4, s12, s18
	s_addc_u32 s5, s13, s19
	s_add_u32 s18, s4, 0x100
	s_addc_u32 s19, s5, 0
	s_add_i32 s44, 0, 0x10000
	ds_read_b128 v[140:143], v255 offset:0
	ds_read_b128 v[144:147], v255 offset:1024
	ds_read_b128 v[148:151], v255 offset:2048
	ds_read_b128 v[152:155], v255 offset:3072
	s_and_b64 s[4:5], s[16:17], exec
	s_cselect_b32 s16, s8, s18
	s_cselect_b32 s17, s9, s19
	s_add_i32 s5, 0, 0x14000
	s_add_i32 s43, 0, 0x18000
	s_add_i32 s18, 0, 0x1c000
	s_add_i32 s45, s44, s25
	s_add_i32 s51, s5, s25
	s_add_i32 s19, s43, s25
	s_add_i32 s53, s18, s25
	s_mov_b64 s[64:65], 0x8000
	s_mov_b64 s[62:63], 0x10080
	s_add_i32 m0, s31, 0xc000
	s_add_i32 s4, s31, 0xe000
	s_add_i32 s54, s45, 0x2000
	s_add_i32 s50, s51, 0x2000
	s_add_i32 s44, s19, 0x2000
	s_add_i32 s52, s53, 0x2000
	ds_read_b128 v[156:159], v138
	ds_read_b128 v[160:163], v138 offset:1024
	ds_read_b128 v[164:167], v138 offset:2048
	ds_read_b128 v[172:175], v138 offset:3072
	ds_read_b128 v[176:179], v138 offset:4096
	ds_read_b128 v[180:183], v138 offset:5120
	ds_read_b128 v[196:199], v138 offset:6144
	ds_read_b128 v[200:203], v138 offset:7168
	s_add_u32 vcc_lo, s22, s62
	s_addc_u32 vcc_hi, s23, s63
	global_load_lds_dwordx4 v2, vcc
	s_mov_b32 m0, s4
	s_add_u32 vcc_lo, s22, s68
	s_addc_u32 vcc_hi, s23, s69
	global_load_lds_dwordx4 v2, vcc
	s_waitcnt lgkmcnt(8)
	s_cmp_eq_u32 s101, 1
	s_cbranch_scc1 .Ldb_PLE0_skp
	s_barrier
.Ldb_PLE0_skp:
	s_mov_b32 s101, 0
	s_waitcnt lgkmcnt(0)
	v_mfma_f32_16x16x32_bf16 v[132:135], v[140:143], v[156:159], 0
	v_mfma_f32_16x16x32_bf16 v[128:131], v[148:151], v[156:159], 0
	v_mfma_f32_16x16x32_bf16 v[124:127], v[140:143], v[164:167], 0
	v_mfma_f32_16x16x32_bf16 v[116:119], v[148:151], v[164:167], 0
	v_mfma_f32_16x16x32_bf16 v[108:111], v[140:143], v[176:179], 0
	v_mfma_f32_16x16x32_bf16 v[100:103], v[148:151], v[176:179], 0
	v_mfma_f32_16x16x32_bf16 v[92:95], v[140:143], v[196:199], 0
	v_mfma_f32_16x16x32_bf16 v[84:87], v[148:151], v[196:199], 0
	v_mfma_f32_16x16x32_bf16 v[132:135], v[144:147], v[160:163], v[132:135]
	v_mfma_f32_16x16x32_bf16 v[128:131], v[152:155], v[160:163], v[128:131]
	v_mfma_f32_16x16x32_bf16 v[124:127], v[144:147], v[172:175], v[124:127]
	v_mfma_f32_16x16x32_bf16 v[116:119], v[152:155], v[172:175], v[116:119]
	v_mfma_f32_16x16x32_bf16 v[108:111], v[144:147], v[180:183], v[108:111]
	v_mfma_f32_16x16x32_bf16 v[100:103], v[152:155], v[180:183], v[100:103]
	v_mfma_f32_16x16x32_bf16 v[92:95], v[144:147], v[200:203], v[92:95]
	v_mfma_f32_16x16x32_bf16 v[84:87], v[152:155], v[200:203], v[84:87]
	s_barrier
	s_mov_b32 m0, s45
	v_lshl_add_u64 v[184:185], s[16:17], 0, v[0:1]
	ds_read_b128 v[204:207], v255 offset:16384
	ds_read_b128 v[208:211], v255 offset:17408
	ds_read_b128 v[212:215], v255 offset:18432
	ds_read_b128 v[216:219], v255 offset:19456
	global_load_lds_dwordx4 v0, s[16:17]
	s_mov_b32 m0, s54
	s_add_u32 vcc_lo, s16, s64
	s_addc_u32 vcc_hi, s17, s65
	global_load_lds_dwordx4 v0, vcc
	s_barrier
	s_waitcnt lgkmcnt(0)
	v_mfma_f32_16x16x32_bf16 v[120:123], v[204:207], v[156:159], 0
	v_mfma_f32_16x16x32_bf16 v[112:115], v[212:215], v[156:159], 0
	v_mfma_f32_16x16x32_bf16 v[104:107], v[204:207], v[164:167], 0
	v_mfma_f32_16x16x32_bf16 v[96:99], v[212:215], v[164:167], 0
	v_mfma_f32_16x16x32_bf16 v[88:91], v[204:207], v[176:179], 0
	v_mfma_f32_16x16x32_bf16 v[80:83], v[212:215], v[176:179], 0
	v_mfma_f32_16x16x32_bf16 v[76:79], v[204:207], v[196:199], 0
	v_mfma_f32_16x16x32_bf16 v[72:75], v[212:215], v[196:199], 0
	v_mfma_f32_16x16x32_bf16 v[120:123], v[208:211], v[160:163], v[120:123]
	v_mfma_f32_16x16x32_bf16 v[112:115], v[216:219], v[160:163], v[112:115]
	v_mfma_f32_16x16x32_bf16 v[104:107], v[208:211], v[172:175], v[104:107]
	v_mfma_f32_16x16x32_bf16 v[96:99], v[216:219], v[172:175], v[96:99]
	v_mfma_f32_16x16x32_bf16 v[88:91], v[208:211], v[180:183], v[88:91]
	v_mfma_f32_16x16x32_bf16 v[80:83], v[216:219], v[180:183], v[80:83]
	v_mfma_f32_16x16x32_bf16 v[76:79], v[208:211], v[200:203], v[76:79]
	v_mfma_f32_16x16x32_bf16 v[72:75], v[216:219], v[200:203], v[72:75]
	s_barrier
	s_mov_b32 m0, s31
	v_lshl_add_u64 v[220:221], s[20:21], 0, v[2:3]
	s_mov_b64 s[4:5], 0x8000
	ds_read_b128 v[156:159], v138 offset:16384
	ds_read_b128 v[160:163], v138 offset:17408
	ds_read_b128 v[164:167], v138 offset:18432
	ds_read_b128 v[172:175], v138 offset:19456
	ds_read_b128 v[176:179], v138 offset:20480
	ds_read_b128 v[180:183], v138 offset:21504
	ds_read_b128 v[196:199], v138 offset:22528
	ds_read_b128 v[200:203], v138 offset:23552
	global_load_lds_dwordx4 v2, s[20:21]
	s_mov_b32 m0, s33
	s_mov_b64 s[16:17], 0x18000
	s_add_u32 vcc_lo, s20, s4
	s_addc_u32 vcc_hi, s21, s5
	global_load_lds_dwordx4 v2, vcc
	s_barrier
	s_waitcnt lgkmcnt(0)
	s_mov_b64 s[20:21], 0x8080
	s_waitcnt lgkmcnt(0)
	v_mfma_f32_16x16x32_bf16 v[68:71], v[140:143], v[156:159], 0
	v_mfma_f32_16x16x32_bf16 v[64:67], v[148:151], v[156:159], 0
	v_mfma_f32_16x16x32_bf16 v[60:63], v[140:143], v[164:167], 0
	v_mfma_f32_16x16x32_bf16 v[52:55], v[148:151], v[164:167], 0
	v_mfma_f32_16x16x32_bf16 v[44:47], v[140:143], v[176:179], 0
	v_mfma_f32_16x16x32_bf16 v[36:39], v[148:151], v[176:179], 0
	v_mfma_f32_16x16x32_bf16 v[28:31], v[140:143], v[196:199], 0
	v_mfma_f32_16x16x32_bf16 v[20:23], v[148:151], v[196:199], 0
	v_mfma_f32_16x16x32_bf16 v[68:71], v[144:147], v[160:163], v[68:71]
	v_mfma_f32_16x16x32_bf16 v[64:67], v[152:155], v[160:163], v[64:67]
	v_mfma_f32_16x16x32_bf16 v[60:63], v[144:147], v[172:175], v[60:63]
	v_mfma_f32_16x16x32_bf16 v[52:55], v[152:155], v[172:175], v[52:55]
	v_mfma_f32_16x16x32_bf16 v[44:47], v[144:147], v[180:183], v[44:47]
	v_mfma_f32_16x16x32_bf16 v[36:39], v[152:155], v[180:183], v[36:39]
	v_mfma_f32_16x16x32_bf16 v[28:31], v[144:147], v[200:203], v[28:31]
	v_mfma_f32_16x16x32_bf16 v[20:23], v[152:155], v[200:203], v[20:23]
	s_barrier
	s_mov_b32 m0, s51
	v_lshl_add_u64 v[140:141], v[184:185], 0, s[58:59]
	global_load_lds_dwordx4 v[140:141], off
	v_lshl_add_u64 v[140:141], v[184:185], 0, s[16:17]
	s_mov_b32 m0, s50
	s_nop 0
	global_load_lds_dwordx4 v[140:141], off
	s_waitcnt vmcnt(6)
	s_barrier
	v_mfma_f32_16x16x32_bf16 v[56:59], v[204:207], v[156:159], 0
	v_mfma_f32_16x16x32_bf16 v[48:51], v[212:215], v[156:159], 0
	v_mfma_f32_16x16x32_bf16 v[40:43], v[204:207], v[164:167], 0
	v_mfma_f32_16x16x32_bf16 v[32:35], v[212:215], v[164:167], 0
	v_mfma_f32_16x16x32_bf16 v[24:27], v[204:207], v[176:179], 0
	v_mfma_f32_16x16x32_bf16 v[16:19], v[212:215], v[176:179], 0
	v_mfma_f32_16x16x32_bf16 v[12:15], v[204:207], v[196:199], 0
	v_mfma_f32_16x16x32_bf16 v[8:11], v[212:215], v[196:199], 0
	v_mfma_f32_16x16x32_bf16 v[56:59], v[208:211], v[160:163], v[56:59]
	v_mfma_f32_16x16x32_bf16 v[48:51], v[216:219], v[160:163], v[48:51]
	v_mfma_f32_16x16x32_bf16 v[40:43], v[208:211], v[172:175], v[40:43]
	v_mfma_f32_16x16x32_bf16 v[32:35], v[216:219], v[172:175], v[32:35]
	v_mfma_f32_16x16x32_bf16 v[24:27], v[208:211], v[180:183], v[24:27]
	v_mfma_f32_16x16x32_bf16 v[16:19], v[216:219], v[180:183], v[16:19]
	v_mfma_f32_16x16x32_bf16 v[12:15], v[208:211], v[200:203], v[12:15]
	v_mfma_f32_16x16x32_bf16 v[8:11], v[216:219], v[200:203], v[8:11]
	s_barrier
	ds_read_b128 v[140:143], v255 offset:32768
	ds_read_b128 v[144:147], v255 offset:33792
	ds_read_b128 v[148:151], v255 offset:34816
	ds_read_b128 v[152:155], v255 offset:35840
	s_mov_b32 m0, s34
	v_lshl_add_u64 v[204:205], v[220:221], 0, s[58:59]
	ds_read_b128 v[156:159], v138 offset:32768
	ds_read_b128 v[160:163], v138 offset:33792
	ds_read_b128 v[164:167], v138 offset:34816
	ds_read_b128 v[172:175], v138 offset:35840
	ds_read_b128 v[176:179], v138 offset:36864
	ds_read_b128 v[180:183], v138 offset:37888
	ds_read_b128 v[196:199], v138 offset:38912
	ds_read_b128 v[200:203], v138 offset:39936
	global_load_lds_dwordx4 v[204:205], off
	v_lshl_add_u64 v[204:205], v[220:221], 0, s[16:17]
	s_mov_b32 m0, s35
	s_nop 0
	global_load_lds_dwordx4 v[204:205], off
	s_waitcnt lgkmcnt(8)
	s_barrier
	s_waitcnt lgkmcnt(0)
	v_mfma_f32_16x16x32_bf16 v[132:135], v[140:143], v[156:159], v[132:135]
	v_mfma_f32_16x16x32_bf16 v[128:131], v[148:151], v[156:159], v[128:131]
	v_mfma_f32_16x16x32_bf16 v[124:127], v[140:143], v[164:167], v[124:127]
	v_mfma_f32_16x16x32_bf16 v[116:119], v[148:151], v[164:167], v[116:119]
	v_mfma_f32_16x16x32_bf16 v[108:111], v[140:143], v[176:179], v[108:111]
	v_mfma_f32_16x16x32_bf16 v[100:103], v[148:151], v[176:179], v[100:103]
	v_mfma_f32_16x16x32_bf16 v[92:95], v[140:143], v[196:199], v[92:95]
	v_mfma_f32_16x16x32_bf16 v[84:87], v[148:151], v[196:199], v[84:87]
	v_mfma_f32_16x16x32_bf16 v[132:135], v[144:147], v[160:163], v[132:135]
	v_mfma_f32_16x16x32_bf16 v[128:131], v[152:155], v[160:163], v[128:131]
	v_mfma_f32_16x16x32_bf16 v[124:127], v[144:147], v[172:175], v[124:127]
	v_mfma_f32_16x16x32_bf16 v[116:119], v[152:155], v[172:175], v[116:119]
	v_mfma_f32_16x16x32_bf16 v[108:111], v[144:147], v[180:183], v[108:111]
	v_mfma_f32_16x16x32_bf16 v[100:103], v[152:155], v[180:183], v[100:103]
	v_mfma_f32_16x16x32_bf16 v[92:95], v[144:147], v[200:203], v[92:95]
	v_mfma_f32_16x16x32_bf16 v[84:87], v[152:155], v[200:203], v[84:87]
	s_barrier
	s_mov_b32 m0, s19
	v_lshl_add_u64 v[222:223], v[184:185], 0, s[46:47]
	ds_read_b128 v[204:207], v255 offset:49152
	ds_read_b128 v[208:211], v255 offset:50176
	ds_read_b128 v[212:215], v255 offset:51200
	ds_read_b128 v[216:219], v255 offset:52224
	global_load_lds_dwordx4 v[222:223], off
	v_lshl_add_u64 v[222:223], v[184:185], 0, s[20:21]
	s_mov_b32 m0, s44
	s_mov_b64 s[4:5], 0x10080
	global_load_lds_dwordx4 v[222:223], off
	s_barrier
	s_waitcnt lgkmcnt(0)
	v_mfma_f32_16x16x32_bf16 v[120:123], v[204:207], v[156:159], v[120:123]
	v_mfma_f32_16x16x32_bf16 v[112:115], v[212:215], v[156:159], v[112:115]
	v_mfma_f32_16x16x32_bf16 v[104:107], v[204:207], v[164:167], v[104:107]
	v_mfma_f32_16x16x32_bf16 v[96:99], v[212:215], v[164:167], v[96:99]
	v_mfma_f32_16x16x32_bf16 v[88:91], v[204:207], v[176:179], v[88:91]
	v_mfma_f32_16x16x32_bf16 v[80:83], v[212:215], v[176:179], v[80:83]
	v_mfma_f32_16x16x32_bf16 v[76:79], v[204:207], v[196:199], v[76:79]
	v_mfma_f32_16x16x32_bf16 v[72:75], v[212:215], v[196:199], v[72:75]
	v_mfma_f32_16x16x32_bf16 v[120:123], v[208:211], v[160:163], v[120:123]
	v_mfma_f32_16x16x32_bf16 v[112:115], v[216:219], v[160:163], v[112:115]
	v_mfma_f32_16x16x32_bf16 v[104:107], v[208:211], v[172:175], v[104:107]
	v_mfma_f32_16x16x32_bf16 v[96:99], v[216:219], v[172:175], v[96:99]
	v_mfma_f32_16x16x32_bf16 v[88:91], v[208:211], v[180:183], v[88:91]
	v_mfma_f32_16x16x32_bf16 v[80:83], v[216:219], v[180:183], v[80:83]
	v_mfma_f32_16x16x32_bf16 v[76:79], v[208:211], v[200:203], v[76:79]
	v_mfma_f32_16x16x32_bf16 v[72:75], v[216:219], v[200:203], v[72:75]
	s_barrier
	s_mov_b32 m0, s36
	v_lshl_add_u64 v[222:223], v[220:221], 0, s[46:47]
	ds_read_b128 v[156:159], v138 offset:49152
	ds_read_b128 v[160:163], v138 offset:50176
	ds_read_b128 v[164:167], v138 offset:51200
	ds_read_b128 v[172:175], v138 offset:52224
	ds_read_b128 v[176:179], v138 offset:53248
	ds_read_b128 v[180:183], v138 offset:54272
	ds_read_b128 v[196:199], v138 offset:55296
	ds_read_b128 v[200:203], v138 offset:56320
	global_load_lds_dwordx4 v[222:223], off
	v_lshl_add_u64 v[220:221], v[220:221], 0, s[20:21]
	s_mov_b32 m0, s37
	s_nop 0
	global_load_lds_dwordx4 v[220:221], off
	s_barrier
	s_waitcnt lgkmcnt(0)
	v_mfma_f32_16x16x32_bf16 v[68:71], v[140:143], v[156:159], v[68:71]
	v_mfma_f32_16x16x32_bf16 v[64:67], v[148:151], v[156:159], v[64:67]
	v_mfma_f32_16x16x32_bf16 v[60:63], v[140:143], v[164:167], v[60:63]
	v_mfma_f32_16x16x32_bf16 v[52:55], v[148:151], v[164:167], v[52:55]
	v_mfma_f32_16x16x32_bf16 v[44:47], v[140:143], v[176:179], v[44:47]
	v_mfma_f32_16x16x32_bf16 v[36:39], v[148:151], v[176:179], v[36:39]
	v_mfma_f32_16x16x32_bf16 v[28:31], v[140:143], v[196:199], v[28:31]
	v_mfma_f32_16x16x32_bf16 v[20:23], v[148:151], v[196:199], v[20:23]
	v_mfma_f32_16x16x32_bf16 v[68:71], v[144:147], v[160:163], v[68:71]
	v_mfma_f32_16x16x32_bf16 v[64:67], v[152:155], v[160:163], v[64:67]
	v_mfma_f32_16x16x32_bf16 v[60:63], v[144:147], v[172:175], v[60:63]
	v_mfma_f32_16x16x32_bf16 v[52:55], v[152:155], v[172:175], v[52:55]
	v_mfma_f32_16x16x32_bf16 v[44:47], v[144:147], v[180:183], v[44:47]
	v_mfma_f32_16x16x32_bf16 v[36:39], v[152:155], v[180:183], v[36:39]
	v_mfma_f32_16x16x32_bf16 v[28:31], v[144:147], v[200:203], v[28:31]
	v_mfma_f32_16x16x32_bf16 v[20:23], v[152:155], v[200:203], v[20:23]
	s_barrier
	s_mov_b32 m0, s53
	v_lshl_add_u64 v[140:141], v[184:185], 0, s[4:5]
	global_load_lds_dwordx4 v[140:141], off
	v_lshl_add_u64 v[140:141], v[184:185], 0, s[68:69]
	s_mov_b32 m0, s52
	s_nop 0
	global_load_lds_dwordx4 v[140:141], off
	s_waitcnt vmcnt(6)
	s_barrier
	v_mfma_f32_16x16x32_bf16 v[56:59], v[204:207], v[156:159], v[56:59]
	v_mfma_f32_16x16x32_bf16 v[48:51], v[212:215], v[156:159], v[48:51]
	v_mfma_f32_16x16x32_bf16 v[40:43], v[204:207], v[164:167], v[40:43]
	v_mfma_f32_16x16x32_bf16 v[32:35], v[212:215], v[164:167], v[32:35]
	v_mfma_f32_16x16x32_bf16 v[24:27], v[204:207], v[176:179], v[24:27]
	v_mfma_f32_16x16x32_bf16 v[16:19], v[212:215], v[176:179], v[16:19]
	v_mfma_f32_16x16x32_bf16 v[12:15], v[204:207], v[196:199], v[12:15]
	v_mfma_f32_16x16x32_bf16 v[8:11], v[212:215], v[196:199], v[8:11]
	v_mfma_f32_16x16x32_bf16 v[56:59], v[208:211], v[160:163], v[56:59]
	v_mfma_f32_16x16x32_bf16 v[48:51], v[216:219], v[160:163], v[48:51]
	v_mfma_f32_16x16x32_bf16 v[40:43], v[208:211], v[172:175], v[40:43]
	v_mfma_f32_16x16x32_bf16 v[32:35], v[216:219], v[172:175], v[32:35]
	v_mfma_f32_16x16x32_bf16 v[24:27], v[208:211], v[180:183], v[24:27]
	v_mfma_f32_16x16x32_bf16 v[16:19], v[216:219], v[180:183], v[16:19]
	v_mfma_f32_16x16x32_bf16 v[12:15], v[208:211], v[200:203], v[12:15]
	v_mfma_f32_16x16x32_bf16 v[8:11], v[216:219], v[200:203], v[8:11]
	s_andn2_b64 vcc, exec, s[14:15]
	s_mov_b64 s[16:17], -1
	s_mov_b64 s[14:15], 0
	s_mov_b64 s[18:19], 0x100
	s_cbranch_vccz .Ldb_PLE0_cont
	s_branch .Ldb_PLE0_xl
.LBB0_1260:
	s_add_u32 s22, s10, s18
	s_addc_u32 s23, s11, s19
	s_add_u32 s20, s22, 0x100
	s_addc_u32 s21, s23, 0
	s_and_b64 s[4:5], s[16:17], exec
	s_cselect_b32 s20, s6, s20
	s_cselect_b32 s21, s7, s21
	s_add_u32 s4, s12, s18
	s_addc_u32 s5, s13, s19
	s_add_u32 s18, s4, 0x100
	s_addc_u32 s19, s5, 0
	s_add_i32 s44, 0, 0x10000
	ds_read_b128 v[140:143], v255 offset:0
	ds_read_b128 v[144:147], v255 offset:1024
	ds_read_b128 v[148:151], v255 offset:2048
	ds_read_b128 v[152:155], v255 offset:3072
	s_and_b64 s[4:5], s[16:17], exec
	s_cselect_b32 s16, s8, s18
	s_cselect_b32 s17, s9, s19
	s_add_i32 s5, 0, 0x14000
	s_add_i32 s43, 0, 0x18000
	s_add_i32 s18, 0, 0x1c000
	s_add_i32 s45, s44, s25
	s_add_i32 s51, s5, s25
	s_add_i32 s19, s43, s25
	s_add_i32 s53, s18, s25
	s_mov_b64 s[64:65], 0x8000
	s_mov_b64 s[62:63], 0x10080
	s_add_i32 m0, s31, 0xc000
	s_add_i32 s4, s31, 0xe000
	s_add_i32 s54, s45, 0x2000
	s_add_i32 s50, s51, 0x2000
	s_add_i32 s44, s19, 0x2000
	s_add_i32 s52, s53, 0x2000
	ds_read_b128 v[156:159], v138
	ds_read_b128 v[160:163], v138 offset:1024
	ds_read_b128 v[164:167], v138 offset:2048
	ds_read_b128 v[172:175], v138 offset:3072
	ds_read_b128 v[176:179], v138 offset:4096
	ds_read_b128 v[180:183], v138 offset:5120
	ds_read_b128 v[196:199], v138 offset:6144
	ds_read_b128 v[200:203], v138 offset:7168
	s_add_u32 vcc_lo, s22, s62
	s_addc_u32 vcc_hi, s23, s63
	global_load_lds_dwordx4 v2, vcc
	s_mov_b32 m0, s4
	s_add_u32 vcc_lo, s22, s68
	s_addc_u32 vcc_hi, s23, s69
	global_load_lds_dwordx4 v2, vcc
	s_waitcnt lgkmcnt(8)
	s_barrier
	s_waitcnt lgkmcnt(0)
	v_mfma_f32_16x16x32_bf16 v[132:135], v[140:143], v[156:159], v[132:135]
	v_mfma_f32_16x16x32_bf16 v[128:131], v[148:151], v[156:159], v[128:131]
	v_mfma_f32_16x16x32_bf16 v[124:127], v[140:143], v[164:167], v[124:127]
	v_mfma_f32_16x16x32_bf16 v[116:119], v[148:151], v[164:167], v[116:119]
	v_mfma_f32_16x16x32_bf16 v[108:111], v[140:143], v[176:179], v[108:111]
	v_mfma_f32_16x16x32_bf16 v[100:103], v[148:151], v[176:179], v[100:103]
	v_mfma_f32_16x16x32_bf16 v[92:95], v[140:143], v[196:199], v[92:95]
	v_mfma_f32_16x16x32_bf16 v[84:87], v[148:151], v[196:199], v[84:87]
	v_mfma_f32_16x16x32_bf16 v[132:135], v[144:147], v[160:163], v[132:135]
	v_mfma_f32_16x16x32_bf16 v[128:131], v[152:155], v[160:163], v[128:131]
	v_mfma_f32_16x16x32_bf16 v[124:127], v[144:147], v[172:175], v[124:127]
	v_mfma_f32_16x16x32_bf16 v[116:119], v[152:155], v[172:175], v[116:119]
	v_mfma_f32_16x16x32_bf16 v[108:111], v[144:147], v[180:183], v[108:111]
	v_mfma_f32_16x16x32_bf16 v[100:103], v[152:155], v[180:183], v[100:103]
	v_mfma_f32_16x16x32_bf16 v[92:95], v[144:147], v[200:203], v[92:95]
	v_mfma_f32_16x16x32_bf16 v[84:87], v[152:155], v[200:203], v[84:87]
	s_barrier
	s_mov_b32 m0, s45
	v_lshl_add_u64 v[184:185], s[16:17], 0, v[0:1]
	ds_read_b128 v[204:207], v255 offset:16384
	ds_read_b128 v[208:211], v255 offset:17408
	ds_read_b128 v[212:215], v255 offset:18432
	ds_read_b128 v[216:219], v255 offset:19456
	global_load_lds_dwordx4 v0, s[16:17]
	s_mov_b32 m0, s54
	s_add_u32 vcc_lo, s16, s64
	s_addc_u32 vcc_hi, s17, s65
	global_load_lds_dwordx4 v0, vcc
	s_barrier
	s_waitcnt lgkmcnt(0)
	v_mfma_f32_16x16x32_bf16 v[120:123], v[204:207], v[156:159], v[120:123]
	v_mfma_f32_16x16x32_bf16 v[112:115], v[212:215], v[156:159], v[112:115]
	v_mfma_f32_16x16x32_bf16 v[104:107], v[204:207], v[164:167], v[104:107]
	v_mfma_f32_16x16x32_bf16 v[96:99], v[212:215], v[164:167], v[96:99]
	v_mfma_f32_16x16x32_bf16 v[88:91], v[204:207], v[176:179], v[88:91]
	v_mfma_f32_16x16x32_bf16 v[80:83], v[212:215], v[176:179], v[80:83]
	v_mfma_f32_16x16x32_bf16 v[76:79], v[204:207], v[196:199], v[76:79]
	v_mfma_f32_16x16x32_bf16 v[72:75], v[212:215], v[196:199], v[72:75]
	v_mfma_f32_16x16x32_bf16 v[120:123], v[208:211], v[160:163], v[120:123]
	v_mfma_f32_16x16x32_bf16 v[112:115], v[216:219], v[160:163], v[112:115]
	v_mfma_f32_16x16x32_bf16 v[104:107], v[208:211], v[172:175], v[104:107]
	v_mfma_f32_16x16x32_bf16 v[96:99], v[216:219], v[172:175], v[96:99]
	v_mfma_f32_16x16x32_bf16 v[88:91], v[208:211], v[180:183], v[88:91]
	v_mfma_f32_16x16x32_bf16 v[80:83], v[216:219], v[180:183], v[80:83]
	v_mfma_f32_16x16x32_bf16 v[76:79], v[208:211], v[200:203], v[76:79]
	v_mfma_f32_16x16x32_bf16 v[72:75], v[216:219], v[200:203], v[72:75]
	s_barrier
	s_mov_b32 m0, s31
	v_lshl_add_u64 v[220:221], s[20:21], 0, v[2:3]
	s_mov_b64 s[4:5], 0x8000
	ds_read_b128 v[156:159], v138 offset:16384
	ds_read_b128 v[160:163], v138 offset:17408
	ds_read_b128 v[164:167], v138 offset:18432
	ds_read_b128 v[172:175], v138 offset:19456
	ds_read_b128 v[176:179], v138 offset:20480
	ds_read_b128 v[180:183], v138 offset:21504
	ds_read_b128 v[196:199], v138 offset:22528
	ds_read_b128 v[200:203], v138 offset:23552
	global_load_lds_dwordx4 v2, s[20:21]
	s_mov_b32 m0, s33
	s_mov_b64 s[16:17], 0x18000
	s_add_u32 vcc_lo, s20, s4
	s_addc_u32 vcc_hi, s21, s5
	global_load_lds_dwordx4 v2, vcc
	s_barrier
	s_waitcnt lgkmcnt(0)
	s_mov_b64 s[20:21], 0x8080
	s_waitcnt lgkmcnt(0)
	v_mfma_f32_16x16x32_bf16 v[68:71], v[140:143], v[156:159], v[68:71]
	v_mfma_f32_16x16x32_bf16 v[64:67], v[148:151], v[156:159], v[64:67]
	v_mfma_f32_16x16x32_bf16 v[60:63], v[140:143], v[164:167], v[60:63]
	v_mfma_f32_16x16x32_bf16 v[52:55], v[148:151], v[164:167], v[52:55]
	v_mfma_f32_16x16x32_bf16 v[44:47], v[140:143], v[176:179], v[44:47]
	v_mfma_f32_16x16x32_bf16 v[36:39], v[148:151], v[176:179], v[36:39]
	v_mfma_f32_16x16x32_bf16 v[28:31], v[140:143], v[196:199], v[28:31]
	v_mfma_f32_16x16x32_bf16 v[20:23], v[148:151], v[196:199], v[20:23]
	v_mfma_f32_16x16x32_bf16 v[68:71], v[144:147], v[160:163], v[68:71]
	v_mfma_f32_16x16x32_bf16 v[64:67], v[152:155], v[160:163], v[64:67]
	v_mfma_f32_16x16x32_bf16 v[60:63], v[144:147], v[172:175], v[60:63]
	v_mfma_f32_16x16x32_bf16 v[52:55], v[152:155], v[172:175], v[52:55]
	v_mfma_f32_16x16x32_bf16 v[44:47], v[144:147], v[180:183], v[44:47]
	v_mfma_f32_16x16x32_bf16 v[36:39], v[152:155], v[180:183], v[36:39]
	v_mfma_f32_16x16x32_bf16 v[28:31], v[144:147], v[200:203], v[28:31]
	v_mfma_f32_16x16x32_bf16 v[20:23], v[152:155], v[200:203], v[20:23]
	s_barrier
	s_mov_b32 m0, s51
	v_lshl_add_u64 v[140:141], v[184:185], 0, s[58:59]
	global_load_lds_dwordx4 v[140:141], off
	v_lshl_add_u64 v[140:141], v[184:185], 0, s[16:17]
	s_mov_b32 m0, s50
	s_nop 0
	global_load_lds_dwordx4 v[140:141], off
	s_waitcnt vmcnt(6)
	s_barrier
	v_mfma_f32_16x16x32_bf16 v[56:59], v[204:207], v[156:159], v[56:59]
	v_mfma_f32_16x16x32_bf16 v[48:51], v[212:215], v[156:159], v[48:51]
	v_mfma_f32_16x16x32_bf16 v[40:43], v[204:207], v[164:167], v[40:43]
	v_mfma_f32_16x16x32_bf16 v[32:35], v[212:215], v[164:167], v[32:35]
	v_mfma_f32_16x16x32_bf16 v[24:27], v[204:207], v[176:179], v[24:27]
	v_mfma_f32_16x16x32_bf16 v[16:19], v[212:215], v[176:179], v[16:19]
	v_mfma_f32_16x16x32_bf16 v[12:15], v[204:207], v[196:199], v[12:15]
	v_mfma_f32_16x16x32_bf16 v[8:11], v[212:215], v[196:199], v[8:11]
	v_mfma_f32_16x16x32_bf16 v[56:59], v[208:211], v[160:163], v[56:59]
	v_mfma_f32_16x16x32_bf16 v[48:51], v[216:219], v[160:163], v[48:51]
	v_mfma_f32_16x16x32_bf16 v[40:43], v[208:211], v[172:175], v[40:43]
	v_mfma_f32_16x16x32_bf16 v[32:35], v[216:219], v[172:175], v[32:35]
	v_mfma_f32_16x16x32_bf16 v[24:27], v[208:211], v[180:183], v[24:27]
	v_mfma_f32_16x16x32_bf16 v[16:19], v[216:219], v[180:183], v[16:19]
	v_mfma_f32_16x16x32_bf16 v[12:15], v[208:211], v[200:203], v[12:15]
	v_mfma_f32_16x16x32_bf16 v[8:11], v[216:219], v[200:203], v[8:11]
	s_barrier
	ds_read_b128 v[140:143], v255 offset:32768
	ds_read_b128 v[144:147], v255 offset:33792
	ds_read_b128 v[148:151], v255 offset:34816
	ds_read_b128 v[152:155], v255 offset:35840
	s_mov_b32 m0, s34
	v_lshl_add_u64 v[204:205], v[220:221], 0, s[58:59]
	ds_read_b128 v[156:159], v138 offset:32768
	ds_read_b128 v[160:163], v138 offset:33792
	ds_read_b128 v[164:167], v138 offset:34816
	ds_read_b128 v[172:175], v138 offset:35840
	ds_read_b128 v[176:179], v138 offset:36864
	ds_read_b128 v[180:183], v138 offset:37888
	ds_read_b128 v[196:199], v138 offset:38912
	ds_read_b128 v[200:203], v138 offset:39936
	global_load_lds_dwordx4 v[204:205], off
	v_lshl_add_u64 v[204:205], v[220:221], 0, s[16:17]
	s_mov_b32 m0, s35
	s_nop 0
	global_load_lds_dwordx4 v[204:205], off
	s_waitcnt lgkmcnt(8)
	s_barrier
	s_waitcnt lgkmcnt(0)
	v_mfma_f32_16x16x32_bf16 v[132:135], v[140:143], v[156:159], v[132:135]
	v_mfma_f32_16x16x32_bf16 v[128:131], v[148:151], v[156:159], v[128:131]
	v_mfma_f32_16x16x32_bf16 v[124:127], v[140:143], v[164:167], v[124:127]
	v_mfma_f32_16x16x32_bf16 v[116:119], v[148:151], v[164:167], v[116:119]
	v_mfma_f32_16x16x32_bf16 v[108:111], v[140:143], v[176:179], v[108:111]
	v_mfma_f32_16x16x32_bf16 v[100:103], v[148:151], v[176:179], v[100:103]
	v_mfma_f32_16x16x32_bf16 v[92:95], v[140:143], v[196:199], v[92:95]
	v_mfma_f32_16x16x32_bf16 v[84:87], v[148:151], v[196:199], v[84:87]
	v_mfma_f32_16x16x32_bf16 v[132:135], v[144:147], v[160:163], v[132:135]
	v_mfma_f32_16x16x32_bf16 v[128:131], v[152:155], v[160:163], v[128:131]
	v_mfma_f32_16x16x32_bf16 v[124:127], v[144:147], v[172:175], v[124:127]
	v_mfma_f32_16x16x32_bf16 v[116:119], v[152:155], v[172:175], v[116:119]
	v_mfma_f32_16x16x32_bf16 v[108:111], v[144:147], v[180:183], v[108:111]
	v_mfma_f32_16x16x32_bf16 v[100:103], v[152:155], v[180:183], v[100:103]
	v_mfma_f32_16x16x32_bf16 v[92:95], v[144:147], v[200:203], v[92:95]
	v_mfma_f32_16x16x32_bf16 v[84:87], v[152:155], v[200:203], v[84:87]
	s_barrier
	s_mov_b32 m0, s19
	v_lshl_add_u64 v[222:223], v[184:185], 0, s[46:47]
	ds_read_b128 v[204:207], v255 offset:49152
	ds_read_b128 v[208:211], v255 offset:50176
	ds_read_b128 v[212:215], v255 offset:51200
	ds_read_b128 v[216:219], v255 offset:52224
	global_load_lds_dwordx4 v[222:223], off
	v_lshl_add_u64 v[222:223], v[184:185], 0, s[20:21]
	s_mov_b32 m0, s44
	s_mov_b64 s[4:5], 0x10080
	global_load_lds_dwordx4 v[222:223], off
	s_barrier
	s_waitcnt lgkmcnt(0)
	v_mfma_f32_16x16x32_bf16 v[120:123], v[204:207], v[156:159], v[120:123]
	v_mfma_f32_16x16x32_bf16 v[112:115], v[212:215], v[156:159], v[112:115]
	v_mfma_f32_16x16x32_bf16 v[104:107], v[204:207], v[164:167], v[104:107]
	v_mfma_f32_16x16x32_bf16 v[96:99], v[212:215], v[164:167], v[96:99]
	v_mfma_f32_16x16x32_bf16 v[88:91], v[204:207], v[176:179], v[88:91]
	v_mfma_f32_16x16x32_bf16 v[80:83], v[212:215], v[176:179], v[80:83]
	v_mfma_f32_16x16x32_bf16 v[76:79], v[204:207], v[196:199], v[76:79]
	v_mfma_f32_16x16x32_bf16 v[72:75], v[212:215], v[196:199], v[72:75]
	v_mfma_f32_16x16x32_bf16 v[120:123], v[208:211], v[160:163], v[120:123]
	v_mfma_f32_16x16x32_bf16 v[112:115], v[216:219], v[160:163], v[112:115]
	v_mfma_f32_16x16x32_bf16 v[104:107], v[208:211], v[172:175], v[104:107]
	v_mfma_f32_16x16x32_bf16 v[96:99], v[216:219], v[172:175], v[96:99]
	v_mfma_f32_16x16x32_bf16 v[88:91], v[208:211], v[180:183], v[88:91]
	v_mfma_f32_16x16x32_bf16 v[80:83], v[216:219], v[180:183], v[80:83]
	v_mfma_f32_16x16x32_bf16 v[76:79], v[208:211], v[200:203], v[76:79]
	v_mfma_f32_16x16x32_bf16 v[72:75], v[216:219], v[200:203], v[72:75]
	s_barrier
	s_mov_b32 m0, s36
	v_lshl_add_u64 v[222:223], v[220:221], 0, s[46:47]
	ds_read_b128 v[156:159], v138 offset:49152
	ds_read_b128 v[160:163], v138 offset:50176
	ds_read_b128 v[164:167], v138 offset:51200
	ds_read_b128 v[172:175], v138 offset:52224
	ds_read_b128 v[176:179], v138 offset:53248
	ds_read_b128 v[180:183], v138 offset:54272
	ds_read_b128 v[196:199], v138 offset:55296
	ds_read_b128 v[200:203], v138 offset:56320
	global_load_lds_dwordx4 v[222:223], off
	v_lshl_add_u64 v[220:221], v[220:221], 0, s[20:21]
	s_mov_b32 m0, s37
	s_nop 0
	global_load_lds_dwordx4 v[220:221], off
	s_barrier
	s_waitcnt lgkmcnt(0)
	v_mfma_f32_16x16x32_bf16 v[68:71], v[140:143], v[156:159], v[68:71]
	v_mfma_f32_16x16x32_bf16 v[64:67], v[148:151], v[156:159], v[64:67]
	v_mfma_f32_16x16x32_bf16 v[60:63], v[140:143], v[164:167], v[60:63]
	v_mfma_f32_16x16x32_bf16 v[52:55], v[148:151], v[164:167], v[52:55]
	v_mfma_f32_16x16x32_bf16 v[44:47], v[140:143], v[176:179], v[44:47]
	v_mfma_f32_16x16x32_bf16 v[36:39], v[148:151], v[176:179], v[36:39]
	v_mfma_f32_16x16x32_bf16 v[28:31], v[140:143], v[196:199], v[28:31]
	v_mfma_f32_16x16x32_bf16 v[20:23], v[148:151], v[196:199], v[20:23]
	v_mfma_f32_16x16x32_bf16 v[68:71], v[144:147], v[160:163], v[68:71]
	v_mfma_f32_16x16x32_bf16 v[64:67], v[152:155], v[160:163], v[64:67]
	v_mfma_f32_16x16x32_bf16 v[60:63], v[144:147], v[172:175], v[60:63]
	v_mfma_f32_16x16x32_bf16 v[52:55], v[152:155], v[172:175], v[52:55]
	v_mfma_f32_16x16x32_bf16 v[44:47], v[144:147], v[180:183], v[44:47]
	v_mfma_f32_16x16x32_bf16 v[36:39], v[152:155], v[180:183], v[36:39]
	v_mfma_f32_16x16x32_bf16 v[28:31], v[144:147], v[200:203], v[28:31]
	v_mfma_f32_16x16x32_bf16 v[20:23], v[152:155], v[200:203], v[20:23]
	s_barrier
	s_mov_b32 m0, s53
	v_lshl_add_u64 v[140:141], v[184:185], 0, s[4:5]
	global_load_lds_dwordx4 v[140:141], off
	v_lshl_add_u64 v[140:141], v[184:185], 0, s[68:69]
	s_mov_b32 m0, s52
	s_nop 0
	global_load_lds_dwordx4 v[140:141], off
	s_waitcnt vmcnt(6)
	s_barrier
	v_mfma_f32_16x16x32_bf16 v[56:59], v[204:207], v[156:159], v[56:59]
	v_mfma_f32_16x16x32_bf16 v[48:51], v[212:215], v[156:159], v[48:51]
	v_mfma_f32_16x16x32_bf16 v[40:43], v[204:207], v[164:167], v[40:43]
	v_mfma_f32_16x16x32_bf16 v[32:35], v[212:215], v[164:167], v[32:35]
	v_mfma_f32_16x16x32_bf16 v[24:27], v[204:207], v[176:179], v[24:27]
	v_mfma_f32_16x16x32_bf16 v[16:19], v[212:215], v[176:179], v[16:19]
	v_mfma_f32_16x16x32_bf16 v[12:15], v[204:207], v[196:199], v[12:15]
	v_mfma_f32_16x16x32_bf16 v[8:11], v[212:215], v[196:199], v[8:11]
	v_mfma_f32_16x16x32_bf16 v[56:59], v[208:211], v[160:163], v[56:59]
	v_mfma_f32_16x16x32_bf16 v[48:51], v[216:219], v[160:163], v[48:51]
	v_mfma_f32_16x16x32_bf16 v[40:43], v[208:211], v[172:175], v[40:43]
	v_mfma_f32_16x16x32_bf16 v[32:35], v[216:219], v[172:175], v[32:35]
	v_mfma_f32_16x16x32_bf16 v[24:27], v[208:211], v[180:183], v[24:27]
	v_mfma_f32_16x16x32_bf16 v[16:19], v[216:219], v[180:183], v[16:19]
	v_mfma_f32_16x16x32_bf16 v[12:15], v[208:211], v[200:203], v[12:15]
	v_mfma_f32_16x16x32_bf16 v[8:11], v[216:219], v[200:203], v[8:11]
	s_andn2_b64 vcc, exec, s[14:15]
	s_mov_b64 s[16:17], -1
	s_mov_b64 s[14:15], 0
	s_mov_b64 s[18:19], 0x100
	s_cbranch_vccz .Ldb_PLE0_cont

.LBB0_1282:
	s_add_u32 s2, s24, 0x40080
	s_addc_u32 s3, s25, 0
	s_add_u32 s22, s22, 0x100
	s_waitcnt lgkmcnt(0)
	s_addc_u32 s23, s23, 0
	s_mov_b32 s24, -2
	s_mov_b64 s[54:55], 0x40000
	s_mov_b64 s[58:59], 0x60000
	s_mov_b64 s[62:63], 0x20080
	s_mov_b64 s[64:65], 0x40080
	s_mov_b64 s[66:67], 0x60080
	s_cmp_eq_u32 s101, 2
	s_cselect_b32 s101, 0, s101
	s_setprio 0
	v_add_u32_e32 v255, 0x10000, v181
	s_add_u32 s4, s2, 0xfffc0080
	s_addc_u32 s5, s3, -1
	s_add_i32 s25, 0, 0x10000
	ds_read_b128 v[136:139], v255 offset:0
	ds_read_b128 v[140:143], v255 offset:1024
	ds_read_b128 v[144:147], v255 offset:2048
	ds_read_b128 v[148:151], v255 offset:3072
	s_cmp_eq_u32 s24, 12
	s_cselect_b32 s5, s19, s5
	s_cselect_b32 s4, s18, s4
	s_cselect_b32 s41, s21, s23
	s_cselect_b32 s40, s20, s22
	s_add_i32 m0, s29, 0xc000
	ds_read_b128 v[152:155], v182
	ds_read_b128 v[160:163], v182 offset:1024
	ds_read_b128 v[164:167], v182 offset:2048
	ds_read_b128 v[172:175], v182 offset:3072
	ds_read_b128 v[176:179], v182 offset:4096
	ds_read_b128 v[196:199], v182 offset:5120
	ds_read_b128 v[200:203], v182 offset:6144
	ds_read_b128 v[204:207], v182 offset:7168
	global_load_lds_dwordx4 v158, s[2:3]
	s_add_i32 m0, s29, 0xe000
	s_add_u32 vcc_lo, s2, s0
	s_addc_u32 vcc_hi, s3, s1
	global_load_lds_dwordx4 v158, vcc
	s_waitcnt lgkmcnt(8)
	s_cmp_eq_u32 s101, 1
	s_cbranch_scc1 .Ldb_PLE1_skp
	s_barrier
.Ldb_PLE1_skp:
	s_mov_b32 s101, 0
	s_waitcnt lgkmcnt(0)
	v_mfma_f32_16x16x32_bf16 v[132:135], v[136:139], v[152:155], 0
	v_mfma_f32_16x16x32_bf16 v[128:131], v[144:147], v[152:155], 0
	v_mfma_f32_16x16x32_bf16 v[116:119], v[136:139], v[164:167], 0
	v_mfma_f32_16x16x32_bf16 v[112:115], v[144:147], v[164:167], 0
	v_mfma_f32_16x16x32_bf16 v[100:103], v[136:139], v[176:179], 0
	v_mfma_f32_16x16x32_bf16 v[96:99], v[144:147], v[176:179], 0
	v_mfma_f32_16x16x32_bf16 v[84:87], v[136:139], v[200:203], 0
	v_mfma_f32_16x16x32_bf16 v[80:83], v[144:147], v[200:203], 0
	v_mfma_f32_16x16x32_bf16 v[132:135], v[140:143], v[160:163], v[132:135]
	v_mfma_f32_16x16x32_bf16 v[128:131], v[148:151], v[160:163], v[128:131]
	v_mfma_f32_16x16x32_bf16 v[116:119], v[140:143], v[172:175], v[116:119]
	v_mfma_f32_16x16x32_bf16 v[112:115], v[148:151], v[172:175], v[112:115]
	v_mfma_f32_16x16x32_bf16 v[100:103], v[140:143], v[196:199], v[100:103]
	v_mfma_f32_16x16x32_bf16 v[96:99], v[148:151], v[196:199], v[96:99]
	v_mfma_f32_16x16x32_bf16 v[84:87], v[140:143], v[204:207], v[84:87]
	v_mfma_f32_16x16x32_bf16 v[80:83], v[148:151], v[204:207], v[80:83]
	s_barrier
	s_add_i32 s44, 0, 0x14000
	s_add_i32 s25, s25, s27
	s_mov_b32 m0, s25
	ds_read_b128 v[208:211], v255 offset:16384
	ds_read_b128 v[212:215], v255 offset:17408
	ds_read_b128 v[216:219], v255 offset:18432
	ds_read_b128 v[220:223], v255 offset:19456
	global_load_lds_dwordx4 v156, s[40:41]
	s_add_i32 m0, s25, 0x2000
	s_add_u32 vcc_lo, s40, s0
	s_addc_u32 vcc_hi, s41, s1
	global_load_lds_dwordx4 v156, vcc
	s_barrier
	s_waitcnt lgkmcnt(0)
	v_mfma_f32_16x16x32_bf16 v[124:127], v[208:211], v[152:155], 0
	v_mfma_f32_16x16x32_bf16 v[120:123], v[216:219], v[152:155], 0
	v_mfma_f32_16x16x32_bf16 v[108:111], v[208:211], v[164:167], 0
	v_mfma_f32_16x16x32_bf16 v[104:107], v[216:219], v[164:167], 0
	v_mfma_f32_16x16x32_bf16 v[92:95], v[208:211], v[176:179], 0
	v_mfma_f32_16x16x32_bf16 v[88:91], v[216:219], v[176:179], 0
	v_mfma_f32_16x16x32_bf16 v[76:79], v[208:211], v[200:203], 0
	v_mfma_f32_16x16x32_bf16 v[72:75], v[216:219], v[200:203], 0
	v_mfma_f32_16x16x32_bf16 v[124:127], v[212:215], v[160:163], v[124:127]
	v_mfma_f32_16x16x32_bf16 v[120:123], v[220:223], v[160:163], v[120:123]
	v_mfma_f32_16x16x32_bf16 v[108:111], v[212:215], v[172:175], v[108:111]
	v_mfma_f32_16x16x32_bf16 v[104:107], v[220:223], v[172:175], v[104:107]
	v_mfma_f32_16x16x32_bf16 v[92:95], v[212:215], v[196:199], v[92:95]
	v_mfma_f32_16x16x32_bf16 v[88:91], v[220:223], v[196:199], v[88:91]
	v_mfma_f32_16x16x32_bf16 v[76:79], v[212:215], v[204:207], v[76:79]
	v_mfma_f32_16x16x32_bf16 v[72:75], v[220:223], v[204:207], v[72:75]
	s_barrier
	s_mov_b32 m0, s29
	v_lshl_add_u64 v[224:225], s[4:5], 0, v[2:3]
	ds_read_b128 v[152:155], v182 offset:16384
	ds_read_b128 v[160:163], v182 offset:17408
	ds_read_b128 v[164:167], v182 offset:18432
	ds_read_b128 v[172:175], v182 offset:19456
	ds_read_b128 v[176:179], v182 offset:20480
	ds_read_b128 v[196:199], v182 offset:21504
	ds_read_b128 v[200:203], v182 offset:22528
	ds_read_b128 v[204:207], v182 offset:23552
	global_load_lds_dwordx4 v2, s[4:5]
	s_mov_b32 m0, s30
	s_add_u32 vcc_lo, s4, s0
	s_addc_u32 vcc_hi, s5, s1
	global_load_lds_dwordx4 v2, vcc
	s_barrier
	s_waitcnt lgkmcnt(0)
	v_mfma_f32_16x16x32_bf16 v[68:71], v[136:139], v[152:155], 0
	v_mfma_f32_16x16x32_bf16 v[64:67], v[144:147], v[152:155], 0
	v_mfma_f32_16x16x32_bf16 v[52:55], v[136:139], v[164:167], 0
	v_mfma_f32_16x16x32_bf16 v[48:51], v[144:147], v[164:167], 0
	v_mfma_f32_16x16x32_bf16 v[36:39], v[136:139], v[176:179], 0
	v_mfma_f32_16x16x32_bf16 v[32:35], v[144:147], v[176:179], 0
	v_mfma_f32_16x16x32_bf16 v[20:23], v[136:139], v[200:203], 0
	v_mfma_f32_16x16x32_bf16 v[16:19], v[144:147], v[200:203], 0
	v_mfma_f32_16x16x32_bf16 v[68:71], v[140:143], v[160:163], v[68:71]
	v_mfma_f32_16x16x32_bf16 v[64:67], v[148:151], v[160:163], v[64:67]
	v_mfma_f32_16x16x32_bf16 v[52:55], v[140:143], v[172:175], v[52:55]
	v_mfma_f32_16x16x32_bf16 v[48:51], v[148:151], v[172:175], v[48:51]
	v_mfma_f32_16x16x32_bf16 v[36:39], v[140:143], v[196:199], v[36:39]
	v_mfma_f32_16x16x32_bf16 v[32:35], v[148:151], v[196:199], v[32:35]
	v_mfma_f32_16x16x32_bf16 v[20:23], v[140:143], v[204:207], v[20:23]
	v_mfma_f32_16x16x32_bf16 v[16:19], v[148:151], v[204:207], v[16:19]
	s_barrier
; #define G_STAGE(bufoff, gbase, o0, h64) do { \
;         __builtin_amdgcn_global_load_lds((const unsigned*)((const char*)(gbase) + (o0)), (LAS unsigned*)(lds + (bufoff) + ldsw), 16, 0, 0); \
;         __builtin_amdgcn_global_load_lds((const unsigned*)((const char*)(gbase) + (h64) + (o0)), (LAS unsigned*)(lds + (bufoff) + ldsw + 8192), 16, 0, 0); } while (0)
; #define G_LDA(dst, b, h) do { _Pragma("unroll") for (int m = 0; m < 4; ++m) _Pragma("unroll") for (int k = 0; k < 2; ++k) dst[m][k] = *(const LAS bf16x8*)(lds + G_SA(b, h) + aoff + m * 2048 + k * 1024); } while (0)
; #define G_LDB(dst, b, h) do { _Pragma("unroll") for (int n = 0; n < 2; ++n) _Pragma("unroll") for (int k = 0; k < 2; ++k) dst[n][k] = *(const LAS bf16x8*)(lds + G_SB(b, h) + boff + n * 2048 + k * 1024); } while (0)
; #define G_WAIT_V(n) asm volatile("s_waitcnt vmcnt(" #n ")" ::: "memory")
; #define G_BAR __builtin_amdgcn_s_barrier()
;     ...
;         for (int t = 0; t < nt; t += 2) {
;             const bool last = (t == nt - 2);
;             const char* a1 = cA + (size_t)(t + 1) * ckA;
;             const char* a2 = last ? nA : cA + (size_t)(t + 2) * ckA; const char* b2 = last ? nB : cB + (size_t)(t + 2) * kB;
;             const char* a3 = a2 + ckA; const char* b3 = b2 + kB;
;             G_LDB(B0, 0, 0); G_SCHED; G_LDA(At, 0, 0); G_STAGE(G_SA(1, 1), a1 + chA, cA0, qA);
;             G_WAIT_L(8); G_BAR; G_WAIT_L(0); G_MMA(0, 0, At, B0); G_BAR; G_SCHED;
;             G_LDB(B1, 0, 1); G_STAGE(G_SB(0, 0), b2, cB0, qB);
;             G_BAR; G_WAIT_L(0); G_MMA(0, 1, At, B1); G_BAR;
;             G_LDA(At, 0, 1); G_STAGE(G_SA(0, 0), a2, cA0, qA);
;             G_BAR; G_WAIT_L(0); G_MMA(1, 0, At, B0); G_BAR; G_SCHED;
;             G_STAGE(G_SB(0, 1), b2 + chB, cB0, qB);
;             G_WAIT_V(6); G_BAR; G_MMA(1, 1, At, B1); G_BAR;
;             G_LDB(B0, 1, 0); G_SCHED; G_LDA(At, 1, 0); G_STAGE(G_SA(0, 1), a2 + chA, cA0, qA);
;             G_WAIT_L(8); G_BAR; G_WAIT_L(0); G_MMA(0, 0, At, B0); G_BAR; G_SCHED;
;             G_LDB(B1, 1, 1); G_STAGE(G_SB(1, 0), b3, cB0, qB);
;             G_BAR; G_WAIT_L(0); G_MMA(0, 1, At, B1); G_BAR;
;             G_LDA(At, 1, 1); G_STAGE(G_SA(1, 0), a3, cA0, qA);
;             G_BAR; G_WAIT_L(0); G_MMA(1, 0, At, B0); G_BAR; G_SCHED;
;             G_STAGE(G_SB(1, 1), b3 + chB, cB0, qB);
;             G_WAIT_V(6); G_BAR; G_MMA(1, 1, At, B1); G_BAR;
	s_add_i32 s100, s44, s27
	s_mov_b32 m0, s100
	s_add_u32 vcc_lo, s40, s54
	s_addc_u32 vcc_hi, s41, s55
	global_load_lds_dwordx4 v156, vcc
	s_add_i32 m0, s100, 0x2000
	s_add_u32 vcc_lo, s40, s58
	s_addc_u32 vcc_hi, s41, s59
	global_load_lds_dwordx4 v156, vcc
	s_waitcnt vmcnt(6)
	s_barrier
	v_mfma_f32_16x16x32_bf16 v[60:63], v[208:211], v[152:155], 0
	v_mfma_f32_16x16x32_bf16 v[56:59], v[216:219], v[152:155], 0
	v_mfma_f32_16x16x32_bf16 v[44:47], v[208:211], v[164:167], 0
	v_mfma_f32_16x16x32_bf16 v[40:43], v[216:219], v[164:167], 0
	v_mfma_f32_16x16x32_bf16 v[28:31], v[208:211], v[176:179], 0
	v_mfma_f32_16x16x32_bf16 v[24:27], v[216:219], v[176:179], 0
	v_mfma_f32_16x16x32_bf16 v[12:15], v[208:211], v[200:203], 0
	v_mfma_f32_16x16x32_bf16 v[8:11], v[216:219], v[200:203], 0
	v_mfma_f32_16x16x32_bf16 v[60:63], v[212:215], v[160:163], v[60:63]
	v_mfma_f32_16x16x32_bf16 v[56:59], v[220:223], v[160:163], v[56:59]
	v_mfma_f32_16x16x32_bf16 v[44:47], v[212:215], v[172:175], v[44:47]
	v_mfma_f32_16x16x32_bf16 v[40:43], v[220:223], v[172:175], v[40:43]
	v_mfma_f32_16x16x32_bf16 v[28:31], v[212:215], v[196:199], v[28:31]
	v_mfma_f32_16x16x32_bf16 v[24:27], v[220:223], v[196:199], v[24:27]
	v_mfma_f32_16x16x32_bf16 v[12:15], v[212:215], v[204:207], v[12:15]
	v_mfma_f32_16x16x32_bf16 v[8:11], v[220:223], v[204:207], v[8:11]
	s_barrier
	s_add_i32 s100, 0, 0x18000
	ds_read_b128 v[136:139], v255 offset:32768
	ds_read_b128 v[140:143], v255 offset:33792
	ds_read_b128 v[144:147], v255 offset:34816
	ds_read_b128 v[148:151], v255 offset:35840
	s_mov_b32 m0, s31
	ds_read_b128 v[152:155], v182 offset:32768
	ds_read_b128 v[160:163], v182 offset:33792
	ds_read_b128 v[164:167], v182 offset:34816
	ds_read_b128 v[172:175], v182 offset:35840
	ds_read_b128 v[176:179], v182 offset:36864
	ds_read_b128 v[196:199], v182 offset:37888
	ds_read_b128 v[200:203], v182 offset:38912
	ds_read_b128 v[204:207], v182 offset:39936
	s_add_u32 vcc_lo, s4, s54
	s_addc_u32 vcc_hi, s5, s55
	global_load_lds_dwordx4 v2, vcc
	s_mov_b32 m0, s34
	s_add_u32 vcc_lo, s4, s58
	s_addc_u32 vcc_hi, s5, s59
	global_load_lds_dwordx4 v2, vcc
	s_waitcnt lgkmcnt(8)
	s_barrier
	s_waitcnt lgkmcnt(0)
	v_mfma_f32_16x16x32_bf16 v[132:135], v[136:139], v[152:155], v[132:135]
	v_mfma_f32_16x16x32_bf16 v[128:131], v[144:147], v[152:155], v[128:131]
	v_mfma_f32_16x16x32_bf16 v[116:119], v[136:139], v[164:167], v[116:119]
	v_mfma_f32_16x16x32_bf16 v[112:115], v[144:147], v[164:167], v[112:115]
	v_mfma_f32_16x16x32_bf16 v[100:103], v[136:139], v[176:179], v[100:103]
	v_mfma_f32_16x16x32_bf16 v[96:99], v[144:147], v[176:179], v[96:99]
	v_mfma_f32_16x16x32_bf16 v[84:87], v[136:139], v[200:203], v[84:87]
	v_mfma_f32_16x16x32_bf16 v[80:83], v[144:147], v[200:203], v[80:83]
	v_mfma_f32_16x16x32_bf16 v[132:135], v[140:143], v[160:163], v[132:135]
	v_mfma_f32_16x16x32_bf16 v[128:131], v[148:151], v[160:163], v[128:131]
	v_mfma_f32_16x16x32_bf16 v[116:119], v[140:143], v[172:175], v[116:119]
	v_mfma_f32_16x16x32_bf16 v[112:115], v[148:151], v[172:175], v[112:115]
	v_mfma_f32_16x16x32_bf16 v[100:103], v[140:143], v[196:199], v[100:103]
	v_mfma_f32_16x16x32_bf16 v[96:99], v[148:151], v[196:199], v[96:99]
	v_mfma_f32_16x16x32_bf16 v[84:87], v[140:143], v[204:207], v[84:87]
	v_mfma_f32_16x16x32_bf16 v[80:83], v[148:151], v[204:207], v[80:83]
	s_barrier
	s_add_i32 s5, 0, 0x1c000
	s_add_i32 s4, s100, s27
	s_mov_b32 m0, s4
	ds_read_b128 v[208:211], v255 offset:49152
	ds_read_b128 v[212:215], v255 offset:50176
	ds_read_b128 v[216:219], v255 offset:51200
	ds_read_b128 v[220:223], v255 offset:52224
	s_add_u32 vcc_lo, s40, s46
	s_addc_u32 vcc_hi, s41, s47
	global_load_lds_dwordx4 v156, vcc
	s_add_i32 m0, s4, 0x2000
	s_add_u32 vcc_lo, s40, s62
	s_addc_u32 vcc_hi, s41, s63
	global_load_lds_dwordx4 v156, vcc
	s_barrier
	s_waitcnt lgkmcnt(0)
	v_mfma_f32_16x16x32_bf16 v[124:127], v[208:211], v[152:155], v[124:127]
	v_mfma_f32_16x16x32_bf16 v[120:123], v[216:219], v[152:155], v[120:123]
	v_mfma_f32_16x16x32_bf16 v[108:111], v[208:211], v[164:167], v[108:111]
	v_mfma_f32_16x16x32_bf16 v[104:107], v[216:219], v[164:167], v[104:107]
	v_mfma_f32_16x16x32_bf16 v[92:95], v[208:211], v[176:179], v[92:95]
	v_mfma_f32_16x16x32_bf16 v[88:91], v[216:219], v[176:179], v[88:91]
	v_mfma_f32_16x16x32_bf16 v[76:79], v[208:211], v[200:203], v[76:79]
	v_mfma_f32_16x16x32_bf16 v[72:75], v[216:219], v[200:203], v[72:75]
	v_mfma_f32_16x16x32_bf16 v[124:127], v[212:215], v[160:163], v[124:127]
	v_mfma_f32_16x16x32_bf16 v[120:123], v[220:223], v[160:163], v[120:123]
	v_mfma_f32_16x16x32_bf16 v[108:111], v[212:215], v[172:175], v[108:111]
	v_mfma_f32_16x16x32_bf16 v[104:107], v[220:223], v[172:175], v[104:107]
	v_mfma_f32_16x16x32_bf16 v[92:95], v[212:215], v[196:199], v[92:95]
	v_mfma_f32_16x16x32_bf16 v[88:91], v[220:223], v[196:199], v[88:91]
	v_mfma_f32_16x16x32_bf16 v[76:79], v[212:215], v[204:207], v[76:79]
	v_mfma_f32_16x16x32_bf16 v[72:75], v[220:223], v[204:207], v[72:75]
	s_barrier
	s_mov_b32 m0, s35
	v_lshl_add_u64 v[226:227], v[224:225], 0, s[46:47]
	ds_read_b128 v[152:155], v182 offset:49152
	ds_read_b128 v[160:163], v182 offset:50176
	ds_read_b128 v[164:167], v182 offset:51200
	ds_read_b128 v[172:175], v182 offset:52224
	ds_read_b128 v[176:179], v182 offset:53248
	ds_read_b128 v[196:199], v182 offset:54272
	ds_read_b128 v[200:203], v182 offset:55296
	ds_read_b128 v[204:207], v182 offset:56320
	global_load_lds_dwordx4 v[226:227], off
	v_lshl_add_u64 v[224:225], v[224:225], 0, s[62:63]
	s_mov_b32 m0, s36
	s_nop 0
	global_load_lds_dwordx4 v[224:225], off
	s_barrier
; #define G_STAGE(bufoff, gbase, o0, h64) do { \
;         __builtin_amdgcn_global_load_lds((const unsigned*)((const char*)(gbase) + (o0)), (LAS unsigned*)(lds + (bufoff) + ldsw), 16, 0, 0); \
;         __builtin_amdgcn_global_load_lds((const unsigned*)((const char*)(gbase) + (h64) + (o0)), (LAS unsigned*)(lds + (bufoff) + ldsw + 8192), 16, 0, 0); } while (0)
; #define G_LDA(dst, b, h) do { _Pragma("unroll") for (int m = 0; m < 4; ++m) _Pragma("unroll") for (int k = 0; k < 2; ++k) dst[m][k] = *(const LAS bf16x8*)(lds + G_SA(b, h) + aoff + m * 2048 + k * 1024); } while (0)
; #define G_LDB(dst, b, h) do { _Pragma("unroll") for (int n = 0; n < 2; ++n) _Pragma("unroll") for (int k = 0; k < 2; ++k) dst[n][k] = *(const LAS bf16x8*)(lds + G_SB(b, h) + boff + n * 2048 + k * 1024); } while (0)
; #define G_WAIT_V(n) asm volatile("s_waitcnt vmcnt(" #n ")" ::: "memory")
; #define G_BAR __builtin_amdgcn_s_barrier()
;     ...
;         for (int t = 0; t < nt; t += 2) {
;             const bool last = (t == nt - 2);
;             const char* a1 = cA + (size_t)(t + 1) * ckA;
;             const char* a2 = last ? nA : cA + (size_t)(t + 2) * ckA; const char* b2 = last ? nB : cB + (size_t)(t + 2) * kB;
;             const char* a3 = a2 + ckA; const char* b3 = b2 + kB;
;             G_LDB(B0, 0, 0); G_SCHED; G_LDA(At, 0, 0); G_STAGE(G_SA(1, 1), a1 + chA, cA0, qA);
;             G_WAIT_L(8); G_BAR; G_WAIT_L(0); G_MMA(0, 0, At, B0); G_BAR; G_SCHED;
;             G_LDB(B1, 0, 1); G_STAGE(G_SB(0, 0), b2, cB0, qB);
;             G_BAR; G_WAIT_L(0); G_MMA(0, 1, At, B1); G_BAR;
;             G_LDA(At, 0, 1); G_STAGE(G_SA(0, 0), a2, cA0, qA);
;             G_BAR; G_WAIT_L(0); G_MMA(1, 0, At, B0); G_BAR; G_SCHED;
;             G_STAGE(G_SB(0, 1), b2 + chB, cB0, qB);
;             G_WAIT_V(6); G_BAR; G_MMA(1, 1, At, B1); G_BAR;
;             G_LDB(B0, 1, 0); G_SCHED; G_LDA(At, 1, 0); G_STAGE(G_SA(0, 1), a2 + chA, cA0, qA);
;             G_WAIT_L(8); G_BAR; G_WAIT_L(0); G_MMA(0, 0, At, B0); G_BAR; G_SCHED;
;             G_LDB(B1, 1, 1); G_STAGE(G_SB(1, 0), b3, cB0, qB);
;             G_BAR; G_WAIT_L(0); G_MMA(0, 1, At, B1); G_BAR;
;             G_LDA(At, 1, 1); G_STAGE(G_SA(1, 0), a3, cA0, qA);
;             G_BAR; G_WAIT_L(0); G_MMA(1, 0, At, B0); G_BAR; G_SCHED;
;             G_STAGE(G_SB(1, 1), b3 + chB, cB0, qB);
;             G_WAIT_V(6); G_BAR; G_MMA(1, 1, At, B1); G_BAR;
	s_waitcnt lgkmcnt(0)
	v_mfma_f32_16x16x32_bf16 v[68:71], v[136:139], v[152:155], v[68:71]
	v_mfma_f32_16x16x32_bf16 v[64:67], v[144:147], v[152:155], v[64:67]
	v_mfma_f32_16x16x32_bf16 v[52:55], v[136:139], v[164:167], v[52:55]
	v_mfma_f32_16x16x32_bf16 v[48:51], v[144:147], v[164:167], v[48:51]
	v_mfma_f32_16x16x32_bf16 v[36:39], v[136:139], v[176:179], v[36:39]
	v_mfma_f32_16x16x32_bf16 v[32:35], v[144:147], v[176:179], v[32:35]
	v_mfma_f32_16x16x32_bf16 v[20:23], v[136:139], v[200:203], v[20:23]
	v_mfma_f32_16x16x32_bf16 v[16:19], v[144:147], v[200:203], v[16:19]
	v_mfma_f32_16x16x32_bf16 v[68:71], v[140:143], v[160:163], v[68:71]
	v_mfma_f32_16x16x32_bf16 v[64:67], v[148:151], v[160:163], v[64:67]
	v_mfma_f32_16x16x32_bf16 v[52:55], v[140:143], v[172:175], v[52:55]
	v_mfma_f32_16x16x32_bf16 v[48:51], v[148:151], v[172:175], v[48:51]
	v_mfma_f32_16x16x32_bf16 v[36:39], v[140:143], v[196:199], v[36:39]
	v_mfma_f32_16x16x32_bf16 v[32:35], v[148:151], v[196:199], v[32:35]
	v_mfma_f32_16x16x32_bf16 v[20:23], v[140:143], v[204:207], v[20:23]
	v_mfma_f32_16x16x32_bf16 v[16:19], v[148:151], v[204:207], v[16:19]
	s_barrier
	s_add_i32 s4, s5, s27
	s_mov_b32 m0, s4
	s_add_u32 vcc_lo, s40, s64
	s_addc_u32 vcc_hi, s41, s65
	global_load_lds_dwordx4 v156, vcc
	s_add_i32 m0, s4, 0x2000
	s_add_u32 vcc_lo, s40, s66
	s_addc_u32 vcc_hi, s41, s67
	global_load_lds_dwordx4 v156, vcc
	s_add_i32 s24, s24, 2
	s_add_u32 s2, s2, 0x100
	s_addc_u32 s3, s3, 0
	s_add_u32 s22, s22, 0x100
	s_addc_u32 s23, s23, 0
	s_cmp_gt_u32 s24, 13
	s_waitcnt vmcnt(6)
	s_barrier
	v_mfma_f32_16x16x32_bf16 v[60:63], v[208:211], v[152:155], v[60:63]
	v_mfma_f32_16x16x32_bf16 v[56:59], v[216:219], v[152:155], v[56:59]
	v_mfma_f32_16x16x32_bf16 v[44:47], v[208:211], v[164:167], v[44:47]
	v_mfma_f32_16x16x32_bf16 v[40:43], v[216:219], v[164:167], v[40:43]
	v_mfma_f32_16x16x32_bf16 v[28:31], v[208:211], v[176:179], v[28:31]
	v_mfma_f32_16x16x32_bf16 v[24:27], v[216:219], v[176:179], v[24:27]
	v_mfma_f32_16x16x32_bf16 v[12:15], v[208:211], v[200:203], v[12:15]
	v_mfma_f32_16x16x32_bf16 v[8:11], v[216:219], v[200:203], v[8:11]
	v_mfma_f32_16x16x32_bf16 v[60:63], v[212:215], v[160:163], v[60:63]
	v_mfma_f32_16x16x32_bf16 v[56:59], v[220:223], v[160:163], v[56:59]
	v_mfma_f32_16x16x32_bf16 v[44:47], v[212:215], v[172:175], v[44:47]
	v_mfma_f32_16x16x32_bf16 v[40:43], v[220:223], v[172:175], v[40:43]
	v_mfma_f32_16x16x32_bf16 v[28:31], v[212:215], v[196:199], v[28:31]
	v_mfma_f32_16x16x32_bf16 v[24:27], v[220:223], v[196:199], v[24:27]
	v_mfma_f32_16x16x32_bf16 v[12:15], v[212:215], v[204:207], v[12:15]
	v_mfma_f32_16x16x32_bf16 v[8:11], v[220:223], v[204:207], v[8:11]
	s_cbranch_scc0 .Ldb_PLE1_cont
	s_branch .Ldb_PLE1_xl
.LBB0_1283:
	s_add_u32 s4, s2, 0xfffc0080
	s_addc_u32 s5, s3, -1
	s_add_i32 s25, 0, 0x10000
	ds_read_b128 v[136:139], v255 offset:0
	ds_read_b128 v[140:143], v255 offset:1024
	ds_read_b128 v[144:147], v255 offset:2048
	ds_read_b128 v[148:151], v255 offset:3072
	s_cmp_eq_u32 s24, 12
	s_cselect_b32 s5, s19, s5
	s_cselect_b32 s4, s18, s4
	s_cselect_b32 s41, s21, s23
	s_cselect_b32 s40, s20, s22
	s_add_i32 m0, s29, 0xc000
	ds_read_b128 v[152:155], v182
	ds_read_b128 v[160:163], v182 offset:1024
	ds_read_b128 v[164:167], v182 offset:2048
	ds_read_b128 v[172:175], v182 offset:3072
	ds_read_b128 v[176:179], v182 offset:4096
	ds_read_b128 v[196:199], v182 offset:5120
	ds_read_b128 v[200:203], v182 offset:6144
	ds_read_b128 v[204:207], v182 offset:7168
	global_load_lds_dwordx4 v158, s[2:3]
	s_add_i32 m0, s29, 0xe000
	s_add_u32 vcc_lo, s2, s0
	s_addc_u32 vcc_hi, s3, s1
	global_load_lds_dwordx4 v158, vcc
	s_waitcnt lgkmcnt(8)
	s_barrier
	s_waitcnt lgkmcnt(0)
	v_mfma_f32_16x16x32_bf16 v[132:135], v[136:139], v[152:155], v[132:135]
	v_mfma_f32_16x16x32_bf16 v[128:131], v[144:147], v[152:155], v[128:131]
	v_mfma_f32_16x16x32_bf16 v[116:119], v[136:139], v[164:167], v[116:119]
	v_mfma_f32_16x16x32_bf16 v[112:115], v[144:147], v[164:167], v[112:115]
	v_mfma_f32_16x16x32_bf16 v[100:103], v[136:139], v[176:179], v[100:103]
	v_mfma_f32_16x16x32_bf16 v[96:99], v[144:147], v[176:179], v[96:99]
	v_mfma_f32_16x16x32_bf16 v[84:87], v[136:139], v[200:203], v[84:87]
	v_mfma_f32_16x16x32_bf16 v[80:83], v[144:147], v[200:203], v[80:83]
	v_mfma_f32_16x16x32_bf16 v[132:135], v[140:143], v[160:163], v[132:135]
	v_mfma_f32_16x16x32_bf16 v[128:131], v[148:151], v[160:163], v[128:131]
	v_mfma_f32_16x16x32_bf16 v[116:119], v[140:143], v[172:175], v[116:119]
	v_mfma_f32_16x16x32_bf16 v[112:115], v[148:151], v[172:175], v[112:115]
	v_mfma_f32_16x16x32_bf16 v[100:103], v[140:143], v[196:199], v[100:103]
	v_mfma_f32_16x16x32_bf16 v[96:99], v[148:151], v[196:199], v[96:99]
	v_mfma_f32_16x16x32_bf16 v[84:87], v[140:143], v[204:207], v[84:87]
	v_mfma_f32_16x16x32_bf16 v[80:83], v[148:151], v[204:207], v[80:83]
	s_barrier
	s_add_i32 s44, 0, 0x14000
	s_add_i32 s25, s25, s27
	s_mov_b32 m0, s25
	ds_read_b128 v[208:211], v255 offset:16384
	ds_read_b128 v[212:215], v255 offset:17408
	ds_read_b128 v[216:219], v255 offset:18432
	ds_read_b128 v[220:223], v255 offset:19456
	global_load_lds_dwordx4 v156, s[40:41]
	s_add_i32 m0, s25, 0x2000
	s_add_u32 vcc_lo, s40, s0
	s_addc_u32 vcc_hi, s41, s1
	global_load_lds_dwordx4 v156, vcc
	s_barrier
; #define G_STAGE(bufoff, gbase, o0, h64) do { \
;         __builtin_amdgcn_global_load_lds((const unsigned*)((const char*)(gbase) + (o0)), (LAS unsigned*)(lds + (bufoff) + ldsw), 16, 0, 0); \
;         __builtin_amdgcn_global_load_lds((const unsigned*)((const char*)(gbase) + (h64) + (o0)), (LAS unsigned*)(lds + (bufoff) + ldsw + 8192), 16, 0, 0); } while (0)
; #define G_LDA(dst, b, h) do { _Pragma("unroll") for (int m = 0; m < 4; ++m) _Pragma("unroll") for (int k = 0; k < 2; ++k) dst[m][k] = *(const LAS bf16x8*)(lds + G_SA(b, h) + aoff + m * 2048 + k * 1024); } while (0)
; #define G_LDB(dst, b, h) do { _Pragma("unroll") for (int n = 0; n < 2; ++n) _Pragma("unroll") for (int k = 0; k < 2; ++k) dst[n][k] = *(const LAS bf16x8*)(lds + G_SB(b, h) + boff + n * 2048 + k * 1024); } while (0)
; #define G_WAIT_V(n) asm volatile("s_waitcnt vmcnt(" #n ")" ::: "memory")
; #define G_BAR __builtin_amdgcn_s_barrier()
;     ...
;         for (int t = 0; t < nt; t += 2) {
;             const bool last = (t == nt - 2);
;             const char* a1 = cA + (size_t)(t + 1) * ckA;
;             const char* a2 = last ? nA : cA + (size_t)(t + 2) * ckA; const char* b2 = last ? nB : cB + (size_t)(t + 2) * kB;
;             const char* a3 = a2 + ckA; const char* b3 = b2 + kB;
;             G_LDB(B0, 0, 0); G_SCHED; G_LDA(At, 0, 0); G_STAGE(G_SA(1, 1), a1 + chA, cA0, qA);
;             G_WAIT_L(8); G_BAR; G_WAIT_L(0); G_MMA(0, 0, At, B0); G_BAR; G_SCHED;
;             G_LDB(B1, 0, 1); G_STAGE(G_SB(0, 0), b2, cB0, qB);
;             G_BAR; G_WAIT_L(0); G_MMA(0, 1, At, B1); G_BAR;
;             G_LDA(At, 0, 1); G_STAGE(G_SA(0, 0), a2, cA0, qA);
;             G_BAR; G_WAIT_L(0); G_MMA(1, 0, At, B0); G_BAR; G_SCHED;
;             G_STAGE(G_SB(0, 1), b2 + chB, cB0, qB);
;             G_WAIT_V(6); G_BAR; G_MMA(1, 1, At, B1); G_BAR;
;             G_LDB(B0, 1, 0); G_SCHED; G_LDA(At, 1, 0); G_STAGE(G_SA(0, 1), a2 + chA, cA0, qA);
;             G_WAIT_L(8); G_BAR; G_WAIT_L(0); G_MMA(0, 0, At, B0); G_BAR; G_SCHED;
;             G_LDB(B1, 1, 1); G_STAGE(G_SB(1, 0), b3, cB0, qB);
;             G_BAR; G_WAIT_L(0); G_MMA(0, 1, At, B1); G_BAR;
;             G_LDA(At, 1, 1); G_STAGE(G_SA(1, 0), a3, cA0, qA);
;             G_BAR; G_WAIT_L(0); G_MMA(1, 0, At, B0); G_BAR; G_SCHED;
;             G_STAGE(G_SB(1, 1), b3 + chB, cB0, qB);
;             G_WAIT_V(6); G_BAR; G_MMA(1, 1, At, B1); G_BAR;
	s_waitcnt lgkmcnt(0)
	v_mfma_f32_16x16x32_bf16 v[124:127], v[208:211], v[152:155], v[124:127]
	v_mfma_f32_16x16x32_bf16 v[120:123], v[216:219], v[152:155], v[120:123]
	v_mfma_f32_16x16x32_bf16 v[108:111], v[208:211], v[164:167], v[108:111]
	v_mfma_f32_16x16x32_bf16 v[104:107], v[216:219], v[164:167], v[104:107]
	v_mfma_f32_16x16x32_bf16 v[92:95], v[208:211], v[176:179], v[92:95]
	v_mfma_f32_16x16x32_bf16 v[88:91], v[216:219], v[176:179], v[88:91]
	v_mfma_f32_16x16x32_bf16 v[76:79], v[208:211], v[200:203], v[76:79]
	v_mfma_f32_16x16x32_bf16 v[72:75], v[216:219], v[200:203], v[72:75]
	v_mfma_f32_16x16x32_bf16 v[124:127], v[212:215], v[160:163], v[124:127]
	v_mfma_f32_16x16x32_bf16 v[120:123], v[220:223], v[160:163], v[120:123]
	v_mfma_f32_16x16x32_bf16 v[108:111], v[212:215], v[172:175], v[108:111]
	v_mfma_f32_16x16x32_bf16 v[104:107], v[220:223], v[172:175], v[104:107]
	v_mfma_f32_16x16x32_bf16 v[92:95], v[212:215], v[196:199], v[92:95]
	v_mfma_f32_16x16x32_bf16 v[88:91], v[220:223], v[196:199], v[88:91]
	v_mfma_f32_16x16x32_bf16 v[76:79], v[212:215], v[204:207], v[76:79]
	v_mfma_f32_16x16x32_bf16 v[72:75], v[220:223], v[204:207], v[72:75]
	s_barrier
	s_mov_b32 m0, s29
	v_lshl_add_u64 v[224:225], s[4:5], 0, v[2:3]
	ds_read_b128 v[152:155], v182 offset:16384
	ds_read_b128 v[160:163], v182 offset:17408
	ds_read_b128 v[164:167], v182 offset:18432
	ds_read_b128 v[172:175], v182 offset:19456
	ds_read_b128 v[176:179], v182 offset:20480
	ds_read_b128 v[196:199], v182 offset:21504
	ds_read_b128 v[200:203], v182 offset:22528
	ds_read_b128 v[204:207], v182 offset:23552
	global_load_lds_dwordx4 v2, s[4:5]
	s_mov_b32 m0, s30
	s_add_u32 vcc_lo, s4, s0
	s_addc_u32 vcc_hi, s5, s1
	global_load_lds_dwordx4 v2, vcc
	s_barrier
	s_waitcnt lgkmcnt(0)
	v_mfma_f32_16x16x32_bf16 v[68:71], v[136:139], v[152:155], v[68:71]
	v_mfma_f32_16x16x32_bf16 v[64:67], v[144:147], v[152:155], v[64:67]
	v_mfma_f32_16x16x32_bf16 v[52:55], v[136:139], v[164:167], v[52:55]
	v_mfma_f32_16x16x32_bf16 v[48:51], v[144:147], v[164:167], v[48:51]
	v_mfma_f32_16x16x32_bf16 v[36:39], v[136:139], v[176:179], v[36:39]
	v_mfma_f32_16x16x32_bf16 v[32:35], v[144:147], v[176:179], v[32:35]
	v_mfma_f32_16x16x32_bf16 v[20:23], v[136:139], v[200:203], v[20:23]
	v_mfma_f32_16x16x32_bf16 v[16:19], v[144:147], v[200:203], v[16:19]
	v_mfma_f32_16x16x32_bf16 v[68:71], v[140:143], v[160:163], v[68:71]
	v_mfma_f32_16x16x32_bf16 v[64:67], v[148:151], v[160:163], v[64:67]
	v_mfma_f32_16x16x32_bf16 v[52:55], v[140:143], v[172:175], v[52:55]
	v_mfma_f32_16x16x32_bf16 v[48:51], v[148:151], v[172:175], v[48:51]
	v_mfma_f32_16x16x32_bf16 v[36:39], v[140:143], v[196:199], v[36:39]
	v_mfma_f32_16x16x32_bf16 v[32:35], v[148:151], v[196:199], v[32:35]
	v_mfma_f32_16x16x32_bf16 v[20:23], v[140:143], v[204:207], v[20:23]
	v_mfma_f32_16x16x32_bf16 v[16:19], v[148:151], v[204:207], v[16:19]
	s_barrier
	s_add_i32 s100, s44, s27
	s_mov_b32 m0, s100
	s_add_u32 vcc_lo, s40, s54
	s_addc_u32 vcc_hi, s41, s55
	global_load_lds_dwordx4 v156, vcc
	s_add_i32 m0, s100, 0x2000
	s_add_u32 vcc_lo, s40, s58
	s_addc_u32 vcc_hi, s41, s59
	global_load_lds_dwordx4 v156, vcc
	s_waitcnt vmcnt(6)
	s_barrier
	v_mfma_f32_16x16x32_bf16 v[60:63], v[208:211], v[152:155], v[60:63]
	v_mfma_f32_16x16x32_bf16 v[56:59], v[216:219], v[152:155], v[56:59]
	v_mfma_f32_16x16x32_bf16 v[44:47], v[208:211], v[164:167], v[44:47]
	v_mfma_f32_16x16x32_bf16 v[40:43], v[216:219], v[164:167], v[40:43]
	v_mfma_f32_16x16x32_bf16 v[28:31], v[208:211], v[176:179], v[28:31]
	v_mfma_f32_16x16x32_bf16 v[24:27], v[216:219], v[176:179], v[24:27]
	v_mfma_f32_16x16x32_bf16 v[12:15], v[208:211], v[200:203], v[12:15]
	v_mfma_f32_16x16x32_bf16 v[8:11], v[216:219], v[200:203], v[8:11]
	v_mfma_f32_16x16x32_bf16 v[60:63], v[212:215], v[160:163], v[60:63]
	v_mfma_f32_16x16x32_bf16 v[56:59], v[220:223], v[160:163], v[56:59]
	v_mfma_f32_16x16x32_bf16 v[44:47], v[212:215], v[172:175], v[44:47]
	v_mfma_f32_16x16x32_bf16 v[40:43], v[220:223], v[172:175], v[40:43]
	v_mfma_f32_16x16x32_bf16 v[28:31], v[212:215], v[196:199], v[28:31]
	v_mfma_f32_16x16x32_bf16 v[24:27], v[220:223], v[196:199], v[24:27]
	v_mfma_f32_16x16x32_bf16 v[12:15], v[212:215], v[204:207], v[12:15]
	v_mfma_f32_16x16x32_bf16 v[8:11], v[220:223], v[204:207], v[8:11]
	s_barrier
	s_add_i32 s100, 0, 0x18000
	ds_read_b128 v[136:139], v255 offset:32768
	ds_read_b128 v[140:143], v255 offset:33792
	ds_read_b128 v[144:147], v255 offset:34816
	ds_read_b128 v[148:151], v255 offset:35840
	s_mov_b32 m0, s31
	ds_read_b128 v[152:155], v182 offset:32768
	ds_read_b128 v[160:163], v182 offset:33792
	ds_read_b128 v[164:167], v182 offset:34816
	ds_read_b128 v[172:175], v182 offset:35840
	ds_read_b128 v[176:179], v182 offset:36864
	ds_read_b128 v[196:199], v182 offset:37888
	ds_read_b128 v[200:203], v182 offset:38912
	ds_read_b128 v[204:207], v182 offset:39936
	s_add_u32 vcc_lo, s4, s54
	s_addc_u32 vcc_hi, s5, s55
	global_load_lds_dwordx4 v2, vcc
	s_mov_b32 m0, s34
	s_add_u32 vcc_lo, s4, s58
	s_addc_u32 vcc_hi, s5, s59
	global_load_lds_dwordx4 v2, vcc
	s_waitcnt lgkmcnt(8)
	s_barrier
; #define G_STAGE(bufoff, gbase, o0, h64) do { \
;         __builtin_amdgcn_global_load_lds((const unsigned*)((const char*)(gbase) + (o0)), (LAS unsigned*)(lds + (bufoff) + ldsw), 16, 0, 0); \
;         __builtin_amdgcn_global_load_lds((const unsigned*)((const char*)(gbase) + (h64) + (o0)), (LAS unsigned*)(lds + (bufoff) + ldsw + 8192), 16, 0, 0); } while (0)
; #define G_LDA(dst, b, h) do { _Pragma("unroll") for (int m = 0; m < 4; ++m) _Pragma("unroll") for (int k = 0; k < 2; ++k) dst[m][k] = *(const LAS bf16x8*)(lds + G_SA(b, h) + aoff + m * 2048 + k * 1024); } while (0)
; #define G_LDB(dst, b, h) do { _Pragma("unroll") for (int n = 0; n < 2; ++n) _Pragma("unroll") for (int k = 0; k < 2; ++k) dst[n][k] = *(const LAS bf16x8*)(lds + G_SB(b, h) + boff + n * 2048 + k * 1024); } while (0)
; #define G_WAIT_V(n) asm volatile("s_waitcnt vmcnt(" #n ")" ::: "memory")
; #define G_BAR __builtin_amdgcn_s_barrier()
;     ...
;         for (int t = 0; t < nt; t += 2) {
;             const bool last = (t == nt - 2);
;             const char* a1 = cA + (size_t)(t + 1) * ckA;
;             const char* a2 = last ? nA : cA + (size_t)(t + 2) * ckA; const char* b2 = last ? nB : cB + (size_t)(t + 2) * kB;
;             const char* a3 = a2 + ckA; const char* b3 = b2 + kB;
;             G_LDB(B0, 0, 0); G_SCHED; G_LDA(At, 0, 0); G_STAGE(G_SA(1, 1), a1 + chA, cA0, qA);
;             G_WAIT_L(8); G_BAR; G_WAIT_L(0); G_MMA(0, 0, At, B0); G_BAR; G_SCHED;
;             G_LDB(B1, 0, 1); G_STAGE(G_SB(0, 0), b2, cB0, qB);
;             G_BAR; G_WAIT_L(0); G_MMA(0, 1, At, B1); G_BAR;
;             G_LDA(At, 0, 1); G_STAGE(G_SA(0, 0), a2, cA0, qA);
;             G_BAR; G_WAIT_L(0); G_MMA(1, 0, At, B0); G_BAR; G_SCHED;
;             G_STAGE(G_SB(0, 1), b2 + chB, cB0, qB);
;             G_WAIT_V(6); G_BAR; G_MMA(1, 1, At, B1); G_BAR;
;             G_LDB(B0, 1, 0); G_SCHED; G_LDA(At, 1, 0); G_STAGE(G_SA(0, 1), a2 + chA, cA0, qA);
;             G_WAIT_L(8); G_BAR; G_WAIT_L(0); G_MMA(0, 0, At, B0); G_BAR; G_SCHED;
;             G_LDB(B1, 1, 1); G_STAGE(G_SB(1, 0), b3, cB0, qB);
;             G_BAR; G_WAIT_L(0); G_MMA(0, 1, At, B1); G_BAR;
;             G_LDA(At, 1, 1); G_STAGE(G_SA(1, 0), a3, cA0, qA);
;             G_BAR; G_WAIT_L(0); G_MMA(1, 0, At, B0); G_BAR; G_SCHED;
;             G_STAGE(G_SB(1, 1), b3 + chB, cB0, qB);
;             G_WAIT_V(6); G_BAR; G_MMA(1, 1, At, B1); G_BAR;
;         }
	s_waitcnt lgkmcnt(0)
	v_mfma_f32_16x16x32_bf16 v[132:135], v[136:139], v[152:155], v[132:135]
	v_mfma_f32_16x16x32_bf16 v[128:131], v[144:147], v[152:155], v[128:131]
	v_mfma_f32_16x16x32_bf16 v[116:119], v[136:139], v[164:167], v[116:119]
	v_mfma_f32_16x16x32_bf16 v[112:115], v[144:147], v[164:167], v[112:115]
	v_mfma_f32_16x16x32_bf16 v[100:103], v[136:139], v[176:179], v[100:103]
	v_mfma_f32_16x16x32_bf16 v[96:99], v[144:147], v[176:179], v[96:99]
	v_mfma_f32_16x16x32_bf16 v[84:87], v[136:139], v[200:203], v[84:87]
	v_mfma_f32_16x16x32_bf16 v[80:83], v[144:147], v[200:203], v[80:83]
	v_mfma_f32_16x16x32_bf16 v[132:135], v[140:143], v[160:163], v[132:135]
	v_mfma_f32_16x16x32_bf16 v[128:131], v[148:151], v[160:163], v[128:131]
	v_mfma_f32_16x16x32_bf16 v[116:119], v[140:143], v[172:175], v[116:119]
	v_mfma_f32_16x16x32_bf16 v[112:115], v[148:151], v[172:175], v[112:115]
	v_mfma_f32_16x16x32_bf16 v[100:103], v[140:143], v[196:199], v[100:103]
	v_mfma_f32_16x16x32_bf16 v[96:99], v[148:151], v[196:199], v[96:99]
	v_mfma_f32_16x16x32_bf16 v[84:87], v[140:143], v[204:207], v[84:87]
	v_mfma_f32_16x16x32_bf16 v[80:83], v[148:151], v[204:207], v[80:83]
	s_barrier
	s_add_i32 s5, 0, 0x1c000
	s_add_i32 s4, s100, s27
	s_mov_b32 m0, s4
	ds_read_b128 v[208:211], v255 offset:49152
	ds_read_b128 v[212:215], v255 offset:50176
	ds_read_b128 v[216:219], v255 offset:51200
	ds_read_b128 v[220:223], v255 offset:52224
	s_add_u32 vcc_lo, s40, s46
	s_addc_u32 vcc_hi, s41, s47
	global_load_lds_dwordx4 v156, vcc
	s_add_i32 m0, s4, 0x2000
	s_add_u32 vcc_lo, s40, s62
	s_addc_u32 vcc_hi, s41, s63
	global_load_lds_dwordx4 v156, vcc
	s_barrier
	s_waitcnt lgkmcnt(0)
	v_mfma_f32_16x16x32_bf16 v[124:127], v[208:211], v[152:155], v[124:127]
	v_mfma_f32_16x16x32_bf16 v[120:123], v[216:219], v[152:155], v[120:123]
	v_mfma_f32_16x16x32_bf16 v[108:111], v[208:211], v[164:167], v[108:111]
	v_mfma_f32_16x16x32_bf16 v[104:107], v[216:219], v[164:167], v[104:107]
	v_mfma_f32_16x16x32_bf16 v[92:95], v[208:211], v[176:179], v[92:95]
	v_mfma_f32_16x16x32_bf16 v[88:91], v[216:219], v[176:179], v[88:91]
	v_mfma_f32_16x16x32_bf16 v[76:79], v[208:211], v[200:203], v[76:79]
	v_mfma_f32_16x16x32_bf16 v[72:75], v[216:219], v[200:203], v[72:75]
	v_mfma_f32_16x16x32_bf16 v[124:127], v[212:215], v[160:163], v[124:127]
	v_mfma_f32_16x16x32_bf16 v[120:123], v[220:223], v[160:163], v[120:123]
	v_mfma_f32_16x16x32_bf16 v[108:111], v[212:215], v[172:175], v[108:111]
	v_mfma_f32_16x16x32_bf16 v[104:107], v[220:223], v[172:175], v[104:107]
	v_mfma_f32_16x16x32_bf16 v[92:95], v[212:215], v[196:199], v[92:95]
	v_mfma_f32_16x16x32_bf16 v[88:91], v[220:223], v[196:199], v[88:91]
	v_mfma_f32_16x16x32_bf16 v[76:79], v[212:215], v[204:207], v[76:79]
	v_mfma_f32_16x16x32_bf16 v[72:75], v[220:223], v[204:207], v[72:75]
	s_barrier
	s_mov_b32 m0, s35
	v_lshl_add_u64 v[226:227], v[224:225], 0, s[46:47]
	ds_read_b128 v[152:155], v182 offset:49152
	ds_read_b128 v[160:163], v182 offset:50176
	ds_read_b128 v[164:167], v182 offset:51200
	ds_read_b128 v[172:175], v182 offset:52224
	ds_read_b128 v[176:179], v182 offset:53248
	ds_read_b128 v[196:199], v182 offset:54272
	ds_read_b128 v[200:203], v182 offset:55296
	ds_read_b128 v[204:207], v182 offset:56320
	global_load_lds_dwordx4 v[226:227], off
	v_lshl_add_u64 v[224:225], v[224:225], 0, s[62:63]
	s_mov_b32 m0, s36
	s_nop 0
	global_load_lds_dwordx4 v[224:225], off
	s_barrier
	s_waitcnt lgkmcnt(0)
	v_mfma_f32_16x16x32_bf16 v[68:71], v[136:139], v[152:155], v[68:71]
	v_mfma_f32_16x16x32_bf16 v[64:67], v[144:147], v[152:155], v[64:67]
	v_mfma_f32_16x16x32_bf16 v[52:55], v[136:139], v[164:167], v[52:55]
	v_mfma_f32_16x16x32_bf16 v[48:51], v[144:147], v[164:167], v[48:51]
	v_mfma_f32_16x16x32_bf16 v[36:39], v[136:139], v[176:179], v[36:39]
	v_mfma_f32_16x16x32_bf16 v[32:35], v[144:147], v[176:179], v[32:35]
	v_mfma_f32_16x16x32_bf16 v[20:23], v[136:139], v[200:203], v[20:23]
	v_mfma_f32_16x16x32_bf16 v[16:19], v[144:147], v[200:203], v[16:19]
	v_mfma_f32_16x16x32_bf16 v[68:71], v[140:143], v[160:163], v[68:71]
	v_mfma_f32_16x16x32_bf16 v[64:67], v[148:151], v[160:163], v[64:67]
	v_mfma_f32_16x16x32_bf16 v[52:55], v[140:143], v[172:175], v[52:55]
	v_mfma_f32_16x16x32_bf16 v[48:51], v[148:151], v[172:175], v[48:51]
	v_mfma_f32_16x16x32_bf16 v[36:39], v[140:143], v[196:199], v[36:39]
	v_mfma_f32_16x16x32_bf16 v[32:35], v[148:151], v[196:199], v[32:35]
	v_mfma_f32_16x16x32_bf16 v[20:23], v[140:143], v[204:207], v[20:23]
	v_mfma_f32_16x16x32_bf16 v[16:19], v[148:151], v[204:207], v[16:19]
	s_barrier
	s_add_i32 s4, s5, s27
	s_mov_b32 m0, s4
	s_add_u32 vcc_lo, s40, s64
	s_addc_u32 vcc_hi, s41, s65
	global_load_lds_dwordx4 v156, vcc
	s_add_i32 m0, s4, 0x2000
	s_add_u32 vcc_lo, s40, s66
	s_addc_u32 vcc_hi, s41, s67
	global_load_lds_dwordx4 v156, vcc
	s_add_i32 s24, s24, 2
	s_add_u32 s2, s2, 0x100
	s_addc_u32 s3, s3, 0
	s_add_u32 s22, s22, 0x100
	s_addc_u32 s23, s23, 0
	s_cmp_gt_u32 s24, 13
	s_waitcnt vmcnt(6)
	s_barrier
	v_mfma_f32_16x16x32_bf16 v[60:63], v[208:211], v[152:155], v[60:63]
	v_mfma_f32_16x16x32_bf16 v[56:59], v[216:219], v[152:155], v[56:59]
	v_mfma_f32_16x16x32_bf16 v[44:47], v[208:211], v[164:167], v[44:47]
	v_mfma_f32_16x16x32_bf16 v[40:43], v[216:219], v[164:167], v[40:43]
	v_mfma_f32_16x16x32_bf16 v[28:31], v[208:211], v[176:179], v[28:31]
	v_mfma_f32_16x16x32_bf16 v[24:27], v[216:219], v[176:179], v[24:27]
	v_mfma_f32_16x16x32_bf16 v[12:15], v[208:211], v[200:203], v[12:15]
	v_mfma_f32_16x16x32_bf16 v[8:11], v[216:219], v[200:203], v[8:11]
	v_mfma_f32_16x16x32_bf16 v[60:63], v[212:215], v[160:163], v[60:63]
	v_mfma_f32_16x16x32_bf16 v[56:59], v[220:223], v[160:163], v[56:59]
	v_mfma_f32_16x16x32_bf16 v[44:47], v[212:215], v[172:175], v[44:47]
	v_mfma_f32_16x16x32_bf16 v[40:43], v[220:223], v[172:175], v[40:43]
	v_mfma_f32_16x16x32_bf16 v[28:31], v[212:215], v[196:199], v[28:31]
	v_mfma_f32_16x16x32_bf16 v[24:27], v[220:223], v[196:199], v[24:27]
	v_mfma_f32_16x16x32_bf16 v[12:15], v[212:215], v[204:207], v[12:15]
	v_mfma_f32_16x16x32_bf16 v[8:11], v[220:223], v[204:207], v[8:11]
	s_cbranch_scc0 .Ldb_PLE1_cont
